# GEMM K-loops: loop counter and pointer SALU moved above the iteration's closing barrier (loop-edge edit)
# baseline (speedup 1.0000x reference)
; #define PG8_STAGE(bufoff, gbase, voff) do { _Pragma("unroll") for (int _i = 0; _i < 2; ++_i) \
;         __builtin_amdgcn_global_load_lds((const unsigned*)((const char*)(gbase) + (voff)[_i]), (PG8_LAS unsigned*)(lds + (bufoff) + ldsw + _i * 8192), 16, 0, 0); } while (0)
; #define PG8_LDA(dst, b, h) do { _Pragma("unroll") for (int m = 0; m < 4; ++m) _Pragma("unroll") for (int k = 0; k < 2; ++k) dst[m][k] = *(const PG8_LAS bf16x8*)(lds + PG8_SA(b, h) + aoff + m * 2048 + k * 1024); } while (0)
; #define PG8_LDB(dst, b, h) do { _Pragma("unroll") for (int n = 0; n < 2; ++n) _Pragma("unroll") for (int k = 0; k < 2; ++k) dst[n][k] = *(const PG8_LAS bf16x8*)(lds + PG8_SB(b, h) + boff + n * 2048 + k * 1024); } while (0)
; #define PG8_MMA(ai, bj, At, Bt) do { __builtin_amdgcn_s_setprio(1); _Pragma("unroll") for (int m = 0; m < 4; ++m) _Pragma("unroll") for (int n = 0; n < 2; ++n) _Pragma("unroll") for (int k = 0; k < 2; ++k) \
;         acc[ai][bj][m][n] = __builtin_amdgcn_mfma_f32_16x16x32_bf16(Bt[n][k], At[m][k], acc[ai][bj][m][n], 0, 0, 0); __builtin_amdgcn_s_setprio(0); } while (0)
; #define PG8_WAIT_V(n) asm volatile("s_waitcnt vmcnt(" #n ")" ::: "memory")
; #define PG8_WAIT_L(n) asm volatile("s_waitcnt lgkmcnt(" #n ")" ::: "memory")
; template <class Epi, class Sched, bool ALIGN_EPI = false, bool SP2 = false>
; __device__ __forceinline__ void gemm_phase(PG8_LAS unsigned char* lds, const Gemm g, const Sched S, const Epi E) {
;     ...
;             const bool last = (t == nt - 2);
;             const char* a1 = cA + (size_t)(t + 1) * kstepA;
;             const char* a2 = last ? nA : cA + (size_t)(t + 2) * kstepA; const char* b2 = last ? nB : cB + (size_t)(t + 2) * kstep;
;             const char* a3 = a2 + kstepA; const char* b3 = b2 + kstep;
;             if (last && has_next) S.a_ready(nxt);
;             if constexpr (SP2) {
;             PG8_LDB(B0, 0, 0); PG8_LDB(B1, 0, 1); PG8_SCHED; PG8_LDA(At, 0, 0); PG8_STAGE(PG8_SA(1, 1), a1 + hstepA, voffA);
;             PG8_WAIT_V(8); PG8_WAIT_L(0); PG8_BAR; PG8_MMA(0, 0, At, B0); PG8_MMA(0, 1, At, B1); PG8_BAR; PG8_SCHED;
;             PG8_LDA(At, 0, 1); PG8_STAGE(PG8_SB(0, 0), b2, voffB); PG8_STAGE(PG8_SB(0, 1), b2 + hstep, voffB); PG8_STAGE(PG8_SA(0, 0), a2, voffA);
;             PG8_WAIT_V(8); PG8_WAIT_L(0); PG8_BAR; PG8_MMA(1, 0, At, B0); PG8_MMA(1, 1, At, B1); PG8_BAR; PG8_SCHED;
.LBB0_92:
	ds_read_b128 v[154:157], v150
	ds_read_b128 v[158:161], v150 offset:1024
	ds_read_b128 v[162:165], v150 offset:2048
	ds_read_b128 v[166:169], v150 offset:3072
	ds_read_b128 v[170:173], v151
	ds_read_b128 v[174:177], v151 offset:1024
	ds_read_b128 v[178:181], v151 offset:2048
	ds_read_b128 v[182:185], v151 offset:3072
	s_add_u32 s46, s44, 0xfffc0080
	s_addc_u32 s47, s45, -1
	s_cmp_eq_u32 s84, 12
	s_cselect_b32 s61, s37, s47
	s_cselect_b32 s60, s80, s46
	s_cselect_b32 s47, s35, s83
	s_cselect_b32 s46, s81, s82
	v_lshl_add_u64 v[144:145], s[44:45], 0, v[136:137]
	s_add_i32 m0, s43, 0xc000
	ds_read_b128 v[186:189], v152
	ds_read_b128 v[190:193], v152 offset:1024
	ds_read_b128 v[194:197], v152 offset:2048
	ds_read_b128 v[198:201], v152 offset:3072
	ds_read_b128 v[206:209], v152 offset:4096
	ds_read_b128 v[210:213], v152 offset:5120
	ds_read_b128 v[214:217], v152 offset:6144
	ds_read_b128 v[218:221], v152 offset:7168
	global_load_lds_dwordx4 v[144:145], off
	v_lshl_add_u64 v[144:145], s[44:45], 0, v[138:139]
	s_add_i32 m0, s43, 0xe000
	s_nop 0
	global_load_lds_dwordx4 v[144:145], off
	s_waitcnt vmcnt(8)
	s_waitcnt lgkmcnt(0)
	s_barrier
	s_setprio 1
	s_waitcnt lgkmcnt(0)
	v_mfma_f32_16x16x32_bf16 v[124:127], v[154:157], v[186:189], v[124:127]
	v_mfma_f32_16x16x32_bf16 v[120:123], v[162:165], v[186:189], v[120:123]
	v_mfma_f32_16x16x32_bf16 v[112:115], v[154:157], v[194:197], v[112:115]
	v_mfma_f32_16x16x32_bf16 v[104:107], v[162:165], v[194:197], v[104:107]
	v_mfma_f32_16x16x32_bf16 v[96:99], v[154:157], v[206:209], v[96:99]
	v_mfma_f32_16x16x32_bf16 v[88:91], v[162:165], v[206:209], v[88:91]
	v_mfma_f32_16x16x32_bf16 v[80:83], v[154:157], v[214:217], v[80:83]
	v_mfma_f32_16x16x32_bf16 v[72:75], v[162:165], v[214:217], v[72:75]
	v_mfma_f32_16x16x32_bf16 v[124:127], v[158:161], v[190:193], v[124:127]
	v_mfma_f32_16x16x32_bf16 v[120:123], v[166:169], v[190:193], v[120:123]
	v_mfma_f32_16x16x32_bf16 v[112:115], v[158:161], v[198:201], v[112:115]
	v_mfma_f32_16x16x32_bf16 v[104:107], v[166:169], v[198:201], v[104:107]
	v_mfma_f32_16x16x32_bf16 v[96:99], v[158:161], v[210:213], v[96:99]
	v_mfma_f32_16x16x32_bf16 v[88:91], v[166:169], v[210:213], v[88:91]
	v_mfma_f32_16x16x32_bf16 v[80:83], v[158:161], v[218:221], v[80:83]
	v_mfma_f32_16x16x32_bf16 v[72:75], v[166:169], v[218:221], v[72:75]
	s_setprio 0
	s_setprio 1
	v_mfma_f32_16x16x32_bf16 v[116:119], v[170:173], v[186:189], v[116:119]
	v_mfma_f32_16x16x32_bf16 v[108:111], v[178:181], v[186:189], v[108:111]
	v_mfma_f32_16x16x32_bf16 v[100:103], v[170:173], v[194:197], v[100:103]
	v_mfma_f32_16x16x32_bf16 v[92:95], v[178:181], v[194:197], v[92:95]
	v_mfma_f32_16x16x32_bf16 v[84:87], v[170:173], v[206:209], v[84:87]
	v_mfma_f32_16x16x32_bf16 v[76:79], v[178:181], v[206:209], v[76:79]
	v_mfma_f32_16x16x32_bf16 v[68:71], v[170:173], v[214:217], v[68:71]
	v_mfma_f32_16x16x32_bf16 v[64:67], v[178:181], v[214:217], v[64:67]
	v_mfma_f32_16x16x32_bf16 v[116:119], v[174:177], v[190:193], v[116:119]
	v_mfma_f32_16x16x32_bf16 v[108:111], v[182:185], v[190:193], v[108:111]
	v_mfma_f32_16x16x32_bf16 v[100:103], v[174:177], v[198:201], v[100:103]
	v_mfma_f32_16x16x32_bf16 v[92:95], v[182:185], v[198:201], v[92:95]
	v_mfma_f32_16x16x32_bf16 v[84:87], v[174:177], v[210:213], v[84:87]
	v_mfma_f32_16x16x32_bf16 v[76:79], v[182:185], v[210:213], v[76:79]
	v_mfma_f32_16x16x32_bf16 v[68:71], v[174:177], v[218:221], v[68:71]
	v_mfma_f32_16x16x32_bf16 v[64:67], v[182:185], v[218:221], v[64:67]
	s_setprio 0
	s_barrier
	s_add_i32 s85, s69, s33
	v_lshl_add_u64 v[144:145], s[46:47], 0, v[130:131]
	s_mov_b32 m0, s85
	ds_read_b128 v[186:189], v152 offset:16384
	ds_read_b128 v[190:193], v152 offset:17408
	ds_read_b128 v[194:197], v152 offset:18432
	ds_read_b128 v[198:201], v152 offset:19456
	ds_read_b128 v[206:209], v152 offset:20480
	ds_read_b128 v[210:213], v152 offset:21504
	ds_read_b128 v[214:217], v152 offset:22528
	ds_read_b128 v[218:221], v152 offset:23552
	global_load_lds_dwordx4 v[144:145], off
	s_add_i32 m0, s85, 0x2000
	s_add_u32 s86, s46, 0x40000
	v_lshl_add_u64 v[202:203], s[46:47], 0, v[134:135]
	s_addc_u32 s87, s47, 0
	s_add_i32 s85, s70, s33
	global_load_lds_dwordx4 v[202:203], off
	v_lshl_add_u64 v[222:223], s[86:87], 0, v[130:131]
	s_mov_b32 m0, s85
	v_lshl_add_u64 v[224:225], s[60:61], 0, v[132:133]
	global_load_lds_dwordx4 v[222:223], off
	v_lshl_add_u64 v[222:223], s[86:87], 0, v[134:135]
	s_add_i32 m0, s85, 0x2000
	s_nop 0
	global_load_lds_dwordx4 v[222:223], off
	v_lshl_add_u64 v[222:223], s[60:61], 0, v[128:129]
	s_mov_b32 m0, s43
	s_nop 0
	global_load_lds_dwordx4 v[222:223], off
	s_mov_b32 m0, s54
	s_nop 0
	global_load_lds_dwordx4 v[224:225], off
	s_waitcnt vmcnt(8)
	s_waitcnt lgkmcnt(0)
	s_barrier
; #define PG8_STAGE(bufoff, gbase, voff) do { _Pragma("unroll") for (int _i = 0; _i < 2; ++_i) \
;         __builtin_amdgcn_global_load_lds((const unsigned*)((const char*)(gbase) + (voff)[_i]), (PG8_LAS unsigned*)(lds + (bufoff) + ldsw + _i * 8192), 16, 0, 0); } while (0)
; #define PG8_LDA(dst, b, h) do { _Pragma("unroll") for (int m = 0; m < 4; ++m) _Pragma("unroll") for (int k = 0; k < 2; ++k) dst[m][k] = *(const PG8_LAS bf16x8*)(lds + PG8_SA(b, h) + aoff + m * 2048 + k * 1024); } while (0)
; #define PG8_LDB(dst, b, h) do { _Pragma("unroll") for (int n = 0; n < 2; ++n) _Pragma("unroll") for (int k = 0; k < 2; ++k) dst[n][k] = *(const PG8_LAS bf16x8*)(lds + PG8_SB(b, h) + boff + n * 2048 + k * 1024); } while (0)
; #define PG8_MMA(ai, bj, At, Bt) do { __builtin_amdgcn_s_setprio(1); _Pragma("unroll") for (int m = 0; m < 4; ++m) _Pragma("unroll") for (int n = 0; n < 2; ++n) _Pragma("unroll") for (int k = 0; k < 2; ++k) \
;         acc[ai][bj][m][n] = __builtin_amdgcn_mfma_f32_16x16x32_bf16(Bt[n][k], At[m][k], acc[ai][bj][m][n], 0, 0, 0); __builtin_amdgcn_s_setprio(0); } while (0)
; #define PG8_WAIT_V(n) asm volatile("s_waitcnt vmcnt(" #n ")" ::: "memory")
; #define PG8_WAIT_L(n) asm volatile("s_waitcnt lgkmcnt(" #n ")" ::: "memory")
; #define PG8_BAR __builtin_amdgcn_s_barrier()
; #define PG8_SCHED __builtin_amdgcn_sched_barrier(0)
; template <class Epi, class Sched, bool ALIGN_EPI = false, bool SP2 = false>
; __device__ __forceinline__ void gemm_phase(PG8_LAS unsigned char* lds, const Gemm g, const Sched S, const Epi E) {
;     ...
;             PG8_WAIT_V(8); PG8_WAIT_L(0); PG8_BAR; PG8_MMA(1, 0, At, B0); PG8_MMA(1, 1, At, B1); PG8_BAR; PG8_SCHED;
;             PG8_LDB(B0, 1, 0); PG8_LDB(B1, 1, 1); PG8_SCHED; PG8_LDA(At, 1, 0); PG8_STAGE(PG8_SA(0, 1), a2 + hstepA, voffA);
;             PG8_WAIT_V(8); PG8_WAIT_L(0); PG8_BAR; PG8_MMA(0, 0, At, B0); PG8_MMA(0, 1, At, B1); PG8_BAR; PG8_SCHED;
	s_setprio 1
	s_waitcnt lgkmcnt(0)
	v_mfma_f32_16x16x32_bf16 v[60:63], v[154:157], v[186:189], v[60:63]
	v_mfma_f32_16x16x32_bf16 v[56:59], v[162:165], v[186:189], v[56:59]
	v_mfma_f32_16x16x32_bf16 v[48:51], v[154:157], v[194:197], v[48:51]
	v_mfma_f32_16x16x32_bf16 v[40:43], v[162:165], v[194:197], v[40:43]
	v_mfma_f32_16x16x32_bf16 v[32:35], v[154:157], v[206:209], v[32:35]
	v_mfma_f32_16x16x32_bf16 v[24:27], v[162:165], v[206:209], v[24:27]
	v_mfma_f32_16x16x32_bf16 v[16:19], v[154:157], v[214:217], v[16:19]
	v_mfma_f32_16x16x32_bf16 v[8:11], v[162:165], v[214:217], v[8:11]
	v_mfma_f32_16x16x32_bf16 v[60:63], v[158:161], v[190:193], v[60:63]
	v_mfma_f32_16x16x32_bf16 v[56:59], v[166:169], v[190:193], v[56:59]
	v_mfma_f32_16x16x32_bf16 v[48:51], v[158:161], v[198:201], v[48:51]
	v_mfma_f32_16x16x32_bf16 v[40:43], v[166:169], v[198:201], v[40:43]
	v_mfma_f32_16x16x32_bf16 v[32:35], v[158:161], v[210:213], v[32:35]
	v_mfma_f32_16x16x32_bf16 v[24:27], v[166:169], v[210:213], v[24:27]
	v_mfma_f32_16x16x32_bf16 v[16:19], v[158:161], v[218:221], v[16:19]
	v_mfma_f32_16x16x32_bf16 v[8:11], v[166:169], v[218:221], v[8:11]
	s_setprio 0
	s_setprio 1
	v_mfma_f32_16x16x32_bf16 v[52:55], v[170:173], v[186:189], v[52:55]
	v_mfma_f32_16x16x32_bf16 v[44:47], v[178:181], v[186:189], v[44:47]
	v_mfma_f32_16x16x32_bf16 v[36:39], v[170:173], v[194:197], v[36:39]
	v_mfma_f32_16x16x32_bf16 v[28:31], v[178:181], v[194:197], v[28:31]
	v_mfma_f32_16x16x32_bf16 v[20:23], v[170:173], v[206:209], v[20:23]
	v_mfma_f32_16x16x32_bf16 v[12:15], v[178:181], v[206:209], v[12:15]
	v_mfma_f32_16x16x32_bf16 v[4:7], v[170:173], v[214:217], v[4:7]
	v_mfma_f32_16x16x32_bf16 v[0:3], v[178:181], v[214:217], v[0:3]
	v_mfma_f32_16x16x32_bf16 v[52:55], v[174:177], v[190:193], v[52:55]
	v_mfma_f32_16x16x32_bf16 v[44:47], v[182:185], v[190:193], v[44:47]
	v_mfma_f32_16x16x32_bf16 v[36:39], v[174:177], v[198:201], v[36:39]
	v_mfma_f32_16x16x32_bf16 v[28:31], v[182:185], v[198:201], v[28:31]
	v_mfma_f32_16x16x32_bf16 v[20:23], v[174:177], v[210:213], v[20:23]
	v_mfma_f32_16x16x32_bf16 v[12:15], v[182:185], v[210:213], v[12:15]
	v_mfma_f32_16x16x32_bf16 v[4:7], v[174:177], v[218:221], v[4:7]
	v_mfma_f32_16x16x32_bf16 v[0:3], v[182:185], v[218:221], v[0:3]
	s_setprio 0
	s_barrier
	s_add_i32 s85, 0, 0x18000
	v_add_u32_e32 v153, s85, v149
	s_add_i32 s86, 0, 0x1c000
	ds_read_b128 v[154:157], v153
	ds_read_b128 v[158:161], v153 offset:1024
	ds_read_b128 v[162:165], v153 offset:2048
	ds_read_b128 v[166:169], v153 offset:3072
	v_add_u32_e32 v153, s86, v149
	ds_read_b128 v[170:173], v153
	ds_read_b128 v[174:177], v153 offset:1024
	ds_read_b128 v[178:181], v153 offset:2048
	ds_read_b128 v[182:185], v153 offset:3072
	s_add_u32 s60, s60, 0x40000
	s_addc_u32 s61, s61, 0
	s_mov_b32 m0, s55
	v_lshl_add_u64 v[226:227], s[60:61], 0, v[128:129]
	ds_read_b128 v[186:189], v152 offset:32768
	ds_read_b128 v[190:193], v152 offset:33792
	ds_read_b128 v[194:197], v152 offset:34816
	ds_read_b128 v[198:201], v152 offset:35840
	ds_read_b128 v[206:209], v152 offset:36864
	ds_read_b128 v[210:213], v152 offset:37888
	ds_read_b128 v[214:217], v152 offset:38912
	ds_read_b128 v[218:221], v152 offset:39936
	global_load_lds_dwordx4 v[226:227], off
	v_lshl_add_u64 v[226:227], s[60:61], 0, v[132:133]
	s_mov_b32 m0, s62
	s_nop 0
	global_load_lds_dwordx4 v[226:227], off
	s_waitcnt vmcnt(8)
	s_waitcnt lgkmcnt(0)
	s_barrier
	s_setprio 1
	s_waitcnt lgkmcnt(0)
	v_mfma_f32_16x16x32_bf16 v[124:127], v[154:157], v[186:189], v[124:127]
	v_mfma_f32_16x16x32_bf16 v[120:123], v[162:165], v[186:189], v[120:123]
	v_mfma_f32_16x16x32_bf16 v[112:115], v[154:157], v[194:197], v[112:115]
	v_mfma_f32_16x16x32_bf16 v[104:107], v[162:165], v[194:197], v[104:107]
	v_mfma_f32_16x16x32_bf16 v[96:99], v[154:157], v[206:209], v[96:99]
	v_mfma_f32_16x16x32_bf16 v[88:91], v[162:165], v[206:209], v[88:91]
	v_mfma_f32_16x16x32_bf16 v[80:83], v[154:157], v[214:217], v[80:83]
	v_mfma_f32_16x16x32_bf16 v[72:75], v[162:165], v[214:217], v[72:75]
	v_mfma_f32_16x16x32_bf16 v[124:127], v[158:161], v[190:193], v[124:127]
	v_mfma_f32_16x16x32_bf16 v[120:123], v[166:169], v[190:193], v[120:123]
	v_mfma_f32_16x16x32_bf16 v[112:115], v[158:161], v[198:201], v[112:115]
	v_mfma_f32_16x16x32_bf16 v[104:107], v[166:169], v[198:201], v[104:107]
	v_mfma_f32_16x16x32_bf16 v[96:99], v[158:161], v[210:213], v[96:99]
	v_mfma_f32_16x16x32_bf16 v[88:91], v[166:169], v[210:213], v[88:91]
	v_mfma_f32_16x16x32_bf16 v[80:83], v[158:161], v[218:221], v[80:83]
	v_mfma_f32_16x16x32_bf16 v[72:75], v[166:169], v[218:221], v[72:75]
	s_setprio 0
	s_setprio 1
	v_mfma_f32_16x16x32_bf16 v[116:119], v[170:173], v[186:189], v[116:119]
	v_mfma_f32_16x16x32_bf16 v[108:111], v[178:181], v[186:189], v[108:111]
	v_mfma_f32_16x16x32_bf16 v[100:103], v[170:173], v[194:197], v[100:103]
	v_mfma_f32_16x16x32_bf16 v[92:95], v[178:181], v[194:197], v[92:95]
	v_mfma_f32_16x16x32_bf16 v[84:87], v[170:173], v[206:209], v[84:87]
	v_mfma_f32_16x16x32_bf16 v[76:79], v[178:181], v[206:209], v[76:79]
	v_mfma_f32_16x16x32_bf16 v[68:71], v[170:173], v[214:217], v[68:71]
	v_mfma_f32_16x16x32_bf16 v[64:67], v[178:181], v[214:217], v[64:67]
	v_mfma_f32_16x16x32_bf16 v[116:119], v[174:177], v[190:193], v[116:119]
	v_mfma_f32_16x16x32_bf16 v[108:111], v[182:185], v[190:193], v[108:111]
	v_mfma_f32_16x16x32_bf16 v[100:103], v[174:177], v[198:201], v[100:103]
	v_mfma_f32_16x16x32_bf16 v[92:95], v[182:185], v[198:201], v[92:95]
	v_mfma_f32_16x16x32_bf16 v[84:87], v[174:177], v[210:213], v[84:87]
	v_mfma_f32_16x16x32_bf16 v[76:79], v[182:185], v[210:213], v[76:79]
	v_mfma_f32_16x16x32_bf16 v[68:71], v[174:177], v[218:221], v[68:71]
	v_mfma_f32_16x16x32_bf16 v[64:67], v[182:185], v[218:221], v[64:67]
	s_setprio 0
	s_barrier
; #define PG8_STAGE(bufoff, gbase, voff) do { _Pragma("unroll") for (int _i = 0; _i < 2; ++_i) \
;         __builtin_amdgcn_global_load_lds((const unsigned*)((const char*)(gbase) + (voff)[_i]), (PG8_LAS unsigned*)(lds + (bufoff) + ldsw + _i * 8192), 16, 0, 0); } while (0)
; #define PG8_LDA(dst, b, h) do { _Pragma("unroll") for (int m = 0; m < 4; ++m) _Pragma("unroll") for (int k = 0; k < 2; ++k) dst[m][k] = *(const PG8_LAS bf16x8*)(lds + PG8_SA(b, h) + aoff + m * 2048 + k * 1024); } while (0)
; #define PG8_MMA(ai, bj, At, Bt) do { __builtin_amdgcn_s_setprio(1); _Pragma("unroll") for (int m = 0; m < 4; ++m) _Pragma("unroll") for (int n = 0; n < 2; ++n) _Pragma("unroll") for (int k = 0; k < 2; ++k) \
;         acc[ai][bj][m][n] = __builtin_amdgcn_mfma_f32_16x16x32_bf16(Bt[n][k], At[m][k], acc[ai][bj][m][n], 0, 0, 0); __builtin_amdgcn_s_setprio(0); } while (0)
; #define PG8_WAIT_V(n) asm volatile("s_waitcnt vmcnt(" #n ")" ::: "memory")
; #define PG8_WAIT_L(n) asm volatile("s_waitcnt lgkmcnt(" #n ")" ::: "memory")
; #define PG8_BAR __builtin_amdgcn_s_barrier()
; #define PG8_SCHED __builtin_amdgcn_sched_barrier(0)
; template <class Epi, class Sched, bool ALIGN_EPI = false, bool SP2 = false>
; __device__ __forceinline__ void gemm_phase(PG8_LAS unsigned char* lds, const Gemm g, const Sched S, const Epi E) {
;     ...
;         for (int t = 0; t < nt; t += 2) {
;     ...
;             PG8_LDA(At, 1, 1); PG8_STAGE(PG8_SB(1, 0), b3, voffB); PG8_STAGE(PG8_SB(1, 1), b3 + hstep, voffB); PG8_STAGE(PG8_SA(1, 0), a3, voffA);
;             PG8_WAIT_V(8); PG8_WAIT_L(0); PG8_BAR; PG8_MMA(1, 0, At, B0); PG8_MMA(1, 1, At, B1); PG8_BAR; PG8_SCHED;
	s_add_i32 s60, s85, s33
	v_lshl_add_u64 v[144:145], v[144:145], 0, s[6:7]
	s_mov_b32 m0, s60
	ds_read_b128 v[186:189], v152 offset:49152
	ds_read_b128 v[190:193], v152 offset:50176
	ds_read_b128 v[194:197], v152 offset:51200
	ds_read_b128 v[198:201], v152 offset:52224
	ds_read_b128 v[206:209], v152 offset:53248
	ds_read_b128 v[210:213], v152 offset:54272
	ds_read_b128 v[214:217], v152 offset:55296
	ds_read_b128 v[218:221], v152 offset:56320
	global_load_lds_dwordx4 v[144:145], off
	s_add_i32 m0, s60, 0x2000
	s_add_u32 s46, s46, 0x40080
	v_lshl_add_u64 v[144:145], v[202:203], 0, s[6:7]
	s_addc_u32 s47, s47, 0
	s_add_i32 s60, s86, s33
	global_load_lds_dwordx4 v[144:145], off
	v_lshl_add_u64 v[144:145], s[46:47], 0, v[130:131]
	s_mov_b32 m0, s60
	s_nop 0
	global_load_lds_dwordx4 v[144:145], off
	v_lshl_add_u64 v[144:145], s[46:47], 0, v[134:135]
	s_add_i32 m0, s60, 0x2000
	s_nop 0
	global_load_lds_dwordx4 v[144:145], off
	v_lshl_add_u64 v[144:145], v[222:223], 0, s[6:7]
	s_mov_b32 m0, s67
	s_nop 0
	global_load_lds_dwordx4 v[144:145], off
	v_lshl_add_u64 v[144:145], v[224:225], 0, s[6:7]
	s_mov_b32 m0, s68
	s_nop 0
	global_load_lds_dwordx4 v[144:145], off
	s_waitcnt vmcnt(8)
	s_waitcnt lgkmcnt(0)
	s_barrier
	s_setprio 1
	s_waitcnt lgkmcnt(0)
	v_mfma_f32_16x16x32_bf16 v[60:63], v[154:157], v[186:189], v[60:63]
	v_mfma_f32_16x16x32_bf16 v[56:59], v[162:165], v[186:189], v[56:59]
	v_mfma_f32_16x16x32_bf16 v[48:51], v[154:157], v[194:197], v[48:51]
	v_mfma_f32_16x16x32_bf16 v[40:43], v[162:165], v[194:197], v[40:43]
	v_mfma_f32_16x16x32_bf16 v[32:35], v[154:157], v[206:209], v[32:35]
	v_mfma_f32_16x16x32_bf16 v[24:27], v[162:165], v[206:209], v[24:27]
	v_mfma_f32_16x16x32_bf16 v[16:19], v[154:157], v[214:217], v[16:19]
	v_mfma_f32_16x16x32_bf16 v[8:11], v[162:165], v[214:217], v[8:11]
	v_mfma_f32_16x16x32_bf16 v[60:63], v[158:161], v[190:193], v[60:63]
	v_mfma_f32_16x16x32_bf16 v[56:59], v[166:169], v[190:193], v[56:59]
	v_mfma_f32_16x16x32_bf16 v[48:51], v[158:161], v[198:201], v[48:51]
	v_mfma_f32_16x16x32_bf16 v[40:43], v[166:169], v[198:201], v[40:43]
	v_mfma_f32_16x16x32_bf16 v[32:35], v[158:161], v[210:213], v[32:35]
	v_mfma_f32_16x16x32_bf16 v[24:27], v[166:169], v[210:213], v[24:27]
	v_mfma_f32_16x16x32_bf16 v[16:19], v[158:161], v[218:221], v[16:19]
	v_mfma_f32_16x16x32_bf16 v[8:11], v[166:169], v[218:221], v[8:11]
	s_setprio 0
	s_setprio 1
	v_mfma_f32_16x16x32_bf16 v[52:55], v[170:173], v[186:189], v[52:55]
	v_mfma_f32_16x16x32_bf16 v[44:47], v[178:181], v[186:189], v[44:47]
	v_mfma_f32_16x16x32_bf16 v[36:39], v[170:173], v[194:197], v[36:39]
	v_mfma_f32_16x16x32_bf16 v[28:31], v[178:181], v[194:197], v[28:31]
	v_mfma_f32_16x16x32_bf16 v[20:23], v[170:173], v[206:209], v[20:23]
	v_mfma_f32_16x16x32_bf16 v[12:15], v[178:181], v[206:209], v[12:15]
	v_mfma_f32_16x16x32_bf16 v[4:7], v[170:173], v[214:217], v[4:7]
	v_mfma_f32_16x16x32_bf16 v[0:3], v[178:181], v[214:217], v[0:3]
	v_mfma_f32_16x16x32_bf16 v[52:55], v[174:177], v[190:193], v[52:55]
	v_mfma_f32_16x16x32_bf16 v[44:47], v[182:185], v[190:193], v[44:47]
	v_mfma_f32_16x16x32_bf16 v[36:39], v[174:177], v[198:201], v[36:39]
	v_mfma_f32_16x16x32_bf16 v[28:31], v[182:185], v[198:201], v[28:31]
	v_mfma_f32_16x16x32_bf16 v[20:23], v[174:177], v[210:213], v[20:23]
	v_mfma_f32_16x16x32_bf16 v[12:15], v[182:185], v[210:213], v[12:15]
	v_mfma_f32_16x16x32_bf16 v[4:7], v[174:177], v[218:221], v[4:7]
	v_mfma_f32_16x16x32_bf16 v[0:3], v[182:185], v[218:221], v[0:3]
	s_setprio 0
	s_add_i32 s84, s84, 2
	s_add_u32 s44, s44, 0x100
	s_addc_u32 s45, s45, 0
	s_add_u32 s82, s82, 0x100
	s_addc_u32 s83, s83, 0
	s_cmp_gt_u32 s84, 13
	s_barrier
	s_cbranch_scc0 .LBB0_92
	s_and_b64 vcc, exec, s[8:9]
	s_cbranch_vccz .LBB0_95
	s_barrier

; #define PG8_STAGE(bufoff, gbase, voff) do { _Pragma("unroll") for (int _i = 0; _i < 2; ++_i) \
;         __builtin_amdgcn_global_load_lds((const unsigned*)((const char*)(gbase) + (voff)[_i]), (PG8_LAS unsigned*)(lds + (bufoff) + ldsw + _i * 8192), 16, 0, 0); } while (0)
; #define PG8_LDA(dst, b, h) do { _Pragma("unroll") for (int m = 0; m < 4; ++m) _Pragma("unroll") for (int k = 0; k < 2; ++k) dst[m][k] = *(const PG8_LAS bf16x8*)(lds + PG8_SA(b, h) + aoff + m * 2048 + k * 1024); } while (0)
; #define PG8_LDB(dst, b, h) do { _Pragma("unroll") for (int n = 0; n < 2; ++n) _Pragma("unroll") for (int k = 0; k < 2; ++k) dst[n][k] = *(const PG8_LAS bf16x8*)(lds + PG8_SB(b, h) + boff + n * 2048 + k * 1024); } while (0)
; #define PG8_MMA(ai, bj, At, Bt) do { __builtin_amdgcn_s_setprio(1); _Pragma("unroll") for (int m = 0; m < 4; ++m) _Pragma("unroll") for (int n = 0; n < 2; ++n) _Pragma("unroll") for (int k = 0; k < 2; ++k) \
;         acc[ai][bj][m][n] = __builtin_amdgcn_mfma_f32_16x16x32_bf16(Bt[n][k], At[m][k], acc[ai][bj][m][n], 0, 0, 0); __builtin_amdgcn_s_setprio(0); } while (0)
; #define PG8_WAIT_V(n) asm volatile("s_waitcnt vmcnt(" #n ")" ::: "memory")
; #define PG8_WAIT_L(n) asm volatile("s_waitcnt lgkmcnt(" #n ")" ::: "memory")
; template <class Epi, class Sched, bool ALIGN_EPI = false, bool SP2 = false>
; __device__ __forceinline__ void gemm_phase(PG8_LAS unsigned char* lds, const Gemm g, const Sched S, const Epi E) {
;     ...
;             const bool last = (t == nt - 2);
;             const char* a1 = cA + (size_t)(t + 1) * kstepA;
;             const char* a2 = last ? nA : cA + (size_t)(t + 2) * kstepA; const char* b2 = last ? nB : cB + (size_t)(t + 2) * kstep;
;             const char* a3 = a2 + kstepA; const char* b3 = b2 + kstep;
;             if (last && has_next) S.a_ready(nxt);
;             if constexpr (SP2) {
;             PG8_LDB(B0, 0, 0); PG8_LDB(B1, 0, 1); PG8_SCHED; PG8_LDA(At, 0, 0); PG8_STAGE(PG8_SA(1, 1), a1 + hstepA, voffA);
;             PG8_WAIT_V(8); PG8_WAIT_L(0); PG8_BAR; PG8_MMA(0, 0, At, B0); PG8_MMA(0, 1, At, B1); PG8_BAR; PG8_SCHED;
;             PG8_LDA(At, 0, 1); PG8_STAGE(PG8_SB(0, 0), b2, voffB); PG8_STAGE(PG8_SB(0, 1), b2 + hstep, voffB); PG8_STAGE(PG8_SA(0, 0), a2, voffA);
;             PG8_WAIT_V(8); PG8_WAIT_L(0); PG8_BAR; PG8_MMA(1, 0, At, B0); PG8_MMA(1, 1, At, B1); PG8_BAR; PG8_SCHED;
.LBB0_116:
	ds_read_b128 v[154:157], v150
	ds_read_b128 v[158:161], v150 offset:1024
	ds_read_b128 v[162:165], v150 offset:2048
	ds_read_b128 v[166:169], v150 offset:3072
	ds_read_b128 v[170:173], v151
	ds_read_b128 v[174:177], v151 offset:1024
	ds_read_b128 v[178:181], v151 offset:2048
	ds_read_b128 v[182:185], v151 offset:3072
	s_add_u32 s60, s46, 0xfffc0080
	s_addc_u32 s61, s47, -1
	s_cmp_eq_u32 s86, 12
	s_cselect_b32 s69, s39, s61
	s_cselect_b32 s68, s82, s60
	s_cselect_b32 s61, s37, s85
	s_cselect_b32 s60, s83, s84
	v_lshl_add_u64 v[144:145], s[46:47], 0, v[136:137]
	s_add_i32 m0, s45, 0xc000
	ds_read_b128 v[186:189], v152
	ds_read_b128 v[190:193], v152 offset:1024
	ds_read_b128 v[194:197], v152 offset:2048
	ds_read_b128 v[198:201], v152 offset:3072
	ds_read_b128 v[206:209], v152 offset:4096
	ds_read_b128 v[210:213], v152 offset:5120
	ds_read_b128 v[214:217], v152 offset:6144
	ds_read_b128 v[218:221], v152 offset:7168
	global_load_lds_dwordx4 v[144:145], off
	v_lshl_add_u64 v[144:145], s[46:47], 0, v[138:139]
	s_add_i32 m0, s45, 0xe000
	s_nop 0
	global_load_lds_dwordx4 v[144:145], off
	s_waitcnt vmcnt(8)
	s_waitcnt lgkmcnt(0)
	s_barrier
	s_setprio 1
	s_waitcnt lgkmcnt(0)
	v_mfma_f32_16x16x32_bf16 v[124:127], v[154:157], v[186:189], v[124:127]
	v_mfma_f32_16x16x32_bf16 v[120:123], v[162:165], v[186:189], v[120:123]
	v_mfma_f32_16x16x32_bf16 v[112:115], v[154:157], v[194:197], v[112:115]
	v_mfma_f32_16x16x32_bf16 v[104:107], v[162:165], v[194:197], v[104:107]
	v_mfma_f32_16x16x32_bf16 v[96:99], v[154:157], v[206:209], v[96:99]
	v_mfma_f32_16x16x32_bf16 v[88:91], v[162:165], v[206:209], v[88:91]
	v_mfma_f32_16x16x32_bf16 v[80:83], v[154:157], v[214:217], v[80:83]
	v_mfma_f32_16x16x32_bf16 v[72:75], v[162:165], v[214:217], v[72:75]
	v_mfma_f32_16x16x32_bf16 v[124:127], v[158:161], v[190:193], v[124:127]
	v_mfma_f32_16x16x32_bf16 v[120:123], v[166:169], v[190:193], v[120:123]
	v_mfma_f32_16x16x32_bf16 v[112:115], v[158:161], v[198:201], v[112:115]
	v_mfma_f32_16x16x32_bf16 v[104:107], v[166:169], v[198:201], v[104:107]
	v_mfma_f32_16x16x32_bf16 v[96:99], v[158:161], v[210:213], v[96:99]
	v_mfma_f32_16x16x32_bf16 v[88:91], v[166:169], v[210:213], v[88:91]
	v_mfma_f32_16x16x32_bf16 v[80:83], v[158:161], v[218:221], v[80:83]
	v_mfma_f32_16x16x32_bf16 v[72:75], v[166:169], v[218:221], v[72:75]
	s_setprio 0
	s_setprio 1
	v_mfma_f32_16x16x32_bf16 v[116:119], v[170:173], v[186:189], v[116:119]
	v_mfma_f32_16x16x32_bf16 v[108:111], v[178:181], v[186:189], v[108:111]
	v_mfma_f32_16x16x32_bf16 v[100:103], v[170:173], v[194:197], v[100:103]
	v_mfma_f32_16x16x32_bf16 v[92:95], v[178:181], v[194:197], v[92:95]
	v_mfma_f32_16x16x32_bf16 v[84:87], v[170:173], v[206:209], v[84:87]
	v_mfma_f32_16x16x32_bf16 v[76:79], v[178:181], v[206:209], v[76:79]
	v_mfma_f32_16x16x32_bf16 v[68:71], v[170:173], v[214:217], v[68:71]
	v_mfma_f32_16x16x32_bf16 v[64:67], v[178:181], v[214:217], v[64:67]
	v_mfma_f32_16x16x32_bf16 v[116:119], v[174:177], v[190:193], v[116:119]
	v_mfma_f32_16x16x32_bf16 v[108:111], v[182:185], v[190:193], v[108:111]
	v_mfma_f32_16x16x32_bf16 v[100:103], v[174:177], v[198:201], v[100:103]
	v_mfma_f32_16x16x32_bf16 v[92:95], v[182:185], v[198:201], v[92:95]
	v_mfma_f32_16x16x32_bf16 v[84:87], v[174:177], v[210:213], v[84:87]
	v_mfma_f32_16x16x32_bf16 v[76:79], v[182:185], v[210:213], v[76:79]
	v_mfma_f32_16x16x32_bf16 v[68:71], v[174:177], v[218:221], v[68:71]
	v_mfma_f32_16x16x32_bf16 v[64:67], v[182:185], v[218:221], v[64:67]
	s_setprio 0
	s_barrier
	s_add_i32 s87, s70, s33
	v_lshl_add_u64 v[144:145], s[60:61], 0, v[130:131]
	s_mov_b32 m0, s87
	ds_read_b128 v[186:189], v152 offset:16384
	ds_read_b128 v[190:193], v152 offset:17408
	ds_read_b128 v[194:197], v152 offset:18432
	ds_read_b128 v[198:201], v152 offset:19456
	ds_read_b128 v[206:209], v152 offset:20480
	ds_read_b128 v[210:213], v152 offset:21504
	ds_read_b128 v[214:217], v152 offset:22528
	ds_read_b128 v[218:221], v152 offset:23552
	global_load_lds_dwordx4 v[144:145], off
	s_add_i32 m0, s87, 0x2000
	s_add_u32 s88, s60, 0x40000
	v_lshl_add_u64 v[202:203], s[60:61], 0, v[134:135]
	s_addc_u32 s89, s61, 0
	s_add_i32 s87, s71, s33
	global_load_lds_dwordx4 v[202:203], off
	v_lshl_add_u64 v[222:223], s[88:89], 0, v[130:131]
	s_mov_b32 m0, s87
	v_lshl_add_u64 v[224:225], s[68:69], 0, v[132:133]
	global_load_lds_dwordx4 v[222:223], off
	v_lshl_add_u64 v[222:223], s[88:89], 0, v[134:135]
	s_add_i32 m0, s87, 0x2000
	s_nop 0
	global_load_lds_dwordx4 v[222:223], off
	v_lshl_add_u64 v[222:223], s[68:69], 0, v[128:129]
	s_mov_b32 m0, s45
	s_nop 0
	global_load_lds_dwordx4 v[222:223], off
	s_mov_b32 m0, s54
	s_nop 0
	global_load_lds_dwordx4 v[224:225], off
	s_waitcnt vmcnt(8)
	s_waitcnt lgkmcnt(0)
	s_barrier
; #define PG8_STAGE(bufoff, gbase, voff) do { _Pragma("unroll") for (int _i = 0; _i < 2; ++_i) \
;         __builtin_amdgcn_global_load_lds((const unsigned*)((const char*)(gbase) + (voff)[_i]), (PG8_LAS unsigned*)(lds + (bufoff) + ldsw + _i * 8192), 16, 0, 0); } while (0)
; #define PG8_LDA(dst, b, h) do { _Pragma("unroll") for (int m = 0; m < 4; ++m) _Pragma("unroll") for (int k = 0; k < 2; ++k) dst[m][k] = *(const PG8_LAS bf16x8*)(lds + PG8_SA(b, h) + aoff + m * 2048 + k * 1024); } while (0)
; #define PG8_LDB(dst, b, h) do { _Pragma("unroll") for (int n = 0; n < 2; ++n) _Pragma("unroll") for (int k = 0; k < 2; ++k) dst[n][k] = *(const PG8_LAS bf16x8*)(lds + PG8_SB(b, h) + boff + n * 2048 + k * 1024); } while (0)
; #define PG8_MMA(ai, bj, At, Bt) do { __builtin_amdgcn_s_setprio(1); _Pragma("unroll") for (int m = 0; m < 4; ++m) _Pragma("unroll") for (int n = 0; n < 2; ++n) _Pragma("unroll") for (int k = 0; k < 2; ++k) \
;         acc[ai][bj][m][n] = __builtin_amdgcn_mfma_f32_16x16x32_bf16(Bt[n][k], At[m][k], acc[ai][bj][m][n], 0, 0, 0); __builtin_amdgcn_s_setprio(0); } while (0)
; #define PG8_WAIT_V(n) asm volatile("s_waitcnt vmcnt(" #n ")" ::: "memory")
; #define PG8_WAIT_L(n) asm volatile("s_waitcnt lgkmcnt(" #n ")" ::: "memory")
; #define PG8_BAR __builtin_amdgcn_s_barrier()
; #define PG8_SCHED __builtin_amdgcn_sched_barrier(0)
; template <class Epi, class Sched, bool ALIGN_EPI = false, bool SP2 = false>
; __device__ __forceinline__ void gemm_phase(PG8_LAS unsigned char* lds, const Gemm g, const Sched S, const Epi E) {
;     ...
;             PG8_WAIT_V(8); PG8_WAIT_L(0); PG8_BAR; PG8_MMA(1, 0, At, B0); PG8_MMA(1, 1, At, B1); PG8_BAR; PG8_SCHED;
;             PG8_LDB(B0, 1, 0); PG8_LDB(B1, 1, 1); PG8_SCHED; PG8_LDA(At, 1, 0); PG8_STAGE(PG8_SA(0, 1), a2 + hstepA, voffA);
;             PG8_WAIT_V(8); PG8_WAIT_L(0); PG8_BAR; PG8_MMA(0, 0, At, B0); PG8_MMA(0, 1, At, B1); PG8_BAR; PG8_SCHED;
	s_setprio 1
	s_waitcnt lgkmcnt(0)
	v_mfma_f32_16x16x32_bf16 v[60:63], v[154:157], v[186:189], v[60:63]
	v_mfma_f32_16x16x32_bf16 v[56:59], v[162:165], v[186:189], v[56:59]
	v_mfma_f32_16x16x32_bf16 v[48:51], v[154:157], v[194:197], v[48:51]
	v_mfma_f32_16x16x32_bf16 v[40:43], v[162:165], v[194:197], v[40:43]
	v_mfma_f32_16x16x32_bf16 v[32:35], v[154:157], v[206:209], v[32:35]
	v_mfma_f32_16x16x32_bf16 v[24:27], v[162:165], v[206:209], v[24:27]
	v_mfma_f32_16x16x32_bf16 v[16:19], v[154:157], v[214:217], v[16:19]
	v_mfma_f32_16x16x32_bf16 v[8:11], v[162:165], v[214:217], v[8:11]
	v_mfma_f32_16x16x32_bf16 v[60:63], v[158:161], v[190:193], v[60:63]
	v_mfma_f32_16x16x32_bf16 v[56:59], v[166:169], v[190:193], v[56:59]
	v_mfma_f32_16x16x32_bf16 v[48:51], v[158:161], v[198:201], v[48:51]
	v_mfma_f32_16x16x32_bf16 v[40:43], v[166:169], v[198:201], v[40:43]
	v_mfma_f32_16x16x32_bf16 v[32:35], v[158:161], v[210:213], v[32:35]
	v_mfma_f32_16x16x32_bf16 v[24:27], v[166:169], v[210:213], v[24:27]
	v_mfma_f32_16x16x32_bf16 v[16:19], v[158:161], v[218:221], v[16:19]
	v_mfma_f32_16x16x32_bf16 v[8:11], v[166:169], v[218:221], v[8:11]
	s_setprio 0
	s_setprio 1
	v_mfma_f32_16x16x32_bf16 v[52:55], v[170:173], v[186:189], v[52:55]
	v_mfma_f32_16x16x32_bf16 v[44:47], v[178:181], v[186:189], v[44:47]
	v_mfma_f32_16x16x32_bf16 v[36:39], v[170:173], v[194:197], v[36:39]
	v_mfma_f32_16x16x32_bf16 v[28:31], v[178:181], v[194:197], v[28:31]
	v_mfma_f32_16x16x32_bf16 v[20:23], v[170:173], v[206:209], v[20:23]
	v_mfma_f32_16x16x32_bf16 v[12:15], v[178:181], v[206:209], v[12:15]
	v_mfma_f32_16x16x32_bf16 v[4:7], v[170:173], v[214:217], v[4:7]
	v_mfma_f32_16x16x32_bf16 v[0:3], v[178:181], v[214:217], v[0:3]
	v_mfma_f32_16x16x32_bf16 v[52:55], v[174:177], v[190:193], v[52:55]
	v_mfma_f32_16x16x32_bf16 v[44:47], v[182:185], v[190:193], v[44:47]
	v_mfma_f32_16x16x32_bf16 v[36:39], v[174:177], v[198:201], v[36:39]
	v_mfma_f32_16x16x32_bf16 v[28:31], v[182:185], v[198:201], v[28:31]
	v_mfma_f32_16x16x32_bf16 v[20:23], v[174:177], v[210:213], v[20:23]
	v_mfma_f32_16x16x32_bf16 v[12:15], v[182:185], v[210:213], v[12:15]
	v_mfma_f32_16x16x32_bf16 v[4:7], v[174:177], v[218:221], v[4:7]
	v_mfma_f32_16x16x32_bf16 v[0:3], v[182:185], v[218:221], v[0:3]
	s_setprio 0
	s_barrier
	s_add_i32 s87, 0, 0x18000
	v_add_u32_e32 v153, s87, v149
	s_add_i32 s88, 0, 0x1c000
	ds_read_b128 v[154:157], v153
	ds_read_b128 v[158:161], v153 offset:1024
	ds_read_b128 v[162:165], v153 offset:2048
	ds_read_b128 v[166:169], v153 offset:3072
	v_add_u32_e32 v153, s88, v149
	ds_read_b128 v[170:173], v153
	ds_read_b128 v[174:177], v153 offset:1024
	ds_read_b128 v[178:181], v153 offset:2048
	ds_read_b128 v[182:185], v153 offset:3072
	s_add_u32 s68, s68, 0x40000
	s_addc_u32 s69, s69, 0
	s_mov_b32 m0, s55
	v_lshl_add_u64 v[226:227], s[68:69], 0, v[128:129]
	ds_read_b128 v[186:189], v152 offset:32768
	ds_read_b128 v[190:193], v152 offset:33792
	ds_read_b128 v[194:197], v152 offset:34816
	ds_read_b128 v[198:201], v152 offset:35840
	ds_read_b128 v[206:209], v152 offset:36864
	ds_read_b128 v[210:213], v152 offset:37888
	ds_read_b128 v[214:217], v152 offset:38912
	ds_read_b128 v[218:221], v152 offset:39936
	global_load_lds_dwordx4 v[226:227], off
	v_lshl_add_u64 v[226:227], s[68:69], 0, v[132:133]
	s_mov_b32 m0, s62
	s_nop 0
	global_load_lds_dwordx4 v[226:227], off
	s_waitcnt vmcnt(8)
	s_waitcnt lgkmcnt(0)
	s_barrier
	s_setprio 1
	s_waitcnt lgkmcnt(0)
	v_mfma_f32_16x16x32_bf16 v[124:127], v[154:157], v[186:189], v[124:127]
	v_mfma_f32_16x16x32_bf16 v[120:123], v[162:165], v[186:189], v[120:123]
	v_mfma_f32_16x16x32_bf16 v[112:115], v[154:157], v[194:197], v[112:115]
	v_mfma_f32_16x16x32_bf16 v[104:107], v[162:165], v[194:197], v[104:107]
	v_mfma_f32_16x16x32_bf16 v[96:99], v[154:157], v[206:209], v[96:99]
	v_mfma_f32_16x16x32_bf16 v[88:91], v[162:165], v[206:209], v[88:91]
	v_mfma_f32_16x16x32_bf16 v[80:83], v[154:157], v[214:217], v[80:83]
	v_mfma_f32_16x16x32_bf16 v[72:75], v[162:165], v[214:217], v[72:75]
	v_mfma_f32_16x16x32_bf16 v[124:127], v[158:161], v[190:193], v[124:127]
	v_mfma_f32_16x16x32_bf16 v[120:123], v[166:169], v[190:193], v[120:123]
	v_mfma_f32_16x16x32_bf16 v[112:115], v[158:161], v[198:201], v[112:115]
	v_mfma_f32_16x16x32_bf16 v[104:107], v[166:169], v[198:201], v[104:107]
	v_mfma_f32_16x16x32_bf16 v[96:99], v[158:161], v[210:213], v[96:99]
	v_mfma_f32_16x16x32_bf16 v[88:91], v[166:169], v[210:213], v[88:91]
	v_mfma_f32_16x16x32_bf16 v[80:83], v[158:161], v[218:221], v[80:83]
	v_mfma_f32_16x16x32_bf16 v[72:75], v[166:169], v[218:221], v[72:75]
	s_setprio 0
	s_setprio 1
	v_mfma_f32_16x16x32_bf16 v[116:119], v[170:173], v[186:189], v[116:119]
	v_mfma_f32_16x16x32_bf16 v[108:111], v[178:181], v[186:189], v[108:111]
	v_mfma_f32_16x16x32_bf16 v[100:103], v[170:173], v[194:197], v[100:103]
	v_mfma_f32_16x16x32_bf16 v[92:95], v[178:181], v[194:197], v[92:95]
	v_mfma_f32_16x16x32_bf16 v[84:87], v[170:173], v[206:209], v[84:87]
	v_mfma_f32_16x16x32_bf16 v[76:79], v[178:181], v[206:209], v[76:79]
	v_mfma_f32_16x16x32_bf16 v[68:71], v[170:173], v[214:217], v[68:71]
	v_mfma_f32_16x16x32_bf16 v[64:67], v[178:181], v[214:217], v[64:67]
	v_mfma_f32_16x16x32_bf16 v[116:119], v[174:177], v[190:193], v[116:119]
	v_mfma_f32_16x16x32_bf16 v[108:111], v[182:185], v[190:193], v[108:111]
	v_mfma_f32_16x16x32_bf16 v[100:103], v[174:177], v[198:201], v[100:103]
	v_mfma_f32_16x16x32_bf16 v[92:95], v[182:185], v[198:201], v[92:95]
	v_mfma_f32_16x16x32_bf16 v[84:87], v[174:177], v[210:213], v[84:87]
	v_mfma_f32_16x16x32_bf16 v[76:79], v[182:185], v[210:213], v[76:79]
	v_mfma_f32_16x16x32_bf16 v[68:71], v[174:177], v[218:221], v[68:71]
	v_mfma_f32_16x16x32_bf16 v[64:67], v[182:185], v[218:221], v[64:67]
	s_setprio 0
	s_barrier
; #define PG8_STAGE(bufoff, gbase, voff) do { _Pragma("unroll") for (int _i = 0; _i < 2; ++_i) \
;         __builtin_amdgcn_global_load_lds((const unsigned*)((const char*)(gbase) + (voff)[_i]), (PG8_LAS unsigned*)(lds + (bufoff) + ldsw + _i * 8192), 16, 0, 0); } while (0)
; #define PG8_LDA(dst, b, h) do { _Pragma("unroll") for (int m = 0; m < 4; ++m) _Pragma("unroll") for (int k = 0; k < 2; ++k) dst[m][k] = *(const PG8_LAS bf16x8*)(lds + PG8_SA(b, h) + aoff + m * 2048 + k * 1024); } while (0)
; #define PG8_MMA(ai, bj, At, Bt) do { __builtin_amdgcn_s_setprio(1); _Pragma("unroll") for (int m = 0; m < 4; ++m) _Pragma("unroll") for (int n = 0; n < 2; ++n) _Pragma("unroll") for (int k = 0; k < 2; ++k) \
;         acc[ai][bj][m][n] = __builtin_amdgcn_mfma_f32_16x16x32_bf16(Bt[n][k], At[m][k], acc[ai][bj][m][n], 0, 0, 0); __builtin_amdgcn_s_setprio(0); } while (0)
; #define PG8_WAIT_V(n) asm volatile("s_waitcnt vmcnt(" #n ")" ::: "memory")
; #define PG8_WAIT_L(n) asm volatile("s_waitcnt lgkmcnt(" #n ")" ::: "memory")
; #define PG8_BAR __builtin_amdgcn_s_barrier()
; #define PG8_SCHED __builtin_amdgcn_sched_barrier(0)
; template <class Epi, class Sched, bool ALIGN_EPI = false, bool SP2 = false>
; __device__ __forceinline__ void gemm_phase(PG8_LAS unsigned char* lds, const Gemm g, const Sched S, const Epi E) {
;     ...
;         for (int t = 0; t < nt; t += 2) {
;     ...
;             PG8_LDA(At, 1, 1); PG8_STAGE(PG8_SB(1, 0), b3, voffB); PG8_STAGE(PG8_SB(1, 1), b3 + hstep, voffB); PG8_STAGE(PG8_SA(1, 0), a3, voffA);
;             PG8_WAIT_V(8); PG8_WAIT_L(0); PG8_BAR; PG8_MMA(1, 0, At, B0); PG8_MMA(1, 1, At, B1); PG8_BAR; PG8_SCHED;
	s_add_i32 s68, s87, s33
	v_lshl_add_u64 v[144:145], v[144:145], 0, s[8:9]
	s_mov_b32 m0, s68
	ds_read_b128 v[186:189], v152 offset:49152
	ds_read_b128 v[190:193], v152 offset:50176
	ds_read_b128 v[194:197], v152 offset:51200
	ds_read_b128 v[198:201], v152 offset:52224
	ds_read_b128 v[206:209], v152 offset:53248
	ds_read_b128 v[210:213], v152 offset:54272
	ds_read_b128 v[214:217], v152 offset:55296
	ds_read_b128 v[218:221], v152 offset:56320
	global_load_lds_dwordx4 v[144:145], off
	s_add_i32 m0, s68, 0x2000
	s_add_u32 s60, s60, 0x40080
	v_lshl_add_u64 v[144:145], v[202:203], 0, s[8:9]
	s_addc_u32 s61, s61, 0
	s_add_i32 s68, s88, s33
	global_load_lds_dwordx4 v[144:145], off
	v_lshl_add_u64 v[144:145], s[60:61], 0, v[130:131]
	s_mov_b32 m0, s68
	s_nop 0
	global_load_lds_dwordx4 v[144:145], off
	v_lshl_add_u64 v[144:145], s[60:61], 0, v[134:135]
	s_add_i32 m0, s68, 0x2000
	s_nop 0
	global_load_lds_dwordx4 v[144:145], off
	v_lshl_add_u64 v[144:145], v[222:223], 0, s[8:9]
	s_mov_b32 m0, s66
	s_nop 0
	global_load_lds_dwordx4 v[144:145], off
	v_lshl_add_u64 v[144:145], v[224:225], 0, s[8:9]
	s_mov_b32 m0, s67
	s_nop 0
	global_load_lds_dwordx4 v[144:145], off
	s_waitcnt vmcnt(8)
	s_waitcnt lgkmcnt(0)
	s_barrier
	s_setprio 1
	s_waitcnt lgkmcnt(0)
	v_mfma_f32_16x16x32_bf16 v[60:63], v[154:157], v[186:189], v[60:63]
	v_mfma_f32_16x16x32_bf16 v[56:59], v[162:165], v[186:189], v[56:59]
	v_mfma_f32_16x16x32_bf16 v[48:51], v[154:157], v[194:197], v[48:51]
	v_mfma_f32_16x16x32_bf16 v[40:43], v[162:165], v[194:197], v[40:43]
	v_mfma_f32_16x16x32_bf16 v[32:35], v[154:157], v[206:209], v[32:35]
	v_mfma_f32_16x16x32_bf16 v[24:27], v[162:165], v[206:209], v[24:27]
	v_mfma_f32_16x16x32_bf16 v[16:19], v[154:157], v[214:217], v[16:19]
	v_mfma_f32_16x16x32_bf16 v[8:11], v[162:165], v[214:217], v[8:11]
	v_mfma_f32_16x16x32_bf16 v[60:63], v[158:161], v[190:193], v[60:63]
	v_mfma_f32_16x16x32_bf16 v[56:59], v[166:169], v[190:193], v[56:59]
	v_mfma_f32_16x16x32_bf16 v[48:51], v[158:161], v[198:201], v[48:51]
	v_mfma_f32_16x16x32_bf16 v[40:43], v[166:169], v[198:201], v[40:43]
	v_mfma_f32_16x16x32_bf16 v[32:35], v[158:161], v[210:213], v[32:35]
	v_mfma_f32_16x16x32_bf16 v[24:27], v[166:169], v[210:213], v[24:27]
	v_mfma_f32_16x16x32_bf16 v[16:19], v[158:161], v[218:221], v[16:19]
	v_mfma_f32_16x16x32_bf16 v[8:11], v[166:169], v[218:221], v[8:11]
	s_setprio 0
	s_setprio 1
	v_mfma_f32_16x16x32_bf16 v[52:55], v[170:173], v[186:189], v[52:55]
	v_mfma_f32_16x16x32_bf16 v[44:47], v[178:181], v[186:189], v[44:47]
	v_mfma_f32_16x16x32_bf16 v[36:39], v[170:173], v[194:197], v[36:39]
	v_mfma_f32_16x16x32_bf16 v[28:31], v[178:181], v[194:197], v[28:31]
	v_mfma_f32_16x16x32_bf16 v[20:23], v[170:173], v[206:209], v[20:23]
	v_mfma_f32_16x16x32_bf16 v[12:15], v[178:181], v[206:209], v[12:15]
	v_mfma_f32_16x16x32_bf16 v[4:7], v[170:173], v[214:217], v[4:7]
	v_mfma_f32_16x16x32_bf16 v[0:3], v[178:181], v[214:217], v[0:3]
	v_mfma_f32_16x16x32_bf16 v[52:55], v[174:177], v[190:193], v[52:55]
	v_mfma_f32_16x16x32_bf16 v[44:47], v[182:185], v[190:193], v[44:47]
	v_mfma_f32_16x16x32_bf16 v[36:39], v[174:177], v[198:201], v[36:39]
	v_mfma_f32_16x16x32_bf16 v[28:31], v[182:185], v[198:201], v[28:31]
	v_mfma_f32_16x16x32_bf16 v[20:23], v[174:177], v[210:213], v[20:23]
	v_mfma_f32_16x16x32_bf16 v[12:15], v[182:185], v[210:213], v[12:15]
	v_mfma_f32_16x16x32_bf16 v[4:7], v[174:177], v[218:221], v[4:7]
	v_mfma_f32_16x16x32_bf16 v[0:3], v[182:185], v[218:221], v[0:3]
	s_setprio 0
	s_add_i32 s86, s86, 2
	s_add_u32 s46, s46, 0x100
	s_addc_u32 s47, s47, 0
	s_add_u32 s84, s84, 0x100
	s_addc_u32 s85, s85, 0
	s_cmp_gt_u32 s86, 13
	s_barrier
	s_cbranch_scc0 .LBB0_116
	s_and_b64 vcc, exec, s[10:11]
	s_cbranch_vccz .LBB0_119
	s_barrier

; #define PG8_STAGE(bufoff, gbase, voff) do { _Pragma("unroll") for (int _i = 0; _i < 2; ++_i) \
;         __builtin_amdgcn_global_load_lds((const unsigned*)((const char*)(gbase) + (voff)[_i]), (PG8_LAS unsigned*)(lds + (bufoff) + ldsw + _i * 8192), 16, 0, 0); } while (0)
; #define PG8_LDA(dst, b, h) do { _Pragma("unroll") for (int m = 0; m < 4; ++m) _Pragma("unroll") for (int k = 0; k < 2; ++k) dst[m][k] = *(const PG8_LAS bf16x8*)(lds + PG8_SA(b, h) + aoff + m * 2048 + k * 1024); } while (0)
; #define PG8_LDB(dst, b, h) do { _Pragma("unroll") for (int n = 0; n < 2; ++n) _Pragma("unroll") for (int k = 0; k < 2; ++k) dst[n][k] = *(const PG8_LAS bf16x8*)(lds + PG8_SB(b, h) + boff + n * 2048 + k * 1024); } while (0)
; #define PG8_MMA(ai, bj, At, Bt) do { __builtin_amdgcn_s_setprio(1); _Pragma("unroll") for (int m = 0; m < 4; ++m) _Pragma("unroll") for (int n = 0; n < 2; ++n) _Pragma("unroll") for (int k = 0; k < 2; ++k) \
;         acc[ai][bj][m][n] = __builtin_amdgcn_mfma_f32_16x16x32_bf16(Bt[n][k], At[m][k], acc[ai][bj][m][n], 0, 0, 0); __builtin_amdgcn_s_setprio(0); } while (0)
; #define PG8_WAIT_V(n) asm volatile("s_waitcnt vmcnt(" #n ")" ::: "memory")
; #define PG8_WAIT_L(n) asm volatile("s_waitcnt lgkmcnt(" #n ")" ::: "memory")
; template <class Epi, class Sched, bool ALIGN_EPI = false, bool SP2 = false>
; __device__ __forceinline__ void gemm_phase(PG8_LAS unsigned char* lds, const Gemm g, const Sched S, const Epi E) {
;     ...
;             const bool last = (t == nt - 2);
;             const char* a1 = cA + (size_t)(t + 1) * kstepA;
;             const char* a2 = last ? nA : cA + (size_t)(t + 2) * kstepA; const char* b2 = last ? nB : cB + (size_t)(t + 2) * kstep;
;             const char* a3 = a2 + kstepA; const char* b3 = b2 + kstep;
;             if (last && has_next) S.a_ready(nxt);
;             if constexpr (SP2) {
;             PG8_LDB(B0, 0, 0); PG8_LDB(B1, 0, 1); PG8_SCHED; PG8_LDA(At, 0, 0); PG8_STAGE(PG8_SA(1, 1), a1 + hstepA, voffA);
;             PG8_WAIT_V(8); PG8_WAIT_L(0); PG8_BAR; PG8_MMA(0, 0, At, B0); PG8_MMA(0, 1, At, B1); PG8_BAR; PG8_SCHED;
;             PG8_LDA(At, 0, 1); PG8_STAGE(PG8_SB(0, 0), b2, voffB); PG8_STAGE(PG8_SB(0, 1), b2 + hstep, voffB); PG8_STAGE(PG8_SA(0, 0), a2, voffA);
;             PG8_WAIT_V(8); PG8_WAIT_L(0); PG8_BAR; PG8_MMA(1, 0, At, B0); PG8_MMA(1, 1, At, B1); PG8_BAR; PG8_SCHED;
.LBB0_259:
	ds_read_b128 v[140:143], v148
	ds_read_b128 v[152:155], v148 offset:1024
	ds_read_b128 v[156:159], v148 offset:2048
	ds_read_b128 v[160:163], v148 offset:3072
	ds_read_b128 v[164:167], v149
	ds_read_b128 v[168:171], v149 offset:1024
	ds_read_b128 v[172:175], v149 offset:2048
	ds_read_b128 v[176:179], v149 offset:3072
	s_add_u32 s40, s38, 0xfffc0080
	s_addc_u32 s41, s39, -1
	s_cmp_eq_u32 s66, 12
	s_cselect_b32 s43, s29, s41
	s_cselect_b32 s42, s62, s40
	s_cselect_b32 s41, s27, s65
	s_cselect_b32 s40, s63, s64
	v_lshl_add_u64 v[214:215], s[38:39], 0, v[132:133]
	s_add_i32 m0, s15, 0xc000
	ds_read_b128 v[180:183], v150
	ds_read_b128 v[184:187], v150 offset:1024
	ds_read_b128 v[188:191], v150 offset:2048
	ds_read_b128 v[192:195], v150 offset:3072
	ds_read_b128 v[196:199], v150 offset:4096
	ds_read_b128 v[200:203], v150 offset:5120
	ds_read_b128 v[206:209], v150 offset:6144
	ds_read_b128 v[210:213], v150 offset:7168
	global_load_lds_dwordx4 v[214:215], off
	v_lshl_add_u64 v[214:215], s[38:39], 0, v[134:135]
	s_add_i32 m0, s15, 0xe000
	s_nop 0
	global_load_lds_dwordx4 v[214:215], off
	s_waitcnt vmcnt(8)
	s_waitcnt lgkmcnt(0)
	s_barrier
	s_setprio 1
	s_waitcnt lgkmcnt(0)
	v_mfma_f32_16x16x32_bf16 v[124:127], v[140:143], v[180:183], v[124:127]
	v_mfma_f32_16x16x32_bf16 v[120:123], v[156:159], v[180:183], v[120:123]
	v_mfma_f32_16x16x32_bf16 v[112:115], v[140:143], v[188:191], v[112:115]
	v_mfma_f32_16x16x32_bf16 v[108:111], v[156:159], v[188:191], v[108:111]
	v_mfma_f32_16x16x32_bf16 v[96:99], v[140:143], v[196:199], v[96:99]
	v_mfma_f32_16x16x32_bf16 v[92:95], v[156:159], v[196:199], v[92:95]
	v_mfma_f32_16x16x32_bf16 v[80:83], v[140:143], v[206:209], v[80:83]
	v_mfma_f32_16x16x32_bf16 v[76:79], v[156:159], v[206:209], v[76:79]
	v_mfma_f32_16x16x32_bf16 v[124:127], v[152:155], v[184:187], v[124:127]
	v_mfma_f32_16x16x32_bf16 v[120:123], v[160:163], v[184:187], v[120:123]
	v_mfma_f32_16x16x32_bf16 v[112:115], v[152:155], v[192:195], v[112:115]
	v_mfma_f32_16x16x32_bf16 v[108:111], v[160:163], v[192:195], v[108:111]
	v_mfma_f32_16x16x32_bf16 v[96:99], v[152:155], v[200:203], v[96:99]
	v_mfma_f32_16x16x32_bf16 v[92:95], v[160:163], v[200:203], v[92:95]
	v_mfma_f32_16x16x32_bf16 v[80:83], v[152:155], v[210:213], v[80:83]
	v_mfma_f32_16x16x32_bf16 v[76:79], v[160:163], v[210:213], v[76:79]
	s_setprio 0
	s_setprio 1
	v_mfma_f32_16x16x32_bf16 v[116:119], v[164:167], v[180:183], v[116:119]
	v_mfma_f32_16x16x32_bf16 v[104:107], v[172:175], v[180:183], v[104:107]
	v_mfma_f32_16x16x32_bf16 v[100:103], v[164:167], v[188:191], v[100:103]
	v_mfma_f32_16x16x32_bf16 v[88:91], v[172:175], v[188:191], v[88:91]
	v_mfma_f32_16x16x32_bf16 v[84:87], v[164:167], v[196:199], v[84:87]
	v_mfma_f32_16x16x32_bf16 v[72:75], v[172:175], v[196:199], v[72:75]
	v_mfma_f32_16x16x32_bf16 v[68:71], v[164:167], v[206:209], v[68:71]
	v_mfma_f32_16x16x32_bf16 v[64:67], v[172:175], v[206:209], v[64:67]
	v_mfma_f32_16x16x32_bf16 v[116:119], v[168:171], v[184:187], v[116:119]
	v_mfma_f32_16x16x32_bf16 v[104:107], v[176:179], v[184:187], v[104:107]
	v_mfma_f32_16x16x32_bf16 v[100:103], v[168:171], v[192:195], v[100:103]
	v_mfma_f32_16x16x32_bf16 v[88:91], v[176:179], v[192:195], v[88:91]
	v_mfma_f32_16x16x32_bf16 v[84:87], v[168:171], v[200:203], v[84:87]
	v_mfma_f32_16x16x32_bf16 v[72:75], v[176:179], v[200:203], v[72:75]
	v_mfma_f32_16x16x32_bf16 v[68:71], v[168:171], v[210:213], v[68:71]
	v_mfma_f32_16x16x32_bf16 v[64:67], v[176:179], v[210:213], v[64:67]
	s_setprio 0
	s_barrier
	s_add_i32 s67, s55, s4
	v_lshl_add_u64 v[214:215], s[40:41], 0, v[128:129]
	s_mov_b32 m0, s67
	ds_read_b128 v[180:183], v150 offset:16384
	ds_read_b128 v[184:187], v150 offset:17408
	ds_read_b128 v[188:191], v150 offset:18432
	ds_read_b128 v[192:195], v150 offset:19456
	ds_read_b128 v[196:199], v150 offset:20480
	ds_read_b128 v[200:203], v150 offset:21504
	ds_read_b128 v[206:209], v150 offset:22528
	ds_read_b128 v[210:213], v150 offset:23552
	global_load_lds_dwordx4 v[214:215], off
	s_add_i32 m0, s67, 0x2000
	s_add_u32 s68, s40, 0x40000
	v_lshl_add_u64 v[216:217], s[40:41], 0, v[130:131]
	s_addc_u32 s69, s41, 0
	s_add_i32 s67, s60, s4
	global_load_lds_dwordx4 v[216:217], off
	v_lshl_add_u64 v[218:219], s[68:69], 0, v[128:129]
	s_mov_b32 m0, s67
	v_lshl_add_u64 v[220:221], s[42:43], 0, v[130:131]
	global_load_lds_dwordx4 v[218:219], off
	v_lshl_add_u64 v[218:219], s[68:69], 0, v[130:131]
	s_add_i32 m0, s67, 0x2000
	s_nop 0
	global_load_lds_dwordx4 v[218:219], off
	v_lshl_add_u64 v[218:219], s[42:43], 0, v[128:129]
	s_mov_b32 m0, s15
	s_nop 0
	global_load_lds_dwordx4 v[218:219], off
	s_mov_b32 m0, s23
	s_nop 0
	global_load_lds_dwordx4 v[220:221], off
	s_waitcnt vmcnt(8)
	s_waitcnt lgkmcnt(0)
	s_barrier
; #define PG8_STAGE(bufoff, gbase, voff) do { _Pragma("unroll") for (int _i = 0; _i < 2; ++_i) \
;         __builtin_amdgcn_global_load_lds((const unsigned*)((const char*)(gbase) + (voff)[_i]), (PG8_LAS unsigned*)(lds + (bufoff) + ldsw + _i * 8192), 16, 0, 0); } while (0)
; #define PG8_LDA(dst, b, h) do { _Pragma("unroll") for (int m = 0; m < 4; ++m) _Pragma("unroll") for (int k = 0; k < 2; ++k) dst[m][k] = *(const PG8_LAS bf16x8*)(lds + PG8_SA(b, h) + aoff + m * 2048 + k * 1024); } while (0)
; #define PG8_LDB(dst, b, h) do { _Pragma("unroll") for (int n = 0; n < 2; ++n) _Pragma("unroll") for (int k = 0; k < 2; ++k) dst[n][k] = *(const PG8_LAS bf16x8*)(lds + PG8_SB(b, h) + boff + n * 2048 + k * 1024); } while (0)
; #define PG8_MMA(ai, bj, At, Bt) do { __builtin_amdgcn_s_setprio(1); _Pragma("unroll") for (int m = 0; m < 4; ++m) _Pragma("unroll") for (int n = 0; n < 2; ++n) _Pragma("unroll") for (int k = 0; k < 2; ++k) \
;         acc[ai][bj][m][n] = __builtin_amdgcn_mfma_f32_16x16x32_bf16(Bt[n][k], At[m][k], acc[ai][bj][m][n], 0, 0, 0); __builtin_amdgcn_s_setprio(0); } while (0)
; #define PG8_WAIT_V(n) asm volatile("s_waitcnt vmcnt(" #n ")" ::: "memory")
; #define PG8_WAIT_L(n) asm volatile("s_waitcnt lgkmcnt(" #n ")" ::: "memory")
; #define PG8_BAR __builtin_amdgcn_s_barrier()
; #define PG8_SCHED __builtin_amdgcn_sched_barrier(0)
; template <class Epi, class Sched, bool ALIGN_EPI = false, bool SP2 = false>
; __device__ __forceinline__ void gemm_phase(PG8_LAS unsigned char* lds, const Gemm g, const Sched S, const Epi E) {
;     ...
;             PG8_WAIT_V(8); PG8_WAIT_L(0); PG8_BAR; PG8_MMA(1, 0, At, B0); PG8_MMA(1, 1, At, B1); PG8_BAR; PG8_SCHED;
;             PG8_LDB(B0, 1, 0); PG8_LDB(B1, 1, 1); PG8_SCHED; PG8_LDA(At, 1, 0); PG8_STAGE(PG8_SA(0, 1), a2 + hstepA, voffA);
;             PG8_WAIT_V(8); PG8_WAIT_L(0); PG8_BAR; PG8_MMA(0, 0, At, B0); PG8_MMA(0, 1, At, B1); PG8_BAR; PG8_SCHED;
	s_setprio 1
	s_waitcnt lgkmcnt(0)
	v_mfma_f32_16x16x32_bf16 v[60:63], v[140:143], v[180:183], v[60:63]
	v_mfma_f32_16x16x32_bf16 v[56:59], v[156:159], v[180:183], v[56:59]
	v_mfma_f32_16x16x32_bf16 v[48:51], v[140:143], v[188:191], v[48:51]
	v_mfma_f32_16x16x32_bf16 v[44:47], v[156:159], v[188:191], v[44:47]
	v_mfma_f32_16x16x32_bf16 v[32:35], v[140:143], v[196:199], v[32:35]
	v_mfma_f32_16x16x32_bf16 v[28:31], v[156:159], v[196:199], v[28:31]
	v_mfma_f32_16x16x32_bf16 v[16:19], v[140:143], v[206:209], v[16:19]
	v_mfma_f32_16x16x32_bf16 v[12:15], v[156:159], v[206:209], v[12:15]
	v_mfma_f32_16x16x32_bf16 v[60:63], v[152:155], v[184:187], v[60:63]
	v_mfma_f32_16x16x32_bf16 v[56:59], v[160:163], v[184:187], v[56:59]
	v_mfma_f32_16x16x32_bf16 v[48:51], v[152:155], v[192:195], v[48:51]
	v_mfma_f32_16x16x32_bf16 v[44:47], v[160:163], v[192:195], v[44:47]
	v_mfma_f32_16x16x32_bf16 v[32:35], v[152:155], v[200:203], v[32:35]
	v_mfma_f32_16x16x32_bf16 v[28:31], v[160:163], v[200:203], v[28:31]
	v_mfma_f32_16x16x32_bf16 v[16:19], v[152:155], v[210:213], v[16:19]
	v_mfma_f32_16x16x32_bf16 v[12:15], v[160:163], v[210:213], v[12:15]
	s_setprio 0
	s_setprio 1
	v_mfma_f32_16x16x32_bf16 v[52:55], v[164:167], v[180:183], v[52:55]
	v_mfma_f32_16x16x32_bf16 v[40:43], v[172:175], v[180:183], v[40:43]
	v_mfma_f32_16x16x32_bf16 v[36:39], v[164:167], v[188:191], v[36:39]
	v_mfma_f32_16x16x32_bf16 v[24:27], v[172:175], v[188:191], v[24:27]
	v_mfma_f32_16x16x32_bf16 v[20:23], v[164:167], v[196:199], v[20:23]
	v_mfma_f32_16x16x32_bf16 v[8:11], v[172:175], v[196:199], v[8:11]
	v_mfma_f32_16x16x32_bf16 v[4:7], v[164:167], v[206:209], v[4:7]
	v_mfma_f32_16x16x32_bf16 v[0:3], v[172:175], v[206:209], v[0:3]
	v_mfma_f32_16x16x32_bf16 v[52:55], v[168:171], v[184:187], v[52:55]
	v_mfma_f32_16x16x32_bf16 v[40:43], v[176:179], v[184:187], v[40:43]
	v_mfma_f32_16x16x32_bf16 v[36:39], v[168:171], v[192:195], v[36:39]
	v_mfma_f32_16x16x32_bf16 v[24:27], v[176:179], v[192:195], v[24:27]
	v_mfma_f32_16x16x32_bf16 v[20:23], v[168:171], v[200:203], v[20:23]
	v_mfma_f32_16x16x32_bf16 v[8:11], v[176:179], v[200:203], v[8:11]
	v_mfma_f32_16x16x32_bf16 v[4:7], v[168:171], v[210:213], v[4:7]
	v_mfma_f32_16x16x32_bf16 v[0:3], v[176:179], v[210:213], v[0:3]
	s_setprio 0
	s_barrier
	s_add_i32 s67, 0, 0x18000
	v_add_u32_e32 v151, s67, v147
	s_add_i32 s68, 0, 0x1c000
	ds_read_b128 v[140:143], v151
	ds_read_b128 v[152:155], v151 offset:1024
	ds_read_b128 v[156:159], v151 offset:2048
	ds_read_b128 v[160:163], v151 offset:3072
	v_add_u32_e32 v151, s68, v147
	ds_read_b128 v[164:167], v151
	ds_read_b128 v[168:171], v151 offset:1024
	ds_read_b128 v[172:175], v151 offset:2048
	ds_read_b128 v[176:179], v151 offset:3072
	s_add_u32 s42, s42, 0x40000
	s_addc_u32 s43, s43, 0
	s_mov_b32 m0, s33
	v_lshl_add_u64 v[222:223], s[42:43], 0, v[128:129]
	ds_read_b128 v[180:183], v150 offset:32768
	ds_read_b128 v[184:187], v150 offset:33792
	ds_read_b128 v[188:191], v150 offset:34816
	ds_read_b128 v[192:195], v150 offset:35840
	ds_read_b128 v[196:199], v150 offset:36864
	ds_read_b128 v[200:203], v150 offset:37888
	ds_read_b128 v[206:209], v150 offset:38912
	ds_read_b128 v[210:213], v150 offset:39936
	global_load_lds_dwordx4 v[222:223], off
	v_lshl_add_u64 v[222:223], s[42:43], 0, v[130:131]
	s_mov_b32 m0, s37
	s_nop 0
	global_load_lds_dwordx4 v[222:223], off
	s_waitcnt vmcnt(8)
	s_waitcnt lgkmcnt(0)
	s_barrier
	s_setprio 1
	s_waitcnt lgkmcnt(0)
	v_mfma_f32_16x16x32_bf16 v[124:127], v[140:143], v[180:183], v[124:127]
	v_mfma_f32_16x16x32_bf16 v[120:123], v[156:159], v[180:183], v[120:123]
	v_mfma_f32_16x16x32_bf16 v[112:115], v[140:143], v[188:191], v[112:115]
	v_mfma_f32_16x16x32_bf16 v[108:111], v[156:159], v[188:191], v[108:111]
	v_mfma_f32_16x16x32_bf16 v[96:99], v[140:143], v[196:199], v[96:99]
	v_mfma_f32_16x16x32_bf16 v[92:95], v[156:159], v[196:199], v[92:95]
	v_mfma_f32_16x16x32_bf16 v[80:83], v[140:143], v[206:209], v[80:83]
	v_mfma_f32_16x16x32_bf16 v[76:79], v[156:159], v[206:209], v[76:79]
	v_mfma_f32_16x16x32_bf16 v[124:127], v[152:155], v[184:187], v[124:127]
	v_mfma_f32_16x16x32_bf16 v[120:123], v[160:163], v[184:187], v[120:123]
	v_mfma_f32_16x16x32_bf16 v[112:115], v[152:155], v[192:195], v[112:115]
	v_mfma_f32_16x16x32_bf16 v[108:111], v[160:163], v[192:195], v[108:111]
	v_mfma_f32_16x16x32_bf16 v[96:99], v[152:155], v[200:203], v[96:99]
	v_mfma_f32_16x16x32_bf16 v[92:95], v[160:163], v[200:203], v[92:95]
	v_mfma_f32_16x16x32_bf16 v[80:83], v[152:155], v[210:213], v[80:83]
	v_mfma_f32_16x16x32_bf16 v[76:79], v[160:163], v[210:213], v[76:79]
	s_setprio 0
	s_setprio 1
	v_mfma_f32_16x16x32_bf16 v[116:119], v[164:167], v[180:183], v[116:119]
	v_mfma_f32_16x16x32_bf16 v[104:107], v[172:175], v[180:183], v[104:107]
	v_mfma_f32_16x16x32_bf16 v[100:103], v[164:167], v[188:191], v[100:103]
	v_mfma_f32_16x16x32_bf16 v[88:91], v[172:175], v[188:191], v[88:91]
	v_mfma_f32_16x16x32_bf16 v[84:87], v[164:167], v[196:199], v[84:87]
	v_mfma_f32_16x16x32_bf16 v[72:75], v[172:175], v[196:199], v[72:75]
	v_mfma_f32_16x16x32_bf16 v[68:71], v[164:167], v[206:209], v[68:71]
	v_mfma_f32_16x16x32_bf16 v[64:67], v[172:175], v[206:209], v[64:67]
	v_mfma_f32_16x16x32_bf16 v[116:119], v[168:171], v[184:187], v[116:119]
	v_mfma_f32_16x16x32_bf16 v[104:107], v[176:179], v[184:187], v[104:107]
	v_mfma_f32_16x16x32_bf16 v[100:103], v[168:171], v[192:195], v[100:103]
	v_mfma_f32_16x16x32_bf16 v[88:91], v[176:179], v[192:195], v[88:91]
	v_mfma_f32_16x16x32_bf16 v[84:87], v[168:171], v[200:203], v[84:87]
	v_mfma_f32_16x16x32_bf16 v[72:75], v[176:179], v[200:203], v[72:75]
	v_mfma_f32_16x16x32_bf16 v[68:71], v[168:171], v[210:213], v[68:71]
	v_mfma_f32_16x16x32_bf16 v[64:67], v[176:179], v[210:213], v[64:67]
	s_setprio 0
	s_barrier
; #define PG8_STAGE(bufoff, gbase, voff) do { _Pragma("unroll") for (int _i = 0; _i < 2; ++_i) \
;         __builtin_amdgcn_global_load_lds((const unsigned*)((const char*)(gbase) + (voff)[_i]), (PG8_LAS unsigned*)(lds + (bufoff) + ldsw + _i * 8192), 16, 0, 0); } while (0)
; #define PG8_LDA(dst, b, h) do { _Pragma("unroll") for (int m = 0; m < 4; ++m) _Pragma("unroll") for (int k = 0; k < 2; ++k) dst[m][k] = *(const PG8_LAS bf16x8*)(lds + PG8_SA(b, h) + aoff + m * 2048 + k * 1024); } while (0)
; #define PG8_MMA(ai, bj, At, Bt) do { __builtin_amdgcn_s_setprio(1); _Pragma("unroll") for (int m = 0; m < 4; ++m) _Pragma("unroll") for (int n = 0; n < 2; ++n) _Pragma("unroll") for (int k = 0; k < 2; ++k) \
;         acc[ai][bj][m][n] = __builtin_amdgcn_mfma_f32_16x16x32_bf16(Bt[n][k], At[m][k], acc[ai][bj][m][n], 0, 0, 0); __builtin_amdgcn_s_setprio(0); } while (0)
; #define PG8_WAIT_V(n) asm volatile("s_waitcnt vmcnt(" #n ")" ::: "memory")
; #define PG8_WAIT_L(n) asm volatile("s_waitcnt lgkmcnt(" #n ")" ::: "memory")
; #define PG8_BAR __builtin_amdgcn_s_barrier()
; #define PG8_SCHED __builtin_amdgcn_sched_barrier(0)
; template <class Epi, class Sched, bool ALIGN_EPI = false, bool SP2 = false>
; __device__ __forceinline__ void gemm_phase(PG8_LAS unsigned char* lds, const Gemm g, const Sched S, const Epi E) {
;     ...
;         for (int t = 0; t < nt; t += 2) {
;     ...
;             PG8_LDA(At, 1, 1); PG8_STAGE(PG8_SB(1, 0), b3, voffB); PG8_STAGE(PG8_SB(1, 1), b3 + hstep, voffB); PG8_STAGE(PG8_SA(1, 0), a3, voffA);
;             PG8_WAIT_V(8); PG8_WAIT_L(0); PG8_BAR; PG8_MMA(1, 0, At, B0); PG8_MMA(1, 1, At, B1); PG8_BAR; PG8_SCHED;
	s_add_i32 s42, s67, s4
	v_lshl_add_u64 v[214:215], v[214:215], 0, s[10:11]
	s_mov_b32 m0, s42
	ds_read_b128 v[180:183], v150 offset:49152
	ds_read_b128 v[184:187], v150 offset:50176
	ds_read_b128 v[188:191], v150 offset:51200
	ds_read_b128 v[192:195], v150 offset:52224
	ds_read_b128 v[196:199], v150 offset:53248
	ds_read_b128 v[200:203], v150 offset:54272
	ds_read_b128 v[206:209], v150 offset:55296
	ds_read_b128 v[210:213], v150 offset:56320
	global_load_lds_dwordx4 v[214:215], off
	s_add_i32 m0, s42, 0x2000
	s_add_u32 s40, s40, 0x40080
	v_lshl_add_u64 v[214:215], v[216:217], 0, s[10:11]
	s_addc_u32 s41, s41, 0
	s_add_i32 s42, s68, s4
	global_load_lds_dwordx4 v[214:215], off
	v_lshl_add_u64 v[214:215], s[40:41], 0, v[128:129]
	s_mov_b32 m0, s42
	s_nop 0
	global_load_lds_dwordx4 v[214:215], off
	v_lshl_add_u64 v[214:215], s[40:41], 0, v[130:131]
	s_add_i32 m0, s42, 0x2000
	s_nop 0
	global_load_lds_dwordx4 v[214:215], off
	v_lshl_add_u64 v[214:215], v[218:219], 0, s[10:11]
	s_mov_b32 m0, s47
	s_nop 0
	global_load_lds_dwordx4 v[214:215], off
	v_lshl_add_u64 v[214:215], v[220:221], 0, s[10:11]
	s_mov_b32 m0, s54
	s_nop 0
	global_load_lds_dwordx4 v[214:215], off
	s_waitcnt vmcnt(8)
	s_waitcnt lgkmcnt(0)
	s_barrier
	s_setprio 1
	s_waitcnt lgkmcnt(0)
	v_mfma_f32_16x16x32_bf16 v[60:63], v[140:143], v[180:183], v[60:63]
	v_mfma_f32_16x16x32_bf16 v[56:59], v[156:159], v[180:183], v[56:59]
	v_mfma_f32_16x16x32_bf16 v[48:51], v[140:143], v[188:191], v[48:51]
	v_mfma_f32_16x16x32_bf16 v[44:47], v[156:159], v[188:191], v[44:47]
	v_mfma_f32_16x16x32_bf16 v[32:35], v[140:143], v[196:199], v[32:35]
	v_mfma_f32_16x16x32_bf16 v[28:31], v[156:159], v[196:199], v[28:31]
	v_mfma_f32_16x16x32_bf16 v[16:19], v[140:143], v[206:209], v[16:19]
	v_mfma_f32_16x16x32_bf16 v[12:15], v[156:159], v[206:209], v[12:15]
	v_mfma_f32_16x16x32_bf16 v[60:63], v[152:155], v[184:187], v[60:63]
	v_mfma_f32_16x16x32_bf16 v[56:59], v[160:163], v[184:187], v[56:59]
	v_mfma_f32_16x16x32_bf16 v[48:51], v[152:155], v[192:195], v[48:51]
	v_mfma_f32_16x16x32_bf16 v[44:47], v[160:163], v[192:195], v[44:47]
	v_mfma_f32_16x16x32_bf16 v[32:35], v[152:155], v[200:203], v[32:35]
	v_mfma_f32_16x16x32_bf16 v[28:31], v[160:163], v[200:203], v[28:31]
	v_mfma_f32_16x16x32_bf16 v[16:19], v[152:155], v[210:213], v[16:19]
	v_mfma_f32_16x16x32_bf16 v[12:15], v[160:163], v[210:213], v[12:15]
	s_setprio 0
	s_setprio 1
	v_mfma_f32_16x16x32_bf16 v[52:55], v[164:167], v[180:183], v[52:55]
	v_mfma_f32_16x16x32_bf16 v[40:43], v[172:175], v[180:183], v[40:43]
	v_mfma_f32_16x16x32_bf16 v[36:39], v[164:167], v[188:191], v[36:39]
	v_mfma_f32_16x16x32_bf16 v[24:27], v[172:175], v[188:191], v[24:27]
	v_mfma_f32_16x16x32_bf16 v[20:23], v[164:167], v[196:199], v[20:23]
	v_mfma_f32_16x16x32_bf16 v[8:11], v[172:175], v[196:199], v[8:11]
	v_mfma_f32_16x16x32_bf16 v[4:7], v[164:167], v[206:209], v[4:7]
	v_mfma_f32_16x16x32_bf16 v[0:3], v[172:175], v[206:209], v[0:3]
	v_mfma_f32_16x16x32_bf16 v[52:55], v[168:171], v[184:187], v[52:55]
	v_mfma_f32_16x16x32_bf16 v[40:43], v[176:179], v[184:187], v[40:43]
	v_mfma_f32_16x16x32_bf16 v[36:39], v[168:171], v[192:195], v[36:39]
	v_mfma_f32_16x16x32_bf16 v[24:27], v[176:179], v[192:195], v[24:27]
	v_mfma_f32_16x16x32_bf16 v[20:23], v[168:171], v[200:203], v[20:23]
	v_mfma_f32_16x16x32_bf16 v[8:11], v[176:179], v[200:203], v[8:11]
	v_mfma_f32_16x16x32_bf16 v[4:7], v[168:171], v[210:213], v[4:7]
	v_mfma_f32_16x16x32_bf16 v[0:3], v[176:179], v[210:213], v[0:3]
	s_setprio 0
	s_add_i32 s66, s66, 2
	s_add_u32 s38, s38, 0x100
	s_addc_u32 s39, s39, 0
	s_add_u32 s64, s64, 0x100
	s_addc_u32 s65, s65, 0
	s_cmp_gt_u32 s66, 13
	s_barrier
	s_cbranch_scc0 .LBB0_259
	s_and_b64 vcc, exec, s[12:13]
	s_cbranch_vccz .LBB0_262
	s_barrier

; #define PG8_STAGE(bufoff, gbase, voff) do { _Pragma("unroll") for (int _i = 0; _i < 2; ++_i) \
;         __builtin_amdgcn_global_load_lds((const unsigned*)((const char*)(gbase) + (voff)[_i]), (PG8_LAS unsigned*)(lds + (bufoff) + ldsw + _i * 8192), 16, 0, 0); } while (0)
; #define PG8_LDA(dst, b, h) do { _Pragma("unroll") for (int m = 0; m < 4; ++m) _Pragma("unroll") for (int k = 0; k < 2; ++k) dst[m][k] = *(const PG8_LAS bf16x8*)(lds + PG8_SA(b, h) + aoff + m * 2048 + k * 1024); } while (0)
; #define PG8_LDB(dst, b, h) do { _Pragma("unroll") for (int n = 0; n < 2; ++n) _Pragma("unroll") for (int k = 0; k < 2; ++k) dst[n][k] = *(const PG8_LAS bf16x8*)(lds + PG8_SB(b, h) + boff + n * 2048 + k * 1024); } while (0)
; #define PG8_MMA(ai, bj, At, Bt) do { __builtin_amdgcn_s_setprio(1); _Pragma("unroll") for (int m = 0; m < 4; ++m) _Pragma("unroll") for (int n = 0; n < 2; ++n) _Pragma("unroll") for (int k = 0; k < 2; ++k) \
;         acc[ai][bj][m][n] = __builtin_amdgcn_mfma_f32_16x16x32_bf16(Bt[n][k], At[m][k], acc[ai][bj][m][n], 0, 0, 0); __builtin_amdgcn_s_setprio(0); } while (0)
; #define PG8_WAIT_V(n) asm volatile("s_waitcnt vmcnt(" #n ")" ::: "memory")
; #define PG8_WAIT_L(n) asm volatile("s_waitcnt lgkmcnt(" #n ")" ::: "memory")
; template <class Epi, class Sched, bool ALIGN_EPI = false, bool SP2 = false>
; __device__ __forceinline__ void gemm_phase(PG8_LAS unsigned char* lds, const Gemm g, const Sched S, const Epi E) {
;     ...
;             const bool last = (t == nt - 2);
;             const char* a1 = cA + (size_t)(t + 1) * kstepA;
;             const char* a2 = last ? nA : cA + (size_t)(t + 2) * kstepA; const char* b2 = last ? nB : cB + (size_t)(t + 2) * kstep;
;             const char* a3 = a2 + kstepA; const char* b3 = b2 + kstep;
;             if (last && has_next) S.a_ready(nxt);
;             if constexpr (SP2) {
;             PG8_LDB(B0, 0, 0); PG8_LDB(B1, 0, 1); PG8_SCHED; PG8_LDA(At, 0, 0); PG8_STAGE(PG8_SA(1, 1), a1 + hstepA, voffA);
;             PG8_WAIT_V(8); PG8_WAIT_L(0); PG8_BAR; PG8_MMA(0, 0, At, B0); PG8_MMA(0, 1, At, B1); PG8_BAR; PG8_SCHED;
;             PG8_LDA(At, 0, 1); PG8_STAGE(PG8_SB(0, 0), b2, voffB); PG8_STAGE(PG8_SB(0, 1), b2 + hstep, voffB); PG8_STAGE(PG8_SA(0, 0), a2, voffA);
;             PG8_WAIT_V(8); PG8_WAIT_L(0); PG8_BAR; PG8_MMA(1, 0, At, B0); PG8_MMA(1, 1, At, B1); PG8_BAR; PG8_SCHED;
.LBB0_390:
	ds_read_b128 v[152:155], v149
	ds_read_b128 v[156:159], v149 offset:1024
	ds_read_b128 v[162:165], v149 offset:2048
	ds_read_b128 v[166:169], v149 offset:3072
	ds_read_b128 v[170:173], v150
	ds_read_b128 v[174:177], v150 offset:1024
	ds_read_b128 v[178:181], v150 offset:2048
	ds_read_b128 v[182:185], v150 offset:3072
	s_add_u32 s46, s44, 0xfffc0080
	s_addc_u32 s47, s45, -1
	s_cmp_eq_u32 s77, 12
	s_cselect_b32 s71, s37, s47
	s_cselect_b32 s70, s73, s46
	s_cselect_b32 s47, s35, s76
	s_cselect_b32 s46, s74, s75
	v_lshl_add_u64 v[144:145], s[44:45], 0, v[136:137]
	s_add_i32 m0, s15, 0xc000
	ds_read_b128 v[186:189], v151
	ds_read_b128 v[190:193], v151 offset:1024
	ds_read_b128 v[194:197], v151 offset:2048
	ds_read_b128 v[198:201], v151 offset:3072
	ds_read_b128 v[206:209], v151 offset:4096
	ds_read_b128 v[210:213], v151 offset:5120
	ds_read_b128 v[214:217], v151 offset:6144
	ds_read_b128 v[218:221], v151 offset:7168
	global_load_lds_dwordx4 v[144:145], off
	v_lshl_add_u64 v[144:145], s[44:45], 0, v[138:139]
	s_add_i32 m0, s15, 0xe000
	s_nop 0
	global_load_lds_dwordx4 v[144:145], off
	s_waitcnt vmcnt(8)
	s_waitcnt lgkmcnt(0)
	s_barrier
	s_setprio 1
	s_waitcnt lgkmcnt(0)
	v_mfma_f32_16x16x32_bf16 v[124:127], v[152:155], v[186:189], v[124:127]
	v_mfma_f32_16x16x32_bf16 v[120:123], v[162:165], v[186:189], v[120:123]
	v_mfma_f32_16x16x32_bf16 v[108:111], v[152:155], v[194:197], v[108:111]
	v_mfma_f32_16x16x32_bf16 v[104:107], v[162:165], v[194:197], v[104:107]
	v_mfma_f32_16x16x32_bf16 v[92:95], v[152:155], v[206:209], v[92:95]
	v_mfma_f32_16x16x32_bf16 v[88:91], v[162:165], v[206:209], v[88:91]
	v_mfma_f32_16x16x32_bf16 v[76:79], v[152:155], v[214:217], v[76:79]
	v_mfma_f32_16x16x32_bf16 v[72:75], v[162:165], v[214:217], v[72:75]
	v_mfma_f32_16x16x32_bf16 v[124:127], v[156:159], v[190:193], v[124:127]
	v_mfma_f32_16x16x32_bf16 v[120:123], v[166:169], v[190:193], v[120:123]
	v_mfma_f32_16x16x32_bf16 v[108:111], v[156:159], v[198:201], v[108:111]
	v_mfma_f32_16x16x32_bf16 v[104:107], v[166:169], v[198:201], v[104:107]
	v_mfma_f32_16x16x32_bf16 v[92:95], v[156:159], v[210:213], v[92:95]
	v_mfma_f32_16x16x32_bf16 v[88:91], v[166:169], v[210:213], v[88:91]
	v_mfma_f32_16x16x32_bf16 v[76:79], v[156:159], v[218:221], v[76:79]
	v_mfma_f32_16x16x32_bf16 v[72:75], v[166:169], v[218:221], v[72:75]
	s_setprio 0
	s_setprio 1
	v_mfma_f32_16x16x32_bf16 v[116:119], v[170:173], v[186:189], v[116:119]
	v_mfma_f32_16x16x32_bf16 v[112:115], v[178:181], v[186:189], v[112:115]
	v_mfma_f32_16x16x32_bf16 v[100:103], v[170:173], v[194:197], v[100:103]
	v_mfma_f32_16x16x32_bf16 v[96:99], v[178:181], v[194:197], v[96:99]
	v_mfma_f32_16x16x32_bf16 v[84:87], v[170:173], v[206:209], v[84:87]
	v_mfma_f32_16x16x32_bf16 v[80:83], v[178:181], v[206:209], v[80:83]
	v_mfma_f32_16x16x32_bf16 v[68:71], v[170:173], v[214:217], v[68:71]
	v_mfma_f32_16x16x32_bf16 v[64:67], v[178:181], v[214:217], v[64:67]
	v_mfma_f32_16x16x32_bf16 v[116:119], v[174:177], v[190:193], v[116:119]
	v_mfma_f32_16x16x32_bf16 v[112:115], v[182:185], v[190:193], v[112:115]
	v_mfma_f32_16x16x32_bf16 v[100:103], v[174:177], v[198:201], v[100:103]
	v_mfma_f32_16x16x32_bf16 v[96:99], v[182:185], v[198:201], v[96:99]
	v_mfma_f32_16x16x32_bf16 v[84:87], v[174:177], v[210:213], v[84:87]
	v_mfma_f32_16x16x32_bf16 v[80:83], v[182:185], v[210:213], v[80:83]
	v_mfma_f32_16x16x32_bf16 v[68:71], v[174:177], v[218:221], v[68:71]
	v_mfma_f32_16x16x32_bf16 v[64:67], v[182:185], v[218:221], v[64:67]
	s_setprio 0
	s_barrier
	s_add_i32 s78, s63, s4
	v_lshl_add_u64 v[144:145], s[46:47], 0, v[132:133]
	s_mov_b32 m0, s78
	ds_read_b128 v[186:189], v151 offset:16384
	ds_read_b128 v[190:193], v151 offset:17408
	ds_read_b128 v[194:197], v151 offset:18432
	ds_read_b128 v[198:201], v151 offset:19456
	ds_read_b128 v[206:209], v151 offset:20480
	ds_read_b128 v[210:213], v151 offset:21504
	ds_read_b128 v[214:217], v151 offset:22528
	ds_read_b128 v[218:221], v151 offset:23552
	global_load_lds_dwordx4 v[144:145], off
	s_add_i32 m0, s78, 0x2000
	s_add_u32 s78, s46, 0x40000
	v_lshl_add_u64 v[202:203], s[46:47], 0, v[128:129]
	s_addc_u32 s79, s47, 0
	s_add_i32 s80, s64, s4
	global_load_lds_dwordx4 v[202:203], off
	v_lshl_add_u64 v[222:223], s[78:79], 0, v[132:133]
	s_mov_b32 m0, s80
	v_lshl_add_u64 v[224:225], s[70:71], 0, v[130:131]
	global_load_lds_dwordx4 v[222:223], off
	v_lshl_add_u64 v[222:223], s[78:79], 0, v[128:129]
	s_add_i32 m0, s80, 0x2000
	s_nop 0
	global_load_lds_dwordx4 v[222:223], off
	v_lshl_add_u64 v[222:223], s[70:71], 0, v[134:135]
	s_mov_b32 m0, s15
	s_nop 0
	global_load_lds_dwordx4 v[222:223], off
	s_mov_b32 m0, s33
	s_nop 0
	global_load_lds_dwordx4 v[224:225], off
	s_waitcnt vmcnt(8)
	s_waitcnt lgkmcnt(0)
	s_barrier
; #define PG8_STAGE(bufoff, gbase, voff) do { _Pragma("unroll") for (int _i = 0; _i < 2; ++_i) \
;         __builtin_amdgcn_global_load_lds((const unsigned*)((const char*)(gbase) + (voff)[_i]), (PG8_LAS unsigned*)(lds + (bufoff) + ldsw + _i * 8192), 16, 0, 0); } while (0)
; #define PG8_LDA(dst, b, h) do { _Pragma("unroll") for (int m = 0; m < 4; ++m) _Pragma("unroll") for (int k = 0; k < 2; ++k) dst[m][k] = *(const PG8_LAS bf16x8*)(lds + PG8_SA(b, h) + aoff + m * 2048 + k * 1024); } while (0)
; #define PG8_LDB(dst, b, h) do { _Pragma("unroll") for (int n = 0; n < 2; ++n) _Pragma("unroll") for (int k = 0; k < 2; ++k) dst[n][k] = *(const PG8_LAS bf16x8*)(lds + PG8_SB(b, h) + boff + n * 2048 + k * 1024); } while (0)
; #define PG8_MMA(ai, bj, At, Bt) do { __builtin_amdgcn_s_setprio(1); _Pragma("unroll") for (int m = 0; m < 4; ++m) _Pragma("unroll") for (int n = 0; n < 2; ++n) _Pragma("unroll") for (int k = 0; k < 2; ++k) \
;         acc[ai][bj][m][n] = __builtin_amdgcn_mfma_f32_16x16x32_bf16(Bt[n][k], At[m][k], acc[ai][bj][m][n], 0, 0, 0); __builtin_amdgcn_s_setprio(0); } while (0)
; #define PG8_WAIT_V(n) asm volatile("s_waitcnt vmcnt(" #n ")" ::: "memory")
; #define PG8_WAIT_L(n) asm volatile("s_waitcnt lgkmcnt(" #n ")" ::: "memory")
; #define PG8_BAR __builtin_amdgcn_s_barrier()
; #define PG8_SCHED __builtin_amdgcn_sched_barrier(0)
; template <class Epi, class Sched, bool ALIGN_EPI = false, bool SP2 = false>
; __device__ __forceinline__ void gemm_phase(PG8_LAS unsigned char* lds, const Gemm g, const Sched S, const Epi E) {
;     ...
;             PG8_WAIT_V(8); PG8_WAIT_L(0); PG8_BAR; PG8_MMA(1, 0, At, B0); PG8_MMA(1, 1, At, B1); PG8_BAR; PG8_SCHED;
;             PG8_LDB(B0, 1, 0); PG8_LDB(B1, 1, 1); PG8_SCHED; PG8_LDA(At, 1, 0); PG8_STAGE(PG8_SA(0, 1), a2 + hstepA, voffA);
;             PG8_WAIT_V(8); PG8_WAIT_L(0); PG8_BAR; PG8_MMA(0, 0, At, B0); PG8_MMA(0, 1, At, B1); PG8_BAR; PG8_SCHED;
	s_setprio 1
	s_waitcnt lgkmcnt(0)
	v_mfma_f32_16x16x32_bf16 v[60:63], v[152:155], v[186:189], v[60:63]
	v_mfma_f32_16x16x32_bf16 v[56:59], v[162:165], v[186:189], v[56:59]
	v_mfma_f32_16x16x32_bf16 v[44:47], v[152:155], v[194:197], v[44:47]
	v_mfma_f32_16x16x32_bf16 v[40:43], v[162:165], v[194:197], v[40:43]
	v_mfma_f32_16x16x32_bf16 v[28:31], v[152:155], v[206:209], v[28:31]
	v_mfma_f32_16x16x32_bf16 v[24:27], v[162:165], v[206:209], v[24:27]
	v_mfma_f32_16x16x32_bf16 v[12:15], v[152:155], v[214:217], v[12:15]
	v_mfma_f32_16x16x32_bf16 v[8:11], v[162:165], v[214:217], v[8:11]
	v_mfma_f32_16x16x32_bf16 v[60:63], v[156:159], v[190:193], v[60:63]
	v_mfma_f32_16x16x32_bf16 v[56:59], v[166:169], v[190:193], v[56:59]
	v_mfma_f32_16x16x32_bf16 v[44:47], v[156:159], v[198:201], v[44:47]
	v_mfma_f32_16x16x32_bf16 v[40:43], v[166:169], v[198:201], v[40:43]
	v_mfma_f32_16x16x32_bf16 v[28:31], v[156:159], v[210:213], v[28:31]
	v_mfma_f32_16x16x32_bf16 v[24:27], v[166:169], v[210:213], v[24:27]
	v_mfma_f32_16x16x32_bf16 v[12:15], v[156:159], v[218:221], v[12:15]
	v_mfma_f32_16x16x32_bf16 v[8:11], v[166:169], v[218:221], v[8:11]
	s_setprio 0
	s_setprio 1
	v_mfma_f32_16x16x32_bf16 v[52:55], v[170:173], v[186:189], v[52:55]
	v_mfma_f32_16x16x32_bf16 v[48:51], v[178:181], v[186:189], v[48:51]
	v_mfma_f32_16x16x32_bf16 v[36:39], v[170:173], v[194:197], v[36:39]
	v_mfma_f32_16x16x32_bf16 v[32:35], v[178:181], v[194:197], v[32:35]
	v_mfma_f32_16x16x32_bf16 v[20:23], v[170:173], v[206:209], v[20:23]
	v_mfma_f32_16x16x32_bf16 v[16:19], v[178:181], v[206:209], v[16:19]
	v_mfma_f32_16x16x32_bf16 v[4:7], v[170:173], v[214:217], v[4:7]
	v_mfma_f32_16x16x32_bf16 v[0:3], v[178:181], v[214:217], v[0:3]
	v_mfma_f32_16x16x32_bf16 v[52:55], v[174:177], v[190:193], v[52:55]
	v_mfma_f32_16x16x32_bf16 v[48:51], v[182:185], v[190:193], v[48:51]
	v_mfma_f32_16x16x32_bf16 v[36:39], v[174:177], v[198:201], v[36:39]
	v_mfma_f32_16x16x32_bf16 v[32:35], v[182:185], v[198:201], v[32:35]
	v_mfma_f32_16x16x32_bf16 v[20:23], v[174:177], v[210:213], v[20:23]
	v_mfma_f32_16x16x32_bf16 v[16:19], v[182:185], v[210:213], v[16:19]
	v_mfma_f32_16x16x32_bf16 v[4:7], v[174:177], v[218:221], v[4:7]
	v_mfma_f32_16x16x32_bf16 v[0:3], v[182:185], v[218:221], v[0:3]
	s_setprio 0
	s_barrier
	s_add_i32 s78, 0, 0x18000
	v_add_u32_e32 v161, s78, v148
	s_add_i32 s79, 0, 0x1c000
	ds_read_b128 v[152:155], v161
	ds_read_b128 v[156:159], v161 offset:1024
	ds_read_b128 v[162:165], v161 offset:2048
	ds_read_b128 v[166:169], v161 offset:3072
	v_add_u32_e32 v161, s79, v148
	ds_read_b128 v[170:173], v161
	ds_read_b128 v[174:177], v161 offset:1024
	ds_read_b128 v[178:181], v161 offset:2048
	ds_read_b128 v[182:185], v161 offset:3072
	s_add_u32 s70, s70, 0x40000
	s_addc_u32 s71, s71, 0
	s_mov_b32 m0, s43
	v_lshl_add_u64 v[226:227], s[70:71], 0, v[134:135]
	ds_read_b128 v[186:189], v151 offset:32768
	ds_read_b128 v[190:193], v151 offset:33792
	ds_read_b128 v[194:197], v151 offset:34816
	ds_read_b128 v[198:201], v151 offset:35840
	ds_read_b128 v[206:209], v151 offset:36864
	ds_read_b128 v[210:213], v151 offset:37888
	ds_read_b128 v[214:217], v151 offset:38912
	ds_read_b128 v[218:221], v151 offset:39936
	global_load_lds_dwordx4 v[226:227], off
	v_lshl_add_u64 v[226:227], s[70:71], 0, v[130:131]
	s_mov_b32 m0, s54
	s_nop 0
	global_load_lds_dwordx4 v[226:227], off
	s_waitcnt vmcnt(8)
	s_waitcnt lgkmcnt(0)
	s_barrier
	s_setprio 1
	s_waitcnt lgkmcnt(0)
	v_mfma_f32_16x16x32_bf16 v[124:127], v[152:155], v[186:189], v[124:127]
	v_mfma_f32_16x16x32_bf16 v[120:123], v[162:165], v[186:189], v[120:123]
	v_mfma_f32_16x16x32_bf16 v[108:111], v[152:155], v[194:197], v[108:111]
	v_mfma_f32_16x16x32_bf16 v[104:107], v[162:165], v[194:197], v[104:107]
	v_mfma_f32_16x16x32_bf16 v[92:95], v[152:155], v[206:209], v[92:95]
	v_mfma_f32_16x16x32_bf16 v[88:91], v[162:165], v[206:209], v[88:91]
	v_mfma_f32_16x16x32_bf16 v[76:79], v[152:155], v[214:217], v[76:79]
	v_mfma_f32_16x16x32_bf16 v[72:75], v[162:165], v[214:217], v[72:75]
	v_mfma_f32_16x16x32_bf16 v[124:127], v[156:159], v[190:193], v[124:127]
	v_mfma_f32_16x16x32_bf16 v[120:123], v[166:169], v[190:193], v[120:123]
	v_mfma_f32_16x16x32_bf16 v[108:111], v[156:159], v[198:201], v[108:111]
	v_mfma_f32_16x16x32_bf16 v[104:107], v[166:169], v[198:201], v[104:107]
	v_mfma_f32_16x16x32_bf16 v[92:95], v[156:159], v[210:213], v[92:95]
	v_mfma_f32_16x16x32_bf16 v[88:91], v[166:169], v[210:213], v[88:91]
	v_mfma_f32_16x16x32_bf16 v[76:79], v[156:159], v[218:221], v[76:79]
	v_mfma_f32_16x16x32_bf16 v[72:75], v[166:169], v[218:221], v[72:75]
	s_setprio 0
	s_setprio 1
	v_mfma_f32_16x16x32_bf16 v[116:119], v[170:173], v[186:189], v[116:119]
	v_mfma_f32_16x16x32_bf16 v[112:115], v[178:181], v[186:189], v[112:115]
	v_mfma_f32_16x16x32_bf16 v[100:103], v[170:173], v[194:197], v[100:103]
	v_mfma_f32_16x16x32_bf16 v[96:99], v[178:181], v[194:197], v[96:99]
	v_mfma_f32_16x16x32_bf16 v[84:87], v[170:173], v[206:209], v[84:87]
	v_mfma_f32_16x16x32_bf16 v[80:83], v[178:181], v[206:209], v[80:83]
	v_mfma_f32_16x16x32_bf16 v[68:71], v[170:173], v[214:217], v[68:71]
	v_mfma_f32_16x16x32_bf16 v[64:67], v[178:181], v[214:217], v[64:67]
	v_mfma_f32_16x16x32_bf16 v[116:119], v[174:177], v[190:193], v[116:119]
	v_mfma_f32_16x16x32_bf16 v[112:115], v[182:185], v[190:193], v[112:115]
	v_mfma_f32_16x16x32_bf16 v[100:103], v[174:177], v[198:201], v[100:103]
	v_mfma_f32_16x16x32_bf16 v[96:99], v[182:185], v[198:201], v[96:99]
	v_mfma_f32_16x16x32_bf16 v[84:87], v[174:177], v[210:213], v[84:87]
	v_mfma_f32_16x16x32_bf16 v[80:83], v[182:185], v[210:213], v[80:83]
	v_mfma_f32_16x16x32_bf16 v[68:71], v[174:177], v[218:221], v[68:71]
	v_mfma_f32_16x16x32_bf16 v[64:67], v[182:185], v[218:221], v[64:67]
	s_setprio 0
	s_barrier
; #define PG8_STAGE(bufoff, gbase, voff) do { _Pragma("unroll") for (int _i = 0; _i < 2; ++_i) \
;         __builtin_amdgcn_global_load_lds((const unsigned*)((const char*)(gbase) + (voff)[_i]), (PG8_LAS unsigned*)(lds + (bufoff) + ldsw + _i * 8192), 16, 0, 0); } while (0)
; #define PG8_LDA(dst, b, h) do { _Pragma("unroll") for (int m = 0; m < 4; ++m) _Pragma("unroll") for (int k = 0; k < 2; ++k) dst[m][k] = *(const PG8_LAS bf16x8*)(lds + PG8_SA(b, h) + aoff + m * 2048 + k * 1024); } while (0)
; #define PG8_MMA(ai, bj, At, Bt) do { __builtin_amdgcn_s_setprio(1); _Pragma("unroll") for (int m = 0; m < 4; ++m) _Pragma("unroll") for (int n = 0; n < 2; ++n) _Pragma("unroll") for (int k = 0; k < 2; ++k) \
;         acc[ai][bj][m][n] = __builtin_amdgcn_mfma_f32_16x16x32_bf16(Bt[n][k], At[m][k], acc[ai][bj][m][n], 0, 0, 0); __builtin_amdgcn_s_setprio(0); } while (0)
; #define PG8_WAIT_V(n) asm volatile("s_waitcnt vmcnt(" #n ")" ::: "memory")
; #define PG8_WAIT_L(n) asm volatile("s_waitcnt lgkmcnt(" #n ")" ::: "memory")
; #define PG8_BAR __builtin_amdgcn_s_barrier()
; #define PG8_SCHED __builtin_amdgcn_sched_barrier(0)
; template <class Epi, class Sched, bool ALIGN_EPI = false, bool SP2 = false>
; __device__ __forceinline__ void gemm_phase(PG8_LAS unsigned char* lds, const Gemm g, const Sched S, const Epi E) {
;     ...
;         for (int t = 0; t < nt; t += 2) {
;     ...
;             PG8_LDA(At, 1, 1); PG8_STAGE(PG8_SB(1, 0), b3, voffB); PG8_STAGE(PG8_SB(1, 1), b3 + hstep, voffB); PG8_STAGE(PG8_SA(1, 0), a3, voffA);
;             PG8_WAIT_V(8); PG8_WAIT_L(0); PG8_BAR; PG8_MMA(1, 0, At, B0); PG8_MMA(1, 1, At, B1); PG8_BAR; PG8_SCHED;
	s_add_i32 s70, s78, s4
	v_lshl_add_u64 v[144:145], v[144:145], 0, s[8:9]
	s_mov_b32 m0, s70
	ds_read_b128 v[186:189], v151 offset:49152
	ds_read_b128 v[190:193], v151 offset:50176
	ds_read_b128 v[194:197], v151 offset:51200
	ds_read_b128 v[198:201], v151 offset:52224
	ds_read_b128 v[206:209], v151 offset:53248
	ds_read_b128 v[210:213], v151 offset:54272
	ds_read_b128 v[214:217], v151 offset:55296
	ds_read_b128 v[218:221], v151 offset:56320
	global_load_lds_dwordx4 v[144:145], off
	s_add_i32 m0, s70, 0x2000
	s_add_u32 s46, s46, 0x40080
	v_lshl_add_u64 v[144:145], v[202:203], 0, s[8:9]
	s_addc_u32 s47, s47, 0
	s_add_i32 s70, s79, s4
	global_load_lds_dwordx4 v[144:145], off
	v_lshl_add_u64 v[144:145], s[46:47], 0, v[132:133]
	s_mov_b32 m0, s70
	s_nop 0
	global_load_lds_dwordx4 v[144:145], off
	v_lshl_add_u64 v[144:145], s[46:47], 0, v[128:129]
	s_add_i32 m0, s70, 0x2000
	s_nop 0
	global_load_lds_dwordx4 v[144:145], off
	v_lshl_add_u64 v[144:145], v[222:223], 0, s[8:9]
	s_mov_b32 m0, s61
	s_nop 0
	global_load_lds_dwordx4 v[144:145], off
	v_lshl_add_u64 v[144:145], v[224:225], 0, s[8:9]
	s_mov_b32 m0, s62
	s_nop 0
	global_load_lds_dwordx4 v[144:145], off
	s_waitcnt vmcnt(8)
	s_waitcnt lgkmcnt(0)
	s_barrier
	s_setprio 1
	s_waitcnt lgkmcnt(0)
	v_mfma_f32_16x16x32_bf16 v[60:63], v[152:155], v[186:189], v[60:63]
	v_mfma_f32_16x16x32_bf16 v[56:59], v[162:165], v[186:189], v[56:59]
	v_mfma_f32_16x16x32_bf16 v[44:47], v[152:155], v[194:197], v[44:47]
	v_mfma_f32_16x16x32_bf16 v[40:43], v[162:165], v[194:197], v[40:43]
	v_mfma_f32_16x16x32_bf16 v[28:31], v[152:155], v[206:209], v[28:31]
	v_mfma_f32_16x16x32_bf16 v[24:27], v[162:165], v[206:209], v[24:27]
	v_mfma_f32_16x16x32_bf16 v[12:15], v[152:155], v[214:217], v[12:15]
	v_mfma_f32_16x16x32_bf16 v[8:11], v[162:165], v[214:217], v[8:11]
	v_mfma_f32_16x16x32_bf16 v[60:63], v[156:159], v[190:193], v[60:63]
	v_mfma_f32_16x16x32_bf16 v[56:59], v[166:169], v[190:193], v[56:59]
	v_mfma_f32_16x16x32_bf16 v[44:47], v[156:159], v[198:201], v[44:47]
	v_mfma_f32_16x16x32_bf16 v[40:43], v[166:169], v[198:201], v[40:43]
	v_mfma_f32_16x16x32_bf16 v[28:31], v[156:159], v[210:213], v[28:31]
	v_mfma_f32_16x16x32_bf16 v[24:27], v[166:169], v[210:213], v[24:27]
	v_mfma_f32_16x16x32_bf16 v[12:15], v[156:159], v[218:221], v[12:15]
	v_mfma_f32_16x16x32_bf16 v[8:11], v[166:169], v[218:221], v[8:11]
	s_setprio 0
	s_setprio 1
	v_mfma_f32_16x16x32_bf16 v[52:55], v[170:173], v[186:189], v[52:55]
	v_mfma_f32_16x16x32_bf16 v[48:51], v[178:181], v[186:189], v[48:51]
	v_mfma_f32_16x16x32_bf16 v[36:39], v[170:173], v[194:197], v[36:39]
	v_mfma_f32_16x16x32_bf16 v[32:35], v[178:181], v[194:197], v[32:35]
	v_mfma_f32_16x16x32_bf16 v[20:23], v[170:173], v[206:209], v[20:23]
	v_mfma_f32_16x16x32_bf16 v[16:19], v[178:181], v[206:209], v[16:19]
	v_mfma_f32_16x16x32_bf16 v[4:7], v[170:173], v[214:217], v[4:7]
	v_mfma_f32_16x16x32_bf16 v[0:3], v[178:181], v[214:217], v[0:3]
	v_mfma_f32_16x16x32_bf16 v[52:55], v[174:177], v[190:193], v[52:55]
	v_mfma_f32_16x16x32_bf16 v[48:51], v[182:185], v[190:193], v[48:51]
	v_mfma_f32_16x16x32_bf16 v[36:39], v[174:177], v[198:201], v[36:39]
	v_mfma_f32_16x16x32_bf16 v[32:35], v[182:185], v[198:201], v[32:35]
	v_mfma_f32_16x16x32_bf16 v[20:23], v[174:177], v[210:213], v[20:23]
	v_mfma_f32_16x16x32_bf16 v[16:19], v[182:185], v[210:213], v[16:19]
	v_mfma_f32_16x16x32_bf16 v[4:7], v[174:177], v[218:221], v[4:7]
	v_mfma_f32_16x16x32_bf16 v[0:3], v[182:185], v[218:221], v[0:3]
	s_setprio 0
	s_add_i32 s77, s77, 2
	s_add_u32 s44, s44, 0x100
	s_addc_u32 s45, s45, 0
	s_add_u32 s75, s75, 0x100
	s_addc_u32 s76, s76, 0
	s_cmp_gt_u32 s77, 13
	s_barrier
	s_cbranch_scc0 .LBB0_390
	s_and_b64 vcc, exec, s[24:25]
	s_cbranch_vccz .LBB0_393
	s_barrier

; #define PG8_STAGE(bufoff, gbase, voff) do { _Pragma("unroll") for (int _i = 0; _i < 2; ++_i) \
;         __builtin_amdgcn_global_load_lds((const unsigned*)((const char*)(gbase) + (voff)[_i]), (PG8_LAS unsigned*)(lds + (bufoff) + ldsw + _i * 8192), 16, 0, 0); } while (0)
; #define PG8_LDA(dst, b, h) do { _Pragma("unroll") for (int m = 0; m < 4; ++m) _Pragma("unroll") for (int k = 0; k < 2; ++k) dst[m][k] = *(const PG8_LAS bf16x8*)(lds + PG8_SA(b, h) + aoff + m * 2048 + k * 1024); } while (0)
; #define PG8_LDB(dst, b, h) do { _Pragma("unroll") for (int n = 0; n < 2; ++n) _Pragma("unroll") for (int k = 0; k < 2; ++k) dst[n][k] = *(const PG8_LAS bf16x8*)(lds + PG8_SB(b, h) + boff + n * 2048 + k * 1024); } while (0)
; #define PG8_MMA(ai, bj, At, Bt) do { __builtin_amdgcn_s_setprio(1); _Pragma("unroll") for (int m = 0; m < 4; ++m) _Pragma("unroll") for (int n = 0; n < 2; ++n) _Pragma("unroll") for (int k = 0; k < 2; ++k) \
;         acc[ai][bj][m][n] = __builtin_amdgcn_mfma_f32_16x16x32_bf16(Bt[n][k], At[m][k], acc[ai][bj][m][n], 0, 0, 0); __builtin_amdgcn_s_setprio(0); } while (0)
; #define PG8_WAIT_V(n) asm volatile("s_waitcnt vmcnt(" #n ")" ::: "memory")
; #define PG8_WAIT_L(n) asm volatile("s_waitcnt lgkmcnt(" #n ")" ::: "memory")
; template <class Epi, class Sched, bool ALIGN_EPI = false, bool SP2 = false>
; __device__ __forceinline__ void gemm_phase(PG8_LAS unsigned char* lds, const Gemm g, const Sched S, const Epi E) {
;     ...
;             const bool last = (t == nt - 2);
;             const char* a1 = cA + (size_t)(t + 1) * kstepA;
;             const char* a2 = last ? nA : cA + (size_t)(t + 2) * kstepA; const char* b2 = last ? nB : cB + (size_t)(t + 2) * kstep;
;             const char* a3 = a2 + kstepA; const char* b3 = b2 + kstep;
;             if (last && has_next) S.a_ready(nxt);
;             if constexpr (SP2) {
;             PG8_LDB(B0, 0, 0); PG8_LDB(B1, 0, 1); PG8_SCHED; PG8_LDA(At, 0, 0); PG8_STAGE(PG8_SA(1, 1), a1 + hstepA, voffA);
;             PG8_WAIT_V(8); PG8_WAIT_L(0); PG8_BAR; PG8_MMA(0, 0, At, B0); PG8_MMA(0, 1, At, B1); PG8_BAR; PG8_SCHED;
;             PG8_LDA(At, 0, 1); PG8_STAGE(PG8_SB(0, 0), b2, voffB); PG8_STAGE(PG8_SB(0, 1), b2 + hstep, voffB); PG8_STAGE(PG8_SA(0, 0), a2, voffA);
;             PG8_WAIT_V(8); PG8_WAIT_L(0); PG8_BAR; PG8_MMA(1, 0, At, B0); PG8_MMA(1, 1, At, B1); PG8_BAR; PG8_SCHED;
.LBB0_469:
	ds_read_b128 v[64:67], v188
	ds_read_b128 v[68:71], v188 offset:1024
	ds_read_b128 v[72:75], v188 offset:2048
	ds_read_b128 v[76:79], v188 offset:3072
	ds_read_b128 v[80:83], v189
	ds_read_b128 v[84:87], v189 offset:1024
	ds_read_b128 v[88:91], v189 offset:2048
	ds_read_b128 v[92:95], v189 offset:3072
	s_add_u32 s69, s72, 0xfff00080
	s_addc_u32 s71, s73, -1
	s_cmp_eq_u32 s68, 60
	s_cselect_b32 s77, s1, s71
	s_cselect_b32 s76, s43, s69
	s_cselect_b32 s75, s41, s67
	s_cselect_b32 s74, s65, s66
	v_lshl_add_u64 v[180:181], s[72:73], 0, v[166:167]
	s_add_i32 m0, s15, 0xc000
	ds_read_b128 v[174:177], v190
	ds_read_b128 v[184:187], v190 offset:1024
	ds_read_b128 v[192:195], v190 offset:2048
	ds_read_b128 v[196:199], v190 offset:3072
	ds_read_b128 v[200:203], v190 offset:4096
	ds_read_b128 v[206:209], v190 offset:5120
	ds_read_b128 v[210:213], v190 offset:6144
	ds_read_b128 v[214:217], v190 offset:7168
	global_load_lds_dwordx4 v[180:181], off
	v_lshl_add_u64 v[180:181], s[72:73], 0, v[168:169]
	s_add_i32 m0, s15, 0xe000
	s_nop 0
	global_load_lds_dwordx4 v[180:181], off
	s_waitcnt vmcnt(8)
	s_waitcnt lgkmcnt(0)
	s_barrier
	s_setprio 1
	s_waitcnt lgkmcnt(0)
	v_mfma_f32_16x16x32_bf16 v[156:159], v[64:67], v[174:177], v[156:159]
	v_mfma_f32_16x16x32_bf16 v[152:155], v[72:75], v[174:177], v[152:155]
	v_mfma_f32_16x16x32_bf16 v[140:143], v[64:67], v[192:195], v[140:143]
	v_mfma_f32_16x16x32_bf16 v[136:139], v[72:75], v[192:195], v[136:139]
	v_mfma_f32_16x16x32_bf16 v[124:127], v[64:67], v[200:203], v[124:127]
	v_mfma_f32_16x16x32_bf16 v[120:123], v[72:75], v[200:203], v[120:123]
	v_mfma_f32_16x16x32_bf16 v[108:111], v[64:67], v[210:213], v[108:111]
	v_mfma_f32_16x16x32_bf16 v[104:107], v[72:75], v[210:213], v[104:107]
	v_mfma_f32_16x16x32_bf16 v[156:159], v[68:71], v[184:187], v[156:159]
	v_mfma_f32_16x16x32_bf16 v[152:155], v[76:79], v[184:187], v[152:155]
	v_mfma_f32_16x16x32_bf16 v[140:143], v[68:71], v[196:199], v[140:143]
	v_mfma_f32_16x16x32_bf16 v[136:139], v[76:79], v[196:199], v[136:139]
	v_mfma_f32_16x16x32_bf16 v[124:127], v[68:71], v[206:209], v[124:127]
	v_mfma_f32_16x16x32_bf16 v[120:123], v[76:79], v[206:209], v[120:123]
	v_mfma_f32_16x16x32_bf16 v[108:111], v[68:71], v[214:217], v[108:111]
	v_mfma_f32_16x16x32_bf16 v[104:107], v[76:79], v[214:217], v[104:107]
	s_setprio 0
	s_setprio 1
	v_mfma_f32_16x16x32_bf16 v[148:151], v[80:83], v[174:177], v[148:151]
	v_mfma_f32_16x16x32_bf16 v[144:147], v[88:91], v[174:177], v[144:147]
	v_mfma_f32_16x16x32_bf16 v[132:135], v[80:83], v[192:195], v[132:135]
	v_mfma_f32_16x16x32_bf16 v[128:131], v[88:91], v[192:195], v[128:131]
	v_mfma_f32_16x16x32_bf16 v[116:119], v[80:83], v[200:203], v[116:119]
	v_mfma_f32_16x16x32_bf16 v[112:115], v[88:91], v[200:203], v[112:115]
	v_mfma_f32_16x16x32_bf16 v[100:103], v[80:83], v[210:213], v[100:103]
	v_mfma_f32_16x16x32_bf16 v[96:99], v[88:91], v[210:213], v[96:99]
	v_mfma_f32_16x16x32_bf16 v[148:151], v[84:87], v[184:187], v[148:151]
	v_mfma_f32_16x16x32_bf16 v[144:147], v[92:95], v[184:187], v[144:147]
	v_mfma_f32_16x16x32_bf16 v[132:135], v[84:87], v[196:199], v[132:135]
	v_mfma_f32_16x16x32_bf16 v[128:131], v[92:95], v[196:199], v[128:131]
	v_mfma_f32_16x16x32_bf16 v[116:119], v[84:87], v[206:209], v[116:119]
	v_mfma_f32_16x16x32_bf16 v[112:115], v[92:95], v[206:209], v[112:115]
	v_mfma_f32_16x16x32_bf16 v[100:103], v[84:87], v[214:217], v[100:103]
	v_mfma_f32_16x16x32_bf16 v[96:99], v[92:95], v[214:217], v[96:99]
	s_setprio 0
	s_barrier
	s_add_i32 s69, s63, s14
	v_lshl_add_u64 v[180:181], s[74:75], 0, v[162:163]
	s_mov_b32 m0, s69
	ds_read_b128 v[174:177], v190 offset:16384
	ds_read_b128 v[184:187], v190 offset:17408
	ds_read_b128 v[192:195], v190 offset:18432
	ds_read_b128 v[196:199], v190 offset:19456
	ds_read_b128 v[200:203], v190 offset:20480
	ds_read_b128 v[206:209], v190 offset:21504
	ds_read_b128 v[210:213], v190 offset:22528
	ds_read_b128 v[214:217], v190 offset:23552
	global_load_lds_dwordx4 v[180:181], off
	s_add_i32 m0, s69, 0x2000
	s_add_u32 s78, s74, 0x100000
	v_lshl_add_u64 v[218:219], s[74:75], 0, v[164:165]
	s_addc_u32 s79, s75, 0
	s_add_i32 s69, s64, s14
	global_load_lds_dwordx4 v[218:219], off
	v_lshl_add_u64 v[220:221], s[78:79], 0, v[162:163]
	s_mov_b32 m0, s69
	v_lshl_add_u64 v[222:223], s[76:77], 0, v[164:165]
	global_load_lds_dwordx4 v[220:221], off
	v_lshl_add_u64 v[220:221], s[78:79], 0, v[164:165]
	s_add_i32 m0, s69, 0x2000
	s_nop 0
	global_load_lds_dwordx4 v[220:221], off
	v_lshl_add_u64 v[220:221], s[76:77], 0, v[162:163]
	s_mov_b32 m0, s15
	s_nop 0
	global_load_lds_dwordx4 v[220:221], off
	s_mov_b32 m0, s33
	s_nop 0
	global_load_lds_dwordx4 v[222:223], off
	s_waitcnt vmcnt(8)
	s_waitcnt lgkmcnt(0)
	s_barrier
; #define PG8_STAGE(bufoff, gbase, voff) do { _Pragma("unroll") for (int _i = 0; _i < 2; ++_i) \
;         __builtin_amdgcn_global_load_lds((const unsigned*)((const char*)(gbase) + (voff)[_i]), (PG8_LAS unsigned*)(lds + (bufoff) + ldsw + _i * 8192), 16, 0, 0); } while (0)
; #define PG8_LDA(dst, b, h) do { _Pragma("unroll") for (int m = 0; m < 4; ++m) _Pragma("unroll") for (int k = 0; k < 2; ++k) dst[m][k] = *(const PG8_LAS bf16x8*)(lds + PG8_SA(b, h) + aoff + m * 2048 + k * 1024); } while (0)
; #define PG8_LDB(dst, b, h) do { _Pragma("unroll") for (int n = 0; n < 2; ++n) _Pragma("unroll") for (int k = 0; k < 2; ++k) dst[n][k] = *(const PG8_LAS bf16x8*)(lds + PG8_SB(b, h) + boff + n * 2048 + k * 1024); } while (0)
; #define PG8_MMA(ai, bj, At, Bt) do { __builtin_amdgcn_s_setprio(1); _Pragma("unroll") for (int m = 0; m < 4; ++m) _Pragma("unroll") for (int n = 0; n < 2; ++n) _Pragma("unroll") for (int k = 0; k < 2; ++k) \
;         acc[ai][bj][m][n] = __builtin_amdgcn_mfma_f32_16x16x32_bf16(Bt[n][k], At[m][k], acc[ai][bj][m][n], 0, 0, 0); __builtin_amdgcn_s_setprio(0); } while (0)
; #define PG8_WAIT_V(n) asm volatile("s_waitcnt vmcnt(" #n ")" ::: "memory")
; #define PG8_WAIT_L(n) asm volatile("s_waitcnt lgkmcnt(" #n ")" ::: "memory")
; #define PG8_BAR __builtin_amdgcn_s_barrier()
; #define PG8_SCHED __builtin_amdgcn_sched_barrier(0)
; template <class Epi, class Sched, bool ALIGN_EPI = false, bool SP2 = false>
; __device__ __forceinline__ void gemm_phase(PG8_LAS unsigned char* lds, const Gemm g, const Sched S, const Epi E) {
;     ...
;             PG8_WAIT_V(8); PG8_WAIT_L(0); PG8_BAR; PG8_MMA(1, 0, At, B0); PG8_MMA(1, 1, At, B1); PG8_BAR; PG8_SCHED;
;             PG8_LDB(B0, 1, 0); PG8_LDB(B1, 1, 1); PG8_SCHED; PG8_LDA(At, 1, 0); PG8_STAGE(PG8_SA(0, 1), a2 + hstepA, voffA);
;             PG8_WAIT_V(8); PG8_WAIT_L(0); PG8_BAR; PG8_MMA(0, 0, At, B0); PG8_MMA(0, 1, At, B1); PG8_BAR; PG8_SCHED;
	s_setprio 1
	s_waitcnt lgkmcnt(0)
	v_mfma_f32_16x16x32_bf16 v[60:63], v[64:67], v[174:177], v[60:63]
	v_mfma_f32_16x16x32_bf16 v[56:59], v[72:75], v[174:177], v[56:59]
	v_mfma_f32_16x16x32_bf16 v[44:47], v[64:67], v[192:195], v[44:47]
	v_mfma_f32_16x16x32_bf16 v[40:43], v[72:75], v[192:195], v[40:43]
	v_mfma_f32_16x16x32_bf16 v[28:31], v[64:67], v[200:203], v[28:31]
	v_mfma_f32_16x16x32_bf16 v[24:27], v[72:75], v[200:203], v[24:27]
	v_mfma_f32_16x16x32_bf16 v[12:15], v[64:67], v[210:213], v[12:15]
	v_mfma_f32_16x16x32_bf16 v[8:11], v[72:75], v[210:213], v[8:11]
	v_mfma_f32_16x16x32_bf16 v[60:63], v[68:71], v[184:187], v[60:63]
	v_mfma_f32_16x16x32_bf16 v[56:59], v[76:79], v[184:187], v[56:59]
	v_mfma_f32_16x16x32_bf16 v[44:47], v[68:71], v[196:199], v[44:47]
	v_mfma_f32_16x16x32_bf16 v[40:43], v[76:79], v[196:199], v[40:43]
	v_mfma_f32_16x16x32_bf16 v[28:31], v[68:71], v[206:209], v[28:31]
	v_mfma_f32_16x16x32_bf16 v[24:27], v[76:79], v[206:209], v[24:27]
	v_mfma_f32_16x16x32_bf16 v[12:15], v[68:71], v[214:217], v[12:15]
	v_mfma_f32_16x16x32_bf16 v[8:11], v[76:79], v[214:217], v[8:11]
	s_setprio 0
	s_setprio 1
	v_mfma_f32_16x16x32_bf16 v[52:55], v[80:83], v[174:177], v[52:55]
	v_mfma_f32_16x16x32_bf16 v[48:51], v[88:91], v[174:177], v[48:51]
	v_mfma_f32_16x16x32_bf16 v[36:39], v[80:83], v[192:195], v[36:39]
	v_mfma_f32_16x16x32_bf16 v[32:35], v[88:91], v[192:195], v[32:35]
	v_mfma_f32_16x16x32_bf16 v[20:23], v[80:83], v[200:203], v[20:23]
	v_mfma_f32_16x16x32_bf16 v[16:19], v[88:91], v[200:203], v[16:19]
	v_mfma_f32_16x16x32_bf16 v[4:7], v[80:83], v[210:213], v[4:7]
	v_mfma_f32_16x16x32_bf16 v[0:3], v[88:91], v[210:213], v[0:3]
	v_mfma_f32_16x16x32_bf16 v[52:55], v[84:87], v[184:187], v[52:55]
	v_mfma_f32_16x16x32_bf16 v[48:51], v[92:95], v[184:187], v[48:51]
	v_mfma_f32_16x16x32_bf16 v[36:39], v[84:87], v[196:199], v[36:39]
	v_mfma_f32_16x16x32_bf16 v[32:35], v[92:95], v[196:199], v[32:35]
	v_mfma_f32_16x16x32_bf16 v[20:23], v[84:87], v[206:209], v[20:23]
	v_mfma_f32_16x16x32_bf16 v[16:19], v[92:95], v[206:209], v[16:19]
	v_mfma_f32_16x16x32_bf16 v[4:7], v[84:87], v[214:217], v[4:7]
	v_mfma_f32_16x16x32_bf16 v[0:3], v[92:95], v[214:217], v[0:3]
	s_setprio 0
	s_barrier
	s_add_i32 s69, 0, 0x18000
	s_add_i32 s71, 0, 0x1c000
	v_add_u32_e32 v76, s69, v183
	v_add_u32_e32 v92, s71, v183
	ds_read_b128 v[64:67], v76
	ds_read_b128 v[68:71], v76 offset:1024
	ds_read_b128 v[72:75], v76 offset:2048
	ds_read_b128 v[76:79], v76 offset:3072
	ds_read_b128 v[80:83], v92
	ds_read_b128 v[84:87], v92 offset:1024
	ds_read_b128 v[88:91], v92 offset:2048
	ds_read_b128 v[92:95], v92 offset:3072
	s_add_u32 s76, s76, 0x100000
	s_addc_u32 s77, s77, 0
	s_mov_b32 m0, s39
	v_lshl_add_u64 v[224:225], s[76:77], 0, v[162:163]
	ds_read_b128 v[174:177], v190 offset:32768
	ds_read_b128 v[184:187], v190 offset:33792
	ds_read_b128 v[192:195], v190 offset:34816
	ds_read_b128 v[196:199], v190 offset:35840
	ds_read_b128 v[200:203], v190 offset:36864
	ds_read_b128 v[206:209], v190 offset:37888
	ds_read_b128 v[210:213], v190 offset:38912
	ds_read_b128 v[214:217], v190 offset:39936
	global_load_lds_dwordx4 v[224:225], off
	v_lshl_add_u64 v[224:225], s[76:77], 0, v[164:165]
	s_mov_b32 m0, s54
	s_nop 0
	global_load_lds_dwordx4 v[224:225], off
	s_waitcnt vmcnt(8)
	s_waitcnt lgkmcnt(0)
	s_barrier
	s_setprio 1
	s_waitcnt lgkmcnt(0)
	v_mfma_f32_16x16x32_bf16 v[156:159], v[64:67], v[174:177], v[156:159]
	v_mfma_f32_16x16x32_bf16 v[152:155], v[72:75], v[174:177], v[152:155]
	v_mfma_f32_16x16x32_bf16 v[140:143], v[64:67], v[192:195], v[140:143]
	v_mfma_f32_16x16x32_bf16 v[136:139], v[72:75], v[192:195], v[136:139]
	v_mfma_f32_16x16x32_bf16 v[124:127], v[64:67], v[200:203], v[124:127]
	v_mfma_f32_16x16x32_bf16 v[120:123], v[72:75], v[200:203], v[120:123]
	v_mfma_f32_16x16x32_bf16 v[108:111], v[64:67], v[210:213], v[108:111]
	v_mfma_f32_16x16x32_bf16 v[104:107], v[72:75], v[210:213], v[104:107]
	v_mfma_f32_16x16x32_bf16 v[156:159], v[68:71], v[184:187], v[156:159]
	v_mfma_f32_16x16x32_bf16 v[152:155], v[76:79], v[184:187], v[152:155]
	v_mfma_f32_16x16x32_bf16 v[140:143], v[68:71], v[196:199], v[140:143]
	v_mfma_f32_16x16x32_bf16 v[136:139], v[76:79], v[196:199], v[136:139]
	v_mfma_f32_16x16x32_bf16 v[124:127], v[68:71], v[206:209], v[124:127]
	v_mfma_f32_16x16x32_bf16 v[120:123], v[76:79], v[206:209], v[120:123]
	v_mfma_f32_16x16x32_bf16 v[108:111], v[68:71], v[214:217], v[108:111]
	v_mfma_f32_16x16x32_bf16 v[104:107], v[76:79], v[214:217], v[104:107]
	s_setprio 0
	s_setprio 1
	v_mfma_f32_16x16x32_bf16 v[148:151], v[80:83], v[174:177], v[148:151]
	v_mfma_f32_16x16x32_bf16 v[144:147], v[88:91], v[174:177], v[144:147]
	v_mfma_f32_16x16x32_bf16 v[132:135], v[80:83], v[192:195], v[132:135]
	v_mfma_f32_16x16x32_bf16 v[128:131], v[88:91], v[192:195], v[128:131]
	v_mfma_f32_16x16x32_bf16 v[116:119], v[80:83], v[200:203], v[116:119]
	v_mfma_f32_16x16x32_bf16 v[112:115], v[88:91], v[200:203], v[112:115]
	v_mfma_f32_16x16x32_bf16 v[100:103], v[80:83], v[210:213], v[100:103]
	v_mfma_f32_16x16x32_bf16 v[96:99], v[88:91], v[210:213], v[96:99]
	v_mfma_f32_16x16x32_bf16 v[148:151], v[84:87], v[184:187], v[148:151]
	v_mfma_f32_16x16x32_bf16 v[144:147], v[92:95], v[184:187], v[144:147]
	v_mfma_f32_16x16x32_bf16 v[132:135], v[84:87], v[196:199], v[132:135]
	v_mfma_f32_16x16x32_bf16 v[128:131], v[92:95], v[196:199], v[128:131]
	v_mfma_f32_16x16x32_bf16 v[116:119], v[84:87], v[206:209], v[116:119]
	v_mfma_f32_16x16x32_bf16 v[112:115], v[92:95], v[206:209], v[112:115]
	v_mfma_f32_16x16x32_bf16 v[100:103], v[84:87], v[214:217], v[100:103]
	v_mfma_f32_16x16x32_bf16 v[96:99], v[92:95], v[214:217], v[96:99]
	s_setprio 0
	s_barrier
; #define PG8_STAGE(bufoff, gbase, voff) do { _Pragma("unroll") for (int _i = 0; _i < 2; ++_i) \
;         __builtin_amdgcn_global_load_lds((const unsigned*)((const char*)(gbase) + (voff)[_i]), (PG8_LAS unsigned*)(lds + (bufoff) + ldsw + _i * 8192), 16, 0, 0); } while (0)
; #define PG8_LDA(dst, b, h) do { _Pragma("unroll") for (int m = 0; m < 4; ++m) _Pragma("unroll") for (int k = 0; k < 2; ++k) dst[m][k] = *(const PG8_LAS bf16x8*)(lds + PG8_SA(b, h) + aoff + m * 2048 + k * 1024); } while (0)
; #define PG8_MMA(ai, bj, At, Bt) do { __builtin_amdgcn_s_setprio(1); _Pragma("unroll") for (int m = 0; m < 4; ++m) _Pragma("unroll") for (int n = 0; n < 2; ++n) _Pragma("unroll") for (int k = 0; k < 2; ++k) \
;         acc[ai][bj][m][n] = __builtin_amdgcn_mfma_f32_16x16x32_bf16(Bt[n][k], At[m][k], acc[ai][bj][m][n], 0, 0, 0); __builtin_amdgcn_s_setprio(0); } while (0)
; #define PG8_WAIT_V(n) asm volatile("s_waitcnt vmcnt(" #n ")" ::: "memory")
; #define PG8_WAIT_L(n) asm volatile("s_waitcnt lgkmcnt(" #n ")" ::: "memory")
; #define PG8_BAR __builtin_amdgcn_s_barrier()
; #define PG8_SCHED __builtin_amdgcn_sched_barrier(0)
; template <class Epi, class Sched, bool ALIGN_EPI = false, bool SP2 = false>
; __device__ __forceinline__ void gemm_phase(PG8_LAS unsigned char* lds, const Gemm g, const Sched S, const Epi E) {
;     ...
;         for (int t = 0; t < nt; t += 2) {
;     ...
;             PG8_LDA(At, 1, 1); PG8_STAGE(PG8_SB(1, 0), b3, voffB); PG8_STAGE(PG8_SB(1, 1), b3 + hstep, voffB); PG8_STAGE(PG8_SA(1, 0), a3, voffA);
;             PG8_WAIT_V(8); PG8_WAIT_L(0); PG8_BAR; PG8_MMA(1, 0, At, B0); PG8_MMA(1, 1, At, B1); PG8_BAR; PG8_SCHED;
	s_add_i32 s69, s69, s14
	v_lshl_add_u64 v[180:181], v[180:181], 0, s[30:31]
	s_mov_b32 m0, s69
	ds_read_b128 v[174:177], v190 offset:49152
	ds_read_b128 v[184:187], v190 offset:50176
	ds_read_b128 v[192:195], v190 offset:51200
	ds_read_b128 v[196:199], v190 offset:52224
	ds_read_b128 v[200:203], v190 offset:53248
	ds_read_b128 v[206:209], v190 offset:54272
	ds_read_b128 v[210:213], v190 offset:55296
	ds_read_b128 v[214:217], v190 offset:56320
	global_load_lds_dwordx4 v[180:181], off
	s_add_i32 m0, s69, 0x2000
	s_add_u32 s74, s74, 0x100080
	v_lshl_add_u64 v[180:181], v[218:219], 0, s[30:31]
	s_addc_u32 s75, s75, 0
	s_add_i32 s69, s71, s14
	global_load_lds_dwordx4 v[180:181], off
	v_lshl_add_u64 v[180:181], s[74:75], 0, v[162:163]
	s_mov_b32 m0, s69
	s_nop 0
	global_load_lds_dwordx4 v[180:181], off
	v_lshl_add_u64 v[180:181], s[74:75], 0, v[164:165]
	s_add_i32 m0, s69, 0x2000
	s_nop 0
	global_load_lds_dwordx4 v[180:181], off
	v_lshl_add_u64 v[180:181], v[220:221], 0, s[30:31]
	s_mov_b32 m0, s61
	s_nop 0
	global_load_lds_dwordx4 v[180:181], off
	v_lshl_add_u64 v[180:181], v[222:223], 0, s[30:31]
	s_mov_b32 m0, s62
	s_nop 0
	global_load_lds_dwordx4 v[180:181], off
	s_waitcnt vmcnt(8)
	s_waitcnt lgkmcnt(0)
	s_barrier
	s_setprio 1
	s_waitcnt lgkmcnt(0)
	v_mfma_f32_16x16x32_bf16 v[60:63], v[64:67], v[174:177], v[60:63]
	v_mfma_f32_16x16x32_bf16 v[56:59], v[72:75], v[174:177], v[56:59]
	v_mfma_f32_16x16x32_bf16 v[44:47], v[64:67], v[192:195], v[44:47]
	v_mfma_f32_16x16x32_bf16 v[40:43], v[72:75], v[192:195], v[40:43]
	v_mfma_f32_16x16x32_bf16 v[28:31], v[64:67], v[200:203], v[28:31]
	v_mfma_f32_16x16x32_bf16 v[24:27], v[72:75], v[200:203], v[24:27]
	v_mfma_f32_16x16x32_bf16 v[12:15], v[64:67], v[210:213], v[12:15]
	v_mfma_f32_16x16x32_bf16 v[8:11], v[72:75], v[210:213], v[8:11]
	v_mfma_f32_16x16x32_bf16 v[60:63], v[68:71], v[184:187], v[60:63]
	v_mfma_f32_16x16x32_bf16 v[56:59], v[76:79], v[184:187], v[56:59]
	v_mfma_f32_16x16x32_bf16 v[44:47], v[68:71], v[196:199], v[44:47]
	v_mfma_f32_16x16x32_bf16 v[40:43], v[76:79], v[196:199], v[40:43]
	v_mfma_f32_16x16x32_bf16 v[28:31], v[68:71], v[206:209], v[28:31]
	v_mfma_f32_16x16x32_bf16 v[24:27], v[76:79], v[206:209], v[24:27]
	v_mfma_f32_16x16x32_bf16 v[12:15], v[68:71], v[214:217], v[12:15]
	v_mfma_f32_16x16x32_bf16 v[8:11], v[76:79], v[214:217], v[8:11]
	s_setprio 0
	s_setprio 1
	v_mfma_f32_16x16x32_bf16 v[52:55], v[80:83], v[174:177], v[52:55]
	v_mfma_f32_16x16x32_bf16 v[48:51], v[88:91], v[174:177], v[48:51]
	v_mfma_f32_16x16x32_bf16 v[36:39], v[80:83], v[192:195], v[36:39]
	v_mfma_f32_16x16x32_bf16 v[32:35], v[88:91], v[192:195], v[32:35]
	v_mfma_f32_16x16x32_bf16 v[20:23], v[80:83], v[200:203], v[20:23]
	v_mfma_f32_16x16x32_bf16 v[16:19], v[88:91], v[200:203], v[16:19]
	v_mfma_f32_16x16x32_bf16 v[4:7], v[80:83], v[210:213], v[4:7]
	v_mfma_f32_16x16x32_bf16 v[0:3], v[88:91], v[210:213], v[0:3]
	v_mfma_f32_16x16x32_bf16 v[52:55], v[84:87], v[184:187], v[52:55]
	v_mfma_f32_16x16x32_bf16 v[48:51], v[92:95], v[184:187], v[48:51]
	v_mfma_f32_16x16x32_bf16 v[36:39], v[84:87], v[196:199], v[36:39]
	v_mfma_f32_16x16x32_bf16 v[32:35], v[92:95], v[196:199], v[32:35]
	v_mfma_f32_16x16x32_bf16 v[20:23], v[84:87], v[206:209], v[20:23]
	v_mfma_f32_16x16x32_bf16 v[16:19], v[92:95], v[206:209], v[16:19]
	v_mfma_f32_16x16x32_bf16 v[4:7], v[84:87], v[214:217], v[4:7]
	v_mfma_f32_16x16x32_bf16 v[0:3], v[92:95], v[214:217], v[0:3]
	s_setprio 0
	s_add_i32 s68, s68, 2
	s_add_u32 s72, s72, 0x100
	s_addc_u32 s73, s73, 0
	s_add_u32 s66, s66, 0x100
	s_addc_u32 s67, s67, 0
	s_cmp_gt_u32 s68, 61
	s_barrier
	s_cbranch_scc0 .LBB0_469
	s_and_b64 vcc, exec, s[34:35]
	s_cbranch_vccz .LBB0_472
	s_barrier

; #define PG8_STAGE(bufoff, gbase, voff) do { _Pragma("unroll") for (int _i = 0; _i < 2; ++_i) \
;         __builtin_amdgcn_global_load_lds((const unsigned*)((const char*)(gbase) + (voff)[_i]), (PG8_LAS unsigned*)(lds + (bufoff) + ldsw + _i * 8192), 16, 0, 0); } while (0)
; #define PG8_LDA(dst, b, h) do { _Pragma("unroll") for (int m = 0; m < 4; ++m) _Pragma("unroll") for (int k = 0; k < 2; ++k) dst[m][k] = *(const PG8_LAS bf16x8*)(lds + PG8_SA(b, h) + aoff + m * 2048 + k * 1024); } while (0)
; #define PG8_LDB(dst, b, h) do { _Pragma("unroll") for (int n = 0; n < 2; ++n) _Pragma("unroll") for (int k = 0; k < 2; ++k) dst[n][k] = *(const PG8_LAS bf16x8*)(lds + PG8_SB(b, h) + boff + n * 2048 + k * 1024); } while (0)
; #define PG8_MMA(ai, bj, At, Bt) do { __builtin_amdgcn_s_setprio(1); _Pragma("unroll") for (int m = 0; m < 4; ++m) _Pragma("unroll") for (int n = 0; n < 2; ++n) _Pragma("unroll") for (int k = 0; k < 2; ++k) \
;         acc[ai][bj][m][n] = __builtin_amdgcn_mfma_f32_16x16x32_bf16(Bt[n][k], At[m][k], acc[ai][bj][m][n], 0, 0, 0); __builtin_amdgcn_s_setprio(0); } while (0)
; #define PG8_WAIT_V(n) asm volatile("s_waitcnt vmcnt(" #n ")" ::: "memory")
; #define PG8_WAIT_L(n) asm volatile("s_waitcnt lgkmcnt(" #n ")" ::: "memory")
; template <class Epi, class Sched, bool ALIGN_EPI = false, bool SP2 = false>
; __device__ __forceinline__ void gemm_phase(PG8_LAS unsigned char* lds, const Gemm g, const Sched S, const Epi E) {
;     ...
;             const bool last = (t == nt - 2);
;             const char* a1 = cA + (size_t)(t + 1) * kstepA;
;             const char* a2 = last ? nA : cA + (size_t)(t + 2) * kstepA; const char* b2 = last ? nB : cB + (size_t)(t + 2) * kstep;
;             const char* a3 = a2 + kstepA; const char* b3 = b2 + kstep;
;             if (last && has_next) S.a_ready(nxt);
;             if constexpr (SP2) {
;             PG8_LDB(B0, 0, 0); PG8_LDB(B1, 0, 1); PG8_SCHED; PG8_LDA(At, 0, 0); PG8_STAGE(PG8_SA(1, 1), a1 + hstepA, voffA);
;             PG8_WAIT_V(8); PG8_WAIT_L(0); PG8_BAR; PG8_MMA(0, 0, At, B0); PG8_MMA(0, 1, At, B1); PG8_BAR; PG8_SCHED;
;             PG8_LDA(At, 0, 1); PG8_STAGE(PG8_SB(0, 0), b2, voffB); PG8_STAGE(PG8_SB(0, 1), b2 + hstep, voffB); PG8_STAGE(PG8_SA(0, 0), a2, voffA);
;             PG8_WAIT_V(8); PG8_WAIT_L(0); PG8_BAR; PG8_MMA(1, 0, At, B0); PG8_MMA(1, 1, At, B1); PG8_BAR; PG8_SCHED;
.LBB0_622:
	ds_read_b128 v[152:155], v149
	ds_read_b128 v[156:159], v149 offset:1024
	ds_read_b128 v[162:165], v149 offset:2048
	ds_read_b128 v[166:169], v149 offset:3072
	ds_read_b128 v[170:173], v150
	ds_read_b128 v[174:177], v150 offset:1024
	ds_read_b128 v[178:181], v150 offset:2048
	ds_read_b128 v[182:185], v150 offset:3072
	s_add_u32 s38, s36, 0xfffc0080
	s_addc_u32 s39, s37, -1
	s_cmp_eq_u32 s76, 12
	s_cselect_b32 s41, s27, s39
	s_cselect_b32 s40, s68, s38
	s_cselect_b32 s39, s25, s75
	s_cselect_b32 s38, s69, s74
	v_lshl_add_u64 v[144:145], s[36:37], 0, v[136:137]
	s_add_i32 m0, s15, 0xc000
	ds_read_b128 v[186:189], v151
	ds_read_b128 v[190:193], v151 offset:1024
	ds_read_b128 v[194:197], v151 offset:2048
	ds_read_b128 v[198:201], v151 offset:3072
	ds_read_b128 v[206:209], v151 offset:4096
	ds_read_b128 v[210:213], v151 offset:5120
	ds_read_b128 v[214:217], v151 offset:6144
	ds_read_b128 v[218:221], v151 offset:7168
	global_load_lds_dwordx4 v[144:145], off
	v_lshl_add_u64 v[144:145], s[36:37], 0, v[138:139]
	s_add_i32 m0, s15, 0xe000
	s_nop 0
	global_load_lds_dwordx4 v[144:145], off
	s_waitcnt vmcnt(8)
	s_waitcnt lgkmcnt(0)
	s_barrier
	s_setprio 1
	s_waitcnt lgkmcnt(0)
	v_mfma_f32_16x16x32_bf16 v[124:127], v[152:155], v[186:189], v[124:127]
	v_mfma_f32_16x16x32_bf16 v[120:123], v[162:165], v[186:189], v[120:123]
	v_mfma_f32_16x16x32_bf16 v[112:115], v[152:155], v[194:197], v[112:115]
	v_mfma_f32_16x16x32_bf16 v[104:107], v[162:165], v[194:197], v[104:107]
	v_mfma_f32_16x16x32_bf16 v[96:99], v[152:155], v[206:209], v[96:99]
	v_mfma_f32_16x16x32_bf16 v[88:91], v[162:165], v[206:209], v[88:91]
	v_mfma_f32_16x16x32_bf16 v[80:83], v[152:155], v[214:217], v[80:83]
	v_mfma_f32_16x16x32_bf16 v[72:75], v[162:165], v[214:217], v[72:75]
	v_mfma_f32_16x16x32_bf16 v[124:127], v[156:159], v[190:193], v[124:127]
	v_mfma_f32_16x16x32_bf16 v[120:123], v[166:169], v[190:193], v[120:123]
	v_mfma_f32_16x16x32_bf16 v[112:115], v[156:159], v[198:201], v[112:115]
	v_mfma_f32_16x16x32_bf16 v[104:107], v[166:169], v[198:201], v[104:107]
	v_mfma_f32_16x16x32_bf16 v[96:99], v[156:159], v[210:213], v[96:99]
	v_mfma_f32_16x16x32_bf16 v[88:91], v[166:169], v[210:213], v[88:91]
	v_mfma_f32_16x16x32_bf16 v[80:83], v[156:159], v[218:221], v[80:83]
	v_mfma_f32_16x16x32_bf16 v[72:75], v[166:169], v[218:221], v[72:75]
	s_setprio 0
	s_setprio 1
	v_mfma_f32_16x16x32_bf16 v[116:119], v[170:173], v[186:189], v[116:119]
	v_mfma_f32_16x16x32_bf16 v[108:111], v[178:181], v[186:189], v[108:111]
	v_mfma_f32_16x16x32_bf16 v[100:103], v[170:173], v[194:197], v[100:103]
	v_mfma_f32_16x16x32_bf16 v[92:95], v[178:181], v[194:197], v[92:95]
	v_mfma_f32_16x16x32_bf16 v[84:87], v[170:173], v[206:209], v[84:87]
	v_mfma_f32_16x16x32_bf16 v[76:79], v[178:181], v[206:209], v[76:79]
	v_mfma_f32_16x16x32_bf16 v[68:71], v[170:173], v[214:217], v[68:71]
	v_mfma_f32_16x16x32_bf16 v[64:67], v[178:181], v[214:217], v[64:67]
	v_mfma_f32_16x16x32_bf16 v[116:119], v[174:177], v[190:193], v[116:119]
	v_mfma_f32_16x16x32_bf16 v[108:111], v[182:185], v[190:193], v[108:111]
	v_mfma_f32_16x16x32_bf16 v[100:103], v[174:177], v[198:201], v[100:103]
	v_mfma_f32_16x16x32_bf16 v[92:95], v[182:185], v[198:201], v[92:95]
	v_mfma_f32_16x16x32_bf16 v[84:87], v[174:177], v[210:213], v[84:87]
	v_mfma_f32_16x16x32_bf16 v[76:79], v[182:185], v[210:213], v[76:79]
	v_mfma_f32_16x16x32_bf16 v[68:71], v[174:177], v[218:221], v[68:71]
	v_mfma_f32_16x16x32_bf16 v[64:67], v[182:185], v[218:221], v[64:67]
	s_setprio 0
	s_barrier
	s_add_i32 s77, s54, s14
	v_lshl_add_u64 v[144:145], s[38:39], 0, v[130:131]
	s_mov_b32 m0, s77
	ds_read_b128 v[186:189], v151 offset:16384
	ds_read_b128 v[190:193], v151 offset:17408
	ds_read_b128 v[194:197], v151 offset:18432
	ds_read_b128 v[198:201], v151 offset:19456
	ds_read_b128 v[206:209], v151 offset:20480
	ds_read_b128 v[210:213], v151 offset:21504
	ds_read_b128 v[214:217], v151 offset:22528
	ds_read_b128 v[218:221], v151 offset:23552
	global_load_lds_dwordx4 v[144:145], off
	s_add_i32 m0, s77, 0x2000
	s_add_u32 s78, s38, 0x40000
	v_lshl_add_u64 v[202:203], s[38:39], 0, v[134:135]
	s_addc_u32 s79, s39, 0
	s_add_i32 s77, s55, s14
	global_load_lds_dwordx4 v[202:203], off
	v_lshl_add_u64 v[222:223], s[78:79], 0, v[130:131]
	s_mov_b32 m0, s77
	v_lshl_add_u64 v[224:225], s[40:41], 0, v[132:133]
	global_load_lds_dwordx4 v[222:223], off
	v_lshl_add_u64 v[222:223], s[78:79], 0, v[134:135]
	s_add_i32 m0, s77, 0x2000
	s_nop 0
	global_load_lds_dwordx4 v[222:223], off
	v_lshl_add_u64 v[222:223], s[40:41], 0, v[128:129]
	s_mov_b32 m0, s15
	s_nop 0
	global_load_lds_dwordx4 v[222:223], off
	s_mov_b32 m0, s33
	s_nop 0
	global_load_lds_dwordx4 v[224:225], off
	s_waitcnt vmcnt(8)
	s_waitcnt lgkmcnt(0)
	s_barrier
; #define PG8_STAGE(bufoff, gbase, voff) do { _Pragma("unroll") for (int _i = 0; _i < 2; ++_i) \
;         __builtin_amdgcn_global_load_lds((const unsigned*)((const char*)(gbase) + (voff)[_i]), (PG8_LAS unsigned*)(lds + (bufoff) + ldsw + _i * 8192), 16, 0, 0); } while (0)
; #define PG8_LDA(dst, b, h) do { _Pragma("unroll") for (int m = 0; m < 4; ++m) _Pragma("unroll") for (int k = 0; k < 2; ++k) dst[m][k] = *(const PG8_LAS bf16x8*)(lds + PG8_SA(b, h) + aoff + m * 2048 + k * 1024); } while (0)
; #define PG8_LDB(dst, b, h) do { _Pragma("unroll") for (int n = 0; n < 2; ++n) _Pragma("unroll") for (int k = 0; k < 2; ++k) dst[n][k] = *(const PG8_LAS bf16x8*)(lds + PG8_SB(b, h) + boff + n * 2048 + k * 1024); } while (0)
; #define PG8_MMA(ai, bj, At, Bt) do { __builtin_amdgcn_s_setprio(1); _Pragma("unroll") for (int m = 0; m < 4; ++m) _Pragma("unroll") for (int n = 0; n < 2; ++n) _Pragma("unroll") for (int k = 0; k < 2; ++k) \
;         acc[ai][bj][m][n] = __builtin_amdgcn_mfma_f32_16x16x32_bf16(Bt[n][k], At[m][k], acc[ai][bj][m][n], 0, 0, 0); __builtin_amdgcn_s_setprio(0); } while (0)
; #define PG8_WAIT_V(n) asm volatile("s_waitcnt vmcnt(" #n ")" ::: "memory")
; #define PG8_WAIT_L(n) asm volatile("s_waitcnt lgkmcnt(" #n ")" ::: "memory")
; #define PG8_BAR __builtin_amdgcn_s_barrier()
; #define PG8_SCHED __builtin_amdgcn_sched_barrier(0)
; template <class Epi, class Sched, bool ALIGN_EPI = false, bool SP2 = false>
; __device__ __forceinline__ void gemm_phase(PG8_LAS unsigned char* lds, const Gemm g, const Sched S, const Epi E) {
;     ...
;             PG8_WAIT_V(8); PG8_WAIT_L(0); PG8_BAR; PG8_MMA(1, 0, At, B0); PG8_MMA(1, 1, At, B1); PG8_BAR; PG8_SCHED;
;             PG8_LDB(B0, 1, 0); PG8_LDB(B1, 1, 1); PG8_SCHED; PG8_LDA(At, 1, 0); PG8_STAGE(PG8_SA(0, 1), a2 + hstepA, voffA);
;             PG8_WAIT_V(8); PG8_WAIT_L(0); PG8_BAR; PG8_MMA(0, 0, At, B0); PG8_MMA(0, 1, At, B1); PG8_BAR; PG8_SCHED;
	s_setprio 1
	s_waitcnt lgkmcnt(0)
	v_mfma_f32_16x16x32_bf16 v[60:63], v[152:155], v[186:189], v[60:63]
	v_mfma_f32_16x16x32_bf16 v[56:59], v[162:165], v[186:189], v[56:59]
	v_mfma_f32_16x16x32_bf16 v[48:51], v[152:155], v[194:197], v[48:51]
	v_mfma_f32_16x16x32_bf16 v[40:43], v[162:165], v[194:197], v[40:43]
	v_mfma_f32_16x16x32_bf16 v[32:35], v[152:155], v[206:209], v[32:35]
	v_mfma_f32_16x16x32_bf16 v[24:27], v[162:165], v[206:209], v[24:27]
	v_mfma_f32_16x16x32_bf16 v[16:19], v[152:155], v[214:217], v[16:19]
	v_mfma_f32_16x16x32_bf16 v[8:11], v[162:165], v[214:217], v[8:11]
	v_mfma_f32_16x16x32_bf16 v[60:63], v[156:159], v[190:193], v[60:63]
	v_mfma_f32_16x16x32_bf16 v[56:59], v[166:169], v[190:193], v[56:59]
	v_mfma_f32_16x16x32_bf16 v[48:51], v[156:159], v[198:201], v[48:51]
	v_mfma_f32_16x16x32_bf16 v[40:43], v[166:169], v[198:201], v[40:43]
	v_mfma_f32_16x16x32_bf16 v[32:35], v[156:159], v[210:213], v[32:35]
	v_mfma_f32_16x16x32_bf16 v[24:27], v[166:169], v[210:213], v[24:27]
	v_mfma_f32_16x16x32_bf16 v[16:19], v[156:159], v[218:221], v[16:19]
	v_mfma_f32_16x16x32_bf16 v[8:11], v[166:169], v[218:221], v[8:11]
	s_setprio 0
	s_setprio 1
	v_mfma_f32_16x16x32_bf16 v[52:55], v[170:173], v[186:189], v[52:55]
	v_mfma_f32_16x16x32_bf16 v[44:47], v[178:181], v[186:189], v[44:47]
	v_mfma_f32_16x16x32_bf16 v[36:39], v[170:173], v[194:197], v[36:39]
	v_mfma_f32_16x16x32_bf16 v[28:31], v[178:181], v[194:197], v[28:31]
	v_mfma_f32_16x16x32_bf16 v[20:23], v[170:173], v[206:209], v[20:23]
	v_mfma_f32_16x16x32_bf16 v[12:15], v[178:181], v[206:209], v[12:15]
	v_mfma_f32_16x16x32_bf16 v[4:7], v[170:173], v[214:217], v[4:7]
	v_mfma_f32_16x16x32_bf16 v[0:3], v[178:181], v[214:217], v[0:3]
	v_mfma_f32_16x16x32_bf16 v[52:55], v[174:177], v[190:193], v[52:55]
	v_mfma_f32_16x16x32_bf16 v[44:47], v[182:185], v[190:193], v[44:47]
	v_mfma_f32_16x16x32_bf16 v[36:39], v[174:177], v[198:201], v[36:39]
	v_mfma_f32_16x16x32_bf16 v[28:31], v[182:185], v[198:201], v[28:31]
	v_mfma_f32_16x16x32_bf16 v[20:23], v[174:177], v[210:213], v[20:23]
	v_mfma_f32_16x16x32_bf16 v[12:15], v[182:185], v[210:213], v[12:15]
	v_mfma_f32_16x16x32_bf16 v[4:7], v[174:177], v[218:221], v[4:7]
	v_mfma_f32_16x16x32_bf16 v[0:3], v[182:185], v[218:221], v[0:3]
	s_setprio 0
	s_barrier
	s_add_i32 s77, 0, 0x18000
	v_add_u32_e32 v161, s77, v148
	s_add_i32 s78, 0, 0x1c000
	ds_read_b128 v[152:155], v161
	ds_read_b128 v[156:159], v161 offset:1024
	ds_read_b128 v[162:165], v161 offset:2048
	ds_read_b128 v[166:169], v161 offset:3072
	v_add_u32_e32 v161, s78, v148
	ds_read_b128 v[170:173], v161
	ds_read_b128 v[174:177], v161 offset:1024
	ds_read_b128 v[178:181], v161 offset:2048
	ds_read_b128 v[182:185], v161 offset:3072
	s_add_u32 s40, s40, 0x40000
	s_addc_u32 s41, s41, 0
	s_mov_b32 m0, s35
	v_lshl_add_u64 v[226:227], s[40:41], 0, v[128:129]
	ds_read_b128 v[186:189], v151 offset:32768
	ds_read_b128 v[190:193], v151 offset:33792
	ds_read_b128 v[194:197], v151 offset:34816
	ds_read_b128 v[198:201], v151 offset:35840
	ds_read_b128 v[206:209], v151 offset:36864
	ds_read_b128 v[210:213], v151 offset:37888
	ds_read_b128 v[214:217], v151 offset:38912
	ds_read_b128 v[218:221], v151 offset:39936
	global_load_lds_dwordx4 v[226:227], off
	v_lshl_add_u64 v[226:227], s[40:41], 0, v[132:133]
	s_mov_b32 m0, s42
	s_nop 0
	global_load_lds_dwordx4 v[226:227], off
	s_waitcnt vmcnt(8)
	s_waitcnt lgkmcnt(0)
	s_barrier
	s_setprio 1
	s_waitcnt lgkmcnt(0)
	v_mfma_f32_16x16x32_bf16 v[124:127], v[152:155], v[186:189], v[124:127]
	v_mfma_f32_16x16x32_bf16 v[120:123], v[162:165], v[186:189], v[120:123]
	v_mfma_f32_16x16x32_bf16 v[112:115], v[152:155], v[194:197], v[112:115]
	v_mfma_f32_16x16x32_bf16 v[104:107], v[162:165], v[194:197], v[104:107]
	v_mfma_f32_16x16x32_bf16 v[96:99], v[152:155], v[206:209], v[96:99]
	v_mfma_f32_16x16x32_bf16 v[88:91], v[162:165], v[206:209], v[88:91]
	v_mfma_f32_16x16x32_bf16 v[80:83], v[152:155], v[214:217], v[80:83]
	v_mfma_f32_16x16x32_bf16 v[72:75], v[162:165], v[214:217], v[72:75]
	v_mfma_f32_16x16x32_bf16 v[124:127], v[156:159], v[190:193], v[124:127]
	v_mfma_f32_16x16x32_bf16 v[120:123], v[166:169], v[190:193], v[120:123]
	v_mfma_f32_16x16x32_bf16 v[112:115], v[156:159], v[198:201], v[112:115]
	v_mfma_f32_16x16x32_bf16 v[104:107], v[166:169], v[198:201], v[104:107]
	v_mfma_f32_16x16x32_bf16 v[96:99], v[156:159], v[210:213], v[96:99]
	v_mfma_f32_16x16x32_bf16 v[88:91], v[166:169], v[210:213], v[88:91]
	v_mfma_f32_16x16x32_bf16 v[80:83], v[156:159], v[218:221], v[80:83]
	v_mfma_f32_16x16x32_bf16 v[72:75], v[166:169], v[218:221], v[72:75]
	s_setprio 0
	s_setprio 1
	v_mfma_f32_16x16x32_bf16 v[116:119], v[170:173], v[186:189], v[116:119]
	v_mfma_f32_16x16x32_bf16 v[108:111], v[178:181], v[186:189], v[108:111]
	v_mfma_f32_16x16x32_bf16 v[100:103], v[170:173], v[194:197], v[100:103]
	v_mfma_f32_16x16x32_bf16 v[92:95], v[178:181], v[194:197], v[92:95]
	v_mfma_f32_16x16x32_bf16 v[84:87], v[170:173], v[206:209], v[84:87]
	v_mfma_f32_16x16x32_bf16 v[76:79], v[178:181], v[206:209], v[76:79]
	v_mfma_f32_16x16x32_bf16 v[68:71], v[170:173], v[214:217], v[68:71]
	v_mfma_f32_16x16x32_bf16 v[64:67], v[178:181], v[214:217], v[64:67]
	v_mfma_f32_16x16x32_bf16 v[116:119], v[174:177], v[190:193], v[116:119]
	v_mfma_f32_16x16x32_bf16 v[108:111], v[182:185], v[190:193], v[108:111]
	v_mfma_f32_16x16x32_bf16 v[100:103], v[174:177], v[198:201], v[100:103]
	v_mfma_f32_16x16x32_bf16 v[92:95], v[182:185], v[198:201], v[92:95]
	v_mfma_f32_16x16x32_bf16 v[84:87], v[174:177], v[210:213], v[84:87]
	v_mfma_f32_16x16x32_bf16 v[76:79], v[182:185], v[210:213], v[76:79]
	v_mfma_f32_16x16x32_bf16 v[68:71], v[174:177], v[218:221], v[68:71]
	v_mfma_f32_16x16x32_bf16 v[64:67], v[182:185], v[218:221], v[64:67]
	s_setprio 0
	s_barrier
; #define PG8_STAGE(bufoff, gbase, voff) do { _Pragma("unroll") for (int _i = 0; _i < 2; ++_i) \
;         __builtin_amdgcn_global_load_lds((const unsigned*)((const char*)(gbase) + (voff)[_i]), (PG8_LAS unsigned*)(lds + (bufoff) + ldsw + _i * 8192), 16, 0, 0); } while (0)
; #define PG8_LDA(dst, b, h) do { _Pragma("unroll") for (int m = 0; m < 4; ++m) _Pragma("unroll") for (int k = 0; k < 2; ++k) dst[m][k] = *(const PG8_LAS bf16x8*)(lds + PG8_SA(b, h) + aoff + m * 2048 + k * 1024); } while (0)
; #define PG8_MMA(ai, bj, At, Bt) do { __builtin_amdgcn_s_setprio(1); _Pragma("unroll") for (int m = 0; m < 4; ++m) _Pragma("unroll") for (int n = 0; n < 2; ++n) _Pragma("unroll") for (int k = 0; k < 2; ++k) \
;         acc[ai][bj][m][n] = __builtin_amdgcn_mfma_f32_16x16x32_bf16(Bt[n][k], At[m][k], acc[ai][bj][m][n], 0, 0, 0); __builtin_amdgcn_s_setprio(0); } while (0)
; #define PG8_WAIT_V(n) asm volatile("s_waitcnt vmcnt(" #n ")" ::: "memory")
; #define PG8_WAIT_L(n) asm volatile("s_waitcnt lgkmcnt(" #n ")" ::: "memory")
; #define PG8_BAR __builtin_amdgcn_s_barrier()
; #define PG8_SCHED __builtin_amdgcn_sched_barrier(0)
; template <class Epi, class Sched, bool ALIGN_EPI = false, bool SP2 = false>
; __device__ __forceinline__ void gemm_phase(PG8_LAS unsigned char* lds, const Gemm g, const Sched S, const Epi E) {
;     ...
;         for (int t = 0; t < nt; t += 2) {
;     ...
;             PG8_LDA(At, 1, 1); PG8_STAGE(PG8_SB(1, 0), b3, voffB); PG8_STAGE(PG8_SB(1, 1), b3 + hstep, voffB); PG8_STAGE(PG8_SA(1, 0), a3, voffA);
;             PG8_WAIT_V(8); PG8_WAIT_L(0); PG8_BAR; PG8_MMA(1, 0, At, B0); PG8_MMA(1, 1, At, B1); PG8_BAR; PG8_SCHED;
	s_add_i32 s40, s77, s14
	v_lshl_add_u64 v[144:145], v[144:145], 0, s[8:9]
	s_mov_b32 m0, s40
	ds_read_b128 v[186:189], v151 offset:49152
	ds_read_b128 v[190:193], v151 offset:50176
	ds_read_b128 v[194:197], v151 offset:51200
	ds_read_b128 v[198:201], v151 offset:52224
	ds_read_b128 v[206:209], v151 offset:53248
	ds_read_b128 v[210:213], v151 offset:54272
	ds_read_b128 v[214:217], v151 offset:55296
	ds_read_b128 v[218:221], v151 offset:56320
	global_load_lds_dwordx4 v[144:145], off
	s_add_i32 m0, s40, 0x2000
	s_add_u32 s38, s38, 0x40080
	v_lshl_add_u64 v[144:145], v[202:203], 0, s[8:9]
	s_addc_u32 s39, s39, 0
	s_add_i32 s40, s78, s14
	global_load_lds_dwordx4 v[144:145], off
	v_lshl_add_u64 v[144:145], s[38:39], 0, v[130:131]
	s_mov_b32 m0, s40
	s_nop 0
	global_load_lds_dwordx4 v[144:145], off
	v_lshl_add_u64 v[144:145], s[38:39], 0, v[134:135]
	s_add_i32 m0, s40, 0x2000
	s_nop 0
	global_load_lds_dwordx4 v[144:145], off
	v_lshl_add_u64 v[144:145], v[222:223], 0, s[8:9]
	s_mov_b32 m0, s46
	s_nop 0
	global_load_lds_dwordx4 v[144:145], off
	v_lshl_add_u64 v[144:145], v[224:225], 0, s[8:9]
	s_mov_b32 m0, s47
	s_nop 0
	global_load_lds_dwordx4 v[144:145], off
	s_waitcnt vmcnt(8)
	s_waitcnt lgkmcnt(0)
	s_barrier
	s_setprio 1
	s_waitcnt lgkmcnt(0)
	v_mfma_f32_16x16x32_bf16 v[60:63], v[152:155], v[186:189], v[60:63]
	v_mfma_f32_16x16x32_bf16 v[56:59], v[162:165], v[186:189], v[56:59]
	v_mfma_f32_16x16x32_bf16 v[48:51], v[152:155], v[194:197], v[48:51]
	v_mfma_f32_16x16x32_bf16 v[40:43], v[162:165], v[194:197], v[40:43]
	v_mfma_f32_16x16x32_bf16 v[32:35], v[152:155], v[206:209], v[32:35]
	v_mfma_f32_16x16x32_bf16 v[24:27], v[162:165], v[206:209], v[24:27]
	v_mfma_f32_16x16x32_bf16 v[16:19], v[152:155], v[214:217], v[16:19]
	v_mfma_f32_16x16x32_bf16 v[8:11], v[162:165], v[214:217], v[8:11]
	v_mfma_f32_16x16x32_bf16 v[60:63], v[156:159], v[190:193], v[60:63]
	v_mfma_f32_16x16x32_bf16 v[56:59], v[166:169], v[190:193], v[56:59]
	v_mfma_f32_16x16x32_bf16 v[48:51], v[156:159], v[198:201], v[48:51]
	v_mfma_f32_16x16x32_bf16 v[40:43], v[166:169], v[198:201], v[40:43]
	v_mfma_f32_16x16x32_bf16 v[32:35], v[156:159], v[210:213], v[32:35]
	v_mfma_f32_16x16x32_bf16 v[24:27], v[166:169], v[210:213], v[24:27]
	v_mfma_f32_16x16x32_bf16 v[16:19], v[156:159], v[218:221], v[16:19]
	v_mfma_f32_16x16x32_bf16 v[8:11], v[166:169], v[218:221], v[8:11]
	s_setprio 0
	s_setprio 1
	v_mfma_f32_16x16x32_bf16 v[52:55], v[170:173], v[186:189], v[52:55]
	v_mfma_f32_16x16x32_bf16 v[44:47], v[178:181], v[186:189], v[44:47]
	v_mfma_f32_16x16x32_bf16 v[36:39], v[170:173], v[194:197], v[36:39]
	v_mfma_f32_16x16x32_bf16 v[28:31], v[178:181], v[194:197], v[28:31]
	v_mfma_f32_16x16x32_bf16 v[20:23], v[170:173], v[206:209], v[20:23]
	v_mfma_f32_16x16x32_bf16 v[12:15], v[178:181], v[206:209], v[12:15]
	v_mfma_f32_16x16x32_bf16 v[4:7], v[170:173], v[214:217], v[4:7]
	v_mfma_f32_16x16x32_bf16 v[0:3], v[178:181], v[214:217], v[0:3]
	v_mfma_f32_16x16x32_bf16 v[52:55], v[174:177], v[190:193], v[52:55]
	v_mfma_f32_16x16x32_bf16 v[44:47], v[182:185], v[190:193], v[44:47]
	v_mfma_f32_16x16x32_bf16 v[36:39], v[174:177], v[198:201], v[36:39]
	v_mfma_f32_16x16x32_bf16 v[28:31], v[182:185], v[198:201], v[28:31]
	v_mfma_f32_16x16x32_bf16 v[20:23], v[174:177], v[210:213], v[20:23]
	v_mfma_f32_16x16x32_bf16 v[12:15], v[182:185], v[210:213], v[12:15]
	v_mfma_f32_16x16x32_bf16 v[4:7], v[174:177], v[218:221], v[4:7]
	v_mfma_f32_16x16x32_bf16 v[0:3], v[182:185], v[218:221], v[0:3]
	s_setprio 0
	s_add_i32 s76, s76, 2
	s_add_u32 s36, s36, 0x100
	s_addc_u32 s37, s37, 0
	s_add_u32 s74, s74, 0x100
	s_addc_u32 s75, s75, 0
	s_cmp_gt_u32 s76, 13
	s_barrier
	s_cbranch_scc0 .LBB0_622
	s_and_b64 vcc, exec, s[10:11]
	s_cbranch_vccz .LBB0_625
	s_barrier

; #define PG8_STAGE(bufoff, gbase, voff) do { _Pragma("unroll") for (int _i = 0; _i < 2; ++_i) \
;         __builtin_amdgcn_global_load_lds((const unsigned*)((const char*)(gbase) + (voff)[_i]), (PG8_LAS unsigned*)(lds + (bufoff) + ldsw + _i * 8192), 16, 0, 0); } while (0)
; #define PG8_LDA(dst, b, h) do { _Pragma("unroll") for (int m = 0; m < 4; ++m) _Pragma("unroll") for (int k = 0; k < 2; ++k) dst[m][k] = *(const PG8_LAS bf16x8*)(lds + PG8_SA(b, h) + aoff + m * 2048 + k * 1024); } while (0)
; #define PG8_LDB(dst, b, h) do { _Pragma("unroll") for (int n = 0; n < 2; ++n) _Pragma("unroll") for (int k = 0; k < 2; ++k) dst[n][k] = *(const PG8_LAS bf16x8*)(lds + PG8_SB(b, h) + boff + n * 2048 + k * 1024); } while (0)
; #define PG8_MMA(ai, bj, At, Bt) do { __builtin_amdgcn_s_setprio(1); _Pragma("unroll") for (int m = 0; m < 4; ++m) _Pragma("unroll") for (int n = 0; n < 2; ++n) _Pragma("unroll") for (int k = 0; k < 2; ++k) \
;         acc[ai][bj][m][n] = __builtin_amdgcn_mfma_f32_16x16x32_bf16(Bt[n][k], At[m][k], acc[ai][bj][m][n], 0, 0, 0); __builtin_amdgcn_s_setprio(0); } while (0)
; #define PG8_WAIT_V(n) asm volatile("s_waitcnt vmcnt(" #n ")" ::: "memory")
; #define PG8_WAIT_L(n) asm volatile("s_waitcnt lgkmcnt(" #n ")" ::: "memory")
; #define PG8_BAR __builtin_amdgcn_s_barrier()
; #define PG8_SCHED __builtin_amdgcn_sched_barrier(0)
; template <class Epi, class Sched, bool ALIGN_EPI = false, bool SP2 = false>
; __device__ __forceinline__ void gemm_phase(PG8_LAS unsigned char* lds, const Gemm g, const Sched S, const Epi E) {
;     ...
;         for (int t = 0; t < nt; t += 2) {
;             const bool last = (t == nt - 2);
;             const char* a1 = cA + (size_t)(t + 1) * kstepA;
;             const char* a2 = last ? nA : cA + (size_t)(t + 2) * kstepA; const char* b2 = last ? nB : cB + (size_t)(t + 2) * kstep;
;             const char* a3 = a2 + kstepA; const char* b3 = b2 + kstep;
;             if (last && has_next) S.a_ready(nxt);
;             if constexpr (SP2) {
;             PG8_LDB(B0, 0, 0); PG8_LDB(B1, 0, 1); PG8_SCHED; PG8_LDA(At, 0, 0); PG8_STAGE(PG8_SA(1, 1), a1 + hstepA, voffA);
;             PG8_WAIT_V(8); PG8_WAIT_L(0); PG8_BAR; PG8_MMA(0, 0, At, B0); PG8_MMA(0, 1, At, B1); PG8_BAR; PG8_SCHED;
;             PG8_LDA(At, 0, 1); PG8_STAGE(PG8_SB(0, 0), b2, voffB); PG8_STAGE(PG8_SB(0, 1), b2 + hstep, voffB); PG8_STAGE(PG8_SA(0, 0), a2, voffA);
.LBB0_646:
	ds_read_b128 v[152:155], v149
	ds_read_b128 v[156:159], v149 offset:1024
	ds_read_b128 v[162:165], v149 offset:2048
	ds_read_b128 v[166:169], v149 offset:3072
	ds_read_b128 v[170:173], v150
	ds_read_b128 v[174:177], v150 offset:1024
	ds_read_b128 v[178:181], v150 offset:2048
	ds_read_b128 v[182:185], v150 offset:3072
	s_add_u32 s38, s36, 0xfffc0080
	s_addc_u32 s39, s37, -1
	s_cmp_eq_u32 s75, 12
	s_cselect_b32 s41, s27, s39
	s_cselect_b32 s40, s67, s38
	s_cselect_b32 s39, s25, s74
	s_cselect_b32 s38, s68, s69
	v_lshl_add_u64 v[144:145], s[36:37], 0, v[136:137]
	s_add_i32 m0, s15, 0xc000
	ds_read_b128 v[186:189], v151
	ds_read_b128 v[190:193], v151 offset:1024
	ds_read_b128 v[194:197], v151 offset:2048
	ds_read_b128 v[198:201], v151 offset:3072
	ds_read_b128 v[206:209], v151 offset:4096
	ds_read_b128 v[210:213], v151 offset:5120
	ds_read_b128 v[214:217], v151 offset:6144
	ds_read_b128 v[218:221], v151 offset:7168
	global_load_lds_dwordx4 v[144:145], off
	v_lshl_add_u64 v[144:145], s[36:37], 0, v[138:139]
	s_add_i32 m0, s15, 0xe000
	s_nop 0
	global_load_lds_dwordx4 v[144:145], off
	s_waitcnt vmcnt(8)
	s_waitcnt lgkmcnt(0)
	s_barrier
	s_setprio 1
	s_waitcnt lgkmcnt(0)
	v_mfma_f32_16x16x32_bf16 v[124:127], v[152:155], v[186:189], v[124:127]
	v_mfma_f32_16x16x32_bf16 v[120:123], v[162:165], v[186:189], v[120:123]
	v_mfma_f32_16x16x32_bf16 v[112:115], v[152:155], v[194:197], v[112:115]
	v_mfma_f32_16x16x32_bf16 v[104:107], v[162:165], v[194:197], v[104:107]
	v_mfma_f32_16x16x32_bf16 v[96:99], v[152:155], v[206:209], v[96:99]
	v_mfma_f32_16x16x32_bf16 v[88:91], v[162:165], v[206:209], v[88:91]
	v_mfma_f32_16x16x32_bf16 v[80:83], v[152:155], v[214:217], v[80:83]
	v_mfma_f32_16x16x32_bf16 v[72:75], v[162:165], v[214:217], v[72:75]
	v_mfma_f32_16x16x32_bf16 v[124:127], v[156:159], v[190:193], v[124:127]
	v_mfma_f32_16x16x32_bf16 v[120:123], v[166:169], v[190:193], v[120:123]
	v_mfma_f32_16x16x32_bf16 v[112:115], v[156:159], v[198:201], v[112:115]
	v_mfma_f32_16x16x32_bf16 v[104:107], v[166:169], v[198:201], v[104:107]
	v_mfma_f32_16x16x32_bf16 v[96:99], v[156:159], v[210:213], v[96:99]
	v_mfma_f32_16x16x32_bf16 v[88:91], v[166:169], v[210:213], v[88:91]
	v_mfma_f32_16x16x32_bf16 v[80:83], v[156:159], v[218:221], v[80:83]
	v_mfma_f32_16x16x32_bf16 v[72:75], v[166:169], v[218:221], v[72:75]
	s_setprio 0
	s_setprio 1
	v_mfma_f32_16x16x32_bf16 v[116:119], v[170:173], v[186:189], v[116:119]
	v_mfma_f32_16x16x32_bf16 v[108:111], v[178:181], v[186:189], v[108:111]
	v_mfma_f32_16x16x32_bf16 v[100:103], v[170:173], v[194:197], v[100:103]
	v_mfma_f32_16x16x32_bf16 v[92:95], v[178:181], v[194:197], v[92:95]
	v_mfma_f32_16x16x32_bf16 v[84:87], v[170:173], v[206:209], v[84:87]
	v_mfma_f32_16x16x32_bf16 v[76:79], v[178:181], v[206:209], v[76:79]
	v_mfma_f32_16x16x32_bf16 v[68:71], v[170:173], v[214:217], v[68:71]
	v_mfma_f32_16x16x32_bf16 v[64:67], v[178:181], v[214:217], v[64:67]
	v_mfma_f32_16x16x32_bf16 v[116:119], v[174:177], v[190:193], v[116:119]
	v_mfma_f32_16x16x32_bf16 v[108:111], v[182:185], v[190:193], v[108:111]
	v_mfma_f32_16x16x32_bf16 v[100:103], v[174:177], v[198:201], v[100:103]
	v_mfma_f32_16x16x32_bf16 v[92:95], v[182:185], v[198:201], v[92:95]
	v_mfma_f32_16x16x32_bf16 v[84:87], v[174:177], v[210:213], v[84:87]
	v_mfma_f32_16x16x32_bf16 v[76:79], v[182:185], v[210:213], v[76:79]
	v_mfma_f32_16x16x32_bf16 v[68:71], v[174:177], v[218:221], v[68:71]
	v_mfma_f32_16x16x32_bf16 v[64:67], v[182:185], v[218:221], v[64:67]
	s_setprio 0
	s_barrier
	s_add_i32 s76, s54, s14
	v_lshl_add_u64 v[144:145], s[38:39], 0, v[130:131]
	s_mov_b32 m0, s76
	ds_read_b128 v[186:189], v151 offset:16384
	ds_read_b128 v[190:193], v151 offset:17408
	ds_read_b128 v[194:197], v151 offset:18432
	ds_read_b128 v[198:201], v151 offset:19456
	ds_read_b128 v[206:209], v151 offset:20480
	ds_read_b128 v[210:213], v151 offset:21504
	ds_read_b128 v[214:217], v151 offset:22528
	ds_read_b128 v[218:221], v151 offset:23552
	global_load_lds_dwordx4 v[144:145], off
	s_add_i32 m0, s76, 0x2000
	s_add_u32 s76, s38, 0x40000
	v_lshl_add_u64 v[202:203], s[38:39], 0, v[134:135]
	s_addc_u32 s77, s39, 0
	s_add_i32 s78, s55, s14
	global_load_lds_dwordx4 v[202:203], off
	v_lshl_add_u64 v[222:223], s[76:77], 0, v[130:131]
	s_mov_b32 m0, s78
	v_lshl_add_u64 v[224:225], s[40:41], 0, v[132:133]
	global_load_lds_dwordx4 v[222:223], off
	v_lshl_add_u64 v[222:223], s[76:77], 0, v[134:135]
	s_add_i32 m0, s78, 0x2000
	s_nop 0
	global_load_lds_dwordx4 v[222:223], off
	v_lshl_add_u64 v[222:223], s[40:41], 0, v[128:129]
	s_mov_b32 m0, s15
	s_nop 0
	global_load_lds_dwordx4 v[222:223], off
	s_mov_b32 m0, s33
	s_nop 0
	global_load_lds_dwordx4 v[224:225], off
	s_waitcnt vmcnt(8)
	s_waitcnt lgkmcnt(0)
	s_barrier
; #define PG8_STAGE(bufoff, gbase, voff) do { _Pragma("unroll") for (int _i = 0; _i < 2; ++_i) \
;         __builtin_amdgcn_global_load_lds((const unsigned*)((const char*)(gbase) + (voff)[_i]), (PG8_LAS unsigned*)(lds + (bufoff) + ldsw + _i * 8192), 16, 0, 0); } while (0)
; #define PG8_LDA(dst, b, h) do { _Pragma("unroll") for (int m = 0; m < 4; ++m) _Pragma("unroll") for (int k = 0; k < 2; ++k) dst[m][k] = *(const PG8_LAS bf16x8*)(lds + PG8_SA(b, h) + aoff + m * 2048 + k * 1024); } while (0)
; #define PG8_LDB(dst, b, h) do { _Pragma("unroll") for (int n = 0; n < 2; ++n) _Pragma("unroll") for (int k = 0; k < 2; ++k) dst[n][k] = *(const PG8_LAS bf16x8*)(lds + PG8_SB(b, h) + boff + n * 2048 + k * 1024); } while (0)
; #define PG8_MMA(ai, bj, At, Bt) do { __builtin_amdgcn_s_setprio(1); _Pragma("unroll") for (int m = 0; m < 4; ++m) _Pragma("unroll") for (int n = 0; n < 2; ++n) _Pragma("unroll") for (int k = 0; k < 2; ++k) \
;         acc[ai][bj][m][n] = __builtin_amdgcn_mfma_f32_16x16x32_bf16(Bt[n][k], At[m][k], acc[ai][bj][m][n], 0, 0, 0); __builtin_amdgcn_s_setprio(0); } while (0)
; #define PG8_WAIT_V(n) asm volatile("s_waitcnt vmcnt(" #n ")" ::: "memory")
; #define PG8_WAIT_L(n) asm volatile("s_waitcnt lgkmcnt(" #n ")" ::: "memory")
; #define PG8_BAR __builtin_amdgcn_s_barrier()
; #define PG8_SCHED __builtin_amdgcn_sched_barrier(0)
; template <class Epi, class Sched, bool ALIGN_EPI = false, bool SP2 = false>
; __device__ __forceinline__ void gemm_phase(PG8_LAS unsigned char* lds, const Gemm g, const Sched S, const Epi E) {
;     ...
;             PG8_WAIT_V(8); PG8_WAIT_L(0); PG8_BAR; PG8_MMA(1, 0, At, B0); PG8_MMA(1, 1, At, B1); PG8_BAR; PG8_SCHED;
;             PG8_LDB(B0, 1, 0); PG8_LDB(B1, 1, 1); PG8_SCHED; PG8_LDA(At, 1, 0); PG8_STAGE(PG8_SA(0, 1), a2 + hstepA, voffA);
;             PG8_WAIT_V(8); PG8_WAIT_L(0); PG8_BAR; PG8_MMA(0, 0, At, B0); PG8_MMA(0, 1, At, B1); PG8_BAR; PG8_SCHED;
	s_setprio 1
	s_waitcnt lgkmcnt(0)
	v_mfma_f32_16x16x32_bf16 v[60:63], v[152:155], v[186:189], v[60:63]
	v_mfma_f32_16x16x32_bf16 v[56:59], v[162:165], v[186:189], v[56:59]
	v_mfma_f32_16x16x32_bf16 v[48:51], v[152:155], v[194:197], v[48:51]
	v_mfma_f32_16x16x32_bf16 v[40:43], v[162:165], v[194:197], v[40:43]
	v_mfma_f32_16x16x32_bf16 v[32:35], v[152:155], v[206:209], v[32:35]
	v_mfma_f32_16x16x32_bf16 v[24:27], v[162:165], v[206:209], v[24:27]
	v_mfma_f32_16x16x32_bf16 v[16:19], v[152:155], v[214:217], v[16:19]
	v_mfma_f32_16x16x32_bf16 v[8:11], v[162:165], v[214:217], v[8:11]
	v_mfma_f32_16x16x32_bf16 v[60:63], v[156:159], v[190:193], v[60:63]
	v_mfma_f32_16x16x32_bf16 v[56:59], v[166:169], v[190:193], v[56:59]
	v_mfma_f32_16x16x32_bf16 v[48:51], v[156:159], v[198:201], v[48:51]
	v_mfma_f32_16x16x32_bf16 v[40:43], v[166:169], v[198:201], v[40:43]
	v_mfma_f32_16x16x32_bf16 v[32:35], v[156:159], v[210:213], v[32:35]
	v_mfma_f32_16x16x32_bf16 v[24:27], v[166:169], v[210:213], v[24:27]
	v_mfma_f32_16x16x32_bf16 v[16:19], v[156:159], v[218:221], v[16:19]
	v_mfma_f32_16x16x32_bf16 v[8:11], v[166:169], v[218:221], v[8:11]
	s_setprio 0
	s_setprio 1
	v_mfma_f32_16x16x32_bf16 v[52:55], v[170:173], v[186:189], v[52:55]
	v_mfma_f32_16x16x32_bf16 v[44:47], v[178:181], v[186:189], v[44:47]
	v_mfma_f32_16x16x32_bf16 v[36:39], v[170:173], v[194:197], v[36:39]
	v_mfma_f32_16x16x32_bf16 v[28:31], v[178:181], v[194:197], v[28:31]
	v_mfma_f32_16x16x32_bf16 v[20:23], v[170:173], v[206:209], v[20:23]
	v_mfma_f32_16x16x32_bf16 v[12:15], v[178:181], v[206:209], v[12:15]
	v_mfma_f32_16x16x32_bf16 v[4:7], v[170:173], v[214:217], v[4:7]
	v_mfma_f32_16x16x32_bf16 v[0:3], v[178:181], v[214:217], v[0:3]
	v_mfma_f32_16x16x32_bf16 v[52:55], v[174:177], v[190:193], v[52:55]
	v_mfma_f32_16x16x32_bf16 v[44:47], v[182:185], v[190:193], v[44:47]
	v_mfma_f32_16x16x32_bf16 v[36:39], v[174:177], v[198:201], v[36:39]
	v_mfma_f32_16x16x32_bf16 v[28:31], v[182:185], v[198:201], v[28:31]
	v_mfma_f32_16x16x32_bf16 v[20:23], v[174:177], v[210:213], v[20:23]
	v_mfma_f32_16x16x32_bf16 v[12:15], v[182:185], v[210:213], v[12:15]
	v_mfma_f32_16x16x32_bf16 v[4:7], v[174:177], v[218:221], v[4:7]
	v_mfma_f32_16x16x32_bf16 v[0:3], v[182:185], v[218:221], v[0:3]
	s_setprio 0
	s_barrier
	s_add_i32 s76, 0, 0x18000
	v_add_u32_e32 v161, s76, v148
	s_add_i32 s77, 0, 0x1c000
	ds_read_b128 v[152:155], v161
	ds_read_b128 v[156:159], v161 offset:1024
	ds_read_b128 v[162:165], v161 offset:2048
	ds_read_b128 v[166:169], v161 offset:3072
	v_add_u32_e32 v161, s77, v148
	ds_read_b128 v[170:173], v161
	ds_read_b128 v[174:177], v161 offset:1024
	ds_read_b128 v[178:181], v161 offset:2048
	ds_read_b128 v[182:185], v161 offset:3072
	s_add_u32 s40, s40, 0x40000
	s_addc_u32 s41, s41, 0
	s_mov_b32 m0, s35
	v_lshl_add_u64 v[226:227], s[40:41], 0, v[128:129]
	ds_read_b128 v[186:189], v151 offset:32768
	ds_read_b128 v[190:193], v151 offset:33792
	ds_read_b128 v[194:197], v151 offset:34816
	ds_read_b128 v[198:201], v151 offset:35840
	ds_read_b128 v[206:209], v151 offset:36864
	ds_read_b128 v[210:213], v151 offset:37888
	ds_read_b128 v[214:217], v151 offset:38912
	ds_read_b128 v[218:221], v151 offset:39936
	global_load_lds_dwordx4 v[226:227], off
	v_lshl_add_u64 v[226:227], s[40:41], 0, v[132:133]
	s_mov_b32 m0, s42
	s_nop 0
	global_load_lds_dwordx4 v[226:227], off
	s_waitcnt vmcnt(8)
	s_waitcnt lgkmcnt(0)
	s_barrier
	s_setprio 1
	s_waitcnt lgkmcnt(0)
	v_mfma_f32_16x16x32_bf16 v[124:127], v[152:155], v[186:189], v[124:127]
	v_mfma_f32_16x16x32_bf16 v[120:123], v[162:165], v[186:189], v[120:123]
	v_mfma_f32_16x16x32_bf16 v[112:115], v[152:155], v[194:197], v[112:115]
	v_mfma_f32_16x16x32_bf16 v[104:107], v[162:165], v[194:197], v[104:107]
	v_mfma_f32_16x16x32_bf16 v[96:99], v[152:155], v[206:209], v[96:99]
	v_mfma_f32_16x16x32_bf16 v[88:91], v[162:165], v[206:209], v[88:91]
	v_mfma_f32_16x16x32_bf16 v[80:83], v[152:155], v[214:217], v[80:83]
	v_mfma_f32_16x16x32_bf16 v[72:75], v[162:165], v[214:217], v[72:75]
	v_mfma_f32_16x16x32_bf16 v[124:127], v[156:159], v[190:193], v[124:127]
	v_mfma_f32_16x16x32_bf16 v[120:123], v[166:169], v[190:193], v[120:123]
	v_mfma_f32_16x16x32_bf16 v[112:115], v[156:159], v[198:201], v[112:115]
	v_mfma_f32_16x16x32_bf16 v[104:107], v[166:169], v[198:201], v[104:107]
	v_mfma_f32_16x16x32_bf16 v[96:99], v[156:159], v[210:213], v[96:99]
	v_mfma_f32_16x16x32_bf16 v[88:91], v[166:169], v[210:213], v[88:91]
	v_mfma_f32_16x16x32_bf16 v[80:83], v[156:159], v[218:221], v[80:83]
	v_mfma_f32_16x16x32_bf16 v[72:75], v[166:169], v[218:221], v[72:75]
	s_setprio 0
	s_setprio 1
	v_mfma_f32_16x16x32_bf16 v[116:119], v[170:173], v[186:189], v[116:119]
	v_mfma_f32_16x16x32_bf16 v[108:111], v[178:181], v[186:189], v[108:111]
	v_mfma_f32_16x16x32_bf16 v[100:103], v[170:173], v[194:197], v[100:103]
	v_mfma_f32_16x16x32_bf16 v[92:95], v[178:181], v[194:197], v[92:95]
	v_mfma_f32_16x16x32_bf16 v[84:87], v[170:173], v[206:209], v[84:87]
	v_mfma_f32_16x16x32_bf16 v[76:79], v[178:181], v[206:209], v[76:79]
	v_mfma_f32_16x16x32_bf16 v[68:71], v[170:173], v[214:217], v[68:71]
	v_mfma_f32_16x16x32_bf16 v[64:67], v[178:181], v[214:217], v[64:67]
	v_mfma_f32_16x16x32_bf16 v[116:119], v[174:177], v[190:193], v[116:119]
	v_mfma_f32_16x16x32_bf16 v[108:111], v[182:185], v[190:193], v[108:111]
	v_mfma_f32_16x16x32_bf16 v[100:103], v[174:177], v[198:201], v[100:103]
	v_mfma_f32_16x16x32_bf16 v[92:95], v[182:185], v[198:201], v[92:95]
	v_mfma_f32_16x16x32_bf16 v[84:87], v[174:177], v[210:213], v[84:87]
	v_mfma_f32_16x16x32_bf16 v[76:79], v[182:185], v[210:213], v[76:79]
	v_mfma_f32_16x16x32_bf16 v[68:71], v[174:177], v[218:221], v[68:71]
	v_mfma_f32_16x16x32_bf16 v[64:67], v[182:185], v[218:221], v[64:67]
	s_setprio 0
	s_barrier
; #define PG8_STAGE(bufoff, gbase, voff) do { _Pragma("unroll") for (int _i = 0; _i < 2; ++_i) \
;         __builtin_amdgcn_global_load_lds((const unsigned*)((const char*)(gbase) + (voff)[_i]), (PG8_LAS unsigned*)(lds + (bufoff) + ldsw + _i * 8192), 16, 0, 0); } while (0)
; #define PG8_LDA(dst, b, h) do { _Pragma("unroll") for (int m = 0; m < 4; ++m) _Pragma("unroll") for (int k = 0; k < 2; ++k) dst[m][k] = *(const PG8_LAS bf16x8*)(lds + PG8_SA(b, h) + aoff + m * 2048 + k * 1024); } while (0)
; #define PG8_MMA(ai, bj, At, Bt) do { __builtin_amdgcn_s_setprio(1); _Pragma("unroll") for (int m = 0; m < 4; ++m) _Pragma("unroll") for (int n = 0; n < 2; ++n) _Pragma("unroll") for (int k = 0; k < 2; ++k) \
;         acc[ai][bj][m][n] = __builtin_amdgcn_mfma_f32_16x16x32_bf16(Bt[n][k], At[m][k], acc[ai][bj][m][n], 0, 0, 0); __builtin_amdgcn_s_setprio(0); } while (0)
; #define PG8_WAIT_V(n) asm volatile("s_waitcnt vmcnt(" #n ")" ::: "memory")
; #define PG8_WAIT_L(n) asm volatile("s_waitcnt lgkmcnt(" #n ")" ::: "memory")
; #define PG8_BAR __builtin_amdgcn_s_barrier()
; #define PG8_SCHED __builtin_amdgcn_sched_barrier(0)
; template <class Epi, class Sched, bool ALIGN_EPI = false, bool SP2 = false>
; __device__ __forceinline__ void gemm_phase(PG8_LAS unsigned char* lds, const Gemm g, const Sched S, const Epi E) {
;     ...
;         for (int t = 0; t < nt; t += 2) {
;     ...
;             PG8_LDA(At, 1, 1); PG8_STAGE(PG8_SB(1, 0), b3, voffB); PG8_STAGE(PG8_SB(1, 1), b3 + hstep, voffB); PG8_STAGE(PG8_SA(1, 0), a3, voffA);
;             PG8_WAIT_V(8); PG8_WAIT_L(0); PG8_BAR; PG8_MMA(1, 0, At, B0); PG8_MMA(1, 1, At, B1); PG8_BAR; PG8_SCHED;
	s_add_i32 s40, s76, s14
	v_lshl_add_u64 v[144:145], v[144:145], 0, s[10:11]
	s_mov_b32 m0, s40
	ds_read_b128 v[186:189], v151 offset:49152
	ds_read_b128 v[190:193], v151 offset:50176
	ds_read_b128 v[194:197], v151 offset:51200
	ds_read_b128 v[198:201], v151 offset:52224
	ds_read_b128 v[206:209], v151 offset:53248
	ds_read_b128 v[210:213], v151 offset:54272
	ds_read_b128 v[214:217], v151 offset:55296
	ds_read_b128 v[218:221], v151 offset:56320
	global_load_lds_dwordx4 v[144:145], off
	s_add_i32 m0, s40, 0x2000
	s_add_u32 s38, s38, 0x40080
	v_lshl_add_u64 v[144:145], v[202:203], 0, s[10:11]
	s_addc_u32 s39, s39, 0
	s_add_i32 s40, s77, s14
	global_load_lds_dwordx4 v[144:145], off
	v_lshl_add_u64 v[144:145], s[38:39], 0, v[130:131]
	s_mov_b32 m0, s40
	s_nop 0
	global_load_lds_dwordx4 v[144:145], off
	v_lshl_add_u64 v[144:145], s[38:39], 0, v[134:135]
	s_add_i32 m0, s40, 0x2000
	s_nop 0
	global_load_lds_dwordx4 v[144:145], off
	v_lshl_add_u64 v[144:145], v[222:223], 0, s[10:11]
	s_mov_b32 m0, s46
	s_nop 0
	global_load_lds_dwordx4 v[144:145], off
	v_lshl_add_u64 v[144:145], v[224:225], 0, s[10:11]
	s_mov_b32 m0, s47
	s_nop 0
	global_load_lds_dwordx4 v[144:145], off
	s_waitcnt vmcnt(8)
	s_waitcnt lgkmcnt(0)
	s_barrier
	s_setprio 1
	s_waitcnt lgkmcnt(0)
	v_mfma_f32_16x16x32_bf16 v[60:63], v[152:155], v[186:189], v[60:63]
	v_mfma_f32_16x16x32_bf16 v[56:59], v[162:165], v[186:189], v[56:59]
	v_mfma_f32_16x16x32_bf16 v[48:51], v[152:155], v[194:197], v[48:51]
	v_mfma_f32_16x16x32_bf16 v[40:43], v[162:165], v[194:197], v[40:43]
	v_mfma_f32_16x16x32_bf16 v[32:35], v[152:155], v[206:209], v[32:35]
	v_mfma_f32_16x16x32_bf16 v[24:27], v[162:165], v[206:209], v[24:27]
	v_mfma_f32_16x16x32_bf16 v[16:19], v[152:155], v[214:217], v[16:19]
	v_mfma_f32_16x16x32_bf16 v[8:11], v[162:165], v[214:217], v[8:11]
	v_mfma_f32_16x16x32_bf16 v[60:63], v[156:159], v[190:193], v[60:63]
	v_mfma_f32_16x16x32_bf16 v[56:59], v[166:169], v[190:193], v[56:59]
	v_mfma_f32_16x16x32_bf16 v[48:51], v[156:159], v[198:201], v[48:51]
	v_mfma_f32_16x16x32_bf16 v[40:43], v[166:169], v[198:201], v[40:43]
	v_mfma_f32_16x16x32_bf16 v[32:35], v[156:159], v[210:213], v[32:35]
	v_mfma_f32_16x16x32_bf16 v[24:27], v[166:169], v[210:213], v[24:27]
	v_mfma_f32_16x16x32_bf16 v[16:19], v[156:159], v[218:221], v[16:19]
	v_mfma_f32_16x16x32_bf16 v[8:11], v[166:169], v[218:221], v[8:11]
	s_setprio 0
	s_setprio 1
	v_mfma_f32_16x16x32_bf16 v[52:55], v[170:173], v[186:189], v[52:55]
	v_mfma_f32_16x16x32_bf16 v[44:47], v[178:181], v[186:189], v[44:47]
	v_mfma_f32_16x16x32_bf16 v[36:39], v[170:173], v[194:197], v[36:39]
	v_mfma_f32_16x16x32_bf16 v[28:31], v[178:181], v[194:197], v[28:31]
	v_mfma_f32_16x16x32_bf16 v[20:23], v[170:173], v[206:209], v[20:23]
	v_mfma_f32_16x16x32_bf16 v[12:15], v[178:181], v[206:209], v[12:15]
	v_mfma_f32_16x16x32_bf16 v[4:7], v[170:173], v[214:217], v[4:7]
	v_mfma_f32_16x16x32_bf16 v[0:3], v[178:181], v[214:217], v[0:3]
	v_mfma_f32_16x16x32_bf16 v[52:55], v[174:177], v[190:193], v[52:55]
	v_mfma_f32_16x16x32_bf16 v[44:47], v[182:185], v[190:193], v[44:47]
	v_mfma_f32_16x16x32_bf16 v[36:39], v[174:177], v[198:201], v[36:39]
	v_mfma_f32_16x16x32_bf16 v[28:31], v[182:185], v[198:201], v[28:31]
	v_mfma_f32_16x16x32_bf16 v[20:23], v[174:177], v[210:213], v[20:23]
	v_mfma_f32_16x16x32_bf16 v[12:15], v[182:185], v[210:213], v[12:15]
	v_mfma_f32_16x16x32_bf16 v[4:7], v[174:177], v[218:221], v[4:7]
	v_mfma_f32_16x16x32_bf16 v[0:3], v[182:185], v[218:221], v[0:3]
	s_setprio 0
	s_add_i32 s75, s75, 2
	s_add_u32 s36, s36, 0x100
	s_addc_u32 s37, s37, 0
	s_add_u32 s69, s69, 0x100
	s_addc_u32 s74, s74, 0
	s_cmp_gt_u32 s75, 13
	s_barrier
	s_cbranch_scc0 .LBB0_646
	s_and_b64 vcc, exec, s[12:13]
	s_cbranch_vccz .LBB0_649
	s_barrier

; #define PG8_STAGE(bufoff, gbase, voff) do { _Pragma("unroll") for (int _i = 0; _i < 2; ++_i) \
;         __builtin_amdgcn_global_load_lds((const unsigned*)((const char*)(gbase) + (voff)[_i]), (PG8_LAS unsigned*)(lds + (bufoff) + ldsw + _i * 8192), 16, 0, 0); } while (0)
; #define PG8_LDA(dst, b, h) do { _Pragma("unroll") for (int m = 0; m < 4; ++m) _Pragma("unroll") for (int k = 0; k < 2; ++k) dst[m][k] = *(const PG8_LAS bf16x8*)(lds + PG8_SA(b, h) + aoff + m * 2048 + k * 1024); } while (0)
; #define PG8_LDB(dst, b, h) do { _Pragma("unroll") for (int n = 0; n < 2; ++n) _Pragma("unroll") for (int k = 0; k < 2; ++k) dst[n][k] = *(const PG8_LAS bf16x8*)(lds + PG8_SB(b, h) + boff + n * 2048 + k * 1024); } while (0)
; #define PG8_MMA(ai, bj, At, Bt) do { __builtin_amdgcn_s_setprio(1); _Pragma("unroll") for (int m = 0; m < 4; ++m) _Pragma("unroll") for (int n = 0; n < 2; ++n) _Pragma("unroll") for (int k = 0; k < 2; ++k) \
;         acc[ai][bj][m][n] = __builtin_amdgcn_mfma_f32_16x16x32_bf16(Bt[n][k], At[m][k], acc[ai][bj][m][n], 0, 0, 0); __builtin_amdgcn_s_setprio(0); } while (0)
; #define PG8_WAIT_V(n) asm volatile("s_waitcnt vmcnt(" #n ")" ::: "memory")
; #define PG8_WAIT_L(n) asm volatile("s_waitcnt lgkmcnt(" #n ")" ::: "memory")
; #define PG8_BAR __builtin_amdgcn_s_barrier()
; #define PG8_SCHED __builtin_amdgcn_sched_barrier(0)
; template <class Epi, class Sched, bool ALIGN_EPI = false, bool SP2 = false>
; __device__ __forceinline__ void gemm_phase(PG8_LAS unsigned char* lds, const Gemm g, const Sched S, const Epi E) {
;     ...
;         for (int t = 0; t < nt; t += 2) {
;             const bool last = (t == nt - 2);
;             const char* a1 = cA + (size_t)(t + 1) * kstepA;
;             const char* a2 = last ? nA : cA + (size_t)(t + 2) * kstepA; const char* b2 = last ? nB : cB + (size_t)(t + 2) * kstep;
;             const char* a3 = a2 + kstepA; const char* b3 = b2 + kstep;
;             if (last && has_next) S.a_ready(nxt);
;             if constexpr (SP2) {
;             PG8_LDB(B0, 0, 0); PG8_LDB(B1, 0, 1); PG8_SCHED; PG8_LDA(At, 0, 0); PG8_STAGE(PG8_SA(1, 1), a1 + hstepA, voffA);
;             PG8_WAIT_V(8); PG8_WAIT_L(0); PG8_BAR; PG8_MMA(0, 0, At, B0); PG8_MMA(0, 1, At, B1); PG8_BAR; PG8_SCHED;
;             PG8_LDA(At, 0, 1); PG8_STAGE(PG8_SB(0, 0), b2, voffB); PG8_STAGE(PG8_SB(0, 1), b2 + hstep, voffB); PG8_STAGE(PG8_SA(0, 0), a2, voffA);
.LBB0_1175:
	ds_read_b128 v[64:67], v188
	ds_read_b128 v[68:71], v188 offset:1024
	ds_read_b128 v[72:75], v188 offset:2048
	ds_read_b128 v[76:79], v188 offset:3072
	ds_read_b128 v[80:83], v189
	ds_read_b128 v[84:87], v189 offset:1024
	ds_read_b128 v[88:91], v189 offset:2048
	ds_read_b128 v[92:95], v189 offset:3072
	s_add_u32 s42, s40, 0xfffc0080
	s_addc_u32 s43, s41, -1
	s_cmp_eq_u32 s65, 12
	s_cselect_b32 s45, s1, s43
	s_cselect_b32 s44, s31, s42
	s_cselect_b32 s43, s29, s64
	s_cselect_b32 s42, s62, s63
	v_lshl_add_u64 v[180:181], s[40:41], 0, v[166:167]
	s_add_i32 m0, s15, 0xc000
	ds_read_b128 v[174:177], v190
	ds_read_b128 v[184:187], v190 offset:1024
	ds_read_b128 v[192:195], v190 offset:2048
	ds_read_b128 v[196:199], v190 offset:3072
	ds_read_b128 v[200:203], v190 offset:4096
	ds_read_b128 v[206:209], v190 offset:5120
	ds_read_b128 v[210:213], v190 offset:6144
	ds_read_b128 v[214:217], v190 offset:7168
	global_load_lds_dwordx4 v[180:181], off
	v_lshl_add_u64 v[180:181], s[40:41], 0, v[168:169]
	s_add_i32 m0, s15, 0xe000
	s_nop 0
	global_load_lds_dwordx4 v[180:181], off
	s_waitcnt vmcnt(8)
	s_waitcnt lgkmcnt(0)
	s_barrier
	s_setprio 1
	s_waitcnt lgkmcnt(0)
	v_mfma_f32_16x16x32_bf16 v[156:159], v[64:67], v[174:177], v[156:159]
	v_mfma_f32_16x16x32_bf16 v[152:155], v[72:75], v[174:177], v[152:155]
	v_mfma_f32_16x16x32_bf16 v[140:143], v[64:67], v[192:195], v[140:143]
	v_mfma_f32_16x16x32_bf16 v[136:139], v[72:75], v[192:195], v[136:139]
	v_mfma_f32_16x16x32_bf16 v[124:127], v[64:67], v[200:203], v[124:127]
	v_mfma_f32_16x16x32_bf16 v[120:123], v[72:75], v[200:203], v[120:123]
	v_mfma_f32_16x16x32_bf16 v[108:111], v[64:67], v[210:213], v[108:111]
	v_mfma_f32_16x16x32_bf16 v[104:107], v[72:75], v[210:213], v[104:107]
	v_mfma_f32_16x16x32_bf16 v[156:159], v[68:71], v[184:187], v[156:159]
	v_mfma_f32_16x16x32_bf16 v[152:155], v[76:79], v[184:187], v[152:155]
	v_mfma_f32_16x16x32_bf16 v[140:143], v[68:71], v[196:199], v[140:143]
	v_mfma_f32_16x16x32_bf16 v[136:139], v[76:79], v[196:199], v[136:139]
	v_mfma_f32_16x16x32_bf16 v[124:127], v[68:71], v[206:209], v[124:127]
	v_mfma_f32_16x16x32_bf16 v[120:123], v[76:79], v[206:209], v[120:123]
	v_mfma_f32_16x16x32_bf16 v[108:111], v[68:71], v[214:217], v[108:111]
	v_mfma_f32_16x16x32_bf16 v[104:107], v[76:79], v[214:217], v[104:107]
	s_setprio 0
	s_setprio 1
	v_mfma_f32_16x16x32_bf16 v[148:151], v[80:83], v[174:177], v[148:151]
	v_mfma_f32_16x16x32_bf16 v[144:147], v[88:91], v[174:177], v[144:147]
	v_mfma_f32_16x16x32_bf16 v[132:135], v[80:83], v[192:195], v[132:135]
	v_mfma_f32_16x16x32_bf16 v[128:131], v[88:91], v[192:195], v[128:131]
	v_mfma_f32_16x16x32_bf16 v[116:119], v[80:83], v[200:203], v[116:119]
	v_mfma_f32_16x16x32_bf16 v[112:115], v[88:91], v[200:203], v[112:115]
	v_mfma_f32_16x16x32_bf16 v[100:103], v[80:83], v[210:213], v[100:103]
	v_mfma_f32_16x16x32_bf16 v[96:99], v[88:91], v[210:213], v[96:99]
	v_mfma_f32_16x16x32_bf16 v[148:151], v[84:87], v[184:187], v[148:151]
	v_mfma_f32_16x16x32_bf16 v[144:147], v[92:95], v[184:187], v[144:147]
	v_mfma_f32_16x16x32_bf16 v[132:135], v[84:87], v[196:199], v[132:135]
	v_mfma_f32_16x16x32_bf16 v[128:131], v[92:95], v[196:199], v[128:131]
	v_mfma_f32_16x16x32_bf16 v[116:119], v[84:87], v[206:209], v[116:119]
	v_mfma_f32_16x16x32_bf16 v[112:115], v[92:95], v[206:209], v[112:115]
	v_mfma_f32_16x16x32_bf16 v[100:103], v[84:87], v[214:217], v[100:103]
	v_mfma_f32_16x16x32_bf16 v[96:99], v[92:95], v[214:217], v[96:99]
	s_setprio 0
	s_barrier
	s_add_i32 s66, s60, s4
	v_lshl_add_u64 v[180:181], s[42:43], 0, v[162:163]
	s_mov_b32 m0, s66
	ds_read_b128 v[174:177], v190 offset:16384
	ds_read_b128 v[184:187], v190 offset:17408
	ds_read_b128 v[192:195], v190 offset:18432
	ds_read_b128 v[196:199], v190 offset:19456
	ds_read_b128 v[200:203], v190 offset:20480
	ds_read_b128 v[206:209], v190 offset:21504
	ds_read_b128 v[210:213], v190 offset:22528
	ds_read_b128 v[214:217], v190 offset:23552
	global_load_lds_dwordx4 v[180:181], off
	s_add_i32 m0, s66, 0x2000
	s_add_u32 s66, s42, 0x40000
	v_lshl_add_u64 v[218:219], s[42:43], 0, v[164:165]
	s_addc_u32 s67, s43, 0
	s_add_i32 s68, s61, s4
	global_load_lds_dwordx4 v[218:219], off
	v_lshl_add_u64 v[220:221], s[66:67], 0, v[162:163]
	s_mov_b32 m0, s68
	v_lshl_add_u64 v[222:223], s[44:45], 0, v[164:165]
	global_load_lds_dwordx4 v[220:221], off
	v_lshl_add_u64 v[220:221], s[66:67], 0, v[164:165]
	s_add_i32 m0, s68, 0x2000
	s_nop 0
	global_load_lds_dwordx4 v[220:221], off
	v_lshl_add_u64 v[220:221], s[44:45], 0, v[162:163]
	s_mov_b32 m0, s15
	s_nop 0
	global_load_lds_dwordx4 v[220:221], off
	s_mov_b32 m0, s27
	s_nop 0
	global_load_lds_dwordx4 v[222:223], off
	s_waitcnt vmcnt(8)
	s_waitcnt lgkmcnt(0)
	s_barrier
; #define PG8_STAGE(bufoff, gbase, voff) do { _Pragma("unroll") for (int _i = 0; _i < 2; ++_i) \
;         __builtin_amdgcn_global_load_lds((const unsigned*)((const char*)(gbase) + (voff)[_i]), (PG8_LAS unsigned*)(lds + (bufoff) + ldsw + _i * 8192), 16, 0, 0); } while (0)
; #define PG8_LDA(dst, b, h) do { _Pragma("unroll") for (int m = 0; m < 4; ++m) _Pragma("unroll") for (int k = 0; k < 2; ++k) dst[m][k] = *(const PG8_LAS bf16x8*)(lds + PG8_SA(b, h) + aoff + m * 2048 + k * 1024); } while (0)
; #define PG8_LDB(dst, b, h) do { _Pragma("unroll") for (int n = 0; n < 2; ++n) _Pragma("unroll") for (int k = 0; k < 2; ++k) dst[n][k] = *(const PG8_LAS bf16x8*)(lds + PG8_SB(b, h) + boff + n * 2048 + k * 1024); } while (0)
; #define PG8_MMA(ai, bj, At, Bt) do { __builtin_amdgcn_s_setprio(1); _Pragma("unroll") for (int m = 0; m < 4; ++m) _Pragma("unroll") for (int n = 0; n < 2; ++n) _Pragma("unroll") for (int k = 0; k < 2; ++k) \
;         acc[ai][bj][m][n] = __builtin_amdgcn_mfma_f32_16x16x32_bf16(Bt[n][k], At[m][k], acc[ai][bj][m][n], 0, 0, 0); __builtin_amdgcn_s_setprio(0); } while (0)
; #define PG8_WAIT_V(n) asm volatile("s_waitcnt vmcnt(" #n ")" ::: "memory")
; #define PG8_WAIT_L(n) asm volatile("s_waitcnt lgkmcnt(" #n ")" ::: "memory")
; #define PG8_BAR __builtin_amdgcn_s_barrier()
; #define PG8_SCHED __builtin_amdgcn_sched_barrier(0)
; template <class Epi, class Sched, bool ALIGN_EPI = false, bool SP2 = false>
; __device__ __forceinline__ void gemm_phase(PG8_LAS unsigned char* lds, const Gemm g, const Sched S, const Epi E) {
;     ...
;             PG8_WAIT_V(8); PG8_WAIT_L(0); PG8_BAR; PG8_MMA(1, 0, At, B0); PG8_MMA(1, 1, At, B1); PG8_BAR; PG8_SCHED;
;             PG8_LDB(B0, 1, 0); PG8_LDB(B1, 1, 1); PG8_SCHED; PG8_LDA(At, 1, 0); PG8_STAGE(PG8_SA(0, 1), a2 + hstepA, voffA);
;             PG8_WAIT_V(8); PG8_WAIT_L(0); PG8_BAR; PG8_MMA(0, 0, At, B0); PG8_MMA(0, 1, At, B1); PG8_BAR; PG8_SCHED;
	s_setprio 1
	s_waitcnt lgkmcnt(0)
	v_mfma_f32_16x16x32_bf16 v[60:63], v[64:67], v[174:177], v[60:63]
	v_mfma_f32_16x16x32_bf16 v[56:59], v[72:75], v[174:177], v[56:59]
	v_mfma_f32_16x16x32_bf16 v[44:47], v[64:67], v[192:195], v[44:47]
	v_mfma_f32_16x16x32_bf16 v[40:43], v[72:75], v[192:195], v[40:43]
	v_mfma_f32_16x16x32_bf16 v[28:31], v[64:67], v[200:203], v[28:31]
	v_mfma_f32_16x16x32_bf16 v[24:27], v[72:75], v[200:203], v[24:27]
	v_mfma_f32_16x16x32_bf16 v[12:15], v[64:67], v[210:213], v[12:15]
	v_mfma_f32_16x16x32_bf16 v[8:11], v[72:75], v[210:213], v[8:11]
	v_mfma_f32_16x16x32_bf16 v[60:63], v[68:71], v[184:187], v[60:63]
	v_mfma_f32_16x16x32_bf16 v[56:59], v[76:79], v[184:187], v[56:59]
	v_mfma_f32_16x16x32_bf16 v[44:47], v[68:71], v[196:199], v[44:47]
	v_mfma_f32_16x16x32_bf16 v[40:43], v[76:79], v[196:199], v[40:43]
	v_mfma_f32_16x16x32_bf16 v[28:31], v[68:71], v[206:209], v[28:31]
	v_mfma_f32_16x16x32_bf16 v[24:27], v[76:79], v[206:209], v[24:27]
	v_mfma_f32_16x16x32_bf16 v[12:15], v[68:71], v[214:217], v[12:15]
	v_mfma_f32_16x16x32_bf16 v[8:11], v[76:79], v[214:217], v[8:11]
	s_setprio 0
	s_setprio 1
	v_mfma_f32_16x16x32_bf16 v[52:55], v[80:83], v[174:177], v[52:55]
	v_mfma_f32_16x16x32_bf16 v[48:51], v[88:91], v[174:177], v[48:51]
	v_mfma_f32_16x16x32_bf16 v[36:39], v[80:83], v[192:195], v[36:39]
	v_mfma_f32_16x16x32_bf16 v[32:35], v[88:91], v[192:195], v[32:35]
	v_mfma_f32_16x16x32_bf16 v[20:23], v[80:83], v[200:203], v[20:23]
	v_mfma_f32_16x16x32_bf16 v[16:19], v[88:91], v[200:203], v[16:19]
	v_mfma_f32_16x16x32_bf16 v[4:7], v[80:83], v[210:213], v[4:7]
	v_mfma_f32_16x16x32_bf16 v[0:3], v[88:91], v[210:213], v[0:3]
	v_mfma_f32_16x16x32_bf16 v[52:55], v[84:87], v[184:187], v[52:55]
	v_mfma_f32_16x16x32_bf16 v[48:51], v[92:95], v[184:187], v[48:51]
	v_mfma_f32_16x16x32_bf16 v[36:39], v[84:87], v[196:199], v[36:39]
	v_mfma_f32_16x16x32_bf16 v[32:35], v[92:95], v[196:199], v[32:35]
	v_mfma_f32_16x16x32_bf16 v[20:23], v[84:87], v[206:209], v[20:23]
	v_mfma_f32_16x16x32_bf16 v[16:19], v[92:95], v[206:209], v[16:19]
	v_mfma_f32_16x16x32_bf16 v[4:7], v[84:87], v[214:217], v[4:7]
	v_mfma_f32_16x16x32_bf16 v[0:3], v[92:95], v[214:217], v[0:3]
	s_setprio 0
	s_barrier
	s_add_i32 s66, 0, 0x18000
	s_add_i32 s67, 0, 0x1c000
	v_add_u32_e32 v76, s66, v183
	v_add_u32_e32 v92, s67, v183
	ds_read_b128 v[64:67], v76
	ds_read_b128 v[68:71], v76 offset:1024
	ds_read_b128 v[72:75], v76 offset:2048
	ds_read_b128 v[76:79], v76 offset:3072
	ds_read_b128 v[80:83], v92
	ds_read_b128 v[84:87], v92 offset:1024
	ds_read_b128 v[88:91], v92 offset:2048
	ds_read_b128 v[92:95], v92 offset:3072
	s_add_u32 s44, s44, 0x40000
	s_addc_u32 s45, s45, 0
	s_mov_b32 m0, s33
	v_lshl_add_u64 v[224:225], s[44:45], 0, v[162:163]
	ds_read_b128 v[174:177], v190 offset:32768
	ds_read_b128 v[184:187], v190 offset:33792
	ds_read_b128 v[192:195], v190 offset:34816
	ds_read_b128 v[196:199], v190 offset:35840
	ds_read_b128 v[200:203], v190 offset:36864
	ds_read_b128 v[206:209], v190 offset:37888
	ds_read_b128 v[210:213], v190 offset:38912
	ds_read_b128 v[214:217], v190 offset:39936
	global_load_lds_dwordx4 v[224:225], off
	v_lshl_add_u64 v[224:225], s[44:45], 0, v[164:165]
	s_mov_b32 m0, s39
	s_nop 0
	global_load_lds_dwordx4 v[224:225], off
	s_waitcnt vmcnt(8)
	s_waitcnt lgkmcnt(0)
	s_barrier
	s_setprio 1
	s_waitcnt lgkmcnt(0)
	v_mfma_f32_16x16x32_bf16 v[156:159], v[64:67], v[174:177], v[156:159]
	v_mfma_f32_16x16x32_bf16 v[152:155], v[72:75], v[174:177], v[152:155]
	v_mfma_f32_16x16x32_bf16 v[140:143], v[64:67], v[192:195], v[140:143]
	v_mfma_f32_16x16x32_bf16 v[136:139], v[72:75], v[192:195], v[136:139]
	v_mfma_f32_16x16x32_bf16 v[124:127], v[64:67], v[200:203], v[124:127]
	v_mfma_f32_16x16x32_bf16 v[120:123], v[72:75], v[200:203], v[120:123]
	v_mfma_f32_16x16x32_bf16 v[108:111], v[64:67], v[210:213], v[108:111]
	v_mfma_f32_16x16x32_bf16 v[104:107], v[72:75], v[210:213], v[104:107]
	v_mfma_f32_16x16x32_bf16 v[156:159], v[68:71], v[184:187], v[156:159]
	v_mfma_f32_16x16x32_bf16 v[152:155], v[76:79], v[184:187], v[152:155]
	v_mfma_f32_16x16x32_bf16 v[140:143], v[68:71], v[196:199], v[140:143]
	v_mfma_f32_16x16x32_bf16 v[136:139], v[76:79], v[196:199], v[136:139]
	v_mfma_f32_16x16x32_bf16 v[124:127], v[68:71], v[206:209], v[124:127]
	v_mfma_f32_16x16x32_bf16 v[120:123], v[76:79], v[206:209], v[120:123]
	v_mfma_f32_16x16x32_bf16 v[108:111], v[68:71], v[214:217], v[108:111]
	v_mfma_f32_16x16x32_bf16 v[104:107], v[76:79], v[214:217], v[104:107]
	s_setprio 0
	s_setprio 1
	v_mfma_f32_16x16x32_bf16 v[148:151], v[80:83], v[174:177], v[148:151]
	v_mfma_f32_16x16x32_bf16 v[144:147], v[88:91], v[174:177], v[144:147]
	v_mfma_f32_16x16x32_bf16 v[132:135], v[80:83], v[192:195], v[132:135]
	v_mfma_f32_16x16x32_bf16 v[128:131], v[88:91], v[192:195], v[128:131]
	v_mfma_f32_16x16x32_bf16 v[116:119], v[80:83], v[200:203], v[116:119]
	v_mfma_f32_16x16x32_bf16 v[112:115], v[88:91], v[200:203], v[112:115]
	v_mfma_f32_16x16x32_bf16 v[100:103], v[80:83], v[210:213], v[100:103]
	v_mfma_f32_16x16x32_bf16 v[96:99], v[88:91], v[210:213], v[96:99]
	v_mfma_f32_16x16x32_bf16 v[148:151], v[84:87], v[184:187], v[148:151]
	v_mfma_f32_16x16x32_bf16 v[144:147], v[92:95], v[184:187], v[144:147]
	v_mfma_f32_16x16x32_bf16 v[132:135], v[84:87], v[196:199], v[132:135]
	v_mfma_f32_16x16x32_bf16 v[128:131], v[92:95], v[196:199], v[128:131]
	v_mfma_f32_16x16x32_bf16 v[116:119], v[84:87], v[206:209], v[116:119]
	v_mfma_f32_16x16x32_bf16 v[112:115], v[92:95], v[206:209], v[112:115]
	v_mfma_f32_16x16x32_bf16 v[100:103], v[84:87], v[214:217], v[100:103]
	v_mfma_f32_16x16x32_bf16 v[96:99], v[92:95], v[214:217], v[96:99]
	s_setprio 0
	s_barrier
; #define PG8_STAGE(bufoff, gbase, voff) do { _Pragma("unroll") for (int _i = 0; _i < 2; ++_i) \
;         __builtin_amdgcn_global_load_lds((const unsigned*)((const char*)(gbase) + (voff)[_i]), (PG8_LAS unsigned*)(lds + (bufoff) + ldsw + _i * 8192), 16, 0, 0); } while (0)
; #define PG8_LDA(dst, b, h) do { _Pragma("unroll") for (int m = 0; m < 4; ++m) _Pragma("unroll") for (int k = 0; k < 2; ++k) dst[m][k] = *(const PG8_LAS bf16x8*)(lds + PG8_SA(b, h) + aoff + m * 2048 + k * 1024); } while (0)
; #define PG8_MMA(ai, bj, At, Bt) do { __builtin_amdgcn_s_setprio(1); _Pragma("unroll") for (int m = 0; m < 4; ++m) _Pragma("unroll") for (int n = 0; n < 2; ++n) _Pragma("unroll") for (int k = 0; k < 2; ++k) \
;         acc[ai][bj][m][n] = __builtin_amdgcn_mfma_f32_16x16x32_bf16(Bt[n][k], At[m][k], acc[ai][bj][m][n], 0, 0, 0); __builtin_amdgcn_s_setprio(0); } while (0)
; #define PG8_WAIT_V(n) asm volatile("s_waitcnt vmcnt(" #n ")" ::: "memory")
; #define PG8_WAIT_L(n) asm volatile("s_waitcnt lgkmcnt(" #n ")" ::: "memory")
; #define PG8_BAR __builtin_amdgcn_s_barrier()
; #define PG8_SCHED __builtin_amdgcn_sched_barrier(0)
; template <class Epi, class Sched, bool ALIGN_EPI = false, bool SP2 = false>
; __device__ __forceinline__ void gemm_phase(PG8_LAS unsigned char* lds, const Gemm g, const Sched S, const Epi E) {
;     ...
;         for (int t = 0; t < nt; t += 2) {
;     ...
;             PG8_LDA(At, 1, 1); PG8_STAGE(PG8_SB(1, 0), b3, voffB); PG8_STAGE(PG8_SB(1, 1), b3 + hstep, voffB); PG8_STAGE(PG8_SA(1, 0), a3, voffA);
;             PG8_WAIT_V(8); PG8_WAIT_L(0); PG8_BAR; PG8_MMA(1, 0, At, B0); PG8_MMA(1, 1, At, B1); PG8_BAR; PG8_SCHED;
	s_add_i32 s44, s66, s4
	v_lshl_add_u64 v[180:181], v[180:181], 0, s[20:21]
	s_mov_b32 m0, s44
	ds_read_b128 v[174:177], v190 offset:49152
	ds_read_b128 v[184:187], v190 offset:50176
	ds_read_b128 v[192:195], v190 offset:51200
	ds_read_b128 v[196:199], v190 offset:52224
	ds_read_b128 v[200:203], v190 offset:53248
	ds_read_b128 v[206:209], v190 offset:54272
	ds_read_b128 v[210:213], v190 offset:55296
	ds_read_b128 v[214:217], v190 offset:56320
	global_load_lds_dwordx4 v[180:181], off
	s_add_i32 m0, s44, 0x2000
	s_add_u32 s42, s42, 0x40080
	v_lshl_add_u64 v[180:181], v[218:219], 0, s[20:21]
	s_addc_u32 s43, s43, 0
	s_add_i32 s44, s67, s4
	global_load_lds_dwordx4 v[180:181], off
	v_lshl_add_u64 v[180:181], s[42:43], 0, v[162:163]
	s_mov_b32 m0, s44
	s_nop 0
	global_load_lds_dwordx4 v[180:181], off
	v_lshl_add_u64 v[180:181], s[42:43], 0, v[164:165]
	s_add_i32 m0, s44, 0x2000
	s_nop 0
	global_load_lds_dwordx4 v[180:181], off
	v_lshl_add_u64 v[180:181], v[220:221], 0, s[20:21]
	s_mov_b32 m0, s55
	s_nop 0
	global_load_lds_dwordx4 v[180:181], off
	v_lshl_add_u64 v[180:181], v[222:223], 0, s[20:21]
	s_mov_b32 m0, s57
	s_nop 0
	global_load_lds_dwordx4 v[180:181], off
	s_waitcnt vmcnt(8)
	s_waitcnt lgkmcnt(0)
	s_barrier
	s_setprio 1
	s_waitcnt lgkmcnt(0)
	v_mfma_f32_16x16x32_bf16 v[60:63], v[64:67], v[174:177], v[60:63]
	v_mfma_f32_16x16x32_bf16 v[56:59], v[72:75], v[174:177], v[56:59]
	v_mfma_f32_16x16x32_bf16 v[44:47], v[64:67], v[192:195], v[44:47]
	v_mfma_f32_16x16x32_bf16 v[40:43], v[72:75], v[192:195], v[40:43]
	v_mfma_f32_16x16x32_bf16 v[28:31], v[64:67], v[200:203], v[28:31]
	v_mfma_f32_16x16x32_bf16 v[24:27], v[72:75], v[200:203], v[24:27]
	v_mfma_f32_16x16x32_bf16 v[12:15], v[64:67], v[210:213], v[12:15]
	v_mfma_f32_16x16x32_bf16 v[8:11], v[72:75], v[210:213], v[8:11]
	v_mfma_f32_16x16x32_bf16 v[60:63], v[68:71], v[184:187], v[60:63]
	v_mfma_f32_16x16x32_bf16 v[56:59], v[76:79], v[184:187], v[56:59]
	v_mfma_f32_16x16x32_bf16 v[44:47], v[68:71], v[196:199], v[44:47]
	v_mfma_f32_16x16x32_bf16 v[40:43], v[76:79], v[196:199], v[40:43]
	v_mfma_f32_16x16x32_bf16 v[28:31], v[68:71], v[206:209], v[28:31]
	v_mfma_f32_16x16x32_bf16 v[24:27], v[76:79], v[206:209], v[24:27]
	v_mfma_f32_16x16x32_bf16 v[12:15], v[68:71], v[214:217], v[12:15]
	v_mfma_f32_16x16x32_bf16 v[8:11], v[76:79], v[214:217], v[8:11]
	s_setprio 0
	s_setprio 1
	v_mfma_f32_16x16x32_bf16 v[52:55], v[80:83], v[174:177], v[52:55]
	v_mfma_f32_16x16x32_bf16 v[48:51], v[88:91], v[174:177], v[48:51]
	v_mfma_f32_16x16x32_bf16 v[36:39], v[80:83], v[192:195], v[36:39]
	v_mfma_f32_16x16x32_bf16 v[32:35], v[88:91], v[192:195], v[32:35]
	v_mfma_f32_16x16x32_bf16 v[20:23], v[80:83], v[200:203], v[20:23]
	v_mfma_f32_16x16x32_bf16 v[16:19], v[88:91], v[200:203], v[16:19]
	v_mfma_f32_16x16x32_bf16 v[4:7], v[80:83], v[210:213], v[4:7]
	v_mfma_f32_16x16x32_bf16 v[0:3], v[88:91], v[210:213], v[0:3]
	v_mfma_f32_16x16x32_bf16 v[52:55], v[84:87], v[184:187], v[52:55]
	v_mfma_f32_16x16x32_bf16 v[48:51], v[92:95], v[184:187], v[48:51]
	v_mfma_f32_16x16x32_bf16 v[36:39], v[84:87], v[196:199], v[36:39]
	v_mfma_f32_16x16x32_bf16 v[32:35], v[92:95], v[196:199], v[32:35]
	v_mfma_f32_16x16x32_bf16 v[20:23], v[84:87], v[206:209], v[20:23]
	v_mfma_f32_16x16x32_bf16 v[16:19], v[92:95], v[206:209], v[16:19]
	v_mfma_f32_16x16x32_bf16 v[4:7], v[84:87], v[214:217], v[4:7]
	v_mfma_f32_16x16x32_bf16 v[0:3], v[92:95], v[214:217], v[0:3]
	s_setprio 0
	s_add_i32 s65, s65, 2
	s_add_u32 s40, s40, 0x100
	s_addc_u32 s41, s41, 0
	s_add_u32 s63, s63, 0x100
	s_addc_u32 s64, s64, 0
	s_cmp_gt_u32 s65, 13
	s_barrier
	s_cbranch_scc0 .LBB0_1175
	s_and_b64 vcc, exec, s[22:23]
	s_cbranch_vccz .LBB0_1178
	s_barrier

; #define PG8_STAGE(bufoff, gbase, voff) do { _Pragma("unroll") for (int _i = 0; _i < 2; ++_i) \
;         __builtin_amdgcn_global_load_lds((const unsigned*)((const char*)(gbase) + (voff)[_i]), (PG8_LAS unsigned*)(lds + (bufoff) + ldsw + _i * 8192), 16, 0, 0); } while (0)
; #define PG8_LDA(dst, b, h) do { _Pragma("unroll") for (int m = 0; m < 4; ++m) _Pragma("unroll") for (int k = 0; k < 2; ++k) dst[m][k] = *(const PG8_LAS bf16x8*)(lds + PG8_SA(b, h) + aoff + m * 2048 + k * 1024); } while (0)
; #define PG8_LDB(dst, b, h) do { _Pragma("unroll") for (int n = 0; n < 2; ++n) _Pragma("unroll") for (int k = 0; k < 2; ++k) dst[n][k] = *(const PG8_LAS bf16x8*)(lds + PG8_SB(b, h) + boff + n * 2048 + k * 1024); } while (0)
; #define PG8_MMA(ai, bj, At, Bt) do { __builtin_amdgcn_s_setprio(1); _Pragma("unroll") for (int m = 0; m < 4; ++m) _Pragma("unroll") for (int n = 0; n < 2; ++n) _Pragma("unroll") for (int k = 0; k < 2; ++k) \
;         acc[ai][bj][m][n] = __builtin_amdgcn_mfma_f32_16x16x32_bf16(Bt[n][k], At[m][k], acc[ai][bj][m][n], 0, 0, 0); __builtin_amdgcn_s_setprio(0); } while (0)
; #define PG8_WAIT_V(n) asm volatile("s_waitcnt vmcnt(" #n ")" ::: "memory")
; #define PG8_WAIT_L(n) asm volatile("s_waitcnt lgkmcnt(" #n ")" ::: "memory")
; #define PG8_BAR __builtin_amdgcn_s_barrier()
; #define PG8_SCHED __builtin_amdgcn_sched_barrier(0)
; template <class Epi, class Sched, bool ALIGN_EPI = false, bool SP2 = false>
; __device__ __forceinline__ void gemm_phase(PG8_LAS unsigned char* lds, const Gemm g, const Sched S, const Epi E) {
;     ...
;         for (int t = 0; t < nt; t += 2) {
;             const bool last = (t == nt - 2);
;             const char* a1 = cA + (size_t)(t + 1) * kstepA;
;             const char* a2 = last ? nA : cA + (size_t)(t + 2) * kstepA; const char* b2 = last ? nB : cB + (size_t)(t + 2) * kstep;
;             const char* a3 = a2 + kstepA; const char* b3 = b2 + kstep;
;             if (last && has_next) S.a_ready(nxt);
;             if constexpr (SP2) {
;             PG8_LDB(B0, 0, 0); PG8_LDB(B1, 0, 1); PG8_SCHED; PG8_LDA(At, 0, 0); PG8_STAGE(PG8_SA(1, 1), a1 + hstepA, voffA);
;             PG8_WAIT_V(8); PG8_WAIT_L(0); PG8_BAR; PG8_MMA(0, 0, At, B0); PG8_MMA(0, 1, At, B1); PG8_BAR; PG8_SCHED;
;             PG8_LDA(At, 0, 1); PG8_STAGE(PG8_SB(0, 0), b2, voffB); PG8_STAGE(PG8_SB(0, 1), b2 + hstep, voffB); PG8_STAGE(PG8_SA(0, 0), a2, voffA);
.LBB0_1324:
	ds_read_b128 v[152:155], v149
	ds_read_b128 v[156:159], v149 offset:1024
	ds_read_b128 v[162:165], v149 offset:2048
	ds_read_b128 v[166:169], v149 offset:3072
	ds_read_b128 v[170:173], v150
	ds_read_b128 v[174:177], v150 offset:1024
	ds_read_b128 v[178:181], v150 offset:2048
	ds_read_b128 v[182:185], v150 offset:3072
	s_add_u32 s40, s38, 0xfffc0080
	s_addc_u32 s41, s39, -1
	s_cmp_eq_u32 s75, 12
	s_cselect_b32 s43, s29, s41
	s_cselect_b32 s42, s67, s40
	s_cselect_b32 s41, s27, s74
	s_cselect_b32 s40, s68, s69
	v_lshl_add_u64 v[144:145], s[38:39], 0, v[136:137]
	s_add_i32 m0, s15, 0xc000
	ds_read_b128 v[186:189], v151
	ds_read_b128 v[190:193], v151 offset:1024
	ds_read_b128 v[194:197], v151 offset:2048
	ds_read_b128 v[198:201], v151 offset:3072
	ds_read_b128 v[206:209], v151 offset:4096
	ds_read_b128 v[210:213], v151 offset:5120
	ds_read_b128 v[214:217], v151 offset:6144
	ds_read_b128 v[218:221], v151 offset:7168
	global_load_lds_dwordx4 v[144:145], off
	v_lshl_add_u64 v[144:145], s[38:39], 0, v[138:139]
	s_add_i32 m0, s15, 0xe000
	s_nop 0
	global_load_lds_dwordx4 v[144:145], off
	s_waitcnt vmcnt(8)
	s_waitcnt lgkmcnt(0)
	s_barrier
	s_setprio 1
	s_waitcnt lgkmcnt(0)
	v_mfma_f32_16x16x32_bf16 v[124:127], v[152:155], v[186:189], v[124:127]
	v_mfma_f32_16x16x32_bf16 v[120:123], v[162:165], v[186:189], v[120:123]
	v_mfma_f32_16x16x32_bf16 v[108:111], v[152:155], v[194:197], v[108:111]
	v_mfma_f32_16x16x32_bf16 v[104:107], v[162:165], v[194:197], v[104:107]
	v_mfma_f32_16x16x32_bf16 v[92:95], v[152:155], v[206:209], v[92:95]
	v_mfma_f32_16x16x32_bf16 v[88:91], v[162:165], v[206:209], v[88:91]
	v_mfma_f32_16x16x32_bf16 v[76:79], v[152:155], v[214:217], v[76:79]
	v_mfma_f32_16x16x32_bf16 v[72:75], v[162:165], v[214:217], v[72:75]
	v_mfma_f32_16x16x32_bf16 v[124:127], v[156:159], v[190:193], v[124:127]
	v_mfma_f32_16x16x32_bf16 v[120:123], v[166:169], v[190:193], v[120:123]
	v_mfma_f32_16x16x32_bf16 v[108:111], v[156:159], v[198:201], v[108:111]
	v_mfma_f32_16x16x32_bf16 v[104:107], v[166:169], v[198:201], v[104:107]
	v_mfma_f32_16x16x32_bf16 v[92:95], v[156:159], v[210:213], v[92:95]
	v_mfma_f32_16x16x32_bf16 v[88:91], v[166:169], v[210:213], v[88:91]
	v_mfma_f32_16x16x32_bf16 v[76:79], v[156:159], v[218:221], v[76:79]
	v_mfma_f32_16x16x32_bf16 v[72:75], v[166:169], v[218:221], v[72:75]
	s_setprio 0
	s_setprio 1
	v_mfma_f32_16x16x32_bf16 v[116:119], v[170:173], v[186:189], v[116:119]
	v_mfma_f32_16x16x32_bf16 v[112:115], v[178:181], v[186:189], v[112:115]
	v_mfma_f32_16x16x32_bf16 v[100:103], v[170:173], v[194:197], v[100:103]
	v_mfma_f32_16x16x32_bf16 v[96:99], v[178:181], v[194:197], v[96:99]
	v_mfma_f32_16x16x32_bf16 v[84:87], v[170:173], v[206:209], v[84:87]
	v_mfma_f32_16x16x32_bf16 v[80:83], v[178:181], v[206:209], v[80:83]
	v_mfma_f32_16x16x32_bf16 v[68:71], v[170:173], v[214:217], v[68:71]
	v_mfma_f32_16x16x32_bf16 v[64:67], v[178:181], v[214:217], v[64:67]
	v_mfma_f32_16x16x32_bf16 v[116:119], v[174:177], v[190:193], v[116:119]
	v_mfma_f32_16x16x32_bf16 v[112:115], v[182:185], v[190:193], v[112:115]
	v_mfma_f32_16x16x32_bf16 v[100:103], v[174:177], v[198:201], v[100:103]
	v_mfma_f32_16x16x32_bf16 v[96:99], v[182:185], v[198:201], v[96:99]
	v_mfma_f32_16x16x32_bf16 v[84:87], v[174:177], v[210:213], v[84:87]
	v_mfma_f32_16x16x32_bf16 v[80:83], v[182:185], v[210:213], v[80:83]
	v_mfma_f32_16x16x32_bf16 v[68:71], v[174:177], v[218:221], v[68:71]
	v_mfma_f32_16x16x32_bf16 v[64:67], v[182:185], v[218:221], v[64:67]
	s_setprio 0
	s_barrier
	s_add_i32 s76, s57, s4
	v_lshl_add_u64 v[144:145], s[40:41], 0, v[132:133]
	s_mov_b32 m0, s76
	ds_read_b128 v[186:189], v151 offset:16384
	ds_read_b128 v[190:193], v151 offset:17408
	ds_read_b128 v[194:197], v151 offset:18432
	ds_read_b128 v[198:201], v151 offset:19456
	ds_read_b128 v[206:209], v151 offset:20480
	ds_read_b128 v[210:213], v151 offset:21504
	ds_read_b128 v[214:217], v151 offset:22528
	ds_read_b128 v[218:221], v151 offset:23552
	global_load_lds_dwordx4 v[144:145], off
	s_add_i32 m0, s76, 0x2000
	s_add_u32 s76, s40, 0x40000
	v_lshl_add_u64 v[202:203], s[40:41], 0, v[128:129]
	s_addc_u32 s77, s41, 0
	s_add_i32 s78, s60, s4
	global_load_lds_dwordx4 v[202:203], off
	v_lshl_add_u64 v[222:223], s[76:77], 0, v[132:133]
	s_mov_b32 m0, s78
	v_lshl_add_u64 v[224:225], s[42:43], 0, v[130:131]
	global_load_lds_dwordx4 v[222:223], off
	v_lshl_add_u64 v[222:223], s[76:77], 0, v[128:129]
	s_add_i32 m0, s78, 0x2000
	s_nop 0
	global_load_lds_dwordx4 v[222:223], off
	v_lshl_add_u64 v[222:223], s[42:43], 0, v[134:135]
	s_mov_b32 m0, s15
	s_nop 0
	global_load_lds_dwordx4 v[222:223], off
	s_mov_b32 m0, s33
	s_nop 0
	global_load_lds_dwordx4 v[224:225], off
	s_waitcnt vmcnt(8)
	s_waitcnt lgkmcnt(0)
	s_barrier
; #define PG8_STAGE(bufoff, gbase, voff) do { _Pragma("unroll") for (int _i = 0; _i < 2; ++_i) \
;         __builtin_amdgcn_global_load_lds((const unsigned*)((const char*)(gbase) + (voff)[_i]), (PG8_LAS unsigned*)(lds + (bufoff) + ldsw + _i * 8192), 16, 0, 0); } while (0)
; #define PG8_LDA(dst, b, h) do { _Pragma("unroll") for (int m = 0; m < 4; ++m) _Pragma("unroll") for (int k = 0; k < 2; ++k) dst[m][k] = *(const PG8_LAS bf16x8*)(lds + PG8_SA(b, h) + aoff + m * 2048 + k * 1024); } while (0)
; #define PG8_LDB(dst, b, h) do { _Pragma("unroll") for (int n = 0; n < 2; ++n) _Pragma("unroll") for (int k = 0; k < 2; ++k) dst[n][k] = *(const PG8_LAS bf16x8*)(lds + PG8_SB(b, h) + boff + n * 2048 + k * 1024); } while (0)
; #define PG8_MMA(ai, bj, At, Bt) do { __builtin_amdgcn_s_setprio(1); _Pragma("unroll") for (int m = 0; m < 4; ++m) _Pragma("unroll") for (int n = 0; n < 2; ++n) _Pragma("unroll") for (int k = 0; k < 2; ++k) \
;         acc[ai][bj][m][n] = __builtin_amdgcn_mfma_f32_16x16x32_bf16(Bt[n][k], At[m][k], acc[ai][bj][m][n], 0, 0, 0); __builtin_amdgcn_s_setprio(0); } while (0)
; #define PG8_WAIT_V(n) asm volatile("s_waitcnt vmcnt(" #n ")" ::: "memory")
; #define PG8_WAIT_L(n) asm volatile("s_waitcnt lgkmcnt(" #n ")" ::: "memory")
; #define PG8_BAR __builtin_amdgcn_s_barrier()
; #define PG8_SCHED __builtin_amdgcn_sched_barrier(0)
; template <class Epi, class Sched, bool ALIGN_EPI = false, bool SP2 = false>
; __device__ __forceinline__ void gemm_phase(PG8_LAS unsigned char* lds, const Gemm g, const Sched S, const Epi E) {
;     ...
;             PG8_WAIT_V(8); PG8_WAIT_L(0); PG8_BAR; PG8_MMA(1, 0, At, B0); PG8_MMA(1, 1, At, B1); PG8_BAR; PG8_SCHED;
;             PG8_LDB(B0, 1, 0); PG8_LDB(B1, 1, 1); PG8_SCHED; PG8_LDA(At, 1, 0); PG8_STAGE(PG8_SA(0, 1), a2 + hstepA, voffA);
;             PG8_WAIT_V(8); PG8_WAIT_L(0); PG8_BAR; PG8_MMA(0, 0, At, B0); PG8_MMA(0, 1, At, B1); PG8_BAR; PG8_SCHED;
	s_setprio 1
	s_waitcnt lgkmcnt(0)
	v_mfma_f32_16x16x32_bf16 v[60:63], v[152:155], v[186:189], v[60:63]
	v_mfma_f32_16x16x32_bf16 v[56:59], v[162:165], v[186:189], v[56:59]
	v_mfma_f32_16x16x32_bf16 v[44:47], v[152:155], v[194:197], v[44:47]
	v_mfma_f32_16x16x32_bf16 v[40:43], v[162:165], v[194:197], v[40:43]
	v_mfma_f32_16x16x32_bf16 v[28:31], v[152:155], v[206:209], v[28:31]
	v_mfma_f32_16x16x32_bf16 v[24:27], v[162:165], v[206:209], v[24:27]
	v_mfma_f32_16x16x32_bf16 v[12:15], v[152:155], v[214:217], v[12:15]
	v_mfma_f32_16x16x32_bf16 v[8:11], v[162:165], v[214:217], v[8:11]
	v_mfma_f32_16x16x32_bf16 v[60:63], v[156:159], v[190:193], v[60:63]
	v_mfma_f32_16x16x32_bf16 v[56:59], v[166:169], v[190:193], v[56:59]
	v_mfma_f32_16x16x32_bf16 v[44:47], v[156:159], v[198:201], v[44:47]
	v_mfma_f32_16x16x32_bf16 v[40:43], v[166:169], v[198:201], v[40:43]
	v_mfma_f32_16x16x32_bf16 v[28:31], v[156:159], v[210:213], v[28:31]
	v_mfma_f32_16x16x32_bf16 v[24:27], v[166:169], v[210:213], v[24:27]
	v_mfma_f32_16x16x32_bf16 v[12:15], v[156:159], v[218:221], v[12:15]
	v_mfma_f32_16x16x32_bf16 v[8:11], v[166:169], v[218:221], v[8:11]
	s_setprio 0
	s_setprio 1
	v_mfma_f32_16x16x32_bf16 v[52:55], v[170:173], v[186:189], v[52:55]
	v_mfma_f32_16x16x32_bf16 v[48:51], v[178:181], v[186:189], v[48:51]
	v_mfma_f32_16x16x32_bf16 v[36:39], v[170:173], v[194:197], v[36:39]
	v_mfma_f32_16x16x32_bf16 v[32:35], v[178:181], v[194:197], v[32:35]
	v_mfma_f32_16x16x32_bf16 v[20:23], v[170:173], v[206:209], v[20:23]
	v_mfma_f32_16x16x32_bf16 v[16:19], v[178:181], v[206:209], v[16:19]
	v_mfma_f32_16x16x32_bf16 v[4:7], v[170:173], v[214:217], v[4:7]
	v_mfma_f32_16x16x32_bf16 v[0:3], v[178:181], v[214:217], v[0:3]
	v_mfma_f32_16x16x32_bf16 v[52:55], v[174:177], v[190:193], v[52:55]
	v_mfma_f32_16x16x32_bf16 v[48:51], v[182:185], v[190:193], v[48:51]
	v_mfma_f32_16x16x32_bf16 v[36:39], v[174:177], v[198:201], v[36:39]
	v_mfma_f32_16x16x32_bf16 v[32:35], v[182:185], v[198:201], v[32:35]
	v_mfma_f32_16x16x32_bf16 v[20:23], v[174:177], v[210:213], v[20:23]
	v_mfma_f32_16x16x32_bf16 v[16:19], v[182:185], v[210:213], v[16:19]
	v_mfma_f32_16x16x32_bf16 v[4:7], v[174:177], v[218:221], v[4:7]
	v_mfma_f32_16x16x32_bf16 v[0:3], v[182:185], v[218:221], v[0:3]
	s_setprio 0
	s_barrier
	s_add_i32 s76, 0, 0x18000
	v_add_u32_e32 v161, s76, v148
	s_add_i32 s77, 0, 0x1c000
	ds_read_b128 v[152:155], v161
	ds_read_b128 v[156:159], v161 offset:1024
	ds_read_b128 v[162:165], v161 offset:2048
	ds_read_b128 v[166:169], v161 offset:3072
	v_add_u32_e32 v161, s77, v148
	ds_read_b128 v[170:173], v161
	ds_read_b128 v[174:177], v161 offset:1024
	ds_read_b128 v[178:181], v161 offset:2048
	ds_read_b128 v[182:185], v161 offset:3072
	s_add_u32 s42, s42, 0x40000
	s_addc_u32 s43, s43, 0
	s_mov_b32 m0, s37
	v_lshl_add_u64 v[226:227], s[42:43], 0, v[134:135]
	ds_read_b128 v[186:189], v151 offset:32768
	ds_read_b128 v[190:193], v151 offset:33792
	ds_read_b128 v[194:197], v151 offset:34816
	ds_read_b128 v[198:201], v151 offset:35840
	ds_read_b128 v[206:209], v151 offset:36864
	ds_read_b128 v[210:213], v151 offset:37888
	ds_read_b128 v[214:217], v151 offset:38912
	ds_read_b128 v[218:221], v151 offset:39936
	global_load_lds_dwordx4 v[226:227], off
	v_lshl_add_u64 v[226:227], s[42:43], 0, v[130:131]
	s_mov_b32 m0, s44
	s_nop 0
	global_load_lds_dwordx4 v[226:227], off
	s_waitcnt vmcnt(8)
	s_waitcnt lgkmcnt(0)
	s_barrier
	s_setprio 1
	s_waitcnt lgkmcnt(0)
	v_mfma_f32_16x16x32_bf16 v[124:127], v[152:155], v[186:189], v[124:127]
	v_mfma_f32_16x16x32_bf16 v[120:123], v[162:165], v[186:189], v[120:123]
	v_mfma_f32_16x16x32_bf16 v[108:111], v[152:155], v[194:197], v[108:111]
	v_mfma_f32_16x16x32_bf16 v[104:107], v[162:165], v[194:197], v[104:107]
	v_mfma_f32_16x16x32_bf16 v[92:95], v[152:155], v[206:209], v[92:95]
	v_mfma_f32_16x16x32_bf16 v[88:91], v[162:165], v[206:209], v[88:91]
	v_mfma_f32_16x16x32_bf16 v[76:79], v[152:155], v[214:217], v[76:79]
	v_mfma_f32_16x16x32_bf16 v[72:75], v[162:165], v[214:217], v[72:75]
	v_mfma_f32_16x16x32_bf16 v[124:127], v[156:159], v[190:193], v[124:127]
	v_mfma_f32_16x16x32_bf16 v[120:123], v[166:169], v[190:193], v[120:123]
	v_mfma_f32_16x16x32_bf16 v[108:111], v[156:159], v[198:201], v[108:111]
	v_mfma_f32_16x16x32_bf16 v[104:107], v[166:169], v[198:201], v[104:107]
	v_mfma_f32_16x16x32_bf16 v[92:95], v[156:159], v[210:213], v[92:95]
	v_mfma_f32_16x16x32_bf16 v[88:91], v[166:169], v[210:213], v[88:91]
	v_mfma_f32_16x16x32_bf16 v[76:79], v[156:159], v[218:221], v[76:79]
	v_mfma_f32_16x16x32_bf16 v[72:75], v[166:169], v[218:221], v[72:75]
	s_setprio 0
	s_setprio 1
	v_mfma_f32_16x16x32_bf16 v[116:119], v[170:173], v[186:189], v[116:119]
	v_mfma_f32_16x16x32_bf16 v[112:115], v[178:181], v[186:189], v[112:115]
	v_mfma_f32_16x16x32_bf16 v[100:103], v[170:173], v[194:197], v[100:103]
	v_mfma_f32_16x16x32_bf16 v[96:99], v[178:181], v[194:197], v[96:99]
	v_mfma_f32_16x16x32_bf16 v[84:87], v[170:173], v[206:209], v[84:87]
	v_mfma_f32_16x16x32_bf16 v[80:83], v[178:181], v[206:209], v[80:83]
	v_mfma_f32_16x16x32_bf16 v[68:71], v[170:173], v[214:217], v[68:71]
	v_mfma_f32_16x16x32_bf16 v[64:67], v[178:181], v[214:217], v[64:67]
	v_mfma_f32_16x16x32_bf16 v[116:119], v[174:177], v[190:193], v[116:119]
	v_mfma_f32_16x16x32_bf16 v[112:115], v[182:185], v[190:193], v[112:115]
	v_mfma_f32_16x16x32_bf16 v[100:103], v[174:177], v[198:201], v[100:103]
	v_mfma_f32_16x16x32_bf16 v[96:99], v[182:185], v[198:201], v[96:99]
	v_mfma_f32_16x16x32_bf16 v[84:87], v[174:177], v[210:213], v[84:87]
	v_mfma_f32_16x16x32_bf16 v[80:83], v[182:185], v[210:213], v[80:83]
	v_mfma_f32_16x16x32_bf16 v[68:71], v[174:177], v[218:221], v[68:71]
	v_mfma_f32_16x16x32_bf16 v[64:67], v[182:185], v[218:221], v[64:67]
	s_setprio 0
	s_barrier
; #define PG8_STAGE(bufoff, gbase, voff) do { _Pragma("unroll") for (int _i = 0; _i < 2; ++_i) \
;         __builtin_amdgcn_global_load_lds((const unsigned*)((const char*)(gbase) + (voff)[_i]), (PG8_LAS unsigned*)(lds + (bufoff) + ldsw + _i * 8192), 16, 0, 0); } while (0)
; #define PG8_LDA(dst, b, h) do { _Pragma("unroll") for (int m = 0; m < 4; ++m) _Pragma("unroll") for (int k = 0; k < 2; ++k) dst[m][k] = *(const PG8_LAS bf16x8*)(lds + PG8_SA(b, h) + aoff + m * 2048 + k * 1024); } while (0)
; #define PG8_MMA(ai, bj, At, Bt) do { __builtin_amdgcn_s_setprio(1); _Pragma("unroll") for (int m = 0; m < 4; ++m) _Pragma("unroll") for (int n = 0; n < 2; ++n) _Pragma("unroll") for (int k = 0; k < 2; ++k) \
;         acc[ai][bj][m][n] = __builtin_amdgcn_mfma_f32_16x16x32_bf16(Bt[n][k], At[m][k], acc[ai][bj][m][n], 0, 0, 0); __builtin_amdgcn_s_setprio(0); } while (0)
; #define PG8_WAIT_V(n) asm volatile("s_waitcnt vmcnt(" #n ")" ::: "memory")
; #define PG8_WAIT_L(n) asm volatile("s_waitcnt lgkmcnt(" #n ")" ::: "memory")
; #define PG8_BAR __builtin_amdgcn_s_barrier()
; #define PG8_SCHED __builtin_amdgcn_sched_barrier(0)
; template <class Epi, class Sched, bool ALIGN_EPI = false, bool SP2 = false>
; __device__ __forceinline__ void gemm_phase(PG8_LAS unsigned char* lds, const Gemm g, const Sched S, const Epi E) {
;     ...
;         for (int t = 0; t < nt; t += 2) {
;     ...
;             PG8_LDA(At, 1, 1); PG8_STAGE(PG8_SB(1, 0), b3, voffB); PG8_STAGE(PG8_SB(1, 1), b3 + hstep, voffB); PG8_STAGE(PG8_SA(1, 0), a3, voffA);
;             PG8_WAIT_V(8); PG8_WAIT_L(0); PG8_BAR; PG8_MMA(1, 0, At, B0); PG8_MMA(1, 1, At, B1); PG8_BAR; PG8_SCHED;
	s_add_i32 s42, s76, s4
	v_lshl_add_u64 v[144:145], v[144:145], 0, s[8:9]
	s_mov_b32 m0, s42
	ds_read_b128 v[186:189], v151 offset:49152
	ds_read_b128 v[190:193], v151 offset:50176
	ds_read_b128 v[194:197], v151 offset:51200
	ds_read_b128 v[198:201], v151 offset:52224
	ds_read_b128 v[206:209], v151 offset:53248
	ds_read_b128 v[210:213], v151 offset:54272
	ds_read_b128 v[214:217], v151 offset:55296
	ds_read_b128 v[218:221], v151 offset:56320
	global_load_lds_dwordx4 v[144:145], off
	s_add_i32 m0, s42, 0x2000
	s_add_u32 s40, s40, 0x40080
	v_lshl_add_u64 v[144:145], v[202:203], 0, s[8:9]
	s_addc_u32 s41, s41, 0
	s_add_i32 s42, s77, s4
	global_load_lds_dwordx4 v[144:145], off
	v_lshl_add_u64 v[144:145], s[40:41], 0, v[132:133]
	s_mov_b32 m0, s42
	s_nop 0
	global_load_lds_dwordx4 v[144:145], off
	v_lshl_add_u64 v[144:145], s[40:41], 0, v[128:129]
	s_add_i32 m0, s42, 0x2000
	s_nop 0
	global_load_lds_dwordx4 v[144:145], off
	v_lshl_add_u64 v[144:145], v[222:223], 0, s[8:9]
	s_mov_b32 m0, s54
	s_nop 0
	global_load_lds_dwordx4 v[144:145], off
	v_lshl_add_u64 v[144:145], v[224:225], 0, s[8:9]
	s_mov_b32 m0, s55
	s_nop 0
	global_load_lds_dwordx4 v[144:145], off
	s_waitcnt vmcnt(8)
	s_waitcnt lgkmcnt(0)
	s_barrier
	s_setprio 1
	s_waitcnt lgkmcnt(0)
	v_mfma_f32_16x16x32_bf16 v[60:63], v[152:155], v[186:189], v[60:63]
	v_mfma_f32_16x16x32_bf16 v[56:59], v[162:165], v[186:189], v[56:59]
	v_mfma_f32_16x16x32_bf16 v[44:47], v[152:155], v[194:197], v[44:47]
	v_mfma_f32_16x16x32_bf16 v[40:43], v[162:165], v[194:197], v[40:43]
	v_mfma_f32_16x16x32_bf16 v[28:31], v[152:155], v[206:209], v[28:31]
	v_mfma_f32_16x16x32_bf16 v[24:27], v[162:165], v[206:209], v[24:27]
	v_mfma_f32_16x16x32_bf16 v[12:15], v[152:155], v[214:217], v[12:15]
	v_mfma_f32_16x16x32_bf16 v[8:11], v[162:165], v[214:217], v[8:11]
	v_mfma_f32_16x16x32_bf16 v[60:63], v[156:159], v[190:193], v[60:63]
	v_mfma_f32_16x16x32_bf16 v[56:59], v[166:169], v[190:193], v[56:59]
	v_mfma_f32_16x16x32_bf16 v[44:47], v[156:159], v[198:201], v[44:47]
	v_mfma_f32_16x16x32_bf16 v[40:43], v[166:169], v[198:201], v[40:43]
	v_mfma_f32_16x16x32_bf16 v[28:31], v[156:159], v[210:213], v[28:31]
	v_mfma_f32_16x16x32_bf16 v[24:27], v[166:169], v[210:213], v[24:27]
	v_mfma_f32_16x16x32_bf16 v[12:15], v[156:159], v[218:221], v[12:15]
	v_mfma_f32_16x16x32_bf16 v[8:11], v[166:169], v[218:221], v[8:11]
	s_setprio 0
	s_setprio 1
	v_mfma_f32_16x16x32_bf16 v[52:55], v[170:173], v[186:189], v[52:55]
	v_mfma_f32_16x16x32_bf16 v[48:51], v[178:181], v[186:189], v[48:51]
	v_mfma_f32_16x16x32_bf16 v[36:39], v[170:173], v[194:197], v[36:39]
	v_mfma_f32_16x16x32_bf16 v[32:35], v[178:181], v[194:197], v[32:35]
	v_mfma_f32_16x16x32_bf16 v[20:23], v[170:173], v[206:209], v[20:23]
	v_mfma_f32_16x16x32_bf16 v[16:19], v[178:181], v[206:209], v[16:19]
	v_mfma_f32_16x16x32_bf16 v[4:7], v[170:173], v[214:217], v[4:7]
	v_mfma_f32_16x16x32_bf16 v[0:3], v[178:181], v[214:217], v[0:3]
	v_mfma_f32_16x16x32_bf16 v[52:55], v[174:177], v[190:193], v[52:55]
	v_mfma_f32_16x16x32_bf16 v[48:51], v[182:185], v[190:193], v[48:51]
	v_mfma_f32_16x16x32_bf16 v[36:39], v[174:177], v[198:201], v[36:39]
	v_mfma_f32_16x16x32_bf16 v[32:35], v[182:185], v[198:201], v[32:35]
	v_mfma_f32_16x16x32_bf16 v[20:23], v[174:177], v[210:213], v[20:23]
	v_mfma_f32_16x16x32_bf16 v[16:19], v[182:185], v[210:213], v[16:19]
	v_mfma_f32_16x16x32_bf16 v[4:7], v[174:177], v[218:221], v[4:7]
	v_mfma_f32_16x16x32_bf16 v[0:3], v[182:185], v[218:221], v[0:3]
	s_setprio 0
	s_add_i32 s75, s75, 2
	s_add_u32 s38, s38, 0x100
	s_addc_u32 s39, s39, 0
	s_add_u32 s69, s69, 0x100
	s_addc_u32 s74, s74, 0
	s_cmp_gt_u32 s75, 13
	s_barrier
	s_cbranch_scc0 .LBB0_1324
	s_and_b64 vcc, exec, s[20:21]
	s_cbranch_vccz .LBB0_1327
	s_barrier

; #define PG8_STAGE(bufoff, gbase, voff) do { _Pragma("unroll") for (int _i = 0; _i < 2; ++_i) \
;         __builtin_amdgcn_global_load_lds((const unsigned*)((const char*)(gbase) + (voff)[_i]), (PG8_LAS unsigned*)(lds + (bufoff) + ldsw + _i * 8192), 16, 0, 0); } while (0)
; #define PG8_LDA(dst, b, h) do { _Pragma("unroll") for (int m = 0; m < 4; ++m) _Pragma("unroll") for (int k = 0; k < 2; ++k) dst[m][k] = *(const PG8_LAS bf16x8*)(lds + PG8_SA(b, h) + aoff + m * 2048 + k * 1024); } while (0)
; #define PG8_LDB(dst, b, h) do { _Pragma("unroll") for (int n = 0; n < 2; ++n) _Pragma("unroll") for (int k = 0; k < 2; ++k) dst[n][k] = *(const PG8_LAS bf16x8*)(lds + PG8_SB(b, h) + boff + n * 2048 + k * 1024); } while (0)
; #define PG8_MMA(ai, bj, At, Bt) do { __builtin_amdgcn_s_setprio(1); _Pragma("unroll") for (int m = 0; m < 4; ++m) _Pragma("unroll") for (int n = 0; n < 2; ++n) _Pragma("unroll") for (int k = 0; k < 2; ++k) \
;         acc[ai][bj][m][n] = __builtin_amdgcn_mfma_f32_16x16x32_bf16(Bt[n][k], At[m][k], acc[ai][bj][m][n], 0, 0, 0); __builtin_amdgcn_s_setprio(0); } while (0)
; #define PG8_WAIT_V(n) asm volatile("s_waitcnt vmcnt(" #n ")" ::: "memory")
; #define PG8_WAIT_L(n) asm volatile("s_waitcnt lgkmcnt(" #n ")" ::: "memory")
; #define PG8_BAR __builtin_amdgcn_s_barrier()
; #define PG8_SCHED __builtin_amdgcn_sched_barrier(0)
; template <class Epi, class Sched, bool ALIGN_EPI = false, bool SP2 = false>
; __device__ __forceinline__ void gemm_phase(PG8_LAS unsigned char* lds, const Gemm g, const Sched S, const Epi E) {
;     ...
;         for (int t = 0; t < nt; t += 2) {
;             const bool last = (t == nt - 2);
;             const char* a1 = cA + (size_t)(t + 1) * kstepA;
;             const char* a2 = last ? nA : cA + (size_t)(t + 2) * kstepA; const char* b2 = last ? nB : cB + (size_t)(t + 2) * kstep;
;             const char* a3 = a2 + kstepA; const char* b3 = b2 + kstep;
;             if (last && has_next) S.a_ready(nxt);
;             if constexpr (SP2) {
;             PG8_LDB(B0, 0, 0); PG8_LDB(B1, 0, 1); PG8_SCHED; PG8_LDA(At, 0, 0); PG8_STAGE(PG8_SA(1, 1), a1 + hstepA, voffA);
;             PG8_WAIT_V(8); PG8_WAIT_L(0); PG8_BAR; PG8_MMA(0, 0, At, B0); PG8_MMA(0, 1, At, B1); PG8_BAR; PG8_SCHED;
;             PG8_LDA(At, 0, 1); PG8_STAGE(PG8_SB(0, 0), b2, voffB); PG8_STAGE(PG8_SB(0, 1), b2 + hstep, voffB); PG8_STAGE(PG8_SA(0, 0), a2, voffA);
.LBB0_1403:
	ds_read_b128 v[64:67], v188
	ds_read_b128 v[68:71], v188 offset:1024
	ds_read_b128 v[72:75], v188 offset:2048
	ds_read_b128 v[76:79], v188 offset:3072
	ds_read_b128 v[80:83], v189
	ds_read_b128 v[84:87], v189 offset:1024
	ds_read_b128 v[88:91], v189 offset:2048
	ds_read_b128 v[92:95], v189 offset:3072
	s_add_u32 s68, s46, 0xfff00080
	s_addc_u32 s69, s47, -1
	s_cmp_eq_u32 s67, 60
	s_cselect_b32 s79, s1, s69
	s_cselect_b32 s78, s39, s68
	s_cselect_b32 s77, s37, s66
	s_cselect_b32 s76, s64, s65
	v_lshl_add_u64 v[180:181], s[46:47], 0, v[166:167]
	s_add_i32 m0, s15, 0xc000
	ds_read_b128 v[174:177], v190
	ds_read_b128 v[184:187], v190 offset:1024
	ds_read_b128 v[192:195], v190 offset:2048
	ds_read_b128 v[196:199], v190 offset:3072
	ds_read_b128 v[200:203], v190 offset:4096
	ds_read_b128 v[206:209], v190 offset:5120
	ds_read_b128 v[210:213], v190 offset:6144
	ds_read_b128 v[214:217], v190 offset:7168
	global_load_lds_dwordx4 v[180:181], off
	v_lshl_add_u64 v[180:181], s[46:47], 0, v[168:169]
	s_add_i32 m0, s15, 0xe000
	s_nop 0
	global_load_lds_dwordx4 v[180:181], off
	s_waitcnt vmcnt(8)
	s_waitcnt lgkmcnt(0)
	s_barrier
	s_setprio 1
	s_waitcnt lgkmcnt(0)
	v_mfma_f32_16x16x32_bf16 v[156:159], v[64:67], v[174:177], v[156:159]
	v_mfma_f32_16x16x32_bf16 v[152:155], v[72:75], v[174:177], v[152:155]
	v_mfma_f32_16x16x32_bf16 v[140:143], v[64:67], v[192:195], v[140:143]
	v_mfma_f32_16x16x32_bf16 v[136:139], v[72:75], v[192:195], v[136:139]
	v_mfma_f32_16x16x32_bf16 v[124:127], v[64:67], v[200:203], v[124:127]
	v_mfma_f32_16x16x32_bf16 v[120:123], v[72:75], v[200:203], v[120:123]
	v_mfma_f32_16x16x32_bf16 v[108:111], v[64:67], v[210:213], v[108:111]
	v_mfma_f32_16x16x32_bf16 v[104:107], v[72:75], v[210:213], v[104:107]
	v_mfma_f32_16x16x32_bf16 v[156:159], v[68:71], v[184:187], v[156:159]
	v_mfma_f32_16x16x32_bf16 v[152:155], v[76:79], v[184:187], v[152:155]
	v_mfma_f32_16x16x32_bf16 v[140:143], v[68:71], v[196:199], v[140:143]
	v_mfma_f32_16x16x32_bf16 v[136:139], v[76:79], v[196:199], v[136:139]
	v_mfma_f32_16x16x32_bf16 v[124:127], v[68:71], v[206:209], v[124:127]
	v_mfma_f32_16x16x32_bf16 v[120:123], v[76:79], v[206:209], v[120:123]
	v_mfma_f32_16x16x32_bf16 v[108:111], v[68:71], v[214:217], v[108:111]
	v_mfma_f32_16x16x32_bf16 v[104:107], v[76:79], v[214:217], v[104:107]
	s_setprio 0
	s_setprio 1
	v_mfma_f32_16x16x32_bf16 v[148:151], v[80:83], v[174:177], v[148:151]
	v_mfma_f32_16x16x32_bf16 v[144:147], v[88:91], v[174:177], v[144:147]
	v_mfma_f32_16x16x32_bf16 v[132:135], v[80:83], v[192:195], v[132:135]
	v_mfma_f32_16x16x32_bf16 v[128:131], v[88:91], v[192:195], v[128:131]
	v_mfma_f32_16x16x32_bf16 v[116:119], v[80:83], v[200:203], v[116:119]
	v_mfma_f32_16x16x32_bf16 v[112:115], v[88:91], v[200:203], v[112:115]
	v_mfma_f32_16x16x32_bf16 v[100:103], v[80:83], v[210:213], v[100:103]
	v_mfma_f32_16x16x32_bf16 v[96:99], v[88:91], v[210:213], v[96:99]
	v_mfma_f32_16x16x32_bf16 v[148:151], v[84:87], v[184:187], v[148:151]
	v_mfma_f32_16x16x32_bf16 v[144:147], v[92:95], v[184:187], v[144:147]
	v_mfma_f32_16x16x32_bf16 v[132:135], v[84:87], v[196:199], v[132:135]
	v_mfma_f32_16x16x32_bf16 v[128:131], v[92:95], v[196:199], v[128:131]
	v_mfma_f32_16x16x32_bf16 v[116:119], v[84:87], v[206:209], v[116:119]
	v_mfma_f32_16x16x32_bf16 v[112:115], v[92:95], v[206:209], v[112:115]
	v_mfma_f32_16x16x32_bf16 v[100:103], v[84:87], v[214:217], v[100:103]
	v_mfma_f32_16x16x32_bf16 v[96:99], v[92:95], v[214:217], v[96:99]
	s_setprio 0
	s_barrier
	s_add_i32 s68, s62, s14
	v_lshl_add_u64 v[180:181], s[76:77], 0, v[162:163]
	s_mov_b32 m0, s68
	ds_read_b128 v[174:177], v190 offset:16384
	ds_read_b128 v[184:187], v190 offset:17408
	ds_read_b128 v[192:195], v190 offset:18432
	ds_read_b128 v[196:199], v190 offset:19456
	ds_read_b128 v[200:203], v190 offset:20480
	ds_read_b128 v[206:209], v190 offset:21504
	ds_read_b128 v[210:213], v190 offset:22528
	ds_read_b128 v[214:217], v190 offset:23552
	global_load_lds_dwordx4 v[180:181], off
	s_add_i32 m0, s68, 0x2000
	s_add_u32 s68, s76, 0x100000
	v_lshl_add_u64 v[218:219], s[76:77], 0, v[164:165]
	s_addc_u32 s69, s77, 0
	s_add_i32 s74, s63, s14
	global_load_lds_dwordx4 v[218:219], off
	v_lshl_add_u64 v[220:221], s[68:69], 0, v[162:163]
	s_mov_b32 m0, s74
	v_lshl_add_u64 v[222:223], s[78:79], 0, v[164:165]
	global_load_lds_dwordx4 v[220:221], off
	v_lshl_add_u64 v[220:221], s[68:69], 0, v[164:165]
	s_add_i32 m0, s74, 0x2000
	s_nop 0
	global_load_lds_dwordx4 v[220:221], off
	v_lshl_add_u64 v[220:221], s[78:79], 0, v[162:163]
	s_mov_b32 m0, s15
	s_nop 0
	global_load_lds_dwordx4 v[220:221], off
	s_mov_b32 m0, s33
	s_nop 0
	global_load_lds_dwordx4 v[222:223], off
	s_waitcnt vmcnt(8)
	s_waitcnt lgkmcnt(0)
	s_barrier
; #define PG8_STAGE(bufoff, gbase, voff) do { _Pragma("unroll") for (int _i = 0; _i < 2; ++_i) \
;         __builtin_amdgcn_global_load_lds((const unsigned*)((const char*)(gbase) + (voff)[_i]), (PG8_LAS unsigned*)(lds + (bufoff) + ldsw + _i * 8192), 16, 0, 0); } while (0)
; #define PG8_LDA(dst, b, h) do { _Pragma("unroll") for (int m = 0; m < 4; ++m) _Pragma("unroll") for (int k = 0; k < 2; ++k) dst[m][k] = *(const PG8_LAS bf16x8*)(lds + PG8_SA(b, h) + aoff + m * 2048 + k * 1024); } while (0)
; #define PG8_LDB(dst, b, h) do { _Pragma("unroll") for (int n = 0; n < 2; ++n) _Pragma("unroll") for (int k = 0; k < 2; ++k) dst[n][k] = *(const PG8_LAS bf16x8*)(lds + PG8_SB(b, h) + boff + n * 2048 + k * 1024); } while (0)
; #define PG8_MMA(ai, bj, At, Bt) do { __builtin_amdgcn_s_setprio(1); _Pragma("unroll") for (int m = 0; m < 4; ++m) _Pragma("unroll") for (int n = 0; n < 2; ++n) _Pragma("unroll") for (int k = 0; k < 2; ++k) \
;         acc[ai][bj][m][n] = __builtin_amdgcn_mfma_f32_16x16x32_bf16(Bt[n][k], At[m][k], acc[ai][bj][m][n], 0, 0, 0); __builtin_amdgcn_s_setprio(0); } while (0)
; #define PG8_WAIT_V(n) asm volatile("s_waitcnt vmcnt(" #n ")" ::: "memory")
; #define PG8_WAIT_L(n) asm volatile("s_waitcnt lgkmcnt(" #n ")" ::: "memory")
; #define PG8_BAR __builtin_amdgcn_s_barrier()
; #define PG8_SCHED __builtin_amdgcn_sched_barrier(0)
; template <class Epi, class Sched, bool ALIGN_EPI = false, bool SP2 = false>
; __device__ __forceinline__ void gemm_phase(PG8_LAS unsigned char* lds, const Gemm g, const Sched S, const Epi E) {
;     ...
;             PG8_WAIT_V(8); PG8_WAIT_L(0); PG8_BAR; PG8_MMA(1, 0, At, B0); PG8_MMA(1, 1, At, B1); PG8_BAR; PG8_SCHED;
;             PG8_LDB(B0, 1, 0); PG8_LDB(B1, 1, 1); PG8_SCHED; PG8_LDA(At, 1, 0); PG8_STAGE(PG8_SA(0, 1), a2 + hstepA, voffA);
;             PG8_WAIT_V(8); PG8_WAIT_L(0); PG8_BAR; PG8_MMA(0, 0, At, B0); PG8_MMA(0, 1, At, B1); PG8_BAR; PG8_SCHED;
	s_setprio 1
	s_waitcnt lgkmcnt(0)
	v_mfma_f32_16x16x32_bf16 v[60:63], v[64:67], v[174:177], v[60:63]
	v_mfma_f32_16x16x32_bf16 v[56:59], v[72:75], v[174:177], v[56:59]
	v_mfma_f32_16x16x32_bf16 v[44:47], v[64:67], v[192:195], v[44:47]
	v_mfma_f32_16x16x32_bf16 v[40:43], v[72:75], v[192:195], v[40:43]
	v_mfma_f32_16x16x32_bf16 v[28:31], v[64:67], v[200:203], v[28:31]
	v_mfma_f32_16x16x32_bf16 v[24:27], v[72:75], v[200:203], v[24:27]
	v_mfma_f32_16x16x32_bf16 v[12:15], v[64:67], v[210:213], v[12:15]
	v_mfma_f32_16x16x32_bf16 v[8:11], v[72:75], v[210:213], v[8:11]
	v_mfma_f32_16x16x32_bf16 v[60:63], v[68:71], v[184:187], v[60:63]
	v_mfma_f32_16x16x32_bf16 v[56:59], v[76:79], v[184:187], v[56:59]
	v_mfma_f32_16x16x32_bf16 v[44:47], v[68:71], v[196:199], v[44:47]
	v_mfma_f32_16x16x32_bf16 v[40:43], v[76:79], v[196:199], v[40:43]
	v_mfma_f32_16x16x32_bf16 v[28:31], v[68:71], v[206:209], v[28:31]
	v_mfma_f32_16x16x32_bf16 v[24:27], v[76:79], v[206:209], v[24:27]
	v_mfma_f32_16x16x32_bf16 v[12:15], v[68:71], v[214:217], v[12:15]
	v_mfma_f32_16x16x32_bf16 v[8:11], v[76:79], v[214:217], v[8:11]
	s_setprio 0
	s_setprio 1
	v_mfma_f32_16x16x32_bf16 v[52:55], v[80:83], v[174:177], v[52:55]
	v_mfma_f32_16x16x32_bf16 v[48:51], v[88:91], v[174:177], v[48:51]
	v_mfma_f32_16x16x32_bf16 v[36:39], v[80:83], v[192:195], v[36:39]
	v_mfma_f32_16x16x32_bf16 v[32:35], v[88:91], v[192:195], v[32:35]
	v_mfma_f32_16x16x32_bf16 v[20:23], v[80:83], v[200:203], v[20:23]
	v_mfma_f32_16x16x32_bf16 v[16:19], v[88:91], v[200:203], v[16:19]
	v_mfma_f32_16x16x32_bf16 v[4:7], v[80:83], v[210:213], v[4:7]
	v_mfma_f32_16x16x32_bf16 v[0:3], v[88:91], v[210:213], v[0:3]
	v_mfma_f32_16x16x32_bf16 v[52:55], v[84:87], v[184:187], v[52:55]
	v_mfma_f32_16x16x32_bf16 v[48:51], v[92:95], v[184:187], v[48:51]
	v_mfma_f32_16x16x32_bf16 v[36:39], v[84:87], v[196:199], v[36:39]
	v_mfma_f32_16x16x32_bf16 v[32:35], v[92:95], v[196:199], v[32:35]
	v_mfma_f32_16x16x32_bf16 v[20:23], v[84:87], v[206:209], v[20:23]
	v_mfma_f32_16x16x32_bf16 v[16:19], v[92:95], v[206:209], v[16:19]
	v_mfma_f32_16x16x32_bf16 v[4:7], v[84:87], v[214:217], v[4:7]
	v_mfma_f32_16x16x32_bf16 v[0:3], v[92:95], v[214:217], v[0:3]
	s_setprio 0
	s_barrier
	s_add_i32 s74, 0, 0x18000
	s_add_i32 s75, 0, 0x1c000
	v_add_u32_e32 v76, s74, v183
	v_add_u32_e32 v92, s75, v183
	ds_read_b128 v[64:67], v76
	ds_read_b128 v[68:71], v76 offset:1024
	ds_read_b128 v[72:75], v76 offset:2048
	ds_read_b128 v[76:79], v76 offset:3072
	ds_read_b128 v[80:83], v92
	ds_read_b128 v[84:87], v92 offset:1024
	ds_read_b128 v[88:91], v92 offset:2048
	ds_read_b128 v[92:95], v92 offset:3072
	s_add_u32 s68, s78, 0x100000
	s_addc_u32 s69, s79, 0
	s_mov_b32 m0, s35
	v_lshl_add_u64 v[224:225], s[68:69], 0, v[162:163]
	ds_read_b128 v[174:177], v190 offset:32768
	ds_read_b128 v[184:187], v190 offset:33792
	ds_read_b128 v[192:195], v190 offset:34816
	ds_read_b128 v[196:199], v190 offset:35840
	ds_read_b128 v[200:203], v190 offset:36864
	ds_read_b128 v[206:209], v190 offset:37888
	ds_read_b128 v[210:213], v190 offset:38912
	ds_read_b128 v[214:217], v190 offset:39936
	global_load_lds_dwordx4 v[224:225], off
	v_lshl_add_u64 v[224:225], s[68:69], 0, v[164:165]
	s_mov_b32 m0, s45
	s_nop 0
	global_load_lds_dwordx4 v[224:225], off
	s_waitcnt vmcnt(8)
	s_waitcnt lgkmcnt(0)
	s_barrier
	s_setprio 1
	s_waitcnt lgkmcnt(0)
	v_mfma_f32_16x16x32_bf16 v[156:159], v[64:67], v[174:177], v[156:159]
	v_mfma_f32_16x16x32_bf16 v[152:155], v[72:75], v[174:177], v[152:155]
	v_mfma_f32_16x16x32_bf16 v[140:143], v[64:67], v[192:195], v[140:143]
	v_mfma_f32_16x16x32_bf16 v[136:139], v[72:75], v[192:195], v[136:139]
	v_mfma_f32_16x16x32_bf16 v[124:127], v[64:67], v[200:203], v[124:127]
	v_mfma_f32_16x16x32_bf16 v[120:123], v[72:75], v[200:203], v[120:123]
	v_mfma_f32_16x16x32_bf16 v[108:111], v[64:67], v[210:213], v[108:111]
	v_mfma_f32_16x16x32_bf16 v[104:107], v[72:75], v[210:213], v[104:107]
	v_mfma_f32_16x16x32_bf16 v[156:159], v[68:71], v[184:187], v[156:159]
	v_mfma_f32_16x16x32_bf16 v[152:155], v[76:79], v[184:187], v[152:155]
	v_mfma_f32_16x16x32_bf16 v[140:143], v[68:71], v[196:199], v[140:143]
	v_mfma_f32_16x16x32_bf16 v[136:139], v[76:79], v[196:199], v[136:139]
	v_mfma_f32_16x16x32_bf16 v[124:127], v[68:71], v[206:209], v[124:127]
	v_mfma_f32_16x16x32_bf16 v[120:123], v[76:79], v[206:209], v[120:123]
	v_mfma_f32_16x16x32_bf16 v[108:111], v[68:71], v[214:217], v[108:111]
	v_mfma_f32_16x16x32_bf16 v[104:107], v[76:79], v[214:217], v[104:107]
	s_setprio 0
	s_setprio 1
	v_mfma_f32_16x16x32_bf16 v[148:151], v[80:83], v[174:177], v[148:151]
	v_mfma_f32_16x16x32_bf16 v[144:147], v[88:91], v[174:177], v[144:147]
	v_mfma_f32_16x16x32_bf16 v[132:135], v[80:83], v[192:195], v[132:135]
	v_mfma_f32_16x16x32_bf16 v[128:131], v[88:91], v[192:195], v[128:131]
	v_mfma_f32_16x16x32_bf16 v[116:119], v[80:83], v[200:203], v[116:119]
	v_mfma_f32_16x16x32_bf16 v[112:115], v[88:91], v[200:203], v[112:115]
	v_mfma_f32_16x16x32_bf16 v[100:103], v[80:83], v[210:213], v[100:103]
	v_mfma_f32_16x16x32_bf16 v[96:99], v[88:91], v[210:213], v[96:99]
	v_mfma_f32_16x16x32_bf16 v[148:151], v[84:87], v[184:187], v[148:151]
	v_mfma_f32_16x16x32_bf16 v[144:147], v[92:95], v[184:187], v[144:147]
	v_mfma_f32_16x16x32_bf16 v[132:135], v[84:87], v[196:199], v[132:135]
	v_mfma_f32_16x16x32_bf16 v[128:131], v[92:95], v[196:199], v[128:131]
	v_mfma_f32_16x16x32_bf16 v[116:119], v[84:87], v[206:209], v[116:119]
	v_mfma_f32_16x16x32_bf16 v[112:115], v[92:95], v[206:209], v[112:115]
	v_mfma_f32_16x16x32_bf16 v[100:103], v[84:87], v[214:217], v[100:103]
	v_mfma_f32_16x16x32_bf16 v[96:99], v[92:95], v[214:217], v[96:99]
	s_setprio 0
	s_barrier
; #define PG8_STAGE(bufoff, gbase, voff) do { _Pragma("unroll") for (int _i = 0; _i < 2; ++_i) \
;         __builtin_amdgcn_global_load_lds((const unsigned*)((const char*)(gbase) + (voff)[_i]), (PG8_LAS unsigned*)(lds + (bufoff) + ldsw + _i * 8192), 16, 0, 0); } while (0)
; #define PG8_LDA(dst, b, h) do { _Pragma("unroll") for (int m = 0; m < 4; ++m) _Pragma("unroll") for (int k = 0; k < 2; ++k) dst[m][k] = *(const PG8_LAS bf16x8*)(lds + PG8_SA(b, h) + aoff + m * 2048 + k * 1024); } while (0)
; #define PG8_MMA(ai, bj, At, Bt) do { __builtin_amdgcn_s_setprio(1); _Pragma("unroll") for (int m = 0; m < 4; ++m) _Pragma("unroll") for (int n = 0; n < 2; ++n) _Pragma("unroll") for (int k = 0; k < 2; ++k) \
;         acc[ai][bj][m][n] = __builtin_amdgcn_mfma_f32_16x16x32_bf16(Bt[n][k], At[m][k], acc[ai][bj][m][n], 0, 0, 0); __builtin_amdgcn_s_setprio(0); } while (0)
; #define PG8_WAIT_V(n) asm volatile("s_waitcnt vmcnt(" #n ")" ::: "memory")
; #define PG8_WAIT_L(n) asm volatile("s_waitcnt lgkmcnt(" #n ")" ::: "memory")
; #define PG8_BAR __builtin_amdgcn_s_barrier()
; #define PG8_SCHED __builtin_amdgcn_sched_barrier(0)
; template <class Epi, class Sched, bool ALIGN_EPI = false, bool SP2 = false>
; __device__ __forceinline__ void gemm_phase(PG8_LAS unsigned char* lds, const Gemm g, const Sched S, const Epi E) {
;     ...
;         for (int t = 0; t < nt; t += 2) {
;     ...
;             PG8_LDA(At, 1, 1); PG8_STAGE(PG8_SB(1, 0), b3, voffB); PG8_STAGE(PG8_SB(1, 1), b3 + hstep, voffB); PG8_STAGE(PG8_SA(1, 0), a3, voffA);
;             PG8_WAIT_V(8); PG8_WAIT_L(0); PG8_BAR; PG8_MMA(1, 0, At, B0); PG8_MMA(1, 1, At, B1); PG8_BAR; PG8_SCHED;
	s_add_i32 s68, s74, s14
	v_lshl_add_u64 v[180:181], v[180:181], 0, s[26:27]
	s_mov_b32 m0, s68
	ds_read_b128 v[174:177], v190 offset:49152
	ds_read_b128 v[184:187], v190 offset:50176
	ds_read_b128 v[192:195], v190 offset:51200
	ds_read_b128 v[196:199], v190 offset:52224
	ds_read_b128 v[200:203], v190 offset:53248
	ds_read_b128 v[206:209], v190 offset:54272
	ds_read_b128 v[210:213], v190 offset:55296
	ds_read_b128 v[214:217], v190 offset:56320
	global_load_lds_dwordx4 v[180:181], off
	s_add_i32 m0, s68, 0x2000
	s_add_u32 s68, s76, 0x100080
	v_lshl_add_u64 v[180:181], v[218:219], 0, s[26:27]
	s_addc_u32 s69, s77, 0
	s_add_i32 s74, s75, s14
	global_load_lds_dwordx4 v[180:181], off
	v_lshl_add_u64 v[180:181], s[68:69], 0, v[162:163]
	s_mov_b32 m0, s74
	s_nop 0
	global_load_lds_dwordx4 v[180:181], off
	v_lshl_add_u64 v[180:181], s[68:69], 0, v[164:165]
	s_add_i32 m0, s74, 0x2000
	s_nop 0
	global_load_lds_dwordx4 v[180:181], off
	v_lshl_add_u64 v[180:181], v[220:221], 0, s[26:27]
	s_mov_b32 m0, s60
	s_nop 0
	global_load_lds_dwordx4 v[180:181], off
	v_lshl_add_u64 v[180:181], v[222:223], 0, s[26:27]
	s_mov_b32 m0, s61
	s_nop 0
	global_load_lds_dwordx4 v[180:181], off
	s_waitcnt vmcnt(8)
	s_waitcnt lgkmcnt(0)
	s_barrier
	s_setprio 1
	s_waitcnt lgkmcnt(0)
	v_mfma_f32_16x16x32_bf16 v[60:63], v[64:67], v[174:177], v[60:63]
	v_mfma_f32_16x16x32_bf16 v[56:59], v[72:75], v[174:177], v[56:59]
	v_mfma_f32_16x16x32_bf16 v[44:47], v[64:67], v[192:195], v[44:47]
	v_mfma_f32_16x16x32_bf16 v[40:43], v[72:75], v[192:195], v[40:43]
	v_mfma_f32_16x16x32_bf16 v[28:31], v[64:67], v[200:203], v[28:31]
	v_mfma_f32_16x16x32_bf16 v[24:27], v[72:75], v[200:203], v[24:27]
	v_mfma_f32_16x16x32_bf16 v[12:15], v[64:67], v[210:213], v[12:15]
	v_mfma_f32_16x16x32_bf16 v[8:11], v[72:75], v[210:213], v[8:11]
	v_mfma_f32_16x16x32_bf16 v[60:63], v[68:71], v[184:187], v[60:63]
	v_mfma_f32_16x16x32_bf16 v[56:59], v[76:79], v[184:187], v[56:59]
	v_mfma_f32_16x16x32_bf16 v[44:47], v[68:71], v[196:199], v[44:47]
	v_mfma_f32_16x16x32_bf16 v[40:43], v[76:79], v[196:199], v[40:43]
	v_mfma_f32_16x16x32_bf16 v[28:31], v[68:71], v[206:209], v[28:31]
	v_mfma_f32_16x16x32_bf16 v[24:27], v[76:79], v[206:209], v[24:27]
	v_mfma_f32_16x16x32_bf16 v[12:15], v[68:71], v[214:217], v[12:15]
	v_mfma_f32_16x16x32_bf16 v[8:11], v[76:79], v[214:217], v[8:11]
	s_setprio 0
	s_setprio 1
	v_mfma_f32_16x16x32_bf16 v[52:55], v[80:83], v[174:177], v[52:55]
	v_mfma_f32_16x16x32_bf16 v[48:51], v[88:91], v[174:177], v[48:51]
	v_mfma_f32_16x16x32_bf16 v[36:39], v[80:83], v[192:195], v[36:39]
	v_mfma_f32_16x16x32_bf16 v[32:35], v[88:91], v[192:195], v[32:35]
	v_mfma_f32_16x16x32_bf16 v[20:23], v[80:83], v[200:203], v[20:23]
	v_mfma_f32_16x16x32_bf16 v[16:19], v[88:91], v[200:203], v[16:19]
	v_mfma_f32_16x16x32_bf16 v[4:7], v[80:83], v[210:213], v[4:7]
	v_mfma_f32_16x16x32_bf16 v[0:3], v[88:91], v[210:213], v[0:3]
	v_mfma_f32_16x16x32_bf16 v[52:55], v[84:87], v[184:187], v[52:55]
	v_mfma_f32_16x16x32_bf16 v[48:51], v[92:95], v[184:187], v[48:51]
	v_mfma_f32_16x16x32_bf16 v[36:39], v[84:87], v[196:199], v[36:39]
	v_mfma_f32_16x16x32_bf16 v[32:35], v[92:95], v[196:199], v[32:35]
	v_mfma_f32_16x16x32_bf16 v[20:23], v[84:87], v[206:209], v[20:23]
	v_mfma_f32_16x16x32_bf16 v[16:19], v[92:95], v[206:209], v[16:19]
	v_mfma_f32_16x16x32_bf16 v[4:7], v[84:87], v[214:217], v[4:7]
	v_mfma_f32_16x16x32_bf16 v[0:3], v[92:95], v[214:217], v[0:3]
	s_setprio 0
	s_add_i32 s67, s67, 2
	s_add_u32 s46, s46, 0x100
	s_addc_u32 s47, s47, 0
	s_add_u32 s65, s65, 0x100
	s_addc_u32 s66, s66, 0
	s_cmp_gt_u32 s67, 61
	s_barrier
	s_cbranch_scc0 .LBB0_1403
	s_and_b64 vcc, exec, s[28:29]
	s_cbranch_vccz .LBB0_1406
	s_barrier

; #define PG8_STAGE(bufoff, gbase, voff) do { _Pragma("unroll") for (int _i = 0; _i < 2; ++_i) \
;         __builtin_amdgcn_global_load_lds((const unsigned*)((const char*)(gbase) + (voff)[_i]), (PG8_LAS unsigned*)(lds + (bufoff) + ldsw + _i * 8192), 16, 0, 0); } while (0)
; #define PG8_LDA(dst, b, h) do { _Pragma("unroll") for (int m = 0; m < 4; ++m) _Pragma("unroll") for (int k = 0; k < 2; ++k) dst[m][k] = *(const PG8_LAS bf16x8*)(lds + PG8_SA(b, h) + aoff + m * 2048 + k * 1024); } while (0)
; #define PG8_LDB(dst, b, h) do { _Pragma("unroll") for (int n = 0; n < 2; ++n) _Pragma("unroll") for (int k = 0; k < 2; ++k) dst[n][k] = *(const PG8_LAS bf16x8*)(lds + PG8_SB(b, h) + boff + n * 2048 + k * 1024); } while (0)
; #define PG8_MMA(ai, bj, At, Bt) do { __builtin_amdgcn_s_setprio(1); _Pragma("unroll") for (int m = 0; m < 4; ++m) _Pragma("unroll") for (int n = 0; n < 2; ++n) _Pragma("unroll") for (int k = 0; k < 2; ++k) \
;         acc[ai][bj][m][n] = __builtin_amdgcn_mfma_f32_16x16x32_bf16(Bt[n][k], At[m][k], acc[ai][bj][m][n], 0, 0, 0); __builtin_amdgcn_s_setprio(0); } while (0)
; #define PG8_WAIT_V(n) asm volatile("s_waitcnt vmcnt(" #n ")" ::: "memory")
; #define PG8_WAIT_L(n) asm volatile("s_waitcnt lgkmcnt(" #n ")" ::: "memory")
; #define PG8_BAR __builtin_amdgcn_s_barrier()
; #define PG8_SCHED __builtin_amdgcn_sched_barrier(0)
; template <class Epi, class Sched, bool ALIGN_EPI = false, bool SP2 = false>
; __device__ __forceinline__ void gemm_phase(PG8_LAS unsigned char* lds, const Gemm g, const Sched S, const Epi E) {
;     ...
;         for (int t = 0; t < nt; t += 2) {
;             const bool last = (t == nt - 2);
;             const char* a1 = cA + (size_t)(t + 1) * kstepA;
;             const char* a2 = last ? nA : cA + (size_t)(t + 2) * kstepA; const char* b2 = last ? nB : cB + (size_t)(t + 2) * kstep;
;             const char* a3 = a2 + kstepA; const char* b3 = b2 + kstep;
;             if (last && has_next) S.a_ready(nxt);
;             if constexpr (SP2) {
;             PG8_LDB(B0, 0, 0); PG8_LDB(B1, 0, 1); PG8_SCHED; PG8_LDA(At, 0, 0); PG8_STAGE(PG8_SA(1, 1), a1 + hstepA, voffA);
;             PG8_WAIT_V(8); PG8_WAIT_L(0); PG8_BAR; PG8_MMA(0, 0, At, B0); PG8_MMA(0, 1, At, B1); PG8_BAR; PG8_SCHED;
;             PG8_LDA(At, 0, 1); PG8_STAGE(PG8_SB(0, 0), b2, voffB); PG8_STAGE(PG8_SB(0, 1), b2 + hstep, voffB); PG8_STAGE(PG8_SA(0, 0), a2, voffA);
.LBB0_1556:
	ds_read_b128 v[152:155], v149
	ds_read_b128 v[156:159], v149 offset:1024
	ds_read_b128 v[162:165], v149 offset:2048
	ds_read_b128 v[166:169], v149 offset:3072
	ds_read_b128 v[170:173], v150
	ds_read_b128 v[174:177], v150 offset:1024
	ds_read_b128 v[178:181], v150 offset:2048
	ds_read_b128 v[182:185], v150 offset:3072
	s_add_u32 s44, s42, 0xfffc0080
	s_addc_u32 s45, s43, -1
	s_cmp_eq_u32 s77, 12
	s_cselect_b32 s47, s35, s45
	s_cselect_b32 s46, s73, s44
	s_cselect_b32 s45, s31, s76
	s_cselect_b32 s44, s74, s75
	v_lshl_add_u64 v[144:145], s[42:43], 0, v[136:137]
	s_add_i32 m0, s33, 0xc000
	ds_read_b128 v[186:189], v151
	ds_read_b128 v[190:193], v151 offset:1024
	ds_read_b128 v[194:197], v151 offset:2048
	ds_read_b128 v[198:201], v151 offset:3072
	ds_read_b128 v[206:209], v151 offset:4096
	ds_read_b128 v[210:213], v151 offset:5120
	ds_read_b128 v[214:217], v151 offset:6144
	ds_read_b128 v[218:221], v151 offset:7168
	global_load_lds_dwordx4 v[144:145], off
	v_lshl_add_u64 v[144:145], s[42:43], 0, v[138:139]
	s_add_i32 m0, s33, 0xe000
	s_nop 0
	global_load_lds_dwordx4 v[144:145], off
	s_waitcnt vmcnt(8)
	s_waitcnt lgkmcnt(0)
	s_barrier
	s_setprio 1
	s_waitcnt lgkmcnt(0)
	v_mfma_f32_16x16x32_bf16 v[124:127], v[152:155], v[186:189], v[124:127]
	v_mfma_f32_16x16x32_bf16 v[120:123], v[162:165], v[186:189], v[120:123]
	v_mfma_f32_16x16x32_bf16 v[112:115], v[152:155], v[194:197], v[112:115]
	v_mfma_f32_16x16x32_bf16 v[104:107], v[162:165], v[194:197], v[104:107]
	v_mfma_f32_16x16x32_bf16 v[96:99], v[152:155], v[206:209], v[96:99]
	v_mfma_f32_16x16x32_bf16 v[88:91], v[162:165], v[206:209], v[88:91]
	v_mfma_f32_16x16x32_bf16 v[80:83], v[152:155], v[214:217], v[80:83]
	v_mfma_f32_16x16x32_bf16 v[72:75], v[162:165], v[214:217], v[72:75]
	v_mfma_f32_16x16x32_bf16 v[124:127], v[156:159], v[190:193], v[124:127]
	v_mfma_f32_16x16x32_bf16 v[120:123], v[166:169], v[190:193], v[120:123]
	v_mfma_f32_16x16x32_bf16 v[112:115], v[156:159], v[198:201], v[112:115]
	v_mfma_f32_16x16x32_bf16 v[104:107], v[166:169], v[198:201], v[104:107]
	v_mfma_f32_16x16x32_bf16 v[96:99], v[156:159], v[210:213], v[96:99]
	v_mfma_f32_16x16x32_bf16 v[88:91], v[166:169], v[210:213], v[88:91]
	v_mfma_f32_16x16x32_bf16 v[80:83], v[156:159], v[218:221], v[80:83]
	v_mfma_f32_16x16x32_bf16 v[72:75], v[166:169], v[218:221], v[72:75]
	s_setprio 0
	s_setprio 1
	v_mfma_f32_16x16x32_bf16 v[116:119], v[170:173], v[186:189], v[116:119]
	v_mfma_f32_16x16x32_bf16 v[108:111], v[178:181], v[186:189], v[108:111]
	v_mfma_f32_16x16x32_bf16 v[100:103], v[170:173], v[194:197], v[100:103]
	v_mfma_f32_16x16x32_bf16 v[92:95], v[178:181], v[194:197], v[92:95]
	v_mfma_f32_16x16x32_bf16 v[84:87], v[170:173], v[206:209], v[84:87]
	v_mfma_f32_16x16x32_bf16 v[76:79], v[178:181], v[206:209], v[76:79]
	v_mfma_f32_16x16x32_bf16 v[68:71], v[170:173], v[214:217], v[68:71]
	v_mfma_f32_16x16x32_bf16 v[64:67], v[178:181], v[214:217], v[64:67]
	v_mfma_f32_16x16x32_bf16 v[116:119], v[174:177], v[190:193], v[116:119]
	v_mfma_f32_16x16x32_bf16 v[108:111], v[182:185], v[190:193], v[108:111]
	v_mfma_f32_16x16x32_bf16 v[100:103], v[174:177], v[198:201], v[100:103]
	v_mfma_f32_16x16x32_bf16 v[92:95], v[182:185], v[198:201], v[92:95]
	v_mfma_f32_16x16x32_bf16 v[84:87], v[174:177], v[210:213], v[84:87]
	v_mfma_f32_16x16x32_bf16 v[76:79], v[182:185], v[210:213], v[76:79]
	v_mfma_f32_16x16x32_bf16 v[68:71], v[174:177], v[218:221], v[68:71]
	v_mfma_f32_16x16x32_bf16 v[64:67], v[182:185], v[218:221], v[64:67]
	s_setprio 0
	s_barrier
	s_add_i32 s78, s64, s15
	v_lshl_add_u64 v[144:145], s[44:45], 0, v[130:131]
	s_mov_b32 m0, s78
	ds_read_b128 v[186:189], v151 offset:16384
	ds_read_b128 v[190:193], v151 offset:17408
	ds_read_b128 v[194:197], v151 offset:18432
	ds_read_b128 v[198:201], v151 offset:19456
	ds_read_b128 v[206:209], v151 offset:20480
	ds_read_b128 v[210:213], v151 offset:21504
	ds_read_b128 v[214:217], v151 offset:22528
	ds_read_b128 v[218:221], v151 offset:23552
	global_load_lds_dwordx4 v[144:145], off
	s_add_i32 m0, s78, 0x2000
	s_add_u32 s78, s44, 0x40000
	v_lshl_add_u64 v[202:203], s[44:45], 0, v[134:135]
	s_addc_u32 s79, s45, 0
	s_add_i32 s80, s65, s15
	global_load_lds_dwordx4 v[202:203], off
	v_lshl_add_u64 v[222:223], s[78:79], 0, v[130:131]
	s_mov_b32 m0, s80
	v_lshl_add_u64 v[224:225], s[46:47], 0, v[132:133]
	global_load_lds_dwordx4 v[222:223], off
	v_lshl_add_u64 v[222:223], s[78:79], 0, v[134:135]
	s_add_i32 m0, s80, 0x2000
	s_nop 0
	global_load_lds_dwordx4 v[222:223], off
	v_lshl_add_u64 v[222:223], s[46:47], 0, v[128:129]
	s_mov_b32 m0, s33
	s_nop 0
	global_load_lds_dwordx4 v[222:223], off
	s_mov_b32 m0, s41
	s_nop 0
	global_load_lds_dwordx4 v[224:225], off
	s_waitcnt vmcnt(8)
	s_waitcnt lgkmcnt(0)
	s_barrier
; #define PG8_STAGE(bufoff, gbase, voff) do { _Pragma("unroll") for (int _i = 0; _i < 2; ++_i) \
;         __builtin_amdgcn_global_load_lds((const unsigned*)((const char*)(gbase) + (voff)[_i]), (PG8_LAS unsigned*)(lds + (bufoff) + ldsw + _i * 8192), 16, 0, 0); } while (0)
; #define PG8_LDA(dst, b, h) do { _Pragma("unroll") for (int m = 0; m < 4; ++m) _Pragma("unroll") for (int k = 0; k < 2; ++k) dst[m][k] = *(const PG8_LAS bf16x8*)(lds + PG8_SA(b, h) + aoff + m * 2048 + k * 1024); } while (0)
; #define PG8_LDB(dst, b, h) do { _Pragma("unroll") for (int n = 0; n < 2; ++n) _Pragma("unroll") for (int k = 0; k < 2; ++k) dst[n][k] = *(const PG8_LAS bf16x8*)(lds + PG8_SB(b, h) + boff + n * 2048 + k * 1024); } while (0)
; #define PG8_MMA(ai, bj, At, Bt) do { __builtin_amdgcn_s_setprio(1); _Pragma("unroll") for (int m = 0; m < 4; ++m) _Pragma("unroll") for (int n = 0; n < 2; ++n) _Pragma("unroll") for (int k = 0; k < 2; ++k) \
;         acc[ai][bj][m][n] = __builtin_amdgcn_mfma_f32_16x16x32_bf16(Bt[n][k], At[m][k], acc[ai][bj][m][n], 0, 0, 0); __builtin_amdgcn_s_setprio(0); } while (0)
; #define PG8_WAIT_V(n) asm volatile("s_waitcnt vmcnt(" #n ")" ::: "memory")
; #define PG8_WAIT_L(n) asm volatile("s_waitcnt lgkmcnt(" #n ")" ::: "memory")
; #define PG8_BAR __builtin_amdgcn_s_barrier()
; #define PG8_SCHED __builtin_amdgcn_sched_barrier(0)
; template <class Epi, class Sched, bool ALIGN_EPI = false, bool SP2 = false>
; __device__ __forceinline__ void gemm_phase(PG8_LAS unsigned char* lds, const Gemm g, const Sched S, const Epi E) {
;     ...
;             PG8_WAIT_V(8); PG8_WAIT_L(0); PG8_BAR; PG8_MMA(1, 0, At, B0); PG8_MMA(1, 1, At, B1); PG8_BAR; PG8_SCHED;
;             PG8_LDB(B0, 1, 0); PG8_LDB(B1, 1, 1); PG8_SCHED; PG8_LDA(At, 1, 0); PG8_STAGE(PG8_SA(0, 1), a2 + hstepA, voffA);
;             PG8_WAIT_V(8); PG8_WAIT_L(0); PG8_BAR; PG8_MMA(0, 0, At, B0); PG8_MMA(0, 1, At, B1); PG8_BAR; PG8_SCHED;
	s_setprio 1
	s_waitcnt lgkmcnt(0)
	v_mfma_f32_16x16x32_bf16 v[60:63], v[152:155], v[186:189], v[60:63]
	v_mfma_f32_16x16x32_bf16 v[56:59], v[162:165], v[186:189], v[56:59]
	v_mfma_f32_16x16x32_bf16 v[48:51], v[152:155], v[194:197], v[48:51]
	v_mfma_f32_16x16x32_bf16 v[40:43], v[162:165], v[194:197], v[40:43]
	v_mfma_f32_16x16x32_bf16 v[32:35], v[152:155], v[206:209], v[32:35]
	v_mfma_f32_16x16x32_bf16 v[24:27], v[162:165], v[206:209], v[24:27]
	v_mfma_f32_16x16x32_bf16 v[16:19], v[152:155], v[214:217], v[16:19]
	v_mfma_f32_16x16x32_bf16 v[8:11], v[162:165], v[214:217], v[8:11]
	v_mfma_f32_16x16x32_bf16 v[60:63], v[156:159], v[190:193], v[60:63]
	v_mfma_f32_16x16x32_bf16 v[56:59], v[166:169], v[190:193], v[56:59]
	v_mfma_f32_16x16x32_bf16 v[48:51], v[156:159], v[198:201], v[48:51]
	v_mfma_f32_16x16x32_bf16 v[40:43], v[166:169], v[198:201], v[40:43]
	v_mfma_f32_16x16x32_bf16 v[32:35], v[156:159], v[210:213], v[32:35]
	v_mfma_f32_16x16x32_bf16 v[24:27], v[166:169], v[210:213], v[24:27]
	v_mfma_f32_16x16x32_bf16 v[16:19], v[156:159], v[218:221], v[16:19]
	v_mfma_f32_16x16x32_bf16 v[8:11], v[166:169], v[218:221], v[8:11]
	s_setprio 0
	s_setprio 1
	v_mfma_f32_16x16x32_bf16 v[52:55], v[170:173], v[186:189], v[52:55]
	v_mfma_f32_16x16x32_bf16 v[44:47], v[178:181], v[186:189], v[44:47]
	v_mfma_f32_16x16x32_bf16 v[36:39], v[170:173], v[194:197], v[36:39]
	v_mfma_f32_16x16x32_bf16 v[28:31], v[178:181], v[194:197], v[28:31]
	v_mfma_f32_16x16x32_bf16 v[20:23], v[170:173], v[206:209], v[20:23]
	v_mfma_f32_16x16x32_bf16 v[12:15], v[178:181], v[206:209], v[12:15]
	v_mfma_f32_16x16x32_bf16 v[4:7], v[170:173], v[214:217], v[4:7]
	v_mfma_f32_16x16x32_bf16 v[0:3], v[178:181], v[214:217], v[0:3]
	v_mfma_f32_16x16x32_bf16 v[52:55], v[174:177], v[190:193], v[52:55]
	v_mfma_f32_16x16x32_bf16 v[44:47], v[182:185], v[190:193], v[44:47]
	v_mfma_f32_16x16x32_bf16 v[36:39], v[174:177], v[198:201], v[36:39]
	v_mfma_f32_16x16x32_bf16 v[28:31], v[182:185], v[198:201], v[28:31]
	v_mfma_f32_16x16x32_bf16 v[20:23], v[174:177], v[210:213], v[20:23]
	v_mfma_f32_16x16x32_bf16 v[12:15], v[182:185], v[210:213], v[12:15]
	v_mfma_f32_16x16x32_bf16 v[4:7], v[174:177], v[218:221], v[4:7]
	v_mfma_f32_16x16x32_bf16 v[0:3], v[182:185], v[218:221], v[0:3]
	s_setprio 0
	s_barrier
	s_add_i32 s78, 0, 0x18000
	v_add_u32_e32 v160, s78, v148
	s_add_i32 s79, 0, 0x1c000
	ds_read_b128 v[152:155], v160
	ds_read_b128 v[156:159], v160 offset:1024
	ds_read_b128 v[162:165], v160 offset:2048
	ds_read_b128 v[166:169], v160 offset:3072
	v_add_u32_e32 v160, s79, v148
	ds_read_b128 v[170:173], v160
	ds_read_b128 v[174:177], v160 offset:1024
	ds_read_b128 v[178:181], v160 offset:2048
	ds_read_b128 v[182:185], v160 offset:3072
	s_add_u32 s46, s46, 0x40000
	s_addc_u32 s47, s47, 0
	s_mov_b32 m0, s54
	v_lshl_add_u64 v[226:227], s[46:47], 0, v[128:129]
	ds_read_b128 v[186:189], v151 offset:32768
	ds_read_b128 v[190:193], v151 offset:33792
	ds_read_b128 v[194:197], v151 offset:34816
	ds_read_b128 v[198:201], v151 offset:35840
	ds_read_b128 v[206:209], v151 offset:36864
	ds_read_b128 v[210:213], v151 offset:37888
	ds_read_b128 v[214:217], v151 offset:38912
	ds_read_b128 v[218:221], v151 offset:39936
	global_load_lds_dwordx4 v[226:227], off
	v_lshl_add_u64 v[226:227], s[46:47], 0, v[132:133]
	s_mov_b32 m0, s55
	s_nop 0
	global_load_lds_dwordx4 v[226:227], off
	s_waitcnt vmcnt(8)
	s_waitcnt lgkmcnt(0)
	s_barrier
	s_setprio 1
	s_waitcnt lgkmcnt(0)
	v_mfma_f32_16x16x32_bf16 v[124:127], v[152:155], v[186:189], v[124:127]
	v_mfma_f32_16x16x32_bf16 v[120:123], v[162:165], v[186:189], v[120:123]
	v_mfma_f32_16x16x32_bf16 v[112:115], v[152:155], v[194:197], v[112:115]
	v_mfma_f32_16x16x32_bf16 v[104:107], v[162:165], v[194:197], v[104:107]
	v_mfma_f32_16x16x32_bf16 v[96:99], v[152:155], v[206:209], v[96:99]
	v_mfma_f32_16x16x32_bf16 v[88:91], v[162:165], v[206:209], v[88:91]
	v_mfma_f32_16x16x32_bf16 v[80:83], v[152:155], v[214:217], v[80:83]
	v_mfma_f32_16x16x32_bf16 v[72:75], v[162:165], v[214:217], v[72:75]
	v_mfma_f32_16x16x32_bf16 v[124:127], v[156:159], v[190:193], v[124:127]
	v_mfma_f32_16x16x32_bf16 v[120:123], v[166:169], v[190:193], v[120:123]
	v_mfma_f32_16x16x32_bf16 v[112:115], v[156:159], v[198:201], v[112:115]
	v_mfma_f32_16x16x32_bf16 v[104:107], v[166:169], v[198:201], v[104:107]
	v_mfma_f32_16x16x32_bf16 v[96:99], v[156:159], v[210:213], v[96:99]
	v_mfma_f32_16x16x32_bf16 v[88:91], v[166:169], v[210:213], v[88:91]
	v_mfma_f32_16x16x32_bf16 v[80:83], v[156:159], v[218:221], v[80:83]
	v_mfma_f32_16x16x32_bf16 v[72:75], v[166:169], v[218:221], v[72:75]
	s_setprio 0
	s_setprio 1
	v_mfma_f32_16x16x32_bf16 v[116:119], v[170:173], v[186:189], v[116:119]
	v_mfma_f32_16x16x32_bf16 v[108:111], v[178:181], v[186:189], v[108:111]
	v_mfma_f32_16x16x32_bf16 v[100:103], v[170:173], v[194:197], v[100:103]
	v_mfma_f32_16x16x32_bf16 v[92:95], v[178:181], v[194:197], v[92:95]
	v_mfma_f32_16x16x32_bf16 v[84:87], v[170:173], v[206:209], v[84:87]
	v_mfma_f32_16x16x32_bf16 v[76:79], v[178:181], v[206:209], v[76:79]
	v_mfma_f32_16x16x32_bf16 v[68:71], v[170:173], v[214:217], v[68:71]
	v_mfma_f32_16x16x32_bf16 v[64:67], v[178:181], v[214:217], v[64:67]
	v_mfma_f32_16x16x32_bf16 v[116:119], v[174:177], v[190:193], v[116:119]
	v_mfma_f32_16x16x32_bf16 v[108:111], v[182:185], v[190:193], v[108:111]
	v_mfma_f32_16x16x32_bf16 v[100:103], v[174:177], v[198:201], v[100:103]
	v_mfma_f32_16x16x32_bf16 v[92:95], v[182:185], v[198:201], v[92:95]
	v_mfma_f32_16x16x32_bf16 v[84:87], v[174:177], v[210:213], v[84:87]
	v_mfma_f32_16x16x32_bf16 v[76:79], v[182:185], v[210:213], v[76:79]
	v_mfma_f32_16x16x32_bf16 v[68:71], v[174:177], v[218:221], v[68:71]
	v_mfma_f32_16x16x32_bf16 v[64:67], v[182:185], v[218:221], v[64:67]
	s_setprio 0
	s_barrier
; #define PG8_STAGE(bufoff, gbase, voff) do { _Pragma("unroll") for (int _i = 0; _i < 2; ++_i) \
;         __builtin_amdgcn_global_load_lds((const unsigned*)((const char*)(gbase) + (voff)[_i]), (PG8_LAS unsigned*)(lds + (bufoff) + ldsw + _i * 8192), 16, 0, 0); } while (0)
; #define PG8_LDA(dst, b, h) do { _Pragma("unroll") for (int m = 0; m < 4; ++m) _Pragma("unroll") for (int k = 0; k < 2; ++k) dst[m][k] = *(const PG8_LAS bf16x8*)(lds + PG8_SA(b, h) + aoff + m * 2048 + k * 1024); } while (0)
; #define PG8_MMA(ai, bj, At, Bt) do { __builtin_amdgcn_s_setprio(1); _Pragma("unroll") for (int m = 0; m < 4; ++m) _Pragma("unroll") for (int n = 0; n < 2; ++n) _Pragma("unroll") for (int k = 0; k < 2; ++k) \
;         acc[ai][bj][m][n] = __builtin_amdgcn_mfma_f32_16x16x32_bf16(Bt[n][k], At[m][k], acc[ai][bj][m][n], 0, 0, 0); __builtin_amdgcn_s_setprio(0); } while (0)
; #define PG8_WAIT_V(n) asm volatile("s_waitcnt vmcnt(" #n ")" ::: "memory")
; #define PG8_WAIT_L(n) asm volatile("s_waitcnt lgkmcnt(" #n ")" ::: "memory")
; #define PG8_BAR __builtin_amdgcn_s_barrier()
; #define PG8_SCHED __builtin_amdgcn_sched_barrier(0)
; template <class Epi, class Sched, bool ALIGN_EPI = false, bool SP2 = false>
; __device__ __forceinline__ void gemm_phase(PG8_LAS unsigned char* lds, const Gemm g, const Sched S, const Epi E) {
;     ...
;         for (int t = 0; t < nt; t += 2) {
;     ...
;             PG8_LDA(At, 1, 1); PG8_STAGE(PG8_SB(1, 0), b3, voffB); PG8_STAGE(PG8_SB(1, 1), b3 + hstep, voffB); PG8_STAGE(PG8_SA(1, 0), a3, voffA);
;             PG8_WAIT_V(8); PG8_WAIT_L(0); PG8_BAR; PG8_MMA(1, 0, At, B0); PG8_MMA(1, 1, At, B1); PG8_BAR; PG8_SCHED;
	s_add_i32 s46, s78, s15
	v_lshl_add_u64 v[144:145], v[144:145], 0, s[10:11]
	s_mov_b32 m0, s46
	ds_read_b128 v[186:189], v151 offset:49152
	ds_read_b128 v[190:193], v151 offset:50176
	ds_read_b128 v[194:197], v151 offset:51200
	ds_read_b128 v[198:201], v151 offset:52224
	ds_read_b128 v[206:209], v151 offset:53248
	ds_read_b128 v[210:213], v151 offset:54272
	ds_read_b128 v[214:217], v151 offset:55296
	ds_read_b128 v[218:221], v151 offset:56320
	global_load_lds_dwordx4 v[144:145], off
	s_add_i32 m0, s46, 0x2000
	s_add_u32 s44, s44, 0x40080
	v_lshl_add_u64 v[144:145], v[202:203], 0, s[10:11]
	s_addc_u32 s45, s45, 0
	s_add_i32 s46, s79, s15
	global_load_lds_dwordx4 v[144:145], off
	v_lshl_add_u64 v[144:145], s[44:45], 0, v[130:131]
	s_mov_b32 m0, s46
	s_nop 0
	global_load_lds_dwordx4 v[144:145], off
	v_lshl_add_u64 v[144:145], s[44:45], 0, v[134:135]
	s_add_i32 m0, s46, 0x2000
	s_nop 0
	global_load_lds_dwordx4 v[144:145], off
	v_lshl_add_u64 v[144:145], v[222:223], 0, s[10:11]
	s_mov_b32 m0, s62
	s_nop 0
	global_load_lds_dwordx4 v[144:145], off
	v_lshl_add_u64 v[144:145], v[224:225], 0, s[10:11]
	s_mov_b32 m0, s63
	s_nop 0
	global_load_lds_dwordx4 v[144:145], off
	s_waitcnt vmcnt(8)
	s_waitcnt lgkmcnt(0)
	s_barrier
	s_setprio 1
	s_waitcnt lgkmcnt(0)
	v_mfma_f32_16x16x32_bf16 v[60:63], v[152:155], v[186:189], v[60:63]
	v_mfma_f32_16x16x32_bf16 v[56:59], v[162:165], v[186:189], v[56:59]
	v_mfma_f32_16x16x32_bf16 v[48:51], v[152:155], v[194:197], v[48:51]
	v_mfma_f32_16x16x32_bf16 v[40:43], v[162:165], v[194:197], v[40:43]
	v_mfma_f32_16x16x32_bf16 v[32:35], v[152:155], v[206:209], v[32:35]
	v_mfma_f32_16x16x32_bf16 v[24:27], v[162:165], v[206:209], v[24:27]
	v_mfma_f32_16x16x32_bf16 v[16:19], v[152:155], v[214:217], v[16:19]
	v_mfma_f32_16x16x32_bf16 v[8:11], v[162:165], v[214:217], v[8:11]
	v_mfma_f32_16x16x32_bf16 v[60:63], v[156:159], v[190:193], v[60:63]
	v_mfma_f32_16x16x32_bf16 v[56:59], v[166:169], v[190:193], v[56:59]
	v_mfma_f32_16x16x32_bf16 v[48:51], v[156:159], v[198:201], v[48:51]
	v_mfma_f32_16x16x32_bf16 v[40:43], v[166:169], v[198:201], v[40:43]
	v_mfma_f32_16x16x32_bf16 v[32:35], v[156:159], v[210:213], v[32:35]
	v_mfma_f32_16x16x32_bf16 v[24:27], v[166:169], v[210:213], v[24:27]
	v_mfma_f32_16x16x32_bf16 v[16:19], v[156:159], v[218:221], v[16:19]
	v_mfma_f32_16x16x32_bf16 v[8:11], v[166:169], v[218:221], v[8:11]
	s_setprio 0
	s_setprio 1
	v_mfma_f32_16x16x32_bf16 v[52:55], v[170:173], v[186:189], v[52:55]
	v_mfma_f32_16x16x32_bf16 v[44:47], v[178:181], v[186:189], v[44:47]
	v_mfma_f32_16x16x32_bf16 v[36:39], v[170:173], v[194:197], v[36:39]
	v_mfma_f32_16x16x32_bf16 v[28:31], v[178:181], v[194:197], v[28:31]
	v_mfma_f32_16x16x32_bf16 v[20:23], v[170:173], v[206:209], v[20:23]
	v_mfma_f32_16x16x32_bf16 v[12:15], v[178:181], v[206:209], v[12:15]
	v_mfma_f32_16x16x32_bf16 v[4:7], v[170:173], v[214:217], v[4:7]
	v_mfma_f32_16x16x32_bf16 v[0:3], v[178:181], v[214:217], v[0:3]
	v_mfma_f32_16x16x32_bf16 v[52:55], v[174:177], v[190:193], v[52:55]
	v_mfma_f32_16x16x32_bf16 v[44:47], v[182:185], v[190:193], v[44:47]
	v_mfma_f32_16x16x32_bf16 v[36:39], v[174:177], v[198:201], v[36:39]
	v_mfma_f32_16x16x32_bf16 v[28:31], v[182:185], v[198:201], v[28:31]
	v_mfma_f32_16x16x32_bf16 v[20:23], v[174:177], v[210:213], v[20:23]
	v_mfma_f32_16x16x32_bf16 v[12:15], v[182:185], v[210:213], v[12:15]
	v_mfma_f32_16x16x32_bf16 v[4:7], v[174:177], v[218:221], v[4:7]
	v_mfma_f32_16x16x32_bf16 v[0:3], v[182:185], v[218:221], v[0:3]
	s_setprio 0
	s_add_i32 s77, s77, 2
	s_add_u32 s42, s42, 0x100
	s_addc_u32 s43, s43, 0
	s_add_u32 s75, s75, 0x100
	s_addc_u32 s76, s76, 0
	s_cmp_gt_u32 s77, 13
	s_barrier
	s_cbranch_scc0 .LBB0_1556
	s_and_b64 vcc, exec, s[12:13]
	s_cbranch_vccz .LBB0_1559
	s_barrier

; #define PG8_STAGE(bufoff, gbase, voff) do { _Pragma("unroll") for (int _i = 0; _i < 2; ++_i) \
;         __builtin_amdgcn_global_load_lds((const unsigned*)((const char*)(gbase) + (voff)[_i]), (PG8_LAS unsigned*)(lds + (bufoff) + ldsw + _i * 8192), 16, 0, 0); } while (0)
; #define PG8_LDA(dst, b, h) do { _Pragma("unroll") for (int m = 0; m < 4; ++m) _Pragma("unroll") for (int k = 0; k < 2; ++k) dst[m][k] = *(const PG8_LAS bf16x8*)(lds + PG8_SA(b, h) + aoff + m * 2048 + k * 1024); } while (0)
; #define PG8_LDB(dst, b, h) do { _Pragma("unroll") for (int n = 0; n < 2; ++n) _Pragma("unroll") for (int k = 0; k < 2; ++k) dst[n][k] = *(const PG8_LAS bf16x8*)(lds + PG8_SB(b, h) + boff + n * 2048 + k * 1024); } while (0)
; #define PG8_MMA(ai, bj, At, Bt) do { __builtin_amdgcn_s_setprio(1); _Pragma("unroll") for (int m = 0; m < 4; ++m) _Pragma("unroll") for (int n = 0; n < 2; ++n) _Pragma("unroll") for (int k = 0; k < 2; ++k) \
;         acc[ai][bj][m][n] = __builtin_amdgcn_mfma_f32_16x16x32_bf16(Bt[n][k], At[m][k], acc[ai][bj][m][n], 0, 0, 0); __builtin_amdgcn_s_setprio(0); } while (0)
; #define PG8_WAIT_V(n) asm volatile("s_waitcnt vmcnt(" #n ")" ::: "memory")
; #define PG8_WAIT_L(n) asm volatile("s_waitcnt lgkmcnt(" #n ")" ::: "memory")
; #define PG8_BAR __builtin_amdgcn_s_barrier()
; #define PG8_SCHED __builtin_amdgcn_sched_barrier(0)
; template <class Epi, class Sched, bool ALIGN_EPI = false, bool SP2 = false>
; __device__ __forceinline__ void gemm_phase(PG8_LAS unsigned char* lds, const Gemm g, const Sched S, const Epi E) {
;     ...
;         for (int t = 0; t < nt; t += 2) {
;             const bool last = (t == nt - 2);
;             const char* a1 = cA + (size_t)(t + 1) * kstepA;
;             const char* a2 = last ? nA : cA + (size_t)(t + 2) * kstepA; const char* b2 = last ? nB : cB + (size_t)(t + 2) * kstep;
;             const char* a3 = a2 + kstepA; const char* b3 = b2 + kstep;
;             if (last && has_next) S.a_ready(nxt);
;             if constexpr (SP2) {
;             PG8_LDB(B0, 0, 0); PG8_LDB(B1, 0, 1); PG8_SCHED; PG8_LDA(At, 0, 0); PG8_STAGE(PG8_SA(1, 1), a1 + hstepA, voffA);
;             PG8_WAIT_V(8); PG8_WAIT_L(0); PG8_BAR; PG8_MMA(0, 0, At, B0); PG8_MMA(0, 1, At, B1); PG8_BAR; PG8_SCHED;
;             PG8_LDA(At, 0, 1); PG8_STAGE(PG8_SB(0, 0), b2, voffB); PG8_STAGE(PG8_SB(0, 1), b2 + hstep, voffB); PG8_STAGE(PG8_SA(0, 0), a2, voffA);
.LBB0_1930:
	ds_read_b128 v[64:67], v188
	ds_read_b128 v[68:71], v188 offset:1024
	ds_read_b128 v[72:75], v188 offset:2048
	ds_read_b128 v[76:79], v188 offset:3072
	ds_read_b128 v[80:83], v189
	ds_read_b128 v[84:87], v189 offset:1024
	ds_read_b128 v[88:91], v189 offset:2048
	ds_read_b128 v[92:95], v189 offset:3072
	s_add_u32 s72, s70, 0xfffc0080
	s_addc_u32 s73, s71, -1
	s_cmp_eq_u32 s69, 12
	s_cselect_b32 s75, s1, s73
	s_cselect_b32 s74, s43, s72
	s_cselect_b32 s73, s41, s67
	s_cselect_b32 s72, s64, s65
	v_lshl_add_u64 v[180:181], s[70:71], 0, v[166:167]
	s_add_i32 m0, s15, 0xc000
	ds_read_b128 v[174:177], v190
	ds_read_b128 v[184:187], v190 offset:1024
	ds_read_b128 v[192:195], v190 offset:2048
	ds_read_b128 v[196:199], v190 offset:3072
	ds_read_b128 v[200:203], v190 offset:4096
	ds_read_b128 v[206:209], v190 offset:5120
	ds_read_b128 v[210:213], v190 offset:6144
	ds_read_b128 v[214:217], v190 offset:7168
	global_load_lds_dwordx4 v[180:181], off
	v_lshl_add_u64 v[180:181], s[70:71], 0, v[168:169]
	s_add_i32 m0, s15, 0xe000
	s_nop 0
	global_load_lds_dwordx4 v[180:181], off
	s_waitcnt vmcnt(8)
	s_waitcnt lgkmcnt(0)
	s_barrier
	s_setprio 1
	s_waitcnt lgkmcnt(0)
	v_mfma_f32_16x16x32_bf16 v[156:159], v[64:67], v[174:177], v[156:159]
	v_mfma_f32_16x16x32_bf16 v[152:155], v[72:75], v[174:177], v[152:155]
	v_mfma_f32_16x16x32_bf16 v[140:143], v[64:67], v[192:195], v[140:143]
	v_mfma_f32_16x16x32_bf16 v[136:139], v[72:75], v[192:195], v[136:139]
	v_mfma_f32_16x16x32_bf16 v[124:127], v[64:67], v[200:203], v[124:127]
	v_mfma_f32_16x16x32_bf16 v[120:123], v[72:75], v[200:203], v[120:123]
	v_mfma_f32_16x16x32_bf16 v[108:111], v[64:67], v[210:213], v[108:111]
	v_mfma_f32_16x16x32_bf16 v[104:107], v[72:75], v[210:213], v[104:107]
	v_mfma_f32_16x16x32_bf16 v[156:159], v[68:71], v[184:187], v[156:159]
	v_mfma_f32_16x16x32_bf16 v[152:155], v[76:79], v[184:187], v[152:155]
	v_mfma_f32_16x16x32_bf16 v[140:143], v[68:71], v[196:199], v[140:143]
	v_mfma_f32_16x16x32_bf16 v[136:139], v[76:79], v[196:199], v[136:139]
	v_mfma_f32_16x16x32_bf16 v[124:127], v[68:71], v[206:209], v[124:127]
	v_mfma_f32_16x16x32_bf16 v[120:123], v[76:79], v[206:209], v[120:123]
	v_mfma_f32_16x16x32_bf16 v[108:111], v[68:71], v[214:217], v[108:111]
	v_mfma_f32_16x16x32_bf16 v[104:107], v[76:79], v[214:217], v[104:107]
	s_setprio 0
	s_setprio 1
	v_mfma_f32_16x16x32_bf16 v[148:151], v[80:83], v[174:177], v[148:151]
	v_mfma_f32_16x16x32_bf16 v[144:147], v[88:91], v[174:177], v[144:147]
	v_mfma_f32_16x16x32_bf16 v[132:135], v[80:83], v[192:195], v[132:135]
	v_mfma_f32_16x16x32_bf16 v[128:131], v[88:91], v[192:195], v[128:131]
	v_mfma_f32_16x16x32_bf16 v[116:119], v[80:83], v[200:203], v[116:119]
	v_mfma_f32_16x16x32_bf16 v[112:115], v[88:91], v[200:203], v[112:115]
	v_mfma_f32_16x16x32_bf16 v[100:103], v[80:83], v[210:213], v[100:103]
	v_mfma_f32_16x16x32_bf16 v[96:99], v[88:91], v[210:213], v[96:99]
	v_mfma_f32_16x16x32_bf16 v[148:151], v[84:87], v[184:187], v[148:151]
	v_mfma_f32_16x16x32_bf16 v[144:147], v[92:95], v[184:187], v[144:147]
	v_mfma_f32_16x16x32_bf16 v[132:135], v[84:87], v[196:199], v[132:135]
	v_mfma_f32_16x16x32_bf16 v[128:131], v[92:95], v[196:199], v[128:131]
	v_mfma_f32_16x16x32_bf16 v[116:119], v[84:87], v[206:209], v[116:119]
	v_mfma_f32_16x16x32_bf16 v[112:115], v[92:95], v[206:209], v[112:115]
	v_mfma_f32_16x16x32_bf16 v[100:103], v[84:87], v[214:217], v[100:103]
	v_mfma_f32_16x16x32_bf16 v[96:99], v[92:95], v[214:217], v[96:99]
	s_setprio 0
	s_barrier
	s_add_i32 s76, s62, s4
	v_lshl_add_u64 v[180:181], s[72:73], 0, v[162:163]
	s_mov_b32 m0, s76
	ds_read_b128 v[174:177], v190 offset:16384
	ds_read_b128 v[184:187], v190 offset:17408
	ds_read_b128 v[192:195], v190 offset:18432
	ds_read_b128 v[196:199], v190 offset:19456
	ds_read_b128 v[200:203], v190 offset:20480
	ds_read_b128 v[206:209], v190 offset:21504
	ds_read_b128 v[210:213], v190 offset:22528
	ds_read_b128 v[214:217], v190 offset:23552
	global_load_lds_dwordx4 v[180:181], off
	s_add_i32 m0, s76, 0x2000
	s_add_u32 s76, s72, 0x40000
	v_lshl_add_u64 v[218:219], s[72:73], 0, v[164:165]
	s_addc_u32 s77, s73, 0
	s_add_i32 s78, s63, s4
	global_load_lds_dwordx4 v[218:219], off
	v_lshl_add_u64 v[220:221], s[76:77], 0, v[162:163]
	s_mov_b32 m0, s78
	v_lshl_add_u64 v[222:223], s[74:75], 0, v[164:165]
	global_load_lds_dwordx4 v[220:221], off
	v_lshl_add_u64 v[220:221], s[76:77], 0, v[164:165]
	s_add_i32 m0, s78, 0x2000
	s_nop 0
	global_load_lds_dwordx4 v[220:221], off
	v_lshl_add_u64 v[220:221], s[74:75], 0, v[162:163]
	s_mov_b32 m0, s15
	s_nop 0
	global_load_lds_dwordx4 v[220:221], off
	s_mov_b32 m0, s21
	s_nop 0
	global_load_lds_dwordx4 v[222:223], off
	s_waitcnt vmcnt(8)
	s_waitcnt lgkmcnt(0)
	s_barrier
; #define PG8_STAGE(bufoff, gbase, voff) do { _Pragma("unroll") for (int _i = 0; _i < 2; ++_i) \
;         __builtin_amdgcn_global_load_lds((const unsigned*)((const char*)(gbase) + (voff)[_i]), (PG8_LAS unsigned*)(lds + (bufoff) + ldsw + _i * 8192), 16, 0, 0); } while (0)
; #define PG8_LDA(dst, b, h) do { _Pragma("unroll") for (int m = 0; m < 4; ++m) _Pragma("unroll") for (int k = 0; k < 2; ++k) dst[m][k] = *(const PG8_LAS bf16x8*)(lds + PG8_SA(b, h) + aoff + m * 2048 + k * 1024); } while (0)
; #define PG8_LDB(dst, b, h) do { _Pragma("unroll") for (int n = 0; n < 2; ++n) _Pragma("unroll") for (int k = 0; k < 2; ++k) dst[n][k] = *(const PG8_LAS bf16x8*)(lds + PG8_SB(b, h) + boff + n * 2048 + k * 1024); } while (0)
; #define PG8_MMA(ai, bj, At, Bt) do { __builtin_amdgcn_s_setprio(1); _Pragma("unroll") for (int m = 0; m < 4; ++m) _Pragma("unroll") for (int n = 0; n < 2; ++n) _Pragma("unroll") for (int k = 0; k < 2; ++k) \
;         acc[ai][bj][m][n] = __builtin_amdgcn_mfma_f32_16x16x32_bf16(Bt[n][k], At[m][k], acc[ai][bj][m][n], 0, 0, 0); __builtin_amdgcn_s_setprio(0); } while (0)
; #define PG8_WAIT_V(n) asm volatile("s_waitcnt vmcnt(" #n ")" ::: "memory")
; #define PG8_WAIT_L(n) asm volatile("s_waitcnt lgkmcnt(" #n ")" ::: "memory")
; #define PG8_BAR __builtin_amdgcn_s_barrier()
; #define PG8_SCHED __builtin_amdgcn_sched_barrier(0)
; template <class Epi, class Sched, bool ALIGN_EPI = false, bool SP2 = false>
; __device__ __forceinline__ void gemm_phase(PG8_LAS unsigned char* lds, const Gemm g, const Sched S, const Epi E) {
;     ...
;             PG8_WAIT_V(8); PG8_WAIT_L(0); PG8_BAR; PG8_MMA(1, 0, At, B0); PG8_MMA(1, 1, At, B1); PG8_BAR; PG8_SCHED;
;             PG8_LDB(B0, 1, 0); PG8_LDB(B1, 1, 1); PG8_SCHED; PG8_LDA(At, 1, 0); PG8_STAGE(PG8_SA(0, 1), a2 + hstepA, voffA);
;             PG8_WAIT_V(8); PG8_WAIT_L(0); PG8_BAR; PG8_MMA(0, 0, At, B0); PG8_MMA(0, 1, At, B1); PG8_BAR; PG8_SCHED;
	s_setprio 1
	s_waitcnt lgkmcnt(0)
	v_mfma_f32_16x16x32_bf16 v[60:63], v[64:67], v[174:177], v[60:63]
	v_mfma_f32_16x16x32_bf16 v[56:59], v[72:75], v[174:177], v[56:59]
	v_mfma_f32_16x16x32_bf16 v[44:47], v[64:67], v[192:195], v[44:47]
	v_mfma_f32_16x16x32_bf16 v[40:43], v[72:75], v[192:195], v[40:43]
	v_mfma_f32_16x16x32_bf16 v[28:31], v[64:67], v[200:203], v[28:31]
	v_mfma_f32_16x16x32_bf16 v[24:27], v[72:75], v[200:203], v[24:27]
	v_mfma_f32_16x16x32_bf16 v[12:15], v[64:67], v[210:213], v[12:15]
	v_mfma_f32_16x16x32_bf16 v[8:11], v[72:75], v[210:213], v[8:11]
	v_mfma_f32_16x16x32_bf16 v[60:63], v[68:71], v[184:187], v[60:63]
	v_mfma_f32_16x16x32_bf16 v[56:59], v[76:79], v[184:187], v[56:59]
	v_mfma_f32_16x16x32_bf16 v[44:47], v[68:71], v[196:199], v[44:47]
	v_mfma_f32_16x16x32_bf16 v[40:43], v[76:79], v[196:199], v[40:43]
	v_mfma_f32_16x16x32_bf16 v[28:31], v[68:71], v[206:209], v[28:31]
	v_mfma_f32_16x16x32_bf16 v[24:27], v[76:79], v[206:209], v[24:27]
	v_mfma_f32_16x16x32_bf16 v[12:15], v[68:71], v[214:217], v[12:15]
	v_mfma_f32_16x16x32_bf16 v[8:11], v[76:79], v[214:217], v[8:11]
	s_setprio 0
	s_setprio 1
	v_mfma_f32_16x16x32_bf16 v[52:55], v[80:83], v[174:177], v[52:55]
	v_mfma_f32_16x16x32_bf16 v[48:51], v[88:91], v[174:177], v[48:51]
	v_mfma_f32_16x16x32_bf16 v[36:39], v[80:83], v[192:195], v[36:39]
	v_mfma_f32_16x16x32_bf16 v[32:35], v[88:91], v[192:195], v[32:35]
	v_mfma_f32_16x16x32_bf16 v[20:23], v[80:83], v[200:203], v[20:23]
	v_mfma_f32_16x16x32_bf16 v[16:19], v[88:91], v[200:203], v[16:19]
	v_mfma_f32_16x16x32_bf16 v[4:7], v[80:83], v[210:213], v[4:7]
	v_mfma_f32_16x16x32_bf16 v[0:3], v[88:91], v[210:213], v[0:3]
	v_mfma_f32_16x16x32_bf16 v[52:55], v[84:87], v[184:187], v[52:55]
	v_mfma_f32_16x16x32_bf16 v[48:51], v[92:95], v[184:187], v[48:51]
	v_mfma_f32_16x16x32_bf16 v[36:39], v[84:87], v[196:199], v[36:39]
	v_mfma_f32_16x16x32_bf16 v[32:35], v[92:95], v[196:199], v[32:35]
	v_mfma_f32_16x16x32_bf16 v[20:23], v[84:87], v[206:209], v[20:23]
	v_mfma_f32_16x16x32_bf16 v[16:19], v[92:95], v[206:209], v[16:19]
	v_mfma_f32_16x16x32_bf16 v[4:7], v[84:87], v[214:217], v[4:7]
	v_mfma_f32_16x16x32_bf16 v[0:3], v[92:95], v[214:217], v[0:3]
	s_setprio 0
	s_barrier
	s_add_i32 s76, 0, 0x18000
	s_add_i32 s77, 0, 0x1c000
	v_add_u32_e32 v76, s76, v183
	v_add_u32_e32 v92, s77, v183
	ds_read_b128 v[64:67], v76
	ds_read_b128 v[68:71], v76 offset:1024
	ds_read_b128 v[72:75], v76 offset:2048
	ds_read_b128 v[76:79], v76 offset:3072
	ds_read_b128 v[80:83], v92
	ds_read_b128 v[84:87], v92 offset:1024
	ds_read_b128 v[88:91], v92 offset:2048
	ds_read_b128 v[92:95], v92 offset:3072
	s_add_u32 s74, s74, 0x40000
	s_addc_u32 s75, s75, 0
	s_mov_b32 m0, s33
	v_lshl_add_u64 v[224:225], s[74:75], 0, v[162:163]
	ds_read_b128 v[174:177], v190 offset:32768
	ds_read_b128 v[184:187], v190 offset:33792
	ds_read_b128 v[192:195], v190 offset:34816
	ds_read_b128 v[196:199], v190 offset:35840
	ds_read_b128 v[200:203], v190 offset:36864
	ds_read_b128 v[206:209], v190 offset:37888
	ds_read_b128 v[210:213], v190 offset:38912
	ds_read_b128 v[214:217], v190 offset:39936
	global_load_lds_dwordx4 v[224:225], off
	v_lshl_add_u64 v[224:225], s[74:75], 0, v[164:165]
	s_mov_b32 m0, s39
	s_nop 0
	global_load_lds_dwordx4 v[224:225], off
	s_waitcnt vmcnt(8)
	s_waitcnt lgkmcnt(0)
	s_barrier
	s_setprio 1
	s_waitcnt lgkmcnt(0)
	v_mfma_f32_16x16x32_bf16 v[156:159], v[64:67], v[174:177], v[156:159]
	v_mfma_f32_16x16x32_bf16 v[152:155], v[72:75], v[174:177], v[152:155]
	v_mfma_f32_16x16x32_bf16 v[140:143], v[64:67], v[192:195], v[140:143]
	v_mfma_f32_16x16x32_bf16 v[136:139], v[72:75], v[192:195], v[136:139]
	v_mfma_f32_16x16x32_bf16 v[124:127], v[64:67], v[200:203], v[124:127]
	v_mfma_f32_16x16x32_bf16 v[120:123], v[72:75], v[200:203], v[120:123]
	v_mfma_f32_16x16x32_bf16 v[108:111], v[64:67], v[210:213], v[108:111]
	v_mfma_f32_16x16x32_bf16 v[104:107], v[72:75], v[210:213], v[104:107]
	v_mfma_f32_16x16x32_bf16 v[156:159], v[68:71], v[184:187], v[156:159]
	v_mfma_f32_16x16x32_bf16 v[152:155], v[76:79], v[184:187], v[152:155]
	v_mfma_f32_16x16x32_bf16 v[140:143], v[68:71], v[196:199], v[140:143]
	v_mfma_f32_16x16x32_bf16 v[136:139], v[76:79], v[196:199], v[136:139]
	v_mfma_f32_16x16x32_bf16 v[124:127], v[68:71], v[206:209], v[124:127]
	v_mfma_f32_16x16x32_bf16 v[120:123], v[76:79], v[206:209], v[120:123]
	v_mfma_f32_16x16x32_bf16 v[108:111], v[68:71], v[214:217], v[108:111]
	v_mfma_f32_16x16x32_bf16 v[104:107], v[76:79], v[214:217], v[104:107]
	s_setprio 0
	s_setprio 1
	v_mfma_f32_16x16x32_bf16 v[148:151], v[80:83], v[174:177], v[148:151]
	v_mfma_f32_16x16x32_bf16 v[144:147], v[88:91], v[174:177], v[144:147]
	v_mfma_f32_16x16x32_bf16 v[132:135], v[80:83], v[192:195], v[132:135]
	v_mfma_f32_16x16x32_bf16 v[128:131], v[88:91], v[192:195], v[128:131]
	v_mfma_f32_16x16x32_bf16 v[116:119], v[80:83], v[200:203], v[116:119]
	v_mfma_f32_16x16x32_bf16 v[112:115], v[88:91], v[200:203], v[112:115]
	v_mfma_f32_16x16x32_bf16 v[100:103], v[80:83], v[210:213], v[100:103]
	v_mfma_f32_16x16x32_bf16 v[96:99], v[88:91], v[210:213], v[96:99]
	v_mfma_f32_16x16x32_bf16 v[148:151], v[84:87], v[184:187], v[148:151]
	v_mfma_f32_16x16x32_bf16 v[144:147], v[92:95], v[184:187], v[144:147]
	v_mfma_f32_16x16x32_bf16 v[132:135], v[84:87], v[196:199], v[132:135]
	v_mfma_f32_16x16x32_bf16 v[128:131], v[92:95], v[196:199], v[128:131]
	v_mfma_f32_16x16x32_bf16 v[116:119], v[84:87], v[206:209], v[116:119]
	v_mfma_f32_16x16x32_bf16 v[112:115], v[92:95], v[206:209], v[112:115]
	v_mfma_f32_16x16x32_bf16 v[100:103], v[84:87], v[214:217], v[100:103]
	v_mfma_f32_16x16x32_bf16 v[96:99], v[92:95], v[214:217], v[96:99]
	s_setprio 0
	s_barrier
; #define PG8_STAGE(bufoff, gbase, voff) do { _Pragma("unroll") for (int _i = 0; _i < 2; ++_i) \
;         __builtin_amdgcn_global_load_lds((const unsigned*)((const char*)(gbase) + (voff)[_i]), (PG8_LAS unsigned*)(lds + (bufoff) + ldsw + _i * 8192), 16, 0, 0); } while (0)
; #define PG8_LDA(dst, b, h) do { _Pragma("unroll") for (int m = 0; m < 4; ++m) _Pragma("unroll") for (int k = 0; k < 2; ++k) dst[m][k] = *(const PG8_LAS bf16x8*)(lds + PG8_SA(b, h) + aoff + m * 2048 + k * 1024); } while (0)
; #define PG8_MMA(ai, bj, At, Bt) do { __builtin_amdgcn_s_setprio(1); _Pragma("unroll") for (int m = 0; m < 4; ++m) _Pragma("unroll") for (int n = 0; n < 2; ++n) _Pragma("unroll") for (int k = 0; k < 2; ++k) \
;         acc[ai][bj][m][n] = __builtin_amdgcn_mfma_f32_16x16x32_bf16(Bt[n][k], At[m][k], acc[ai][bj][m][n], 0, 0, 0); __builtin_amdgcn_s_setprio(0); } while (0)
; #define PG8_WAIT_V(n) asm volatile("s_waitcnt vmcnt(" #n ")" ::: "memory")
; #define PG8_WAIT_L(n) asm volatile("s_waitcnt lgkmcnt(" #n ")" ::: "memory")
; #define PG8_BAR __builtin_amdgcn_s_barrier()
; #define PG8_SCHED __builtin_amdgcn_sched_barrier(0)
; template <class Epi, class Sched, bool ALIGN_EPI = false, bool SP2 = false>
; __device__ __forceinline__ void gemm_phase(PG8_LAS unsigned char* lds, const Gemm g, const Sched S, const Epi E) {
;     ...
;         for (int t = 0; t < nt; t += 2) {
;     ...
;             PG8_LDA(At, 1, 1); PG8_STAGE(PG8_SB(1, 0), b3, voffB); PG8_STAGE(PG8_SB(1, 1), b3 + hstep, voffB); PG8_STAGE(PG8_SA(1, 0), a3, voffA);
;             PG8_WAIT_V(8); PG8_WAIT_L(0); PG8_BAR; PG8_MMA(1, 0, At, B0); PG8_MMA(1, 1, At, B1); PG8_BAR; PG8_SCHED;
	s_add_i32 s74, s76, s4
	v_lshl_add_u64 v[180:181], v[180:181], 0, s[30:31]
	s_mov_b32 m0, s74
	ds_read_b128 v[174:177], v190 offset:49152
	ds_read_b128 v[184:187], v190 offset:50176
	ds_read_b128 v[192:195], v190 offset:51200
	ds_read_b128 v[196:199], v190 offset:52224
	ds_read_b128 v[200:203], v190 offset:53248
	ds_read_b128 v[206:209], v190 offset:54272
	ds_read_b128 v[210:213], v190 offset:55296
	ds_read_b128 v[214:217], v190 offset:56320
	global_load_lds_dwordx4 v[180:181], off
	s_add_i32 m0, s74, 0x2000
	s_add_u32 s72, s72, 0x40080
	v_lshl_add_u64 v[180:181], v[218:219], 0, s[30:31]
	s_addc_u32 s73, s73, 0
	s_add_i32 s74, s77, s4
	global_load_lds_dwordx4 v[180:181], off
	v_lshl_add_u64 v[180:181], s[72:73], 0, v[162:163]
	s_mov_b32 m0, s74
	s_nop 0
	global_load_lds_dwordx4 v[180:181], off
	v_lshl_add_u64 v[180:181], s[72:73], 0, v[164:165]
	s_add_i32 m0, s74, 0x2000
	s_nop 0
	global_load_lds_dwordx4 v[180:181], off
	v_lshl_add_u64 v[180:181], v[220:221], 0, s[30:31]
	s_mov_b32 m0, s60
	s_nop 0
	global_load_lds_dwordx4 v[180:181], off
	v_lshl_add_u64 v[180:181], v[222:223], 0, s[30:31]
	s_mov_b32 m0, s61
	s_nop 0
	global_load_lds_dwordx4 v[180:181], off
	s_waitcnt vmcnt(8)
	s_waitcnt lgkmcnt(0)
	s_barrier
	s_setprio 1
	s_waitcnt lgkmcnt(0)
	v_mfma_f32_16x16x32_bf16 v[60:63], v[64:67], v[174:177], v[60:63]
	v_mfma_f32_16x16x32_bf16 v[56:59], v[72:75], v[174:177], v[56:59]
	v_mfma_f32_16x16x32_bf16 v[44:47], v[64:67], v[192:195], v[44:47]
	v_mfma_f32_16x16x32_bf16 v[40:43], v[72:75], v[192:195], v[40:43]
	v_mfma_f32_16x16x32_bf16 v[28:31], v[64:67], v[200:203], v[28:31]
	v_mfma_f32_16x16x32_bf16 v[24:27], v[72:75], v[200:203], v[24:27]
	v_mfma_f32_16x16x32_bf16 v[12:15], v[64:67], v[210:213], v[12:15]
	v_mfma_f32_16x16x32_bf16 v[8:11], v[72:75], v[210:213], v[8:11]
	v_mfma_f32_16x16x32_bf16 v[60:63], v[68:71], v[184:187], v[60:63]
	v_mfma_f32_16x16x32_bf16 v[56:59], v[76:79], v[184:187], v[56:59]
	v_mfma_f32_16x16x32_bf16 v[44:47], v[68:71], v[196:199], v[44:47]
	v_mfma_f32_16x16x32_bf16 v[40:43], v[76:79], v[196:199], v[40:43]
	v_mfma_f32_16x16x32_bf16 v[28:31], v[68:71], v[206:209], v[28:31]
	v_mfma_f32_16x16x32_bf16 v[24:27], v[76:79], v[206:209], v[24:27]
	v_mfma_f32_16x16x32_bf16 v[12:15], v[68:71], v[214:217], v[12:15]
	v_mfma_f32_16x16x32_bf16 v[8:11], v[76:79], v[214:217], v[8:11]
	s_setprio 0
	s_setprio 1
	v_mfma_f32_16x16x32_bf16 v[52:55], v[80:83], v[174:177], v[52:55]
	v_mfma_f32_16x16x32_bf16 v[48:51], v[88:91], v[174:177], v[48:51]
	v_mfma_f32_16x16x32_bf16 v[36:39], v[80:83], v[192:195], v[36:39]
	v_mfma_f32_16x16x32_bf16 v[32:35], v[88:91], v[192:195], v[32:35]
	v_mfma_f32_16x16x32_bf16 v[20:23], v[80:83], v[200:203], v[20:23]
	v_mfma_f32_16x16x32_bf16 v[16:19], v[88:91], v[200:203], v[16:19]
	v_mfma_f32_16x16x32_bf16 v[4:7], v[80:83], v[210:213], v[4:7]
	v_mfma_f32_16x16x32_bf16 v[0:3], v[88:91], v[210:213], v[0:3]
	v_mfma_f32_16x16x32_bf16 v[52:55], v[84:87], v[184:187], v[52:55]
	v_mfma_f32_16x16x32_bf16 v[48:51], v[92:95], v[184:187], v[48:51]
	v_mfma_f32_16x16x32_bf16 v[36:39], v[84:87], v[196:199], v[36:39]
	v_mfma_f32_16x16x32_bf16 v[32:35], v[92:95], v[196:199], v[32:35]
	v_mfma_f32_16x16x32_bf16 v[20:23], v[84:87], v[206:209], v[20:23]
	v_mfma_f32_16x16x32_bf16 v[16:19], v[92:95], v[206:209], v[16:19]
	v_mfma_f32_16x16x32_bf16 v[4:7], v[84:87], v[214:217], v[4:7]
	v_mfma_f32_16x16x32_bf16 v[0:3], v[92:95], v[214:217], v[0:3]
	s_setprio 0
	s_add_i32 s69, s69, 2
	s_add_u32 s70, s70, 0x100
	s_addc_u32 s71, s71, 0
	s_add_u32 s65, s65, 0x100
	s_addc_u32 s67, s67, 0
	s_cmp_gt_u32 s69, 13
	s_barrier
	s_cbranch_scc0 .LBB0_1930
	s_and_b64 vcc, exec, s[34:35]
	s_cbranch_vccz .LBB0_1933
	s_barrier

; #define PG8_STAGE(bufoff, gbase, voff) do { _Pragma("unroll") for (int _i = 0; _i < 2; ++_i) \
;         __builtin_amdgcn_global_load_lds((const unsigned*)((const char*)(gbase) + (voff)[_i]), (PG8_LAS unsigned*)(lds + (bufoff) + ldsw + _i * 8192), 16, 0, 0); } while (0)
; #define PG8_LDA(dst, b, h) do { _Pragma("unroll") for (int m = 0; m < 4; ++m) _Pragma("unroll") for (int k = 0; k < 2; ++k) dst[m][k] = *(const PG8_LAS bf16x8*)(lds + PG8_SA(b, h) + aoff + m * 2048 + k * 1024); } while (0)
; #define PG8_LDB(dst, b, h) do { _Pragma("unroll") for (int n = 0; n < 2; ++n) _Pragma("unroll") for (int k = 0; k < 2; ++k) dst[n][k] = *(const PG8_LAS bf16x8*)(lds + PG8_SB(b, h) + boff + n * 2048 + k * 1024); } while (0)
; #define PG8_MMA(ai, bj, At, Bt) do { __builtin_amdgcn_s_setprio(1); _Pragma("unroll") for (int m = 0; m < 4; ++m) _Pragma("unroll") for (int n = 0; n < 2; ++n) _Pragma("unroll") for (int k = 0; k < 2; ++k) \
;         acc[ai][bj][m][n] = __builtin_amdgcn_mfma_f32_16x16x32_bf16(Bt[n][k], At[m][k], acc[ai][bj][m][n], 0, 0, 0); __builtin_amdgcn_s_setprio(0); } while (0)
; #define PG8_WAIT_V(n) asm volatile("s_waitcnt vmcnt(" #n ")" ::: "memory")
; #define PG8_WAIT_L(n) asm volatile("s_waitcnt lgkmcnt(" #n ")" ::: "memory")
; #define PG8_BAR __builtin_amdgcn_s_barrier()
; #define PG8_SCHED __builtin_amdgcn_sched_barrier(0)
; template <class Epi, class Sched, bool ALIGN_EPI = false, bool SP2 = false>
; __device__ __forceinline__ void gemm_phase(PG8_LAS unsigned char* lds, const Gemm g, const Sched S, const Epi E) {
;     ...
;         for (int t = 0; t < nt; t += 2) {
;             const bool last = (t == nt - 2);
;             const char* a1 = cA + (size_t)(t + 1) * kstepA;
;             const char* a2 = last ? nA : cA + (size_t)(t + 2) * kstepA; const char* b2 = last ? nB : cB + (size_t)(t + 2) * kstep;
;             const char* a3 = a2 + kstepA; const char* b3 = b2 + kstep;
;             if (last && has_next) S.a_ready(nxt);
;             if constexpr (SP2) {
;             PG8_LDB(B0, 0, 0); PG8_LDB(B1, 0, 1); PG8_SCHED; PG8_LDA(At, 0, 0); PG8_STAGE(PG8_SA(1, 1), a1 + hstepA, voffA);
;             PG8_WAIT_V(8); PG8_WAIT_L(0); PG8_BAR; PG8_MMA(0, 0, At, B0); PG8_MMA(0, 1, At, B1); PG8_BAR; PG8_SCHED;
;             PG8_LDA(At, 0, 1); PG8_STAGE(PG8_SB(0, 0), b2, voffB); PG8_STAGE(PG8_SB(0, 1), b2 + hstep, voffB); PG8_STAGE(PG8_SA(0, 0), a2, voffA);
.LBB0_2079:
	ds_read_b128 v[152:155], v149
	ds_read_b128 v[156:159], v149 offset:1024
	ds_read_b128 v[162:165], v149 offset:2048
	ds_read_b128 v[166:169], v149 offset:3072
	ds_read_b128 v[170:173], v150
	ds_read_b128 v[174:177], v150 offset:1024
	ds_read_b128 v[178:181], v150 offset:2048
	ds_read_b128 v[182:185], v150 offset:3072
	s_add_u32 s68, s46, 0xfffc0080
	s_addc_u32 s69, s47, -1
	s_cmp_eq_u32 s80, 12
	s_cselect_b32 s71, s39, s69
	s_cselect_b32 s70, s76, s68
	s_cselect_b32 s69, s37, s79
	s_cselect_b32 s68, s77, s78
	v_lshl_add_u64 v[144:145], s[46:47], 0, v[136:137]
	s_add_i32 m0, s15, 0xc000
	ds_read_b128 v[186:189], v151
	ds_read_b128 v[190:193], v151 offset:1024
	ds_read_b128 v[194:197], v151 offset:2048
	ds_read_b128 v[198:201], v151 offset:3072
	ds_read_b128 v[206:209], v151 offset:4096
	ds_read_b128 v[210:213], v151 offset:5120
	ds_read_b128 v[214:217], v151 offset:6144
	ds_read_b128 v[218:221], v151 offset:7168
	global_load_lds_dwordx4 v[144:145], off
	v_lshl_add_u64 v[144:145], s[46:47], 0, v[138:139]
	s_add_i32 m0, s15, 0xe000
	s_nop 0
	global_load_lds_dwordx4 v[144:145], off
	s_waitcnt vmcnt(8)
	s_waitcnt lgkmcnt(0)
	s_barrier
	s_setprio 1
	s_waitcnt lgkmcnt(0)
	v_mfma_f32_16x16x32_bf16 v[124:127], v[152:155], v[186:189], v[124:127]
	v_mfma_f32_16x16x32_bf16 v[120:123], v[162:165], v[186:189], v[120:123]
	v_mfma_f32_16x16x32_bf16 v[108:111], v[152:155], v[194:197], v[108:111]
	v_mfma_f32_16x16x32_bf16 v[104:107], v[162:165], v[194:197], v[104:107]
	v_mfma_f32_16x16x32_bf16 v[92:95], v[152:155], v[206:209], v[92:95]
	v_mfma_f32_16x16x32_bf16 v[88:91], v[162:165], v[206:209], v[88:91]
	v_mfma_f32_16x16x32_bf16 v[76:79], v[152:155], v[214:217], v[76:79]
	v_mfma_f32_16x16x32_bf16 v[72:75], v[162:165], v[214:217], v[72:75]
	v_mfma_f32_16x16x32_bf16 v[124:127], v[156:159], v[190:193], v[124:127]
	v_mfma_f32_16x16x32_bf16 v[120:123], v[166:169], v[190:193], v[120:123]
	v_mfma_f32_16x16x32_bf16 v[108:111], v[156:159], v[198:201], v[108:111]
	v_mfma_f32_16x16x32_bf16 v[104:107], v[166:169], v[198:201], v[104:107]
	v_mfma_f32_16x16x32_bf16 v[92:95], v[156:159], v[210:213], v[92:95]
	v_mfma_f32_16x16x32_bf16 v[88:91], v[166:169], v[210:213], v[88:91]
	v_mfma_f32_16x16x32_bf16 v[76:79], v[156:159], v[218:221], v[76:79]
	v_mfma_f32_16x16x32_bf16 v[72:75], v[166:169], v[218:221], v[72:75]
	s_setprio 0
	s_setprio 1
	v_mfma_f32_16x16x32_bf16 v[116:119], v[170:173], v[186:189], v[116:119]
	v_mfma_f32_16x16x32_bf16 v[112:115], v[178:181], v[186:189], v[112:115]
	v_mfma_f32_16x16x32_bf16 v[100:103], v[170:173], v[194:197], v[100:103]
	v_mfma_f32_16x16x32_bf16 v[96:99], v[178:181], v[194:197], v[96:99]
	v_mfma_f32_16x16x32_bf16 v[84:87], v[170:173], v[206:209], v[84:87]
	v_mfma_f32_16x16x32_bf16 v[80:83], v[178:181], v[206:209], v[80:83]
	v_mfma_f32_16x16x32_bf16 v[68:71], v[170:173], v[214:217], v[68:71]
	v_mfma_f32_16x16x32_bf16 v[64:67], v[178:181], v[214:217], v[64:67]
	v_mfma_f32_16x16x32_bf16 v[116:119], v[174:177], v[190:193], v[116:119]
	v_mfma_f32_16x16x32_bf16 v[112:115], v[182:185], v[190:193], v[112:115]
	v_mfma_f32_16x16x32_bf16 v[100:103], v[174:177], v[198:201], v[100:103]
	v_mfma_f32_16x16x32_bf16 v[96:99], v[182:185], v[198:201], v[96:99]
	v_mfma_f32_16x16x32_bf16 v[84:87], v[174:177], v[210:213], v[84:87]
	v_mfma_f32_16x16x32_bf16 v[80:83], v[182:185], v[210:213], v[80:83]
	v_mfma_f32_16x16x32_bf16 v[68:71], v[174:177], v[218:221], v[68:71]
	v_mfma_f32_16x16x32_bf16 v[64:67], v[182:185], v[218:221], v[64:67]
	s_setprio 0
	s_barrier
	s_add_i32 s81, s62, s4
	v_lshl_add_u64 v[144:145], s[68:69], 0, v[132:133]
	s_mov_b32 m0, s81
	ds_read_b128 v[186:189], v151 offset:16384
	ds_read_b128 v[190:193], v151 offset:17408
	ds_read_b128 v[194:197], v151 offset:18432
	ds_read_b128 v[198:201], v151 offset:19456
	ds_read_b128 v[206:209], v151 offset:20480
	ds_read_b128 v[210:213], v151 offset:21504
	ds_read_b128 v[214:217], v151 offset:22528
	ds_read_b128 v[218:221], v151 offset:23552
	global_load_lds_dwordx4 v[144:145], off
	s_add_i32 m0, s81, 0x2000
	s_add_u32 s82, s68, 0x40000
	v_lshl_add_u64 v[202:203], s[68:69], 0, v[128:129]
	s_addc_u32 s83, s69, 0
	s_add_i32 s81, s63, s4
	global_load_lds_dwordx4 v[202:203], off
	v_lshl_add_u64 v[222:223], s[82:83], 0, v[132:133]
	s_mov_b32 m0, s81
	v_lshl_add_u64 v[224:225], s[70:71], 0, v[130:131]
	global_load_lds_dwordx4 v[222:223], off
	v_lshl_add_u64 v[222:223], s[82:83], 0, v[128:129]
	s_add_i32 m0, s81, 0x2000
	s_nop 0
	global_load_lds_dwordx4 v[222:223], off
	v_lshl_add_u64 v[222:223], s[70:71], 0, v[134:135]
	s_mov_b32 m0, s15
	s_nop 0
	global_load_lds_dwordx4 v[222:223], off
	s_mov_b32 m0, s21
	s_nop 0
	global_load_lds_dwordx4 v[224:225], off
	s_waitcnt vmcnt(8)
	s_waitcnt lgkmcnt(0)
	s_barrier
; #define PG8_STAGE(bufoff, gbase, voff) do { _Pragma("unroll") for (int _i = 0; _i < 2; ++_i) \
;         __builtin_amdgcn_global_load_lds((const unsigned*)((const char*)(gbase) + (voff)[_i]), (PG8_LAS unsigned*)(lds + (bufoff) + ldsw + _i * 8192), 16, 0, 0); } while (0)
; #define PG8_LDA(dst, b, h) do { _Pragma("unroll") for (int m = 0; m < 4; ++m) _Pragma("unroll") for (int k = 0; k < 2; ++k) dst[m][k] = *(const PG8_LAS bf16x8*)(lds + PG8_SA(b, h) + aoff + m * 2048 + k * 1024); } while (0)
; #define PG8_LDB(dst, b, h) do { _Pragma("unroll") for (int n = 0; n < 2; ++n) _Pragma("unroll") for (int k = 0; k < 2; ++k) dst[n][k] = *(const PG8_LAS bf16x8*)(lds + PG8_SB(b, h) + boff + n * 2048 + k * 1024); } while (0)
; #define PG8_MMA(ai, bj, At, Bt) do { __builtin_amdgcn_s_setprio(1); _Pragma("unroll") for (int m = 0; m < 4; ++m) _Pragma("unroll") for (int n = 0; n < 2; ++n) _Pragma("unroll") for (int k = 0; k < 2; ++k) \
;         acc[ai][bj][m][n] = __builtin_amdgcn_mfma_f32_16x16x32_bf16(Bt[n][k], At[m][k], acc[ai][bj][m][n], 0, 0, 0); __builtin_amdgcn_s_setprio(0); } while (0)
; #define PG8_WAIT_V(n) asm volatile("s_waitcnt vmcnt(" #n ")" ::: "memory")
; #define PG8_WAIT_L(n) asm volatile("s_waitcnt lgkmcnt(" #n ")" ::: "memory")
; #define PG8_BAR __builtin_amdgcn_s_barrier()
; #define PG8_SCHED __builtin_amdgcn_sched_barrier(0)
; template <class Epi, class Sched, bool ALIGN_EPI = false, bool SP2 = false>
; __device__ __forceinline__ void gemm_phase(PG8_LAS unsigned char* lds, const Gemm g, const Sched S, const Epi E) {
;     ...
;             PG8_WAIT_V(8); PG8_WAIT_L(0); PG8_BAR; PG8_MMA(1, 0, At, B0); PG8_MMA(1, 1, At, B1); PG8_BAR; PG8_SCHED;
;             PG8_LDB(B0, 1, 0); PG8_LDB(B1, 1, 1); PG8_SCHED; PG8_LDA(At, 1, 0); PG8_STAGE(PG8_SA(0, 1), a2 + hstepA, voffA);
;             PG8_WAIT_V(8); PG8_WAIT_L(0); PG8_BAR; PG8_MMA(0, 0, At, B0); PG8_MMA(0, 1, At, B1); PG8_BAR; PG8_SCHED;
	s_setprio 1
	s_waitcnt lgkmcnt(0)
	v_mfma_f32_16x16x32_bf16 v[60:63], v[152:155], v[186:189], v[60:63]
	v_mfma_f32_16x16x32_bf16 v[56:59], v[162:165], v[186:189], v[56:59]
	v_mfma_f32_16x16x32_bf16 v[44:47], v[152:155], v[194:197], v[44:47]
	v_mfma_f32_16x16x32_bf16 v[40:43], v[162:165], v[194:197], v[40:43]
	v_mfma_f32_16x16x32_bf16 v[28:31], v[152:155], v[206:209], v[28:31]
	v_mfma_f32_16x16x32_bf16 v[24:27], v[162:165], v[206:209], v[24:27]
	v_mfma_f32_16x16x32_bf16 v[12:15], v[152:155], v[214:217], v[12:15]
	v_mfma_f32_16x16x32_bf16 v[8:11], v[162:165], v[214:217], v[8:11]
	v_mfma_f32_16x16x32_bf16 v[60:63], v[156:159], v[190:193], v[60:63]
	v_mfma_f32_16x16x32_bf16 v[56:59], v[166:169], v[190:193], v[56:59]
	v_mfma_f32_16x16x32_bf16 v[44:47], v[156:159], v[198:201], v[44:47]
	v_mfma_f32_16x16x32_bf16 v[40:43], v[166:169], v[198:201], v[40:43]
	v_mfma_f32_16x16x32_bf16 v[28:31], v[156:159], v[210:213], v[28:31]
	v_mfma_f32_16x16x32_bf16 v[24:27], v[166:169], v[210:213], v[24:27]
	v_mfma_f32_16x16x32_bf16 v[12:15], v[156:159], v[218:221], v[12:15]
	v_mfma_f32_16x16x32_bf16 v[8:11], v[166:169], v[218:221], v[8:11]
	s_setprio 0
	s_setprio 1
	v_mfma_f32_16x16x32_bf16 v[52:55], v[170:173], v[186:189], v[52:55]
	v_mfma_f32_16x16x32_bf16 v[48:51], v[178:181], v[186:189], v[48:51]
	v_mfma_f32_16x16x32_bf16 v[36:39], v[170:173], v[194:197], v[36:39]
	v_mfma_f32_16x16x32_bf16 v[32:35], v[178:181], v[194:197], v[32:35]
	v_mfma_f32_16x16x32_bf16 v[20:23], v[170:173], v[206:209], v[20:23]
	v_mfma_f32_16x16x32_bf16 v[16:19], v[178:181], v[206:209], v[16:19]
	v_mfma_f32_16x16x32_bf16 v[4:7], v[170:173], v[214:217], v[4:7]
	v_mfma_f32_16x16x32_bf16 v[0:3], v[178:181], v[214:217], v[0:3]
	v_mfma_f32_16x16x32_bf16 v[52:55], v[174:177], v[190:193], v[52:55]
	v_mfma_f32_16x16x32_bf16 v[48:51], v[182:185], v[190:193], v[48:51]
	v_mfma_f32_16x16x32_bf16 v[36:39], v[174:177], v[198:201], v[36:39]
	v_mfma_f32_16x16x32_bf16 v[32:35], v[182:185], v[198:201], v[32:35]
	v_mfma_f32_16x16x32_bf16 v[20:23], v[174:177], v[210:213], v[20:23]
	v_mfma_f32_16x16x32_bf16 v[16:19], v[182:185], v[210:213], v[16:19]
	v_mfma_f32_16x16x32_bf16 v[4:7], v[174:177], v[218:221], v[4:7]
	v_mfma_f32_16x16x32_bf16 v[0:3], v[182:185], v[218:221], v[0:3]
	s_setprio 0
	s_barrier
	s_add_i32 s81, 0, 0x18000
	v_add_u32_e32 v161, s81, v148
	s_add_i32 s82, 0, 0x1c000
	ds_read_b128 v[152:155], v161
	ds_read_b128 v[156:159], v161 offset:1024
	ds_read_b128 v[162:165], v161 offset:2048
	ds_read_b128 v[166:169], v161 offset:3072
	v_add_u32_e32 v161, s82, v148
	ds_read_b128 v[170:173], v161
	ds_read_b128 v[174:177], v161 offset:1024
	ds_read_b128 v[178:181], v161 offset:2048
	ds_read_b128 v[182:185], v161 offset:3072
	s_add_u32 s70, s70, 0x40000
	s_addc_u32 s71, s71, 0
	s_mov_b32 m0, s33
	v_lshl_add_u64 v[226:227], s[70:71], 0, v[134:135]
	ds_read_b128 v[186:189], v151 offset:32768
	ds_read_b128 v[190:193], v151 offset:33792
	ds_read_b128 v[194:197], v151 offset:34816
	ds_read_b128 v[198:201], v151 offset:35840
	ds_read_b128 v[206:209], v151 offset:36864
	ds_read_b128 v[210:213], v151 offset:37888
	ds_read_b128 v[214:217], v151 offset:38912
	ds_read_b128 v[218:221], v151 offset:39936
	global_load_lds_dwordx4 v[226:227], off
	v_lshl_add_u64 v[226:227], s[70:71], 0, v[130:131]
	s_mov_b32 m0, s45
	s_nop 0
	global_load_lds_dwordx4 v[226:227], off
	s_waitcnt vmcnt(8)
	s_waitcnt lgkmcnt(0)
	s_barrier
	s_setprio 1
	s_waitcnt lgkmcnt(0)
	v_mfma_f32_16x16x32_bf16 v[124:127], v[152:155], v[186:189], v[124:127]
	v_mfma_f32_16x16x32_bf16 v[120:123], v[162:165], v[186:189], v[120:123]
	v_mfma_f32_16x16x32_bf16 v[108:111], v[152:155], v[194:197], v[108:111]
	v_mfma_f32_16x16x32_bf16 v[104:107], v[162:165], v[194:197], v[104:107]
	v_mfma_f32_16x16x32_bf16 v[92:95], v[152:155], v[206:209], v[92:95]
	v_mfma_f32_16x16x32_bf16 v[88:91], v[162:165], v[206:209], v[88:91]
	v_mfma_f32_16x16x32_bf16 v[76:79], v[152:155], v[214:217], v[76:79]
	v_mfma_f32_16x16x32_bf16 v[72:75], v[162:165], v[214:217], v[72:75]
	v_mfma_f32_16x16x32_bf16 v[124:127], v[156:159], v[190:193], v[124:127]
	v_mfma_f32_16x16x32_bf16 v[120:123], v[166:169], v[190:193], v[120:123]
	v_mfma_f32_16x16x32_bf16 v[108:111], v[156:159], v[198:201], v[108:111]
	v_mfma_f32_16x16x32_bf16 v[104:107], v[166:169], v[198:201], v[104:107]
	v_mfma_f32_16x16x32_bf16 v[92:95], v[156:159], v[210:213], v[92:95]
	v_mfma_f32_16x16x32_bf16 v[88:91], v[166:169], v[210:213], v[88:91]
	v_mfma_f32_16x16x32_bf16 v[76:79], v[156:159], v[218:221], v[76:79]
	v_mfma_f32_16x16x32_bf16 v[72:75], v[166:169], v[218:221], v[72:75]
	s_setprio 0
	s_setprio 1
	v_mfma_f32_16x16x32_bf16 v[116:119], v[170:173], v[186:189], v[116:119]
	v_mfma_f32_16x16x32_bf16 v[112:115], v[178:181], v[186:189], v[112:115]
	v_mfma_f32_16x16x32_bf16 v[100:103], v[170:173], v[194:197], v[100:103]
	v_mfma_f32_16x16x32_bf16 v[96:99], v[178:181], v[194:197], v[96:99]
	v_mfma_f32_16x16x32_bf16 v[84:87], v[170:173], v[206:209], v[84:87]
	v_mfma_f32_16x16x32_bf16 v[80:83], v[178:181], v[206:209], v[80:83]
	v_mfma_f32_16x16x32_bf16 v[68:71], v[170:173], v[214:217], v[68:71]
	v_mfma_f32_16x16x32_bf16 v[64:67], v[178:181], v[214:217], v[64:67]
	v_mfma_f32_16x16x32_bf16 v[116:119], v[174:177], v[190:193], v[116:119]
	v_mfma_f32_16x16x32_bf16 v[112:115], v[182:185], v[190:193], v[112:115]
	v_mfma_f32_16x16x32_bf16 v[100:103], v[174:177], v[198:201], v[100:103]
	v_mfma_f32_16x16x32_bf16 v[96:99], v[182:185], v[198:201], v[96:99]
	v_mfma_f32_16x16x32_bf16 v[84:87], v[174:177], v[210:213], v[84:87]
	v_mfma_f32_16x16x32_bf16 v[80:83], v[182:185], v[210:213], v[80:83]
	v_mfma_f32_16x16x32_bf16 v[68:71], v[174:177], v[218:221], v[68:71]
	v_mfma_f32_16x16x32_bf16 v[64:67], v[182:185], v[218:221], v[64:67]
	s_setprio 0
	s_barrier
; #define PG8_STAGE(bufoff, gbase, voff) do { _Pragma("unroll") for (int _i = 0; _i < 2; ++_i) \
;         __builtin_amdgcn_global_load_lds((const unsigned*)((const char*)(gbase) + (voff)[_i]), (PG8_LAS unsigned*)(lds + (bufoff) + ldsw + _i * 8192), 16, 0, 0); } while (0)
; #define PG8_LDA(dst, b, h) do { _Pragma("unroll") for (int m = 0; m < 4; ++m) _Pragma("unroll") for (int k = 0; k < 2; ++k) dst[m][k] = *(const PG8_LAS bf16x8*)(lds + PG8_SA(b, h) + aoff + m * 2048 + k * 1024); } while (0)
; #define PG8_MMA(ai, bj, At, Bt) do { __builtin_amdgcn_s_setprio(1); _Pragma("unroll") for (int m = 0; m < 4; ++m) _Pragma("unroll") for (int n = 0; n < 2; ++n) _Pragma("unroll") for (int k = 0; k < 2; ++k) \
;         acc[ai][bj][m][n] = __builtin_amdgcn_mfma_f32_16x16x32_bf16(Bt[n][k], At[m][k], acc[ai][bj][m][n], 0, 0, 0); __builtin_amdgcn_s_setprio(0); } while (0)
; #define PG8_WAIT_V(n) asm volatile("s_waitcnt vmcnt(" #n ")" ::: "memory")
; #define PG8_WAIT_L(n) asm volatile("s_waitcnt lgkmcnt(" #n ")" ::: "memory")
; #define PG8_BAR __builtin_amdgcn_s_barrier()
; #define PG8_SCHED __builtin_amdgcn_sched_barrier(0)
; template <class Epi, class Sched, bool ALIGN_EPI = false, bool SP2 = false>
; __device__ __forceinline__ void gemm_phase(PG8_LAS unsigned char* lds, const Gemm g, const Sched S, const Epi E) {
;     ...
;         for (int t = 0; t < nt; t += 2) {
;     ...
;             PG8_LDA(At, 1, 1); PG8_STAGE(PG8_SB(1, 0), b3, voffB); PG8_STAGE(PG8_SB(1, 1), b3 + hstep, voffB); PG8_STAGE(PG8_SA(1, 0), a3, voffA);
;             PG8_WAIT_V(8); PG8_WAIT_L(0); PG8_BAR; PG8_MMA(1, 0, At, B0); PG8_MMA(1, 1, At, B1); PG8_BAR; PG8_SCHED;
	s_add_i32 s70, s81, s4
	v_lshl_add_u64 v[144:145], v[144:145], 0, s[12:13]
	s_mov_b32 m0, s70
	ds_read_b128 v[186:189], v151 offset:49152
	ds_read_b128 v[190:193], v151 offset:50176
	ds_read_b128 v[194:197], v151 offset:51200
	ds_read_b128 v[198:201], v151 offset:52224
	ds_read_b128 v[206:209], v151 offset:53248
	ds_read_b128 v[210:213], v151 offset:54272
	ds_read_b128 v[214:217], v151 offset:55296
	ds_read_b128 v[218:221], v151 offset:56320
	global_load_lds_dwordx4 v[144:145], off
	s_add_i32 m0, s70, 0x2000
	s_add_u32 s68, s68, 0x40080
	v_lshl_add_u64 v[144:145], v[202:203], 0, s[12:13]
	s_addc_u32 s69, s69, 0
	s_add_i32 s70, s82, s4
	global_load_lds_dwordx4 v[144:145], off
	v_lshl_add_u64 v[144:145], s[68:69], 0, v[132:133]
	s_mov_b32 m0, s70
	s_nop 0
	global_load_lds_dwordx4 v[144:145], off
	v_lshl_add_u64 v[144:145], s[68:69], 0, v[128:129]
	s_add_i32 m0, s70, 0x2000
	s_nop 0
	global_load_lds_dwordx4 v[144:145], off
	v_lshl_add_u64 v[144:145], v[222:223], 0, s[12:13]
	s_mov_b32 m0, s60
	s_nop 0
	global_load_lds_dwordx4 v[144:145], off
	v_lshl_add_u64 v[144:145], v[224:225], 0, s[12:13]
	s_mov_b32 m0, s61
	s_nop 0
	global_load_lds_dwordx4 v[144:145], off
	s_waitcnt vmcnt(8)
	s_waitcnt lgkmcnt(0)
	s_barrier
	s_setprio 1
	s_waitcnt lgkmcnt(0)
	v_mfma_f32_16x16x32_bf16 v[60:63], v[152:155], v[186:189], v[60:63]
	v_mfma_f32_16x16x32_bf16 v[56:59], v[162:165], v[186:189], v[56:59]
	v_mfma_f32_16x16x32_bf16 v[44:47], v[152:155], v[194:197], v[44:47]
	v_mfma_f32_16x16x32_bf16 v[40:43], v[162:165], v[194:197], v[40:43]
	v_mfma_f32_16x16x32_bf16 v[28:31], v[152:155], v[206:209], v[28:31]
	v_mfma_f32_16x16x32_bf16 v[24:27], v[162:165], v[206:209], v[24:27]
	v_mfma_f32_16x16x32_bf16 v[12:15], v[152:155], v[214:217], v[12:15]
	v_mfma_f32_16x16x32_bf16 v[8:11], v[162:165], v[214:217], v[8:11]
	v_mfma_f32_16x16x32_bf16 v[60:63], v[156:159], v[190:193], v[60:63]
	v_mfma_f32_16x16x32_bf16 v[56:59], v[166:169], v[190:193], v[56:59]
	v_mfma_f32_16x16x32_bf16 v[44:47], v[156:159], v[198:201], v[44:47]
	v_mfma_f32_16x16x32_bf16 v[40:43], v[166:169], v[198:201], v[40:43]
	v_mfma_f32_16x16x32_bf16 v[28:31], v[156:159], v[210:213], v[28:31]
	v_mfma_f32_16x16x32_bf16 v[24:27], v[166:169], v[210:213], v[24:27]
	v_mfma_f32_16x16x32_bf16 v[12:15], v[156:159], v[218:221], v[12:15]
	v_mfma_f32_16x16x32_bf16 v[8:11], v[166:169], v[218:221], v[8:11]
	s_setprio 0
	s_setprio 1
	v_mfma_f32_16x16x32_bf16 v[52:55], v[170:173], v[186:189], v[52:55]
	v_mfma_f32_16x16x32_bf16 v[48:51], v[178:181], v[186:189], v[48:51]
	v_mfma_f32_16x16x32_bf16 v[36:39], v[170:173], v[194:197], v[36:39]
	v_mfma_f32_16x16x32_bf16 v[32:35], v[178:181], v[194:197], v[32:35]
	v_mfma_f32_16x16x32_bf16 v[20:23], v[170:173], v[206:209], v[20:23]
	v_mfma_f32_16x16x32_bf16 v[16:19], v[178:181], v[206:209], v[16:19]
	v_mfma_f32_16x16x32_bf16 v[4:7], v[170:173], v[214:217], v[4:7]
	v_mfma_f32_16x16x32_bf16 v[0:3], v[178:181], v[214:217], v[0:3]
	v_mfma_f32_16x16x32_bf16 v[52:55], v[174:177], v[190:193], v[52:55]
	v_mfma_f32_16x16x32_bf16 v[48:51], v[182:185], v[190:193], v[48:51]
	v_mfma_f32_16x16x32_bf16 v[36:39], v[174:177], v[198:201], v[36:39]
	v_mfma_f32_16x16x32_bf16 v[32:35], v[182:185], v[198:201], v[32:35]
	v_mfma_f32_16x16x32_bf16 v[20:23], v[174:177], v[210:213], v[20:23]
	v_mfma_f32_16x16x32_bf16 v[16:19], v[182:185], v[210:213], v[16:19]
	v_mfma_f32_16x16x32_bf16 v[4:7], v[174:177], v[218:221], v[4:7]
	v_mfma_f32_16x16x32_bf16 v[0:3], v[182:185], v[218:221], v[0:3]
	s_setprio 0
	s_add_i32 s80, s80, 2
	s_add_u32 s46, s46, 0x100
	s_addc_u32 s47, s47, 0
	s_add_u32 s78, s78, 0x100
	s_addc_u32 s79, s79, 0
	s_cmp_gt_u32 s80, 13
	s_barrier
	s_cbranch_scc0 .LBB0_2079
	s_and_b64 vcc, exec, s[26:27]
	s_cbranch_vccz .LBB0_2082
	s_barrier

; #define PG8_STAGE(bufoff, gbase, voff) do { _Pragma("unroll") for (int _i = 0; _i < 2; ++_i) \
;         __builtin_amdgcn_global_load_lds((const unsigned*)((const char*)(gbase) + (voff)[_i]), (PG8_LAS unsigned*)(lds + (bufoff) + ldsw + _i * 8192), 16, 0, 0); } while (0)
; #define PG8_LDA(dst, b, h) do { _Pragma("unroll") for (int m = 0; m < 4; ++m) _Pragma("unroll") for (int k = 0; k < 2; ++k) dst[m][k] = *(const PG8_LAS bf16x8*)(lds + PG8_SA(b, h) + aoff + m * 2048 + k * 1024); } while (0)
; #define PG8_LDB(dst, b, h) do { _Pragma("unroll") for (int n = 0; n < 2; ++n) _Pragma("unroll") for (int k = 0; k < 2; ++k) dst[n][k] = *(const PG8_LAS bf16x8*)(lds + PG8_SB(b, h) + boff + n * 2048 + k * 1024); } while (0)
; #define PG8_MMA(ai, bj, At, Bt) do { __builtin_amdgcn_s_setprio(1); _Pragma("unroll") for (int m = 0; m < 4; ++m) _Pragma("unroll") for (int n = 0; n < 2; ++n) _Pragma("unroll") for (int k = 0; k < 2; ++k) \
;         acc[ai][bj][m][n] = __builtin_amdgcn_mfma_f32_16x16x32_bf16(Bt[n][k], At[m][k], acc[ai][bj][m][n], 0, 0, 0); __builtin_amdgcn_s_setprio(0); } while (0)
; #define PG8_WAIT_V(n) asm volatile("s_waitcnt vmcnt(" #n ")" ::: "memory")
; #define PG8_WAIT_L(n) asm volatile("s_waitcnt lgkmcnt(" #n ")" ::: "memory")
; #define PG8_BAR __builtin_amdgcn_s_barrier()
; #define PG8_SCHED __builtin_amdgcn_sched_barrier(0)
; template <class Epi, class Sched, bool ALIGN_EPI = false, bool SP2 = false>
; __device__ __forceinline__ void gemm_phase(PG8_LAS unsigned char* lds, const Gemm g, const Sched S, const Epi E) {
;     ...
;         for (int t = 0; t < nt; t += 2) {
;             const bool last = (t == nt - 2);
;             const char* a1 = cA + (size_t)(t + 1) * kstepA;
;             const char* a2 = last ? nA : cA + (size_t)(t + 2) * kstepA; const char* b2 = last ? nB : cB + (size_t)(t + 2) * kstep;
;             const char* a3 = a2 + kstepA; const char* b3 = b2 + kstep;
;             if (last && has_next) S.a_ready(nxt);
;             if constexpr (SP2) {
;             PG8_LDB(B0, 0, 0); PG8_LDB(B1, 0, 1); PG8_SCHED; PG8_LDA(At, 0, 0); PG8_STAGE(PG8_SA(1, 1), a1 + hstepA, voffA);
;             PG8_WAIT_V(8); PG8_WAIT_L(0); PG8_BAR; PG8_MMA(0, 0, At, B0); PG8_MMA(0, 1, At, B1); PG8_BAR; PG8_SCHED;
;             PG8_LDA(At, 0, 1); PG8_STAGE(PG8_SB(0, 0), b2, voffB); PG8_STAGE(PG8_SB(0, 1), b2 + hstep, voffB); PG8_STAGE(PG8_SA(0, 0), a2, voffA);
.LBB0_2158:
	ds_read_b128 v[64:67], v188
	ds_read_b128 v[68:71], v188 offset:1024
	ds_read_b128 v[72:75], v188 offset:2048
	ds_read_b128 v[76:79], v188 offset:3072
	ds_read_b128 v[80:83], v189
	ds_read_b128 v[84:87], v189 offset:1024
	ds_read_b128 v[88:91], v189 offset:2048
	ds_read_b128 v[92:95], v189 offset:3072
	s_add_u32 s74, s72, 0xfff00080
	s_addc_u32 s75, s73, -1
	s_cmp_eq_u32 s71, 60
	s_cselect_b32 s77, s1, s75
	s_cselect_b32 s76, s45, s74
	s_cselect_b32 s75, s43, s67
	s_cselect_b32 s74, s64, s65
	v_lshl_add_u64 v[180:181], s[72:73], 0, v[166:167]
	s_add_i32 m0, s15, 0xc000
	ds_read_b128 v[174:177], v190
	ds_read_b128 v[184:187], v190 offset:1024
	ds_read_b128 v[192:195], v190 offset:2048
	ds_read_b128 v[196:199], v190 offset:3072
	ds_read_b128 v[200:203], v190 offset:4096
	ds_read_b128 v[206:209], v190 offset:5120
	ds_read_b128 v[210:213], v190 offset:6144
	ds_read_b128 v[214:217], v190 offset:7168
	global_load_lds_dwordx4 v[180:181], off
	v_lshl_add_u64 v[180:181], s[72:73], 0, v[168:169]
	s_add_i32 m0, s15, 0xe000
	s_nop 0
	global_load_lds_dwordx4 v[180:181], off
	s_waitcnt vmcnt(8)
	s_waitcnt lgkmcnt(0)
	s_barrier
	s_setprio 1
	s_waitcnt lgkmcnt(0)
	v_mfma_f32_16x16x32_bf16 v[156:159], v[64:67], v[174:177], v[156:159]
	v_mfma_f32_16x16x32_bf16 v[152:155], v[72:75], v[174:177], v[152:155]
	v_mfma_f32_16x16x32_bf16 v[140:143], v[64:67], v[192:195], v[140:143]
	v_mfma_f32_16x16x32_bf16 v[136:139], v[72:75], v[192:195], v[136:139]
	v_mfma_f32_16x16x32_bf16 v[124:127], v[64:67], v[200:203], v[124:127]
	v_mfma_f32_16x16x32_bf16 v[120:123], v[72:75], v[200:203], v[120:123]
	v_mfma_f32_16x16x32_bf16 v[108:111], v[64:67], v[210:213], v[108:111]
	v_mfma_f32_16x16x32_bf16 v[104:107], v[72:75], v[210:213], v[104:107]
	v_mfma_f32_16x16x32_bf16 v[156:159], v[68:71], v[184:187], v[156:159]
	v_mfma_f32_16x16x32_bf16 v[152:155], v[76:79], v[184:187], v[152:155]
	v_mfma_f32_16x16x32_bf16 v[140:143], v[68:71], v[196:199], v[140:143]
	v_mfma_f32_16x16x32_bf16 v[136:139], v[76:79], v[196:199], v[136:139]
	v_mfma_f32_16x16x32_bf16 v[124:127], v[68:71], v[206:209], v[124:127]
	v_mfma_f32_16x16x32_bf16 v[120:123], v[76:79], v[206:209], v[120:123]
	v_mfma_f32_16x16x32_bf16 v[108:111], v[68:71], v[214:217], v[108:111]
	v_mfma_f32_16x16x32_bf16 v[104:107], v[76:79], v[214:217], v[104:107]
	s_setprio 0
	s_setprio 1
	v_mfma_f32_16x16x32_bf16 v[148:151], v[80:83], v[174:177], v[148:151]
	v_mfma_f32_16x16x32_bf16 v[144:147], v[88:91], v[174:177], v[144:147]
	v_mfma_f32_16x16x32_bf16 v[132:135], v[80:83], v[192:195], v[132:135]
	v_mfma_f32_16x16x32_bf16 v[128:131], v[88:91], v[192:195], v[128:131]
	v_mfma_f32_16x16x32_bf16 v[116:119], v[80:83], v[200:203], v[116:119]
	v_mfma_f32_16x16x32_bf16 v[112:115], v[88:91], v[200:203], v[112:115]
	v_mfma_f32_16x16x32_bf16 v[100:103], v[80:83], v[210:213], v[100:103]
	v_mfma_f32_16x16x32_bf16 v[96:99], v[88:91], v[210:213], v[96:99]
	v_mfma_f32_16x16x32_bf16 v[148:151], v[84:87], v[184:187], v[148:151]
	v_mfma_f32_16x16x32_bf16 v[144:147], v[92:95], v[184:187], v[144:147]
	v_mfma_f32_16x16x32_bf16 v[132:135], v[84:87], v[196:199], v[132:135]
	v_mfma_f32_16x16x32_bf16 v[128:131], v[92:95], v[196:199], v[128:131]
	v_mfma_f32_16x16x32_bf16 v[116:119], v[84:87], v[206:209], v[116:119]
	v_mfma_f32_16x16x32_bf16 v[112:115], v[92:95], v[206:209], v[112:115]
	v_mfma_f32_16x16x32_bf16 v[100:103], v[84:87], v[214:217], v[100:103]
	v_mfma_f32_16x16x32_bf16 v[96:99], v[92:95], v[214:217], v[96:99]
	s_setprio 0
	s_barrier
	s_add_i32 s78, s62, s14
	v_lshl_add_u64 v[180:181], s[74:75], 0, v[162:163]
	s_mov_b32 m0, s78
	ds_read_b128 v[174:177], v190 offset:16384
	ds_read_b128 v[184:187], v190 offset:17408
	ds_read_b128 v[192:195], v190 offset:18432
	ds_read_b128 v[196:199], v190 offset:19456
	ds_read_b128 v[200:203], v190 offset:20480
	ds_read_b128 v[206:209], v190 offset:21504
	ds_read_b128 v[210:213], v190 offset:22528
	ds_read_b128 v[214:217], v190 offset:23552
	global_load_lds_dwordx4 v[180:181], off
	s_add_i32 m0, s78, 0x2000
	s_add_u32 s78, s74, 0x100000
	v_lshl_add_u64 v[218:219], s[74:75], 0, v[164:165]
	s_addc_u32 s79, s75, 0
	s_add_i32 s80, s63, s14
	global_load_lds_dwordx4 v[218:219], off
	v_lshl_add_u64 v[220:221], s[78:79], 0, v[162:163]
	s_mov_b32 m0, s80
	v_lshl_add_u64 v[222:223], s[76:77], 0, v[164:165]
	global_load_lds_dwordx4 v[220:221], off
	v_lshl_add_u64 v[220:221], s[78:79], 0, v[164:165]
	s_add_i32 m0, s80, 0x2000
	s_nop 0
	global_load_lds_dwordx4 v[220:221], off
	v_lshl_add_u64 v[220:221], s[76:77], 0, v[162:163]
	s_mov_b32 m0, s15
	s_nop 0
	global_load_lds_dwordx4 v[220:221], off
	s_mov_b32 m0, s21
	s_nop 0
	global_load_lds_dwordx4 v[222:223], off
	s_waitcnt vmcnt(8)
	s_waitcnt lgkmcnt(0)
	s_barrier
; #define PG8_STAGE(bufoff, gbase, voff) do { _Pragma("unroll") for (int _i = 0; _i < 2; ++_i) \
;         __builtin_amdgcn_global_load_lds((const unsigned*)((const char*)(gbase) + (voff)[_i]), (PG8_LAS unsigned*)(lds + (bufoff) + ldsw + _i * 8192), 16, 0, 0); } while (0)
; #define PG8_LDA(dst, b, h) do { _Pragma("unroll") for (int m = 0; m < 4; ++m) _Pragma("unroll") for (int k = 0; k < 2; ++k) dst[m][k] = *(const PG8_LAS bf16x8*)(lds + PG8_SA(b, h) + aoff + m * 2048 + k * 1024); } while (0)
; #define PG8_LDB(dst, b, h) do { _Pragma("unroll") for (int n = 0; n < 2; ++n) _Pragma("unroll") for (int k = 0; k < 2; ++k) dst[n][k] = *(const PG8_LAS bf16x8*)(lds + PG8_SB(b, h) + boff + n * 2048 + k * 1024); } while (0)
; #define PG8_MMA(ai, bj, At, Bt) do { __builtin_amdgcn_s_setprio(1); _Pragma("unroll") for (int m = 0; m < 4; ++m) _Pragma("unroll") for (int n = 0; n < 2; ++n) _Pragma("unroll") for (int k = 0; k < 2; ++k) \
;         acc[ai][bj][m][n] = __builtin_amdgcn_mfma_f32_16x16x32_bf16(Bt[n][k], At[m][k], acc[ai][bj][m][n], 0, 0, 0); __builtin_amdgcn_s_setprio(0); } while (0)
; #define PG8_WAIT_V(n) asm volatile("s_waitcnt vmcnt(" #n ")" ::: "memory")
; #define PG8_WAIT_L(n) asm volatile("s_waitcnt lgkmcnt(" #n ")" ::: "memory")
; #define PG8_BAR __builtin_amdgcn_s_barrier()
; #define PG8_SCHED __builtin_amdgcn_sched_barrier(0)
; template <class Epi, class Sched, bool ALIGN_EPI = false, bool SP2 = false>
; __device__ __forceinline__ void gemm_phase(PG8_LAS unsigned char* lds, const Gemm g, const Sched S, const Epi E) {
;     ...
;             PG8_WAIT_V(8); PG8_WAIT_L(0); PG8_BAR; PG8_MMA(1, 0, At, B0); PG8_MMA(1, 1, At, B1); PG8_BAR; PG8_SCHED;
;             PG8_LDB(B0, 1, 0); PG8_LDB(B1, 1, 1); PG8_SCHED; PG8_LDA(At, 1, 0); PG8_STAGE(PG8_SA(0, 1), a2 + hstepA, voffA);
;             PG8_WAIT_V(8); PG8_WAIT_L(0); PG8_BAR; PG8_MMA(0, 0, At, B0); PG8_MMA(0, 1, At, B1); PG8_BAR; PG8_SCHED;
	s_setprio 1
	s_waitcnt lgkmcnt(0)
	v_mfma_f32_16x16x32_bf16 v[60:63], v[64:67], v[174:177], v[60:63]
	v_mfma_f32_16x16x32_bf16 v[56:59], v[72:75], v[174:177], v[56:59]
	v_mfma_f32_16x16x32_bf16 v[44:47], v[64:67], v[192:195], v[44:47]
	v_mfma_f32_16x16x32_bf16 v[40:43], v[72:75], v[192:195], v[40:43]
	v_mfma_f32_16x16x32_bf16 v[28:31], v[64:67], v[200:203], v[28:31]
	v_mfma_f32_16x16x32_bf16 v[24:27], v[72:75], v[200:203], v[24:27]
	v_mfma_f32_16x16x32_bf16 v[12:15], v[64:67], v[210:213], v[12:15]
	v_mfma_f32_16x16x32_bf16 v[8:11], v[72:75], v[210:213], v[8:11]
	v_mfma_f32_16x16x32_bf16 v[60:63], v[68:71], v[184:187], v[60:63]
	v_mfma_f32_16x16x32_bf16 v[56:59], v[76:79], v[184:187], v[56:59]
	v_mfma_f32_16x16x32_bf16 v[44:47], v[68:71], v[196:199], v[44:47]
	v_mfma_f32_16x16x32_bf16 v[40:43], v[76:79], v[196:199], v[40:43]
	v_mfma_f32_16x16x32_bf16 v[28:31], v[68:71], v[206:209], v[28:31]
	v_mfma_f32_16x16x32_bf16 v[24:27], v[76:79], v[206:209], v[24:27]
	v_mfma_f32_16x16x32_bf16 v[12:15], v[68:71], v[214:217], v[12:15]
	v_mfma_f32_16x16x32_bf16 v[8:11], v[76:79], v[214:217], v[8:11]
	s_setprio 0
	s_setprio 1
	v_mfma_f32_16x16x32_bf16 v[52:55], v[80:83], v[174:177], v[52:55]
	v_mfma_f32_16x16x32_bf16 v[48:51], v[88:91], v[174:177], v[48:51]
	v_mfma_f32_16x16x32_bf16 v[36:39], v[80:83], v[192:195], v[36:39]
	v_mfma_f32_16x16x32_bf16 v[32:35], v[88:91], v[192:195], v[32:35]
	v_mfma_f32_16x16x32_bf16 v[20:23], v[80:83], v[200:203], v[20:23]
	v_mfma_f32_16x16x32_bf16 v[16:19], v[88:91], v[200:203], v[16:19]
	v_mfma_f32_16x16x32_bf16 v[4:7], v[80:83], v[210:213], v[4:7]
	v_mfma_f32_16x16x32_bf16 v[0:3], v[88:91], v[210:213], v[0:3]
	v_mfma_f32_16x16x32_bf16 v[52:55], v[84:87], v[184:187], v[52:55]
	v_mfma_f32_16x16x32_bf16 v[48:51], v[92:95], v[184:187], v[48:51]
	v_mfma_f32_16x16x32_bf16 v[36:39], v[84:87], v[196:199], v[36:39]
	v_mfma_f32_16x16x32_bf16 v[32:35], v[92:95], v[196:199], v[32:35]
	v_mfma_f32_16x16x32_bf16 v[20:23], v[84:87], v[206:209], v[20:23]
	v_mfma_f32_16x16x32_bf16 v[16:19], v[92:95], v[206:209], v[16:19]
	v_mfma_f32_16x16x32_bf16 v[4:7], v[84:87], v[214:217], v[4:7]
	v_mfma_f32_16x16x32_bf16 v[0:3], v[92:95], v[214:217], v[0:3]
	s_setprio 0
	s_barrier
	s_add_i32 s78, 0, 0x18000
	s_add_i32 s79, 0, 0x1c000
	v_add_u32_e32 v76, s78, v183
	v_add_u32_e32 v92, s79, v183
	ds_read_b128 v[64:67], v76
	ds_read_b128 v[68:71], v76 offset:1024
	ds_read_b128 v[72:75], v76 offset:2048
	ds_read_b128 v[76:79], v76 offset:3072
	ds_read_b128 v[80:83], v92
	ds_read_b128 v[84:87], v92 offset:1024
	ds_read_b128 v[88:91], v92 offset:2048
	ds_read_b128 v[92:95], v92 offset:3072
	s_add_u32 s76, s76, 0x100000
	s_addc_u32 s77, s77, 0
	s_mov_b32 m0, s33
	v_lshl_add_u64 v[224:225], s[76:77], 0, v[162:163]
	ds_read_b128 v[174:177], v190 offset:32768
	ds_read_b128 v[184:187], v190 offset:33792
	ds_read_b128 v[192:195], v190 offset:34816
	ds_read_b128 v[196:199], v190 offset:35840
	ds_read_b128 v[200:203], v190 offset:36864
	ds_read_b128 v[206:209], v190 offset:37888
	ds_read_b128 v[210:213], v190 offset:38912
	ds_read_b128 v[214:217], v190 offset:39936
	global_load_lds_dwordx4 v[224:225], off
	v_lshl_add_u64 v[224:225], s[76:77], 0, v[164:165]
	s_mov_b32 m0, s41
	s_nop 0
	global_load_lds_dwordx4 v[224:225], off
	s_waitcnt vmcnt(8)
	s_waitcnt lgkmcnt(0)
	s_barrier
	s_setprio 1
	s_waitcnt lgkmcnt(0)
	v_mfma_f32_16x16x32_bf16 v[156:159], v[64:67], v[174:177], v[156:159]
	v_mfma_f32_16x16x32_bf16 v[152:155], v[72:75], v[174:177], v[152:155]
	v_mfma_f32_16x16x32_bf16 v[140:143], v[64:67], v[192:195], v[140:143]
	v_mfma_f32_16x16x32_bf16 v[136:139], v[72:75], v[192:195], v[136:139]
	v_mfma_f32_16x16x32_bf16 v[124:127], v[64:67], v[200:203], v[124:127]
	v_mfma_f32_16x16x32_bf16 v[120:123], v[72:75], v[200:203], v[120:123]
	v_mfma_f32_16x16x32_bf16 v[108:111], v[64:67], v[210:213], v[108:111]
	v_mfma_f32_16x16x32_bf16 v[104:107], v[72:75], v[210:213], v[104:107]
	v_mfma_f32_16x16x32_bf16 v[156:159], v[68:71], v[184:187], v[156:159]
	v_mfma_f32_16x16x32_bf16 v[152:155], v[76:79], v[184:187], v[152:155]
	v_mfma_f32_16x16x32_bf16 v[140:143], v[68:71], v[196:199], v[140:143]
	v_mfma_f32_16x16x32_bf16 v[136:139], v[76:79], v[196:199], v[136:139]
	v_mfma_f32_16x16x32_bf16 v[124:127], v[68:71], v[206:209], v[124:127]
	v_mfma_f32_16x16x32_bf16 v[120:123], v[76:79], v[206:209], v[120:123]
	v_mfma_f32_16x16x32_bf16 v[108:111], v[68:71], v[214:217], v[108:111]
	v_mfma_f32_16x16x32_bf16 v[104:107], v[76:79], v[214:217], v[104:107]
	s_setprio 0
	s_setprio 1
	v_mfma_f32_16x16x32_bf16 v[148:151], v[80:83], v[174:177], v[148:151]
	v_mfma_f32_16x16x32_bf16 v[144:147], v[88:91], v[174:177], v[144:147]
	v_mfma_f32_16x16x32_bf16 v[132:135], v[80:83], v[192:195], v[132:135]
	v_mfma_f32_16x16x32_bf16 v[128:131], v[88:91], v[192:195], v[128:131]
	v_mfma_f32_16x16x32_bf16 v[116:119], v[80:83], v[200:203], v[116:119]
	v_mfma_f32_16x16x32_bf16 v[112:115], v[88:91], v[200:203], v[112:115]
	v_mfma_f32_16x16x32_bf16 v[100:103], v[80:83], v[210:213], v[100:103]
	v_mfma_f32_16x16x32_bf16 v[96:99], v[88:91], v[210:213], v[96:99]
	v_mfma_f32_16x16x32_bf16 v[148:151], v[84:87], v[184:187], v[148:151]
	v_mfma_f32_16x16x32_bf16 v[144:147], v[92:95], v[184:187], v[144:147]
	v_mfma_f32_16x16x32_bf16 v[132:135], v[84:87], v[196:199], v[132:135]
	v_mfma_f32_16x16x32_bf16 v[128:131], v[92:95], v[196:199], v[128:131]
	v_mfma_f32_16x16x32_bf16 v[116:119], v[84:87], v[206:209], v[116:119]
	v_mfma_f32_16x16x32_bf16 v[112:115], v[92:95], v[206:209], v[112:115]
	v_mfma_f32_16x16x32_bf16 v[100:103], v[84:87], v[214:217], v[100:103]
	v_mfma_f32_16x16x32_bf16 v[96:99], v[92:95], v[214:217], v[96:99]
	s_setprio 0
	s_barrier
; #define PG8_STAGE(bufoff, gbase, voff) do { _Pragma("unroll") for (int _i = 0; _i < 2; ++_i) \
;         __builtin_amdgcn_global_load_lds((const unsigned*)((const char*)(gbase) + (voff)[_i]), (PG8_LAS unsigned*)(lds + (bufoff) + ldsw + _i * 8192), 16, 0, 0); } while (0)
; #define PG8_LDA(dst, b, h) do { _Pragma("unroll") for (int m = 0; m < 4; ++m) _Pragma("unroll") for (int k = 0; k < 2; ++k) dst[m][k] = *(const PG8_LAS bf16x8*)(lds + PG8_SA(b, h) + aoff + m * 2048 + k * 1024); } while (0)
; #define PG8_MMA(ai, bj, At, Bt) do { __builtin_amdgcn_s_setprio(1); _Pragma("unroll") for (int m = 0; m < 4; ++m) _Pragma("unroll") for (int n = 0; n < 2; ++n) _Pragma("unroll") for (int k = 0; k < 2; ++k) \
;         acc[ai][bj][m][n] = __builtin_amdgcn_mfma_f32_16x16x32_bf16(Bt[n][k], At[m][k], acc[ai][bj][m][n], 0, 0, 0); __builtin_amdgcn_s_setprio(0); } while (0)
; #define PG8_WAIT_V(n) asm volatile("s_waitcnt vmcnt(" #n ")" ::: "memory")
; #define PG8_WAIT_L(n) asm volatile("s_waitcnt lgkmcnt(" #n ")" ::: "memory")
; #define PG8_BAR __builtin_amdgcn_s_barrier()
; #define PG8_SCHED __builtin_amdgcn_sched_barrier(0)
; template <class Epi, class Sched, bool ALIGN_EPI = false, bool SP2 = false>
; __device__ __forceinline__ void gemm_phase(PG8_LAS unsigned char* lds, const Gemm g, const Sched S, const Epi E) {
;     ...
;         for (int t = 0; t < nt; t += 2) {
;     ...
;             PG8_LDA(At, 1, 1); PG8_STAGE(PG8_SB(1, 0), b3, voffB); PG8_STAGE(PG8_SB(1, 1), b3 + hstep, voffB); PG8_STAGE(PG8_SA(1, 0), a3, voffA);
;             PG8_WAIT_V(8); PG8_WAIT_L(0); PG8_BAR; PG8_MMA(1, 0, At, B0); PG8_MMA(1, 1, At, B1); PG8_BAR; PG8_SCHED;
	s_add_i32 s76, s78, s14
	v_lshl_add_u64 v[180:181], v[180:181], 0, s[34:35]
	s_mov_b32 m0, s76
	ds_read_b128 v[174:177], v190 offset:49152
	ds_read_b128 v[184:187], v190 offset:50176
	ds_read_b128 v[192:195], v190 offset:51200
	ds_read_b128 v[196:199], v190 offset:52224
	ds_read_b128 v[200:203], v190 offset:53248
	ds_read_b128 v[206:209], v190 offset:54272
	ds_read_b128 v[210:213], v190 offset:55296
	ds_read_b128 v[214:217], v190 offset:56320
	global_load_lds_dwordx4 v[180:181], off
	s_add_i32 m0, s76, 0x2000
	s_add_u32 s74, s74, 0x100080
	v_lshl_add_u64 v[180:181], v[218:219], 0, s[34:35]
	s_addc_u32 s75, s75, 0
	s_add_i32 s76, s79, s14
	global_load_lds_dwordx4 v[180:181], off
	v_lshl_add_u64 v[180:181], s[74:75], 0, v[162:163]
	s_mov_b32 m0, s76
	s_nop 0
	global_load_lds_dwordx4 v[180:181], off
	v_lshl_add_u64 v[180:181], s[74:75], 0, v[164:165]
	s_add_i32 m0, s76, 0x2000
	s_nop 0
	global_load_lds_dwordx4 v[180:181], off
	v_lshl_add_u64 v[180:181], v[220:221], 0, s[34:35]
	s_mov_b32 m0, s60
	s_nop 0
	global_load_lds_dwordx4 v[180:181], off
	v_lshl_add_u64 v[180:181], v[222:223], 0, s[34:35]
	s_mov_b32 m0, s61
	s_nop 0
	global_load_lds_dwordx4 v[180:181], off
	s_waitcnt vmcnt(8)
	s_waitcnt lgkmcnt(0)
	s_barrier
	s_setprio 1
	s_waitcnt lgkmcnt(0)
	v_mfma_f32_16x16x32_bf16 v[60:63], v[64:67], v[174:177], v[60:63]
	v_mfma_f32_16x16x32_bf16 v[56:59], v[72:75], v[174:177], v[56:59]
	v_mfma_f32_16x16x32_bf16 v[44:47], v[64:67], v[192:195], v[44:47]
	v_mfma_f32_16x16x32_bf16 v[40:43], v[72:75], v[192:195], v[40:43]
	v_mfma_f32_16x16x32_bf16 v[28:31], v[64:67], v[200:203], v[28:31]
	v_mfma_f32_16x16x32_bf16 v[24:27], v[72:75], v[200:203], v[24:27]
	v_mfma_f32_16x16x32_bf16 v[12:15], v[64:67], v[210:213], v[12:15]
	v_mfma_f32_16x16x32_bf16 v[8:11], v[72:75], v[210:213], v[8:11]
	v_mfma_f32_16x16x32_bf16 v[60:63], v[68:71], v[184:187], v[60:63]
	v_mfma_f32_16x16x32_bf16 v[56:59], v[76:79], v[184:187], v[56:59]
	v_mfma_f32_16x16x32_bf16 v[44:47], v[68:71], v[196:199], v[44:47]
	v_mfma_f32_16x16x32_bf16 v[40:43], v[76:79], v[196:199], v[40:43]
	v_mfma_f32_16x16x32_bf16 v[28:31], v[68:71], v[206:209], v[28:31]
	v_mfma_f32_16x16x32_bf16 v[24:27], v[76:79], v[206:209], v[24:27]
	v_mfma_f32_16x16x32_bf16 v[12:15], v[68:71], v[214:217], v[12:15]
	v_mfma_f32_16x16x32_bf16 v[8:11], v[76:79], v[214:217], v[8:11]
	s_setprio 0
	s_setprio 1
	v_mfma_f32_16x16x32_bf16 v[52:55], v[80:83], v[174:177], v[52:55]
	v_mfma_f32_16x16x32_bf16 v[48:51], v[88:91], v[174:177], v[48:51]
	v_mfma_f32_16x16x32_bf16 v[36:39], v[80:83], v[192:195], v[36:39]
	v_mfma_f32_16x16x32_bf16 v[32:35], v[88:91], v[192:195], v[32:35]
	v_mfma_f32_16x16x32_bf16 v[20:23], v[80:83], v[200:203], v[20:23]
	v_mfma_f32_16x16x32_bf16 v[16:19], v[88:91], v[200:203], v[16:19]
	v_mfma_f32_16x16x32_bf16 v[4:7], v[80:83], v[210:213], v[4:7]
	v_mfma_f32_16x16x32_bf16 v[0:3], v[88:91], v[210:213], v[0:3]
	v_mfma_f32_16x16x32_bf16 v[52:55], v[84:87], v[184:187], v[52:55]
	v_mfma_f32_16x16x32_bf16 v[48:51], v[92:95], v[184:187], v[48:51]
	v_mfma_f32_16x16x32_bf16 v[36:39], v[84:87], v[196:199], v[36:39]
	v_mfma_f32_16x16x32_bf16 v[32:35], v[92:95], v[196:199], v[32:35]
	v_mfma_f32_16x16x32_bf16 v[20:23], v[84:87], v[206:209], v[20:23]
	v_mfma_f32_16x16x32_bf16 v[16:19], v[92:95], v[206:209], v[16:19]
	v_mfma_f32_16x16x32_bf16 v[4:7], v[84:87], v[214:217], v[4:7]
	v_mfma_f32_16x16x32_bf16 v[0:3], v[92:95], v[214:217], v[0:3]
	s_setprio 0
	s_add_i32 s71, s71, 2
	s_add_u32 s72, s72, 0x100
	s_addc_u32 s73, s73, 0
	s_add_u32 s65, s65, 0x100
	s_addc_u32 s67, s67, 0
	s_cmp_gt_u32 s71, 61
	s_barrier
	s_cbranch_scc0 .LBB0_2158
	s_and_b64 vcc, exec, s[36:37]
	s_cbranch_vccz .LBB0_2161
	s_barrier

; #define PG8_STAGE(bufoff, gbase, voff) do { _Pragma("unroll") for (int _i = 0; _i < 2; ++_i) \
;         __builtin_amdgcn_global_load_lds((const unsigned*)((const char*)(gbase) + (voff)[_i]), (PG8_LAS unsigned*)(lds + (bufoff) + ldsw + _i * 8192), 16, 0, 0); } while (0)
; #define PG8_LDA(dst, b, h) do { _Pragma("unroll") for (int m = 0; m < 4; ++m) _Pragma("unroll") for (int k = 0; k < 2; ++k) dst[m][k] = *(const PG8_LAS bf16x8*)(lds + PG8_SA(b, h) + aoff + m * 2048 + k * 1024); } while (0)
; #define PG8_LDB(dst, b, h) do { _Pragma("unroll") for (int n = 0; n < 2; ++n) _Pragma("unroll") for (int k = 0; k < 2; ++k) dst[n][k] = *(const PG8_LAS bf16x8*)(lds + PG8_SB(b, h) + boff + n * 2048 + k * 1024); } while (0)
; #define PG8_MMA(ai, bj, At, Bt) do { __builtin_amdgcn_s_setprio(1); _Pragma("unroll") for (int m = 0; m < 4; ++m) _Pragma("unroll") for (int n = 0; n < 2; ++n) _Pragma("unroll") for (int k = 0; k < 2; ++k) \
;         acc[ai][bj][m][n] = __builtin_amdgcn_mfma_f32_16x16x32_bf16(Bt[n][k], At[m][k], acc[ai][bj][m][n], 0, 0, 0); __builtin_amdgcn_s_setprio(0); } while (0)
; #define PG8_WAIT_V(n) asm volatile("s_waitcnt vmcnt(" #n ")" ::: "memory")
; #define PG8_WAIT_L(n) asm volatile("s_waitcnt lgkmcnt(" #n ")" ::: "memory")
; #define PG8_BAR __builtin_amdgcn_s_barrier()
; #define PG8_SCHED __builtin_amdgcn_sched_barrier(0)
; template <class Epi, class Sched, bool ALIGN_EPI = false, bool SP2 = false>
; __device__ __forceinline__ void gemm_phase(PG8_LAS unsigned char* lds, const Gemm g, const Sched S, const Epi E) {
;     ...
;         for (int t = 0; t < nt; t += 2) {
;             const bool last = (t == nt - 2);
;             const char* a1 = cA + (size_t)(t + 1) * kstepA;
;             const char* a2 = last ? nA : cA + (size_t)(t + 2) * kstepA; const char* b2 = last ? nB : cB + (size_t)(t + 2) * kstep;
;             const char* a3 = a2 + kstepA; const char* b3 = b2 + kstep;
;             if (last && has_next) S.a_ready(nxt);
;             if constexpr (SP2) {
;             PG8_LDB(B0, 0, 0); PG8_LDB(B1, 0, 1); PG8_SCHED; PG8_LDA(At, 0, 0); PG8_STAGE(PG8_SA(1, 1), a1 + hstepA, voffA);
;             PG8_WAIT_V(8); PG8_WAIT_L(0); PG8_BAR; PG8_MMA(0, 0, At, B0); PG8_MMA(0, 1, At, B1); PG8_BAR; PG8_SCHED;
;             PG8_LDA(At, 0, 1); PG8_STAGE(PG8_SB(0, 0), b2, voffB); PG8_STAGE(PG8_SB(0, 1), b2 + hstep, voffB); PG8_STAGE(PG8_SA(0, 0), a2, voffA);
.LBB0_2303:
	ds_read_b128 v[144:147], v151
	ds_read_b128 v[154:157], v151 offset:1024
	ds_read_b128 v[158:161], v151 offset:2048
	ds_read_b128 v[162:165], v151 offset:3072
	ds_read_b128 v[166:169], v152
	ds_read_b128 v[170:173], v152 offset:1024
	ds_read_b128 v[174:177], v152 offset:2048
	ds_read_b128 v[178:181], v152 offset:3072
	s_add_u32 s12, s30, 0xfffc0080
	s_addc_u32 s13, s31, -1
	s_cmp_eq_u32 s65, 12
	s_cselect_b32 s37, s23, s13
	s_cselect_b32 s36, s61, s12
	s_cselect_b32 s35, s21, s64
	s_cselect_b32 s34, s62, s63
	v_lshl_add_u64 v[202:203], s[30:31], 0, v[136:137]
	s_add_i32 m0, s14, 0xc000
	ds_read_b128 v[182:185], v153
	ds_read_b128 v[186:189], v153 offset:1024
	ds_read_b128 v[190:193], v153 offset:2048
	ds_read_b128 v[194:197], v153 offset:3072
	ds_read_b128 v[198:201], v153 offset:4096
	ds_read_b128 v[208:211], v153 offset:5120
	ds_read_b128 v[212:215], v153 offset:6144
	ds_read_b128 v[216:219], v153 offset:7168
	global_load_lds_dwordx4 v[202:203], off
	v_lshl_add_u64 v[202:203], s[30:31], 0, v[138:139]
	s_add_i32 m0, s14, 0xe000
	s_nop 0
	global_load_lds_dwordx4 v[202:203], off
	s_waitcnt vmcnt(8)
	s_waitcnt lgkmcnt(0)
	s_barrier
	s_setprio 1
	s_waitcnt lgkmcnt(0)
	v_mfma_f32_16x16x32_bf16 v[124:127], v[144:147], v[182:185], v[124:127]
	v_mfma_f32_16x16x32_bf16 v[120:123], v[158:161], v[182:185], v[120:123]
	v_mfma_f32_16x16x32_bf16 v[112:115], v[144:147], v[190:193], v[112:115]
	v_mfma_f32_16x16x32_bf16 v[104:107], v[158:161], v[190:193], v[104:107]
	v_mfma_f32_16x16x32_bf16 v[96:99], v[144:147], v[198:201], v[96:99]
	v_mfma_f32_16x16x32_bf16 v[88:91], v[158:161], v[198:201], v[88:91]
	v_mfma_f32_16x16x32_bf16 v[80:83], v[144:147], v[212:215], v[80:83]
	v_mfma_f32_16x16x32_bf16 v[72:75], v[158:161], v[212:215], v[72:75]
	v_mfma_f32_16x16x32_bf16 v[124:127], v[154:157], v[186:189], v[124:127]
	v_mfma_f32_16x16x32_bf16 v[120:123], v[162:165], v[186:189], v[120:123]
	v_mfma_f32_16x16x32_bf16 v[112:115], v[154:157], v[194:197], v[112:115]
	v_mfma_f32_16x16x32_bf16 v[104:107], v[162:165], v[194:197], v[104:107]
	v_mfma_f32_16x16x32_bf16 v[96:99], v[154:157], v[208:211], v[96:99]
	v_mfma_f32_16x16x32_bf16 v[88:91], v[162:165], v[208:211], v[88:91]
	v_mfma_f32_16x16x32_bf16 v[80:83], v[154:157], v[216:219], v[80:83]
	v_mfma_f32_16x16x32_bf16 v[72:75], v[162:165], v[216:219], v[72:75]
	s_setprio 0
	s_setprio 1
	v_mfma_f32_16x16x32_bf16 v[116:119], v[166:169], v[182:185], v[116:119]
	v_mfma_f32_16x16x32_bf16 v[108:111], v[174:177], v[182:185], v[108:111]
	v_mfma_f32_16x16x32_bf16 v[100:103], v[166:169], v[190:193], v[100:103]
	v_mfma_f32_16x16x32_bf16 v[92:95], v[174:177], v[190:193], v[92:95]
	v_mfma_f32_16x16x32_bf16 v[84:87], v[166:169], v[198:201], v[84:87]
	v_mfma_f32_16x16x32_bf16 v[76:79], v[174:177], v[198:201], v[76:79]
	v_mfma_f32_16x16x32_bf16 v[68:71], v[166:169], v[212:215], v[68:71]
	v_mfma_f32_16x16x32_bf16 v[64:67], v[174:177], v[212:215], v[64:67]
	v_mfma_f32_16x16x32_bf16 v[116:119], v[170:173], v[186:189], v[116:119]
	v_mfma_f32_16x16x32_bf16 v[108:111], v[178:181], v[186:189], v[108:111]
	v_mfma_f32_16x16x32_bf16 v[100:103], v[170:173], v[194:197], v[100:103]
	v_mfma_f32_16x16x32_bf16 v[92:95], v[178:181], v[194:197], v[92:95]
	v_mfma_f32_16x16x32_bf16 v[84:87], v[170:173], v[208:211], v[84:87]
	v_mfma_f32_16x16x32_bf16 v[76:79], v[178:181], v[208:211], v[76:79]
	v_mfma_f32_16x16x32_bf16 v[68:71], v[170:173], v[216:219], v[68:71]
	v_mfma_f32_16x16x32_bf16 v[64:67], v[178:181], v[216:219], v[64:67]
	s_setprio 0
	s_barrier
	s_add_i32 s12, s44, s4
	v_lshl_add_u64 v[202:203], s[34:35], 0, v[132:133]
	s_mov_b32 m0, s12
	ds_read_b128 v[182:185], v153 offset:16384
	ds_read_b128 v[186:189], v153 offset:17408
	ds_read_b128 v[190:193], v153 offset:18432
	ds_read_b128 v[194:197], v153 offset:19456
	ds_read_b128 v[198:201], v153 offset:20480
	ds_read_b128 v[208:211], v153 offset:21504
	ds_read_b128 v[212:215], v153 offset:22528
	ds_read_b128 v[216:219], v153 offset:23552
	global_load_lds_dwordx4 v[202:203], off
	s_add_i32 m0, s12, 0x2000
	s_add_u32 s12, s34, 0x40000
	v_lshl_add_u64 v[220:221], s[34:35], 0, v[128:129]
	s_addc_u32 s13, s35, 0
	s_add_i32 s15, s45, s4
	global_load_lds_dwordx4 v[220:221], off
	v_lshl_add_u64 v[222:223], s[12:13], 0, v[132:133]
	s_mov_b32 m0, s15
	v_lshl_add_u64 v[224:225], s[36:37], 0, v[130:131]
	global_load_lds_dwordx4 v[222:223], off
	v_lshl_add_u64 v[222:223], s[12:13], 0, v[128:129]
	s_add_i32 m0, s15, 0x2000
	s_nop 0
	global_load_lds_dwordx4 v[222:223], off
	v_lshl_add_u64 v[222:223], s[36:37], 0, v[134:135]
	s_mov_b32 m0, s14
	s_nop 0
	global_load_lds_dwordx4 v[222:223], off
	s_mov_b32 m0, s29
	s_nop 0
	global_load_lds_dwordx4 v[224:225], off
	s_waitcnt vmcnt(8)
	s_waitcnt lgkmcnt(0)
	s_barrier
; #define PG8_STAGE(bufoff, gbase, voff) do { _Pragma("unroll") for (int _i = 0; _i < 2; ++_i) \
;         __builtin_amdgcn_global_load_lds((const unsigned*)((const char*)(gbase) + (voff)[_i]), (PG8_LAS unsigned*)(lds + (bufoff) + ldsw + _i * 8192), 16, 0, 0); } while (0)
; #define PG8_LDA(dst, b, h) do { _Pragma("unroll") for (int m = 0; m < 4; ++m) _Pragma("unroll") for (int k = 0; k < 2; ++k) dst[m][k] = *(const PG8_LAS bf16x8*)(lds + PG8_SA(b, h) + aoff + m * 2048 + k * 1024); } while (0)
; #define PG8_LDB(dst, b, h) do { _Pragma("unroll") for (int n = 0; n < 2; ++n) _Pragma("unroll") for (int k = 0; k < 2; ++k) dst[n][k] = *(const PG8_LAS bf16x8*)(lds + PG8_SB(b, h) + boff + n * 2048 + k * 1024); } while (0)
; #define PG8_MMA(ai, bj, At, Bt) do { __builtin_amdgcn_s_setprio(1); _Pragma("unroll") for (int m = 0; m < 4; ++m) _Pragma("unroll") for (int n = 0; n < 2; ++n) _Pragma("unroll") for (int k = 0; k < 2; ++k) \
;         acc[ai][bj][m][n] = __builtin_amdgcn_mfma_f32_16x16x32_bf16(Bt[n][k], At[m][k], acc[ai][bj][m][n], 0, 0, 0); __builtin_amdgcn_s_setprio(0); } while (0)
; #define PG8_WAIT_V(n) asm volatile("s_waitcnt vmcnt(" #n ")" ::: "memory")
; #define PG8_WAIT_L(n) asm volatile("s_waitcnt lgkmcnt(" #n ")" ::: "memory")
; #define PG8_BAR __builtin_amdgcn_s_barrier()
; #define PG8_SCHED __builtin_amdgcn_sched_barrier(0)
; template <class Epi, class Sched, bool ALIGN_EPI = false, bool SP2 = false>
; __device__ __forceinline__ void gemm_phase(PG8_LAS unsigned char* lds, const Gemm g, const Sched S, const Epi E) {
;     ...
;             PG8_WAIT_V(8); PG8_WAIT_L(0); PG8_BAR; PG8_MMA(1, 0, At, B0); PG8_MMA(1, 1, At, B1); PG8_BAR; PG8_SCHED;
;             PG8_LDB(B0, 1, 0); PG8_LDB(B1, 1, 1); PG8_SCHED; PG8_LDA(At, 1, 0); PG8_STAGE(PG8_SA(0, 1), a2 + hstepA, voffA);
;             PG8_WAIT_V(8); PG8_WAIT_L(0); PG8_BAR; PG8_MMA(0, 0, At, B0); PG8_MMA(0, 1, At, B1); PG8_BAR; PG8_SCHED;
	s_setprio 1
	s_waitcnt lgkmcnt(0)
	v_mfma_f32_16x16x32_bf16 v[60:63], v[144:147], v[182:185], v[60:63]
	v_mfma_f32_16x16x32_bf16 v[56:59], v[158:161], v[182:185], v[56:59]
	v_mfma_f32_16x16x32_bf16 v[48:51], v[144:147], v[190:193], v[48:51]
	v_mfma_f32_16x16x32_bf16 v[40:43], v[158:161], v[190:193], v[40:43]
	v_mfma_f32_16x16x32_bf16 v[32:35], v[144:147], v[198:201], v[32:35]
	v_mfma_f32_16x16x32_bf16 v[24:27], v[158:161], v[198:201], v[24:27]
	v_mfma_f32_16x16x32_bf16 v[16:19], v[144:147], v[212:215], v[16:19]
	v_mfma_f32_16x16x32_bf16 v[8:11], v[158:161], v[212:215], v[8:11]
	v_mfma_f32_16x16x32_bf16 v[60:63], v[154:157], v[186:189], v[60:63]
	v_mfma_f32_16x16x32_bf16 v[56:59], v[162:165], v[186:189], v[56:59]
	v_mfma_f32_16x16x32_bf16 v[48:51], v[154:157], v[194:197], v[48:51]
	v_mfma_f32_16x16x32_bf16 v[40:43], v[162:165], v[194:197], v[40:43]
	v_mfma_f32_16x16x32_bf16 v[32:35], v[154:157], v[208:211], v[32:35]
	v_mfma_f32_16x16x32_bf16 v[24:27], v[162:165], v[208:211], v[24:27]
	v_mfma_f32_16x16x32_bf16 v[16:19], v[154:157], v[216:219], v[16:19]
	v_mfma_f32_16x16x32_bf16 v[8:11], v[162:165], v[216:219], v[8:11]
	s_setprio 0
	s_setprio 1
	v_mfma_f32_16x16x32_bf16 v[52:55], v[166:169], v[182:185], v[52:55]
	v_mfma_f32_16x16x32_bf16 v[44:47], v[174:177], v[182:185], v[44:47]
	v_mfma_f32_16x16x32_bf16 v[36:39], v[166:169], v[190:193], v[36:39]
	v_mfma_f32_16x16x32_bf16 v[28:31], v[174:177], v[190:193], v[28:31]
	v_mfma_f32_16x16x32_bf16 v[20:23], v[166:169], v[198:201], v[20:23]
	v_mfma_f32_16x16x32_bf16 v[12:15], v[174:177], v[198:201], v[12:15]
	v_mfma_f32_16x16x32_bf16 v[4:7], v[166:169], v[212:215], v[4:7]
	v_mfma_f32_16x16x32_bf16 v[0:3], v[174:177], v[212:215], v[0:3]
	v_mfma_f32_16x16x32_bf16 v[52:55], v[170:173], v[186:189], v[52:55]
	v_mfma_f32_16x16x32_bf16 v[44:47], v[178:181], v[186:189], v[44:47]
	v_mfma_f32_16x16x32_bf16 v[36:39], v[170:173], v[194:197], v[36:39]
	v_mfma_f32_16x16x32_bf16 v[28:31], v[178:181], v[194:197], v[28:31]
	v_mfma_f32_16x16x32_bf16 v[20:23], v[170:173], v[208:211], v[20:23]
	v_mfma_f32_16x16x32_bf16 v[12:15], v[178:181], v[208:211], v[12:15]
	v_mfma_f32_16x16x32_bf16 v[4:7], v[170:173], v[216:219], v[4:7]
	v_mfma_f32_16x16x32_bf16 v[0:3], v[178:181], v[216:219], v[0:3]
	s_setprio 0
	s_barrier
	s_add_i32 s15, 0, 0x18000
	s_add_i32 s66, 0, 0x1c000
	v_add_u32_e32 v162, s15, v150
	v_add_u32_e32 v178, s66, v150
	ds_read_b128 v[144:147], v162
	ds_read_b128 v[154:157], v162 offset:1024
	ds_read_b128 v[158:161], v162 offset:2048
	ds_read_b128 v[162:165], v162 offset:3072
	ds_read_b128 v[166:169], v178
	ds_read_b128 v[170:173], v178 offset:1024
	ds_read_b128 v[174:177], v178 offset:2048
	ds_read_b128 v[178:181], v178 offset:3072
	s_add_u32 s12, s36, 0x40000
	s_addc_u32 s13, s37, 0
	s_mov_b32 m0, s33
	v_lshl_add_u64 v[226:227], s[12:13], 0, v[134:135]
	ds_read_b128 v[182:185], v153 offset:32768
	ds_read_b128 v[186:189], v153 offset:33792
	ds_read_b128 v[190:193], v153 offset:34816
	ds_read_b128 v[194:197], v153 offset:35840
	ds_read_b128 v[198:201], v153 offset:36864
	ds_read_b128 v[208:211], v153 offset:37888
	ds_read_b128 v[212:215], v153 offset:38912
	ds_read_b128 v[216:219], v153 offset:39936
	global_load_lds_dwordx4 v[226:227], off
	v_lshl_add_u64 v[226:227], s[12:13], 0, v[130:131]
	s_mov_b32 m0, s38
	s_nop 0
	global_load_lds_dwordx4 v[226:227], off
	s_waitcnt vmcnt(8)
	s_waitcnt lgkmcnt(0)
	s_barrier
	s_setprio 1
	s_waitcnt lgkmcnt(0)
	v_mfma_f32_16x16x32_bf16 v[124:127], v[144:147], v[182:185], v[124:127]
	v_mfma_f32_16x16x32_bf16 v[120:123], v[158:161], v[182:185], v[120:123]
	v_mfma_f32_16x16x32_bf16 v[112:115], v[144:147], v[190:193], v[112:115]
	v_mfma_f32_16x16x32_bf16 v[104:107], v[158:161], v[190:193], v[104:107]
	v_mfma_f32_16x16x32_bf16 v[96:99], v[144:147], v[198:201], v[96:99]
	v_mfma_f32_16x16x32_bf16 v[88:91], v[158:161], v[198:201], v[88:91]
	v_mfma_f32_16x16x32_bf16 v[80:83], v[144:147], v[212:215], v[80:83]
	v_mfma_f32_16x16x32_bf16 v[72:75], v[158:161], v[212:215], v[72:75]
	v_mfma_f32_16x16x32_bf16 v[124:127], v[154:157], v[186:189], v[124:127]
	v_mfma_f32_16x16x32_bf16 v[120:123], v[162:165], v[186:189], v[120:123]
	v_mfma_f32_16x16x32_bf16 v[112:115], v[154:157], v[194:197], v[112:115]
	v_mfma_f32_16x16x32_bf16 v[104:107], v[162:165], v[194:197], v[104:107]
	v_mfma_f32_16x16x32_bf16 v[96:99], v[154:157], v[208:211], v[96:99]
	v_mfma_f32_16x16x32_bf16 v[88:91], v[162:165], v[208:211], v[88:91]
	v_mfma_f32_16x16x32_bf16 v[80:83], v[154:157], v[216:219], v[80:83]
	v_mfma_f32_16x16x32_bf16 v[72:75], v[162:165], v[216:219], v[72:75]
	s_setprio 0
	s_setprio 1
	v_mfma_f32_16x16x32_bf16 v[116:119], v[166:169], v[182:185], v[116:119]
	v_mfma_f32_16x16x32_bf16 v[108:111], v[174:177], v[182:185], v[108:111]
	v_mfma_f32_16x16x32_bf16 v[100:103], v[166:169], v[190:193], v[100:103]
	v_mfma_f32_16x16x32_bf16 v[92:95], v[174:177], v[190:193], v[92:95]
	v_mfma_f32_16x16x32_bf16 v[84:87], v[166:169], v[198:201], v[84:87]
	v_mfma_f32_16x16x32_bf16 v[76:79], v[174:177], v[198:201], v[76:79]
	v_mfma_f32_16x16x32_bf16 v[68:71], v[166:169], v[212:215], v[68:71]
	v_mfma_f32_16x16x32_bf16 v[64:67], v[174:177], v[212:215], v[64:67]
	v_mfma_f32_16x16x32_bf16 v[116:119], v[170:173], v[186:189], v[116:119]
	v_mfma_f32_16x16x32_bf16 v[108:111], v[178:181], v[186:189], v[108:111]
	v_mfma_f32_16x16x32_bf16 v[100:103], v[170:173], v[194:197], v[100:103]
	v_mfma_f32_16x16x32_bf16 v[92:95], v[178:181], v[194:197], v[92:95]
	v_mfma_f32_16x16x32_bf16 v[84:87], v[170:173], v[208:211], v[84:87]
	v_mfma_f32_16x16x32_bf16 v[76:79], v[178:181], v[208:211], v[76:79]
	v_mfma_f32_16x16x32_bf16 v[68:71], v[170:173], v[216:219], v[68:71]
	v_mfma_f32_16x16x32_bf16 v[64:67], v[178:181], v[216:219], v[64:67]
	s_setprio 0
	s_barrier
; #define PG8_STAGE(bufoff, gbase, voff) do { _Pragma("unroll") for (int _i = 0; _i < 2; ++_i) \
;         __builtin_amdgcn_global_load_lds((const unsigned*)((const char*)(gbase) + (voff)[_i]), (PG8_LAS unsigned*)(lds + (bufoff) + ldsw + _i * 8192), 16, 0, 0); } while (0)
; #define PG8_LDA(dst, b, h) do { _Pragma("unroll") for (int m = 0; m < 4; ++m) _Pragma("unroll") for (int k = 0; k < 2; ++k) dst[m][k] = *(const PG8_LAS bf16x8*)(lds + PG8_SA(b, h) + aoff + m * 2048 + k * 1024); } while (0)
; #define PG8_MMA(ai, bj, At, Bt) do { __builtin_amdgcn_s_setprio(1); _Pragma("unroll") for (int m = 0; m < 4; ++m) _Pragma("unroll") for (int n = 0; n < 2; ++n) _Pragma("unroll") for (int k = 0; k < 2; ++k) \
;         acc[ai][bj][m][n] = __builtin_amdgcn_mfma_f32_16x16x32_bf16(Bt[n][k], At[m][k], acc[ai][bj][m][n], 0, 0, 0); __builtin_amdgcn_s_setprio(0); } while (0)
; #define PG8_WAIT_V(n) asm volatile("s_waitcnt vmcnt(" #n ")" ::: "memory")
; #define PG8_WAIT_L(n) asm volatile("s_waitcnt lgkmcnt(" #n ")" ::: "memory")
; #define PG8_BAR __builtin_amdgcn_s_barrier()
; #define PG8_SCHED __builtin_amdgcn_sched_barrier(0)
; template <class Epi, class Sched, bool ALIGN_EPI = false, bool SP2 = false>
; __device__ __forceinline__ void gemm_phase(PG8_LAS unsigned char* lds, const Gemm g, const Sched S, const Epi E) {
;     ...
;         for (int t = 0; t < nt; t += 2) {
;             const bool last = (t == nt - 2);
;             const char* a1 = cA + (size_t)(t + 1) * kstepA;
;             const char* a2 = last ? nA : cA + (size_t)(t + 2) * kstepA; const char* b2 = last ? nB : cB + (size_t)(t + 2) * kstep;
;             const char* a3 = a2 + kstepA; const char* b3 = b2 + kstep;
;     ...
;             PG8_LDA(At, 1, 1); PG8_STAGE(PG8_SB(1, 0), b3, voffB); PG8_STAGE(PG8_SB(1, 1), b3 + hstep, voffB); PG8_STAGE(PG8_SA(1, 0), a3, voffA);
;             PG8_WAIT_V(8); PG8_WAIT_L(0); PG8_BAR; PG8_MMA(1, 0, At, B0); PG8_MMA(1, 1, At, B1); PG8_BAR; PG8_SCHED;
	s_add_i32 s12, s15, s4
	v_lshl_add_u64 v[202:203], v[202:203], 0, s[10:11]
	s_mov_b32 m0, s12
	ds_read_b128 v[182:185], v153 offset:49152
	ds_read_b128 v[186:189], v153 offset:50176
	ds_read_b128 v[190:193], v153 offset:51200
	ds_read_b128 v[194:197], v153 offset:52224
	ds_read_b128 v[198:201], v153 offset:53248
	ds_read_b128 v[208:211], v153 offset:54272
	ds_read_b128 v[212:215], v153 offset:55296
	ds_read_b128 v[216:219], v153 offset:56320
	global_load_lds_dwordx4 v[202:203], off
	s_add_i32 m0, s12, 0x2000
	s_add_u32 s12, s34, 0x40080
	v_lshl_add_u64 v[202:203], v[220:221], 0, s[10:11]
	s_addc_u32 s13, s35, 0
	s_add_i32 s15, s66, s4
	global_load_lds_dwordx4 v[202:203], off
	v_lshl_add_u64 v[202:203], s[12:13], 0, v[132:133]
	s_mov_b32 m0, s15
	s_nop 0
	global_load_lds_dwordx4 v[202:203], off
	v_lshl_add_u64 v[202:203], s[12:13], 0, v[128:129]
	s_add_i32 m0, s15, 0x2000
	s_nop 0
	global_load_lds_dwordx4 v[202:203], off
	v_lshl_add_u64 v[202:203], v[222:223], 0, s[10:11]
	s_mov_b32 m0, s42
	s_nop 0
	global_load_lds_dwordx4 v[202:203], off
	v_lshl_add_u64 v[202:203], v[224:225], 0, s[10:11]
	s_mov_b32 m0, s43
	s_nop 0
	global_load_lds_dwordx4 v[202:203], off
	s_waitcnt vmcnt(8)
	s_waitcnt lgkmcnt(0)
	s_barrier
	s_setprio 1
	s_waitcnt lgkmcnt(0)
	v_mfma_f32_16x16x32_bf16 v[60:63], v[144:147], v[182:185], v[60:63]
	v_mfma_f32_16x16x32_bf16 v[56:59], v[158:161], v[182:185], v[56:59]
	v_mfma_f32_16x16x32_bf16 v[48:51], v[144:147], v[190:193], v[48:51]
	v_mfma_f32_16x16x32_bf16 v[40:43], v[158:161], v[190:193], v[40:43]
	v_mfma_f32_16x16x32_bf16 v[32:35], v[144:147], v[198:201], v[32:35]
	v_mfma_f32_16x16x32_bf16 v[24:27], v[158:161], v[198:201], v[24:27]
	v_mfma_f32_16x16x32_bf16 v[16:19], v[144:147], v[212:215], v[16:19]
	v_mfma_f32_16x16x32_bf16 v[8:11], v[158:161], v[212:215], v[8:11]
	v_mfma_f32_16x16x32_bf16 v[60:63], v[154:157], v[186:189], v[60:63]
	v_mfma_f32_16x16x32_bf16 v[56:59], v[162:165], v[186:189], v[56:59]
	v_mfma_f32_16x16x32_bf16 v[48:51], v[154:157], v[194:197], v[48:51]
	v_mfma_f32_16x16x32_bf16 v[40:43], v[162:165], v[194:197], v[40:43]
	v_mfma_f32_16x16x32_bf16 v[32:35], v[154:157], v[208:211], v[32:35]
	v_mfma_f32_16x16x32_bf16 v[24:27], v[162:165], v[208:211], v[24:27]
	v_mfma_f32_16x16x32_bf16 v[16:19], v[154:157], v[216:219], v[16:19]
	v_mfma_f32_16x16x32_bf16 v[8:11], v[162:165], v[216:219], v[8:11]
	s_setprio 0
	s_setprio 1
	v_mfma_f32_16x16x32_bf16 v[52:55], v[166:169], v[182:185], v[52:55]
	v_mfma_f32_16x16x32_bf16 v[44:47], v[174:177], v[182:185], v[44:47]
	v_mfma_f32_16x16x32_bf16 v[36:39], v[166:169], v[190:193], v[36:39]
	v_mfma_f32_16x16x32_bf16 v[28:31], v[174:177], v[190:193], v[28:31]
	v_mfma_f32_16x16x32_bf16 v[20:23], v[166:169], v[198:201], v[20:23]
	v_mfma_f32_16x16x32_bf16 v[12:15], v[174:177], v[198:201], v[12:15]
	v_mfma_f32_16x16x32_bf16 v[4:7], v[166:169], v[212:215], v[4:7]
	v_mfma_f32_16x16x32_bf16 v[0:3], v[174:177], v[212:215], v[0:3]
	v_mfma_f32_16x16x32_bf16 v[52:55], v[170:173], v[186:189], v[52:55]
	v_mfma_f32_16x16x32_bf16 v[44:47], v[178:181], v[186:189], v[44:47]
	v_mfma_f32_16x16x32_bf16 v[36:39], v[170:173], v[194:197], v[36:39]
	v_mfma_f32_16x16x32_bf16 v[28:31], v[178:181], v[194:197], v[28:31]
	v_mfma_f32_16x16x32_bf16 v[20:23], v[170:173], v[208:211], v[20:23]
	v_mfma_f32_16x16x32_bf16 v[12:15], v[178:181], v[208:211], v[12:15]
	v_mfma_f32_16x16x32_bf16 v[4:7], v[170:173], v[216:219], v[4:7]
	v_mfma_f32_16x16x32_bf16 v[0:3], v[178:181], v[216:219], v[0:3]
	s_setprio 0
	s_add_i32 s65, s65, 2
	s_add_u32 s30, s30, 0x100
	s_addc_u32 s31, s31, 0
	s_add_u32 s63, s63, 0x100
	s_addc_u32 s64, s64, 0
	s_cmp_gt_u32 s65, 13
	s_barrier
	s_cbranch_scc0 .LBB0_2303
	s_and_b64 vcc, exec, s[18:19]
	s_cbranch_vccz .LBB0_2306
	s_barrier

; #define PG8_STAGE(bufoff, gbase, voff) do { _Pragma("unroll") for (int _i = 0; _i < 2; ++_i) \
;         __builtin_amdgcn_global_load_lds((const unsigned*)((const char*)(gbase) + (voff)[_i]), (PG8_LAS unsigned*)(lds + (bufoff) + ldsw + _i * 8192), 16, 0, 0); } while (0)
; #define PG8_LDA(dst, b, h) do { _Pragma("unroll") for (int m = 0; m < 4; ++m) _Pragma("unroll") for (int k = 0; k < 2; ++k) dst[m][k] = *(const PG8_LAS bf16x8*)(lds + PG8_SA(b, h) + aoff + m * 2048 + k * 1024); } while (0)
; #define PG8_LDB(dst, b, h) do { _Pragma("unroll") for (int n = 0; n < 2; ++n) _Pragma("unroll") for (int k = 0; k < 2; ++k) dst[n][k] = *(const PG8_LAS bf16x8*)(lds + PG8_SB(b, h) + boff + n * 2048 + k * 1024); } while (0)
; #define PG8_MMA(ai, bj, At, Bt) do { __builtin_amdgcn_s_setprio(1); _Pragma("unroll") for (int m = 0; m < 4; ++m) _Pragma("unroll") for (int n = 0; n < 2; ++n) _Pragma("unroll") for (int k = 0; k < 2; ++k) \
;         acc[ai][bj][m][n] = __builtin_amdgcn_mfma_f32_16x16x32_bf16(Bt[n][k], At[m][k], acc[ai][bj][m][n], 0, 0, 0); __builtin_amdgcn_s_setprio(0); } while (0)
; #define PG8_WAIT_V(n) asm volatile("s_waitcnt vmcnt(" #n ")" ::: "memory")
; #define PG8_WAIT_L(n) asm volatile("s_waitcnt lgkmcnt(" #n ")" ::: "memory")
; #define PG8_BAR __builtin_amdgcn_s_barrier()
; #define PG8_SCHED __builtin_amdgcn_sched_barrier(0)
; template <class Epi, class Sched, bool ALIGN_EPI = false, bool SP2 = false>
; __device__ __forceinline__ void gemm_phase(PG8_LAS unsigned char* lds, const Gemm g, const Sched S, const Epi E) {
;     ...
;             const bool last = (t == nt - 2);
;             const char* a1 = cA + (size_t)(t + 1) * kstepA;
;             const char* a2 = last ? nA : cA + (size_t)(t + 2) * kstepA; const char* b2 = last ? nB : cB + (size_t)(t + 2) * kstep;
;             const char* a3 = a2 + kstepA; const char* b3 = b2 + kstep;
;             if (last && has_next) S.a_ready(nxt);
;             if constexpr (SP2) {
;             PG8_LDB(B0, 0, 0); PG8_LDB(B1, 0, 1); PG8_SCHED; PG8_LDA(At, 0, 0); PG8_STAGE(PG8_SA(1, 1), a1 + hstepA, voffA);
;             PG8_WAIT_V(8); PG8_WAIT_L(0); PG8_BAR; PG8_MMA(0, 0, At, B0); PG8_MMA(0, 1, At, B1); PG8_BAR; PG8_SCHED;
;             PG8_LDA(At, 0, 1); PG8_STAGE(PG8_SB(0, 0), b2, voffB); PG8_STAGE(PG8_SB(0, 1), b2 + hstep, voffB); PG8_STAGE(PG8_SA(0, 0), a2, voffA);
.LBB0_2327:
	ds_read_b128 v[152:155], v149
	ds_read_b128 v[156:159], v149 offset:1024
	ds_read_b128 v[160:163], v149 offset:2048
	ds_read_b128 v[164:167], v149 offset:3072
	ds_read_b128 v[168:171], v150
	ds_read_b128 v[172:175], v150 offset:1024
	ds_read_b128 v[176:179], v150 offset:2048
	ds_read_b128 v[180:183], v150 offset:3072
	s_add_u32 s12, s42, 0xfffc0080
	s_addc_u32 s13, s43, -1
	s_cmp_eq_u32 s80, 12
	s_cselect_b32 s47, s35, s13
	s_cselect_b32 s46, s76, s12
	s_cselect_b32 s45, s31, s79
	s_cselect_b32 s44, s77, s78
	v_lshl_add_u64 v[144:145], s[42:43], 0, v[136:137]
	s_add_i32 m0, s33, 0xc000
	ds_read_b128 v[184:187], v151
	ds_read_b128 v[188:191], v151 offset:1024
	ds_read_b128 v[192:195], v151 offset:2048
	ds_read_b128 v[196:199], v151 offset:3072
	ds_read_b128 v[200:203], v151 offset:4096
	ds_read_b128 v[208:211], v151 offset:5120
	ds_read_b128 v[212:215], v151 offset:6144
	ds_read_b128 v[216:219], v151 offset:7168
	global_load_lds_dwordx4 v[144:145], off
	v_lshl_add_u64 v[144:145], s[42:43], 0, v[138:139]
	s_add_i32 m0, s33, 0xe000
	s_nop 0
	global_load_lds_dwordx4 v[144:145], off
	s_waitcnt vmcnt(8)
	s_waitcnt lgkmcnt(0)
	s_barrier
	s_setprio 1
	s_waitcnt lgkmcnt(0)
	v_mfma_f32_16x16x32_bf16 v[124:127], v[152:155], v[184:187], v[124:127]
	v_mfma_f32_16x16x32_bf16 v[120:123], v[160:163], v[184:187], v[120:123]
	v_mfma_f32_16x16x32_bf16 v[112:115], v[152:155], v[192:195], v[112:115]
	v_mfma_f32_16x16x32_bf16 v[104:107], v[160:163], v[192:195], v[104:107]
	v_mfma_f32_16x16x32_bf16 v[96:99], v[152:155], v[200:203], v[96:99]
	v_mfma_f32_16x16x32_bf16 v[88:91], v[160:163], v[200:203], v[88:91]
	v_mfma_f32_16x16x32_bf16 v[80:83], v[152:155], v[212:215], v[80:83]
	v_mfma_f32_16x16x32_bf16 v[72:75], v[160:163], v[212:215], v[72:75]
	v_mfma_f32_16x16x32_bf16 v[124:127], v[156:159], v[188:191], v[124:127]
	v_mfma_f32_16x16x32_bf16 v[120:123], v[164:167], v[188:191], v[120:123]
	v_mfma_f32_16x16x32_bf16 v[112:115], v[156:159], v[196:199], v[112:115]
	v_mfma_f32_16x16x32_bf16 v[104:107], v[164:167], v[196:199], v[104:107]
	v_mfma_f32_16x16x32_bf16 v[96:99], v[156:159], v[208:211], v[96:99]
	v_mfma_f32_16x16x32_bf16 v[88:91], v[164:167], v[208:211], v[88:91]
	v_mfma_f32_16x16x32_bf16 v[80:83], v[156:159], v[216:219], v[80:83]
	v_mfma_f32_16x16x32_bf16 v[72:75], v[164:167], v[216:219], v[72:75]
	s_setprio 0
	s_setprio 1
	v_mfma_f32_16x16x32_bf16 v[116:119], v[168:171], v[184:187], v[116:119]
	v_mfma_f32_16x16x32_bf16 v[108:111], v[176:179], v[184:187], v[108:111]
	v_mfma_f32_16x16x32_bf16 v[100:103], v[168:171], v[192:195], v[100:103]
	v_mfma_f32_16x16x32_bf16 v[92:95], v[176:179], v[192:195], v[92:95]
	v_mfma_f32_16x16x32_bf16 v[84:87], v[168:171], v[200:203], v[84:87]
	v_mfma_f32_16x16x32_bf16 v[76:79], v[176:179], v[200:203], v[76:79]
	v_mfma_f32_16x16x32_bf16 v[68:71], v[168:171], v[212:215], v[68:71]
	v_mfma_f32_16x16x32_bf16 v[64:67], v[176:179], v[212:215], v[64:67]
	v_mfma_f32_16x16x32_bf16 v[116:119], v[172:175], v[188:191], v[116:119]
	v_mfma_f32_16x16x32_bf16 v[108:111], v[180:183], v[188:191], v[108:111]
	v_mfma_f32_16x16x32_bf16 v[100:103], v[172:175], v[196:199], v[100:103]
	v_mfma_f32_16x16x32_bf16 v[92:95], v[180:183], v[196:199], v[92:95]
	v_mfma_f32_16x16x32_bf16 v[84:87], v[172:175], v[208:211], v[84:87]
	v_mfma_f32_16x16x32_bf16 v[76:79], v[180:183], v[208:211], v[76:79]
	v_mfma_f32_16x16x32_bf16 v[68:71], v[172:175], v[216:219], v[68:71]
	v_mfma_f32_16x16x32_bf16 v[64:67], v[180:183], v[216:219], v[64:67]
	s_setprio 0
	s_barrier
	s_add_i32 s12, s66, s14
	v_lshl_add_u64 v[144:145], s[44:45], 0, v[130:131]
	s_mov_b32 m0, s12
	ds_read_b128 v[184:187], v151 offset:16384
	ds_read_b128 v[188:191], v151 offset:17408
	ds_read_b128 v[192:195], v151 offset:18432
	ds_read_b128 v[196:199], v151 offset:19456
	ds_read_b128 v[200:203], v151 offset:20480
	ds_read_b128 v[208:211], v151 offset:21504
	ds_read_b128 v[212:215], v151 offset:22528
	ds_read_b128 v[216:219], v151 offset:23552
	global_load_lds_dwordx4 v[144:145], off
	s_add_i32 m0, s12, 0x2000
	s_add_u32 s12, s44, 0x40000
	v_lshl_add_u64 v[220:221], s[44:45], 0, v[134:135]
	s_addc_u32 s13, s45, 0
	s_add_i32 s15, s67, s14
	global_load_lds_dwordx4 v[220:221], off
	v_lshl_add_u64 v[222:223], s[12:13], 0, v[130:131]
	s_mov_b32 m0, s15
	v_lshl_add_u64 v[224:225], s[46:47], 0, v[132:133]
	global_load_lds_dwordx4 v[222:223], off
	v_lshl_add_u64 v[222:223], s[12:13], 0, v[134:135]
	s_add_i32 m0, s15, 0x2000
	s_nop 0
	global_load_lds_dwordx4 v[222:223], off
	v_lshl_add_u64 v[222:223], s[46:47], 0, v[128:129]
	s_mov_b32 m0, s33
	s_nop 0
	global_load_lds_dwordx4 v[222:223], off
	s_mov_b32 m0, s41
	s_nop 0
	global_load_lds_dwordx4 v[224:225], off
	s_waitcnt vmcnt(8)
	s_waitcnt lgkmcnt(0)
	s_barrier
; #define PG8_STAGE(bufoff, gbase, voff) do { _Pragma("unroll") for (int _i = 0; _i < 2; ++_i) \
;         __builtin_amdgcn_global_load_lds((const unsigned*)((const char*)(gbase) + (voff)[_i]), (PG8_LAS unsigned*)(lds + (bufoff) + ldsw + _i * 8192), 16, 0, 0); } while (0)
; #define PG8_LDA(dst, b, h) do { _Pragma("unroll") for (int m = 0; m < 4; ++m) _Pragma("unroll") for (int k = 0; k < 2; ++k) dst[m][k] = *(const PG8_LAS bf16x8*)(lds + PG8_SA(b, h) + aoff + m * 2048 + k * 1024); } while (0)
; #define PG8_LDB(dst, b, h) do { _Pragma("unroll") for (int n = 0; n < 2; ++n) _Pragma("unroll") for (int k = 0; k < 2; ++k) dst[n][k] = *(const PG8_LAS bf16x8*)(lds + PG8_SB(b, h) + boff + n * 2048 + k * 1024); } while (0)
; #define PG8_MMA(ai, bj, At, Bt) do { __builtin_amdgcn_s_setprio(1); _Pragma("unroll") for (int m = 0; m < 4; ++m) _Pragma("unroll") for (int n = 0; n < 2; ++n) _Pragma("unroll") for (int k = 0; k < 2; ++k) \
;         acc[ai][bj][m][n] = __builtin_amdgcn_mfma_f32_16x16x32_bf16(Bt[n][k], At[m][k], acc[ai][bj][m][n], 0, 0, 0); __builtin_amdgcn_s_setprio(0); } while (0)
; #define PG8_WAIT_V(n) asm volatile("s_waitcnt vmcnt(" #n ")" ::: "memory")
; #define PG8_WAIT_L(n) asm volatile("s_waitcnt lgkmcnt(" #n ")" ::: "memory")
; #define PG8_BAR __builtin_amdgcn_s_barrier()
; #define PG8_SCHED __builtin_amdgcn_sched_barrier(0)
; template <class Epi, class Sched, bool ALIGN_EPI = false, bool SP2 = false>
; __device__ __forceinline__ void gemm_phase(PG8_LAS unsigned char* lds, const Gemm g, const Sched S, const Epi E) {
;     ...
;             PG8_WAIT_V(8); PG8_WAIT_L(0); PG8_BAR; PG8_MMA(1, 0, At, B0); PG8_MMA(1, 1, At, B1); PG8_BAR; PG8_SCHED;
;             PG8_LDB(B0, 1, 0); PG8_LDB(B1, 1, 1); PG8_SCHED; PG8_LDA(At, 1, 0); PG8_STAGE(PG8_SA(0, 1), a2 + hstepA, voffA);
;             PG8_WAIT_V(8); PG8_WAIT_L(0); PG8_BAR; PG8_MMA(0, 0, At, B0); PG8_MMA(0, 1, At, B1); PG8_BAR; PG8_SCHED;
	s_setprio 1
	s_waitcnt lgkmcnt(0)
	v_mfma_f32_16x16x32_bf16 v[60:63], v[152:155], v[184:187], v[60:63]
	v_mfma_f32_16x16x32_bf16 v[56:59], v[160:163], v[184:187], v[56:59]
	v_mfma_f32_16x16x32_bf16 v[48:51], v[152:155], v[192:195], v[48:51]
	v_mfma_f32_16x16x32_bf16 v[40:43], v[160:163], v[192:195], v[40:43]
	v_mfma_f32_16x16x32_bf16 v[32:35], v[152:155], v[200:203], v[32:35]
	v_mfma_f32_16x16x32_bf16 v[24:27], v[160:163], v[200:203], v[24:27]
	v_mfma_f32_16x16x32_bf16 v[16:19], v[152:155], v[212:215], v[16:19]
	v_mfma_f32_16x16x32_bf16 v[8:11], v[160:163], v[212:215], v[8:11]
	v_mfma_f32_16x16x32_bf16 v[60:63], v[156:159], v[188:191], v[60:63]
	v_mfma_f32_16x16x32_bf16 v[56:59], v[164:167], v[188:191], v[56:59]
	v_mfma_f32_16x16x32_bf16 v[48:51], v[156:159], v[196:199], v[48:51]
	v_mfma_f32_16x16x32_bf16 v[40:43], v[164:167], v[196:199], v[40:43]
	v_mfma_f32_16x16x32_bf16 v[32:35], v[156:159], v[208:211], v[32:35]
	v_mfma_f32_16x16x32_bf16 v[24:27], v[164:167], v[208:211], v[24:27]
	v_mfma_f32_16x16x32_bf16 v[16:19], v[156:159], v[216:219], v[16:19]
	v_mfma_f32_16x16x32_bf16 v[8:11], v[164:167], v[216:219], v[8:11]
	s_setprio 0
	s_setprio 1
	v_mfma_f32_16x16x32_bf16 v[52:55], v[168:171], v[184:187], v[52:55]
	v_mfma_f32_16x16x32_bf16 v[44:47], v[176:179], v[184:187], v[44:47]
	v_mfma_f32_16x16x32_bf16 v[36:39], v[168:171], v[192:195], v[36:39]
	v_mfma_f32_16x16x32_bf16 v[28:31], v[176:179], v[192:195], v[28:31]
	v_mfma_f32_16x16x32_bf16 v[20:23], v[168:171], v[200:203], v[20:23]
	v_mfma_f32_16x16x32_bf16 v[12:15], v[176:179], v[200:203], v[12:15]
	v_mfma_f32_16x16x32_bf16 v[4:7], v[168:171], v[212:215], v[4:7]
	v_mfma_f32_16x16x32_bf16 v[0:3], v[176:179], v[212:215], v[0:3]
	v_mfma_f32_16x16x32_bf16 v[52:55], v[172:175], v[188:191], v[52:55]
	v_mfma_f32_16x16x32_bf16 v[44:47], v[180:183], v[188:191], v[44:47]
	v_mfma_f32_16x16x32_bf16 v[36:39], v[172:175], v[196:199], v[36:39]
	v_mfma_f32_16x16x32_bf16 v[28:31], v[180:183], v[196:199], v[28:31]
	v_mfma_f32_16x16x32_bf16 v[20:23], v[172:175], v[208:211], v[20:23]
	v_mfma_f32_16x16x32_bf16 v[12:15], v[180:183], v[208:211], v[12:15]
	v_mfma_f32_16x16x32_bf16 v[4:7], v[172:175], v[216:219], v[4:7]
	v_mfma_f32_16x16x32_bf16 v[0:3], v[180:183], v[216:219], v[0:3]
	s_setprio 0
	s_barrier
	s_add_i32 s15, 0, 0x18000
	s_add_i32 s18, 0, 0x1c000
	v_add_u32_e32 v164, s15, v148
	v_add_u32_e32 v180, s18, v148
	ds_read_b128 v[152:155], v164
	ds_read_b128 v[156:159], v164 offset:1024
	ds_read_b128 v[160:163], v164 offset:2048
	ds_read_b128 v[164:167], v164 offset:3072
	ds_read_b128 v[168:171], v180
	ds_read_b128 v[172:175], v180 offset:1024
	ds_read_b128 v[176:179], v180 offset:2048
	ds_read_b128 v[180:183], v180 offset:3072
	s_add_u32 s12, s46, 0x40000
	s_addc_u32 s13, s47, 0
	s_mov_b32 m0, s54
	v_lshl_add_u64 v[226:227], s[12:13], 0, v[128:129]
	ds_read_b128 v[184:187], v151 offset:32768
	ds_read_b128 v[188:191], v151 offset:33792
	ds_read_b128 v[192:195], v151 offset:34816
	ds_read_b128 v[196:199], v151 offset:35840
	ds_read_b128 v[200:203], v151 offset:36864
	ds_read_b128 v[208:211], v151 offset:37888
	ds_read_b128 v[212:215], v151 offset:38912
	ds_read_b128 v[216:219], v151 offset:39936
	global_load_lds_dwordx4 v[226:227], off
	v_lshl_add_u64 v[226:227], s[12:13], 0, v[132:133]
	s_mov_b32 m0, s55
	s_nop 0
	global_load_lds_dwordx4 v[226:227], off
	s_waitcnt vmcnt(8)
	s_waitcnt lgkmcnt(0)
	s_barrier
	s_setprio 1
	s_waitcnt lgkmcnt(0)
	v_mfma_f32_16x16x32_bf16 v[124:127], v[152:155], v[184:187], v[124:127]
	v_mfma_f32_16x16x32_bf16 v[120:123], v[160:163], v[184:187], v[120:123]
	v_mfma_f32_16x16x32_bf16 v[112:115], v[152:155], v[192:195], v[112:115]
	v_mfma_f32_16x16x32_bf16 v[104:107], v[160:163], v[192:195], v[104:107]
	v_mfma_f32_16x16x32_bf16 v[96:99], v[152:155], v[200:203], v[96:99]
	v_mfma_f32_16x16x32_bf16 v[88:91], v[160:163], v[200:203], v[88:91]
	v_mfma_f32_16x16x32_bf16 v[80:83], v[152:155], v[212:215], v[80:83]
	v_mfma_f32_16x16x32_bf16 v[72:75], v[160:163], v[212:215], v[72:75]
	v_mfma_f32_16x16x32_bf16 v[124:127], v[156:159], v[188:191], v[124:127]
	v_mfma_f32_16x16x32_bf16 v[120:123], v[164:167], v[188:191], v[120:123]
	v_mfma_f32_16x16x32_bf16 v[112:115], v[156:159], v[196:199], v[112:115]
	v_mfma_f32_16x16x32_bf16 v[104:107], v[164:167], v[196:199], v[104:107]
	v_mfma_f32_16x16x32_bf16 v[96:99], v[156:159], v[208:211], v[96:99]
	v_mfma_f32_16x16x32_bf16 v[88:91], v[164:167], v[208:211], v[88:91]
	v_mfma_f32_16x16x32_bf16 v[80:83], v[156:159], v[216:219], v[80:83]
	v_mfma_f32_16x16x32_bf16 v[72:75], v[164:167], v[216:219], v[72:75]
	s_setprio 0
	s_setprio 1
	v_mfma_f32_16x16x32_bf16 v[116:119], v[168:171], v[184:187], v[116:119]
	v_mfma_f32_16x16x32_bf16 v[108:111], v[176:179], v[184:187], v[108:111]
	v_mfma_f32_16x16x32_bf16 v[100:103], v[168:171], v[192:195], v[100:103]
	v_mfma_f32_16x16x32_bf16 v[92:95], v[176:179], v[192:195], v[92:95]
	v_mfma_f32_16x16x32_bf16 v[84:87], v[168:171], v[200:203], v[84:87]
	v_mfma_f32_16x16x32_bf16 v[76:79], v[176:179], v[200:203], v[76:79]
	v_mfma_f32_16x16x32_bf16 v[68:71], v[168:171], v[212:215], v[68:71]
	v_mfma_f32_16x16x32_bf16 v[64:67], v[176:179], v[212:215], v[64:67]
	v_mfma_f32_16x16x32_bf16 v[116:119], v[172:175], v[188:191], v[116:119]
	v_mfma_f32_16x16x32_bf16 v[108:111], v[180:183], v[188:191], v[108:111]
	v_mfma_f32_16x16x32_bf16 v[100:103], v[172:175], v[196:199], v[100:103]
	v_mfma_f32_16x16x32_bf16 v[92:95], v[180:183], v[196:199], v[92:95]
	v_mfma_f32_16x16x32_bf16 v[84:87], v[172:175], v[208:211], v[84:87]
	v_mfma_f32_16x16x32_bf16 v[76:79], v[180:183], v[208:211], v[76:79]
	v_mfma_f32_16x16x32_bf16 v[68:71], v[172:175], v[216:219], v[68:71]
	v_mfma_f32_16x16x32_bf16 v[64:67], v[180:183], v[216:219], v[64:67]
	s_setprio 0
	s_barrier
; #define PG8_STAGE(bufoff, gbase, voff) do { _Pragma("unroll") for (int _i = 0; _i < 2; ++_i) \
;         __builtin_amdgcn_global_load_lds((const unsigned*)((const char*)(gbase) + (voff)[_i]), (PG8_LAS unsigned*)(lds + (bufoff) + ldsw + _i * 8192), 16, 0, 0); } while (0)
; #define PG8_LDA(dst, b, h) do { _Pragma("unroll") for (int m = 0; m < 4; ++m) _Pragma("unroll") for (int k = 0; k < 2; ++k) dst[m][k] = *(const PG8_LAS bf16x8*)(lds + PG8_SA(b, h) + aoff + m * 2048 + k * 1024); } while (0)
; #define PG8_MMA(ai, bj, At, Bt) do { __builtin_amdgcn_s_setprio(1); _Pragma("unroll") for (int m = 0; m < 4; ++m) _Pragma("unroll") for (int n = 0; n < 2; ++n) _Pragma("unroll") for (int k = 0; k < 2; ++k) \
;         acc[ai][bj][m][n] = __builtin_amdgcn_mfma_f32_16x16x32_bf16(Bt[n][k], At[m][k], acc[ai][bj][m][n], 0, 0, 0); __builtin_amdgcn_s_setprio(0); } while (0)
; #define PG8_WAIT_V(n) asm volatile("s_waitcnt vmcnt(" #n ")" ::: "memory")
; #define PG8_WAIT_L(n) asm volatile("s_waitcnt lgkmcnt(" #n ")" ::: "memory")
; #define PG8_BAR __builtin_amdgcn_s_barrier()
; #define PG8_SCHED __builtin_amdgcn_sched_barrier(0)
; template <class Epi, class Sched, bool ALIGN_EPI = false, bool SP2 = false>
; __device__ __forceinline__ void gemm_phase(PG8_LAS unsigned char* lds, const Gemm g, const Sched S, const Epi E) {
;     ...
;         for (int t = 0; t < nt; t += 2) {
;             const bool last = (t == nt - 2);
;             const char* a1 = cA + (size_t)(t + 1) * kstepA;
;             const char* a2 = last ? nA : cA + (size_t)(t + 2) * kstepA; const char* b2 = last ? nB : cB + (size_t)(t + 2) * kstep;
;             const char* a3 = a2 + kstepA; const char* b3 = b2 + kstep;
;     ...
;             PG8_LDA(At, 1, 1); PG8_STAGE(PG8_SB(1, 0), b3, voffB); PG8_STAGE(PG8_SB(1, 1), b3 + hstep, voffB); PG8_STAGE(PG8_SA(1, 0), a3, voffA);
;             PG8_WAIT_V(8); PG8_WAIT_L(0); PG8_BAR; PG8_MMA(1, 0, At, B0); PG8_MMA(1, 1, At, B1); PG8_BAR; PG8_SCHED;
	s_add_i32 s12, s15, s14
	v_lshl_add_u64 v[144:145], v[144:145], 0, s[8:9]
	s_mov_b32 m0, s12
	ds_read_b128 v[184:187], v151 offset:49152
	ds_read_b128 v[188:191], v151 offset:50176
	ds_read_b128 v[192:195], v151 offset:51200
	ds_read_b128 v[196:199], v151 offset:52224
	ds_read_b128 v[200:203], v151 offset:53248
	ds_read_b128 v[208:211], v151 offset:54272
	ds_read_b128 v[212:215], v151 offset:55296
	ds_read_b128 v[216:219], v151 offset:56320
	global_load_lds_dwordx4 v[144:145], off
	s_add_i32 m0, s12, 0x2000
	s_add_u32 s12, s44, 0x40080
	v_lshl_add_u64 v[144:145], v[220:221], 0, s[8:9]
	s_addc_u32 s13, s45, 0
	s_add_i32 s15, s18, s14
	global_load_lds_dwordx4 v[144:145], off
	v_lshl_add_u64 v[144:145], s[12:13], 0, v[130:131]
	s_mov_b32 m0, s15
	s_nop 0
	global_load_lds_dwordx4 v[144:145], off
	v_lshl_add_u64 v[144:145], s[12:13], 0, v[134:135]
	s_add_i32 m0, s15, 0x2000
	s_nop 0
	global_load_lds_dwordx4 v[144:145], off
	v_lshl_add_u64 v[144:145], v[222:223], 0, s[8:9]
	s_mov_b32 m0, s64
	s_nop 0
	global_load_lds_dwordx4 v[144:145], off
	v_lshl_add_u64 v[144:145], v[224:225], 0, s[8:9]
	s_mov_b32 m0, s65
	s_nop 0
	global_load_lds_dwordx4 v[144:145], off
	s_waitcnt vmcnt(8)
	s_waitcnt lgkmcnt(0)
	s_barrier
	s_setprio 1
	s_waitcnt lgkmcnt(0)
	v_mfma_f32_16x16x32_bf16 v[60:63], v[152:155], v[184:187], v[60:63]
	v_mfma_f32_16x16x32_bf16 v[56:59], v[160:163], v[184:187], v[56:59]
	v_mfma_f32_16x16x32_bf16 v[48:51], v[152:155], v[192:195], v[48:51]
	v_mfma_f32_16x16x32_bf16 v[40:43], v[160:163], v[192:195], v[40:43]
	v_mfma_f32_16x16x32_bf16 v[32:35], v[152:155], v[200:203], v[32:35]
	v_mfma_f32_16x16x32_bf16 v[24:27], v[160:163], v[200:203], v[24:27]
	v_mfma_f32_16x16x32_bf16 v[16:19], v[152:155], v[212:215], v[16:19]
	v_mfma_f32_16x16x32_bf16 v[8:11], v[160:163], v[212:215], v[8:11]
	v_mfma_f32_16x16x32_bf16 v[60:63], v[156:159], v[188:191], v[60:63]
	v_mfma_f32_16x16x32_bf16 v[56:59], v[164:167], v[188:191], v[56:59]
	v_mfma_f32_16x16x32_bf16 v[48:51], v[156:159], v[196:199], v[48:51]
	v_mfma_f32_16x16x32_bf16 v[40:43], v[164:167], v[196:199], v[40:43]
	v_mfma_f32_16x16x32_bf16 v[32:35], v[156:159], v[208:211], v[32:35]
	v_mfma_f32_16x16x32_bf16 v[24:27], v[164:167], v[208:211], v[24:27]
	v_mfma_f32_16x16x32_bf16 v[16:19], v[156:159], v[216:219], v[16:19]
	v_mfma_f32_16x16x32_bf16 v[8:11], v[164:167], v[216:219], v[8:11]
	s_setprio 0
	s_setprio 1
	v_mfma_f32_16x16x32_bf16 v[52:55], v[168:171], v[184:187], v[52:55]
	v_mfma_f32_16x16x32_bf16 v[44:47], v[176:179], v[184:187], v[44:47]
	v_mfma_f32_16x16x32_bf16 v[36:39], v[168:171], v[192:195], v[36:39]
	v_mfma_f32_16x16x32_bf16 v[28:31], v[176:179], v[192:195], v[28:31]
	v_mfma_f32_16x16x32_bf16 v[20:23], v[168:171], v[200:203], v[20:23]
	v_mfma_f32_16x16x32_bf16 v[12:15], v[176:179], v[200:203], v[12:15]
	v_mfma_f32_16x16x32_bf16 v[4:7], v[168:171], v[212:215], v[4:7]
	v_mfma_f32_16x16x32_bf16 v[0:3], v[176:179], v[212:215], v[0:3]
	v_mfma_f32_16x16x32_bf16 v[52:55], v[172:175], v[188:191], v[52:55]
	v_mfma_f32_16x16x32_bf16 v[44:47], v[180:183], v[188:191], v[44:47]
	v_mfma_f32_16x16x32_bf16 v[36:39], v[172:175], v[196:199], v[36:39]
	v_mfma_f32_16x16x32_bf16 v[28:31], v[180:183], v[196:199], v[28:31]
	v_mfma_f32_16x16x32_bf16 v[20:23], v[172:175], v[208:211], v[20:23]
	v_mfma_f32_16x16x32_bf16 v[12:15], v[180:183], v[208:211], v[12:15]
	v_mfma_f32_16x16x32_bf16 v[4:7], v[172:175], v[216:219], v[4:7]
	v_mfma_f32_16x16x32_bf16 v[0:3], v[180:183], v[216:219], v[0:3]
	s_setprio 0
	s_add_i32 s80, s80, 2
	s_add_u32 s42, s42, 0x100
	s_addc_u32 s43, s43, 0
	s_add_u32 s78, s78, 0x100
	s_addc_u32 s79, s79, 0
	s_cmp_gt_u32 s80, 13
	s_barrier
	s_cbranch_scc0 .LBB0_2327
	s_and_b64 vcc, exec, s[10:11]
	s_cbranch_vccz .LBB0_2330
	s_barrier

; #define PG8_STAGE(bufoff, gbase, voff) do { _Pragma("unroll") for (int _i = 0; _i < 2; ++_i) \
;         __builtin_amdgcn_global_load_lds((const unsigned*)((const char*)(gbase) + (voff)[_i]), (PG8_LAS unsigned*)(lds + (bufoff) + ldsw + _i * 8192), 16, 0, 0); } while (0)
; #define PG8_LDA(dst, b, h) do { _Pragma("unroll") for (int m = 0; m < 4; ++m) _Pragma("unroll") for (int k = 0; k < 2; ++k) dst[m][k] = *(const PG8_LAS bf16x8*)(lds + PG8_SA(b, h) + aoff + m * 2048 + k * 1024); } while (0)
; #define PG8_LDB(dst, b, h) do { _Pragma("unroll") for (int n = 0; n < 2; ++n) _Pragma("unroll") for (int k = 0; k < 2; ++k) dst[n][k] = *(const PG8_LAS bf16x8*)(lds + PG8_SB(b, h) + boff + n * 2048 + k * 1024); } while (0)
; #define PG8_MMA(ai, bj, At, Bt) do { __builtin_amdgcn_s_setprio(1); _Pragma("unroll") for (int m = 0; m < 4; ++m) _Pragma("unroll") for (int n = 0; n < 2; ++n) _Pragma("unroll") for (int k = 0; k < 2; ++k) \
;         acc[ai][bj][m][n] = __builtin_amdgcn_mfma_f32_16x16x32_bf16(Bt[n][k], At[m][k], acc[ai][bj][m][n], 0, 0, 0); __builtin_amdgcn_s_setprio(0); } while (0)
; #define PG8_WAIT_V(n) asm volatile("s_waitcnt vmcnt(" #n ")" ::: "memory")
; #define PG8_WAIT_L(n) asm volatile("s_waitcnt lgkmcnt(" #n ")" ::: "memory")
; #define PG8_BAR __builtin_amdgcn_s_barrier()
; #define PG8_SCHED __builtin_amdgcn_sched_barrier(0)
; template <class Epi, class Sched, bool ALIGN_EPI = false, bool SP2 = false>
; __device__ __forceinline__ void gemm_phase(PG8_LAS unsigned char* lds, const Gemm g, const Sched S, const Epi E) {
;     ...
;             const bool last = (t == nt - 2);
;             const char* a1 = cA + (size_t)(t + 1) * kstepA;
;             const char* a2 = last ? nA : cA + (size_t)(t + 2) * kstepA; const char* b2 = last ? nB : cB + (size_t)(t + 2) * kstep;
;             const char* a3 = a2 + kstepA; const char* b3 = b2 + kstep;
;             if (last && has_next) S.a_ready(nxt);
;             if constexpr (SP2) {
;             PG8_LDB(B0, 0, 0); PG8_LDB(B1, 0, 1); PG8_SCHED; PG8_LDA(At, 0, 0); PG8_STAGE(PG8_SA(1, 1), a1 + hstepA, voffA);
;             PG8_WAIT_V(8); PG8_WAIT_L(0); PG8_BAR; PG8_MMA(0, 0, At, B0); PG8_MMA(0, 1, At, B1); PG8_BAR; PG8_SCHED;
;             PG8_LDA(At, 0, 1); PG8_STAGE(PG8_SB(0, 0), b2, voffB); PG8_STAGE(PG8_SB(0, 1), b2 + hstep, voffB); PG8_STAGE(PG8_SA(0, 0), a2, voffA);
.LBB0_2959:
	ds_read_b128 v[64:67], v187
	ds_read_b128 v[68:71], v187 offset:1024
	ds_read_b128 v[72:75], v187 offset:2048
	ds_read_b128 v[76:79], v187 offset:3072
	ds_read_b128 v[80:83], v188
	ds_read_b128 v[84:87], v188 offset:1024
	ds_read_b128 v[88:91], v188 offset:2048
	ds_read_b128 v[92:95], v188 offset:3072
	s_add_u32 s12, s46, 0xfffc0080
	s_addc_u32 s13, s47, -1
	s_cmp_eq_u32 s72, 12
	s_cselect_b32 s65, s1, s13
	s_cselect_b32 s64, s39, s12
	s_cselect_b32 s63, s37, s71
	s_cselect_b32 s62, s69, s70
	v_lshl_add_u64 v[178:179], s[46:47], 0, v[164:165]
	s_add_i32 m0, s33, 0xc000
	ds_read_b128 v[172:175], v189
	ds_read_b128 v[182:185], v189 offset:1024
	ds_read_b128 v[190:193], v189 offset:2048
	ds_read_b128 v[194:197], v189 offset:3072
	ds_read_b128 v[198:201], v189 offset:4096
	ds_read_b128 v[208:211], v189 offset:5120
	ds_read_b128 v[212:215], v189 offset:6144
	ds_read_b128 v[216:219], v189 offset:7168
	global_load_lds_dwordx4 v[178:179], off
	v_lshl_add_u64 v[178:179], s[46:47], 0, v[166:167]
	s_add_i32 m0, s33, 0xe000
	s_nop 0
	global_load_lds_dwordx4 v[178:179], off
	s_waitcnt vmcnt(8)
	s_waitcnt lgkmcnt(0)
	s_barrier
	s_setprio 1
	s_waitcnt lgkmcnt(0)
	v_mfma_f32_16x16x32_bf16 v[156:159], v[64:67], v[172:175], v[156:159]
	v_mfma_f32_16x16x32_bf16 v[152:155], v[72:75], v[172:175], v[152:155]
	v_mfma_f32_16x16x32_bf16 v[140:143], v[64:67], v[190:193], v[140:143]
	v_mfma_f32_16x16x32_bf16 v[136:139], v[72:75], v[190:193], v[136:139]
	v_mfma_f32_16x16x32_bf16 v[124:127], v[64:67], v[198:201], v[124:127]
	v_mfma_f32_16x16x32_bf16 v[120:123], v[72:75], v[198:201], v[120:123]
	v_mfma_f32_16x16x32_bf16 v[108:111], v[64:67], v[212:215], v[108:111]
	v_mfma_f32_16x16x32_bf16 v[104:107], v[72:75], v[212:215], v[104:107]
	v_mfma_f32_16x16x32_bf16 v[156:159], v[68:71], v[182:185], v[156:159]
	v_mfma_f32_16x16x32_bf16 v[152:155], v[76:79], v[182:185], v[152:155]
	v_mfma_f32_16x16x32_bf16 v[140:143], v[68:71], v[194:197], v[140:143]
	v_mfma_f32_16x16x32_bf16 v[136:139], v[76:79], v[194:197], v[136:139]
	v_mfma_f32_16x16x32_bf16 v[124:127], v[68:71], v[208:211], v[124:127]
	v_mfma_f32_16x16x32_bf16 v[120:123], v[76:79], v[208:211], v[120:123]
	v_mfma_f32_16x16x32_bf16 v[108:111], v[68:71], v[216:219], v[108:111]
	v_mfma_f32_16x16x32_bf16 v[104:107], v[76:79], v[216:219], v[104:107]
	s_setprio 0
	s_setprio 1
	v_mfma_f32_16x16x32_bf16 v[148:151], v[80:83], v[172:175], v[148:151]
	v_mfma_f32_16x16x32_bf16 v[144:147], v[88:91], v[172:175], v[144:147]
	v_mfma_f32_16x16x32_bf16 v[132:135], v[80:83], v[190:193], v[132:135]
	v_mfma_f32_16x16x32_bf16 v[128:131], v[88:91], v[190:193], v[128:131]
	v_mfma_f32_16x16x32_bf16 v[116:119], v[80:83], v[198:201], v[116:119]
	v_mfma_f32_16x16x32_bf16 v[112:115], v[88:91], v[198:201], v[112:115]
	v_mfma_f32_16x16x32_bf16 v[100:103], v[80:83], v[212:215], v[100:103]
	v_mfma_f32_16x16x32_bf16 v[96:99], v[88:91], v[212:215], v[96:99]
	v_mfma_f32_16x16x32_bf16 v[148:151], v[84:87], v[182:185], v[148:151]
	v_mfma_f32_16x16x32_bf16 v[144:147], v[92:95], v[182:185], v[144:147]
	v_mfma_f32_16x16x32_bf16 v[132:135], v[84:87], v[194:197], v[132:135]
	v_mfma_f32_16x16x32_bf16 v[128:131], v[92:95], v[194:197], v[128:131]
	v_mfma_f32_16x16x32_bf16 v[116:119], v[84:87], v[208:211], v[116:119]
	v_mfma_f32_16x16x32_bf16 v[112:115], v[92:95], v[208:211], v[112:115]
	v_mfma_f32_16x16x32_bf16 v[100:103], v[84:87], v[216:219], v[100:103]
	v_mfma_f32_16x16x32_bf16 v[96:99], v[92:95], v[216:219], v[96:99]
	s_setprio 0
	s_barrier
	s_add_i32 s12, s67, s4
	v_lshl_add_u64 v[178:179], s[62:63], 0, v[160:161]
	s_mov_b32 m0, s12
	ds_read_b128 v[172:175], v189 offset:16384
	ds_read_b128 v[182:185], v189 offset:17408
	ds_read_b128 v[190:193], v189 offset:18432
	ds_read_b128 v[194:197], v189 offset:19456
	ds_read_b128 v[198:201], v189 offset:20480
	ds_read_b128 v[208:211], v189 offset:21504
	ds_read_b128 v[212:215], v189 offset:22528
	ds_read_b128 v[216:219], v189 offset:23552
	global_load_lds_dwordx4 v[178:179], off
	s_add_i32 m0, s12, 0x2000
	s_add_u32 s12, s62, 0x40000
	v_lshl_add_u64 v[202:203], s[62:63], 0, v[162:163]
	s_addc_u32 s13, s63, 0
	s_add_i32 s15, s68, s4
	global_load_lds_dwordx4 v[202:203], off
	v_lshl_add_u64 v[220:221], s[12:13], 0, v[160:161]
	s_mov_b32 m0, s15
	v_lshl_add_u64 v[222:223], s[64:65], 0, v[162:163]
	global_load_lds_dwordx4 v[220:221], off
	v_lshl_add_u64 v[220:221], s[12:13], 0, v[162:163]
	s_add_i32 m0, s15, 0x2000
	s_nop 0
	global_load_lds_dwordx4 v[220:221], off
	v_lshl_add_u64 v[220:221], s[64:65], 0, v[160:161]
	s_mov_b32 m0, s33
	s_nop 0
	global_load_lds_dwordx4 v[220:221], off
	s_mov_b32 m0, s35
	s_nop 0
	global_load_lds_dwordx4 v[222:223], off
	s_waitcnt vmcnt(8)
	s_waitcnt lgkmcnt(0)
	s_barrier
; #define PG8_STAGE(bufoff, gbase, voff) do { _Pragma("unroll") for (int _i = 0; _i < 2; ++_i) \
;         __builtin_amdgcn_global_load_lds((const unsigned*)((const char*)(gbase) + (voff)[_i]), (PG8_LAS unsigned*)(lds + (bufoff) + ldsw + _i * 8192), 16, 0, 0); } while (0)
; #define PG8_LDA(dst, b, h) do { _Pragma("unroll") for (int m = 0; m < 4; ++m) _Pragma("unroll") for (int k = 0; k < 2; ++k) dst[m][k] = *(const PG8_LAS bf16x8*)(lds + PG8_SA(b, h) + aoff + m * 2048 + k * 1024); } while (0)
; #define PG8_LDB(dst, b, h) do { _Pragma("unroll") for (int n = 0; n < 2; ++n) _Pragma("unroll") for (int k = 0; k < 2; ++k) dst[n][k] = *(const PG8_LAS bf16x8*)(lds + PG8_SB(b, h) + boff + n * 2048 + k * 1024); } while (0)
; #define PG8_MMA(ai, bj, At, Bt) do { __builtin_amdgcn_s_setprio(1); _Pragma("unroll") for (int m = 0; m < 4; ++m) _Pragma("unroll") for (int n = 0; n < 2; ++n) _Pragma("unroll") for (int k = 0; k < 2; ++k) \
;         acc[ai][bj][m][n] = __builtin_amdgcn_mfma_f32_16x16x32_bf16(Bt[n][k], At[m][k], acc[ai][bj][m][n], 0, 0, 0); __builtin_amdgcn_s_setprio(0); } while (0)
; #define PG8_WAIT_V(n) asm volatile("s_waitcnt vmcnt(" #n ")" ::: "memory")
; #define PG8_WAIT_L(n) asm volatile("s_waitcnt lgkmcnt(" #n ")" ::: "memory")
; #define PG8_BAR __builtin_amdgcn_s_barrier()
; #define PG8_SCHED __builtin_amdgcn_sched_barrier(0)
; template <class Epi, class Sched, bool ALIGN_EPI = false, bool SP2 = false>
; __device__ __forceinline__ void gemm_phase(PG8_LAS unsigned char* lds, const Gemm g, const Sched S, const Epi E) {
;     ...
;             PG8_WAIT_V(8); PG8_WAIT_L(0); PG8_BAR; PG8_MMA(1, 0, At, B0); PG8_MMA(1, 1, At, B1); PG8_BAR; PG8_SCHED;
;             PG8_LDB(B0, 1, 0); PG8_LDB(B1, 1, 1); PG8_SCHED; PG8_LDA(At, 1, 0); PG8_STAGE(PG8_SA(0, 1), a2 + hstepA, voffA);
;             PG8_WAIT_V(8); PG8_WAIT_L(0); PG8_BAR; PG8_MMA(0, 0, At, B0); PG8_MMA(0, 1, At, B1); PG8_BAR; PG8_SCHED;
	s_setprio 1
	s_waitcnt lgkmcnt(0)
	v_mfma_f32_16x16x32_bf16 v[60:63], v[64:67], v[172:175], v[60:63]
	v_mfma_f32_16x16x32_bf16 v[56:59], v[72:75], v[172:175], v[56:59]
	v_mfma_f32_16x16x32_bf16 v[44:47], v[64:67], v[190:193], v[44:47]
	v_mfma_f32_16x16x32_bf16 v[40:43], v[72:75], v[190:193], v[40:43]
	v_mfma_f32_16x16x32_bf16 v[28:31], v[64:67], v[198:201], v[28:31]
	v_mfma_f32_16x16x32_bf16 v[24:27], v[72:75], v[198:201], v[24:27]
	v_mfma_f32_16x16x32_bf16 v[12:15], v[64:67], v[212:215], v[12:15]
	v_mfma_f32_16x16x32_bf16 v[8:11], v[72:75], v[212:215], v[8:11]
	v_mfma_f32_16x16x32_bf16 v[60:63], v[68:71], v[182:185], v[60:63]
	v_mfma_f32_16x16x32_bf16 v[56:59], v[76:79], v[182:185], v[56:59]
	v_mfma_f32_16x16x32_bf16 v[44:47], v[68:71], v[194:197], v[44:47]
	v_mfma_f32_16x16x32_bf16 v[40:43], v[76:79], v[194:197], v[40:43]
	v_mfma_f32_16x16x32_bf16 v[28:31], v[68:71], v[208:211], v[28:31]
	v_mfma_f32_16x16x32_bf16 v[24:27], v[76:79], v[208:211], v[24:27]
	v_mfma_f32_16x16x32_bf16 v[12:15], v[68:71], v[216:219], v[12:15]
	v_mfma_f32_16x16x32_bf16 v[8:11], v[76:79], v[216:219], v[8:11]
	s_setprio 0
	s_setprio 1
	v_mfma_f32_16x16x32_bf16 v[52:55], v[80:83], v[172:175], v[52:55]
	v_mfma_f32_16x16x32_bf16 v[48:51], v[88:91], v[172:175], v[48:51]
	v_mfma_f32_16x16x32_bf16 v[36:39], v[80:83], v[190:193], v[36:39]
	v_mfma_f32_16x16x32_bf16 v[32:35], v[88:91], v[190:193], v[32:35]
	v_mfma_f32_16x16x32_bf16 v[20:23], v[80:83], v[198:201], v[20:23]
	v_mfma_f32_16x16x32_bf16 v[16:19], v[88:91], v[198:201], v[16:19]
	v_mfma_f32_16x16x32_bf16 v[4:7], v[80:83], v[212:215], v[4:7]
	v_mfma_f32_16x16x32_bf16 v[0:3], v[88:91], v[212:215], v[0:3]
	v_mfma_f32_16x16x32_bf16 v[52:55], v[84:87], v[182:185], v[52:55]
	v_mfma_f32_16x16x32_bf16 v[48:51], v[92:95], v[182:185], v[48:51]
	v_mfma_f32_16x16x32_bf16 v[36:39], v[84:87], v[194:197], v[36:39]
	v_mfma_f32_16x16x32_bf16 v[32:35], v[92:95], v[194:197], v[32:35]
	v_mfma_f32_16x16x32_bf16 v[20:23], v[84:87], v[208:211], v[20:23]
	v_mfma_f32_16x16x32_bf16 v[16:19], v[92:95], v[208:211], v[16:19]
	v_mfma_f32_16x16x32_bf16 v[4:7], v[84:87], v[216:219], v[4:7]
	v_mfma_f32_16x16x32_bf16 v[0:3], v[92:95], v[216:219], v[0:3]
	s_setprio 0
	s_barrier
	s_add_i32 s15, 0, 0x18000
	s_add_i32 s73, 0, 0x1c000
	v_add_u32_e32 v76, s15, v186
	v_add_u32_e32 v92, s73, v186
	ds_read_b128 v[64:67], v76
	ds_read_b128 v[68:71], v76 offset:1024
	ds_read_b128 v[72:75], v76 offset:2048
	ds_read_b128 v[76:79], v76 offset:3072
	ds_read_b128 v[80:83], v92
	ds_read_b128 v[84:87], v92 offset:1024
	ds_read_b128 v[88:91], v92 offset:2048
	ds_read_b128 v[92:95], v92 offset:3072
	s_add_u32 s12, s64, 0x40000
	s_addc_u32 s13, s65, 0
	s_mov_b32 m0, s45
	v_lshl_add_u64 v[224:225], s[12:13], 0, v[160:161]
	ds_read_b128 v[172:175], v189 offset:32768
	ds_read_b128 v[182:185], v189 offset:33792
	ds_read_b128 v[190:193], v189 offset:34816
	ds_read_b128 v[194:197], v189 offset:35840
	ds_read_b128 v[198:201], v189 offset:36864
	ds_read_b128 v[208:211], v189 offset:37888
	ds_read_b128 v[212:215], v189 offset:38912
	ds_read_b128 v[216:219], v189 offset:39936
	global_load_lds_dwordx4 v[224:225], off
	v_lshl_add_u64 v[224:225], s[12:13], 0, v[162:163]
	s_mov_b32 m0, s54
	s_nop 0
	global_load_lds_dwordx4 v[224:225], off
	s_waitcnt vmcnt(8)
	s_waitcnt lgkmcnt(0)
	s_barrier
	s_setprio 1
	s_waitcnt lgkmcnt(0)
	v_mfma_f32_16x16x32_bf16 v[156:159], v[64:67], v[172:175], v[156:159]
	v_mfma_f32_16x16x32_bf16 v[152:155], v[72:75], v[172:175], v[152:155]
	v_mfma_f32_16x16x32_bf16 v[140:143], v[64:67], v[190:193], v[140:143]
	v_mfma_f32_16x16x32_bf16 v[136:139], v[72:75], v[190:193], v[136:139]
	v_mfma_f32_16x16x32_bf16 v[124:127], v[64:67], v[198:201], v[124:127]
	v_mfma_f32_16x16x32_bf16 v[120:123], v[72:75], v[198:201], v[120:123]
	v_mfma_f32_16x16x32_bf16 v[108:111], v[64:67], v[212:215], v[108:111]
	v_mfma_f32_16x16x32_bf16 v[104:107], v[72:75], v[212:215], v[104:107]
	v_mfma_f32_16x16x32_bf16 v[156:159], v[68:71], v[182:185], v[156:159]
	v_mfma_f32_16x16x32_bf16 v[152:155], v[76:79], v[182:185], v[152:155]
	v_mfma_f32_16x16x32_bf16 v[140:143], v[68:71], v[194:197], v[140:143]
	v_mfma_f32_16x16x32_bf16 v[136:139], v[76:79], v[194:197], v[136:139]
	v_mfma_f32_16x16x32_bf16 v[124:127], v[68:71], v[208:211], v[124:127]
	v_mfma_f32_16x16x32_bf16 v[120:123], v[76:79], v[208:211], v[120:123]
	v_mfma_f32_16x16x32_bf16 v[108:111], v[68:71], v[216:219], v[108:111]
	v_mfma_f32_16x16x32_bf16 v[104:107], v[76:79], v[216:219], v[104:107]
	s_setprio 0
	s_setprio 1
	v_mfma_f32_16x16x32_bf16 v[148:151], v[80:83], v[172:175], v[148:151]
	v_mfma_f32_16x16x32_bf16 v[144:147], v[88:91], v[172:175], v[144:147]
	v_mfma_f32_16x16x32_bf16 v[132:135], v[80:83], v[190:193], v[132:135]
	v_mfma_f32_16x16x32_bf16 v[128:131], v[88:91], v[190:193], v[128:131]
	v_mfma_f32_16x16x32_bf16 v[116:119], v[80:83], v[198:201], v[116:119]
	v_mfma_f32_16x16x32_bf16 v[112:115], v[88:91], v[198:201], v[112:115]
	v_mfma_f32_16x16x32_bf16 v[100:103], v[80:83], v[212:215], v[100:103]
	v_mfma_f32_16x16x32_bf16 v[96:99], v[88:91], v[212:215], v[96:99]
	v_mfma_f32_16x16x32_bf16 v[148:151], v[84:87], v[182:185], v[148:151]
	v_mfma_f32_16x16x32_bf16 v[144:147], v[92:95], v[182:185], v[144:147]
	v_mfma_f32_16x16x32_bf16 v[132:135], v[84:87], v[194:197], v[132:135]
	v_mfma_f32_16x16x32_bf16 v[128:131], v[92:95], v[194:197], v[128:131]
	v_mfma_f32_16x16x32_bf16 v[116:119], v[84:87], v[208:211], v[116:119]
	v_mfma_f32_16x16x32_bf16 v[112:115], v[92:95], v[208:211], v[112:115]
	v_mfma_f32_16x16x32_bf16 v[100:103], v[84:87], v[216:219], v[100:103]
	v_mfma_f32_16x16x32_bf16 v[96:99], v[92:95], v[216:219], v[96:99]
	s_setprio 0
	s_barrier
; #define PG8_STAGE(bufoff, gbase, voff) do { _Pragma("unroll") for (int _i = 0; _i < 2; ++_i) \
;         __builtin_amdgcn_global_load_lds((const unsigned*)((const char*)(gbase) + (voff)[_i]), (PG8_LAS unsigned*)(lds + (bufoff) + ldsw + _i * 8192), 16, 0, 0); } while (0)
; #define PG8_LDA(dst, b, h) do { _Pragma("unroll") for (int m = 0; m < 4; ++m) _Pragma("unroll") for (int k = 0; k < 2; ++k) dst[m][k] = *(const PG8_LAS bf16x8*)(lds + PG8_SA(b, h) + aoff + m * 2048 + k * 1024); } while (0)
; #define PG8_MMA(ai, bj, At, Bt) do { __builtin_amdgcn_s_setprio(1); _Pragma("unroll") for (int m = 0; m < 4; ++m) _Pragma("unroll") for (int n = 0; n < 2; ++n) _Pragma("unroll") for (int k = 0; k < 2; ++k) \
;         acc[ai][bj][m][n] = __builtin_amdgcn_mfma_f32_16x16x32_bf16(Bt[n][k], At[m][k], acc[ai][bj][m][n], 0, 0, 0); __builtin_amdgcn_s_setprio(0); } while (0)
; #define PG8_WAIT_V(n) asm volatile("s_waitcnt vmcnt(" #n ")" ::: "memory")
; #define PG8_WAIT_L(n) asm volatile("s_waitcnt lgkmcnt(" #n ")" ::: "memory")
; #define PG8_BAR __builtin_amdgcn_s_barrier()
; #define PG8_SCHED __builtin_amdgcn_sched_barrier(0)
; template <class Epi, class Sched, bool ALIGN_EPI = false, bool SP2 = false>
; __device__ __forceinline__ void gemm_phase(PG8_LAS unsigned char* lds, const Gemm g, const Sched S, const Epi E) {
;     ...
;         for (int t = 0; t < nt; t += 2) {
;             const bool last = (t == nt - 2);
;             const char* a1 = cA + (size_t)(t + 1) * kstepA;
;             const char* a2 = last ? nA : cA + (size_t)(t + 2) * kstepA; const char* b2 = last ? nB : cB + (size_t)(t + 2) * kstep;
;             const char* a3 = a2 + kstepA; const char* b3 = b2 + kstep;
;     ...
;             PG8_LDA(At, 1, 1); PG8_STAGE(PG8_SB(1, 0), b3, voffB); PG8_STAGE(PG8_SB(1, 1), b3 + hstep, voffB); PG8_STAGE(PG8_SA(1, 0), a3, voffA);
;             PG8_WAIT_V(8); PG8_WAIT_L(0); PG8_BAR; PG8_MMA(1, 0, At, B0); PG8_MMA(1, 1, At, B1); PG8_BAR; PG8_SCHED;
	s_add_i32 s12, s15, s4
	v_lshl_add_u64 v[178:179], v[178:179], 0, s[26:27]
	s_mov_b32 m0, s12
	ds_read_b128 v[172:175], v189 offset:49152
	ds_read_b128 v[182:185], v189 offset:50176
	ds_read_b128 v[190:193], v189 offset:51200
	ds_read_b128 v[194:197], v189 offset:52224
	ds_read_b128 v[198:201], v189 offset:53248
	ds_read_b128 v[208:211], v189 offset:54272
	ds_read_b128 v[212:215], v189 offset:55296
	ds_read_b128 v[216:219], v189 offset:56320
	global_load_lds_dwordx4 v[178:179], off
	s_add_i32 m0, s12, 0x2000
	s_add_u32 s12, s62, 0x40080
	v_lshl_add_u64 v[178:179], v[202:203], 0, s[26:27]
	s_addc_u32 s13, s63, 0
	s_add_i32 s15, s73, s4
	global_load_lds_dwordx4 v[178:179], off
	v_lshl_add_u64 v[178:179], s[12:13], 0, v[160:161]
	s_mov_b32 m0, s15
	s_nop 0
	global_load_lds_dwordx4 v[178:179], off
	v_lshl_add_u64 v[178:179], s[12:13], 0, v[162:163]
	s_add_i32 m0, s15, 0x2000
	s_nop 0
	global_load_lds_dwordx4 v[178:179], off
	v_lshl_add_u64 v[178:179], v[220:221], 0, s[26:27]
	s_mov_b32 m0, s61
	s_nop 0
	global_load_lds_dwordx4 v[178:179], off
	v_lshl_add_u64 v[178:179], v[222:223], 0, s[26:27]
	s_mov_b32 m0, s66
	s_nop 0
	global_load_lds_dwordx4 v[178:179], off
	s_waitcnt vmcnt(8)
	s_waitcnt lgkmcnt(0)
	s_barrier
	s_setprio 1
	s_waitcnt lgkmcnt(0)
	v_mfma_f32_16x16x32_bf16 v[60:63], v[64:67], v[172:175], v[60:63]
	v_mfma_f32_16x16x32_bf16 v[56:59], v[72:75], v[172:175], v[56:59]
	v_mfma_f32_16x16x32_bf16 v[44:47], v[64:67], v[190:193], v[44:47]
	v_mfma_f32_16x16x32_bf16 v[40:43], v[72:75], v[190:193], v[40:43]
	v_mfma_f32_16x16x32_bf16 v[28:31], v[64:67], v[198:201], v[28:31]
	v_mfma_f32_16x16x32_bf16 v[24:27], v[72:75], v[198:201], v[24:27]
	v_mfma_f32_16x16x32_bf16 v[12:15], v[64:67], v[212:215], v[12:15]
	v_mfma_f32_16x16x32_bf16 v[8:11], v[72:75], v[212:215], v[8:11]
	v_mfma_f32_16x16x32_bf16 v[60:63], v[68:71], v[182:185], v[60:63]
	v_mfma_f32_16x16x32_bf16 v[56:59], v[76:79], v[182:185], v[56:59]
	v_mfma_f32_16x16x32_bf16 v[44:47], v[68:71], v[194:197], v[44:47]
	v_mfma_f32_16x16x32_bf16 v[40:43], v[76:79], v[194:197], v[40:43]
	v_mfma_f32_16x16x32_bf16 v[28:31], v[68:71], v[208:211], v[28:31]
	v_mfma_f32_16x16x32_bf16 v[24:27], v[76:79], v[208:211], v[24:27]
	v_mfma_f32_16x16x32_bf16 v[12:15], v[68:71], v[216:219], v[12:15]
	v_mfma_f32_16x16x32_bf16 v[8:11], v[76:79], v[216:219], v[8:11]
	s_setprio 0
	s_setprio 1
	v_mfma_f32_16x16x32_bf16 v[52:55], v[80:83], v[172:175], v[52:55]
	v_mfma_f32_16x16x32_bf16 v[48:51], v[88:91], v[172:175], v[48:51]
	v_mfma_f32_16x16x32_bf16 v[36:39], v[80:83], v[190:193], v[36:39]
	v_mfma_f32_16x16x32_bf16 v[32:35], v[88:91], v[190:193], v[32:35]
	v_mfma_f32_16x16x32_bf16 v[20:23], v[80:83], v[198:201], v[20:23]
	v_mfma_f32_16x16x32_bf16 v[16:19], v[88:91], v[198:201], v[16:19]
	v_mfma_f32_16x16x32_bf16 v[4:7], v[80:83], v[212:215], v[4:7]
	v_mfma_f32_16x16x32_bf16 v[0:3], v[88:91], v[212:215], v[0:3]
	v_mfma_f32_16x16x32_bf16 v[52:55], v[84:87], v[182:185], v[52:55]
	v_mfma_f32_16x16x32_bf16 v[48:51], v[92:95], v[182:185], v[48:51]
	v_mfma_f32_16x16x32_bf16 v[36:39], v[84:87], v[194:197], v[36:39]
	v_mfma_f32_16x16x32_bf16 v[32:35], v[92:95], v[194:197], v[32:35]
	v_mfma_f32_16x16x32_bf16 v[20:23], v[84:87], v[208:211], v[20:23]
	v_mfma_f32_16x16x32_bf16 v[16:19], v[92:95], v[208:211], v[16:19]
	v_mfma_f32_16x16x32_bf16 v[4:7], v[84:87], v[216:219], v[4:7]
	v_mfma_f32_16x16x32_bf16 v[0:3], v[92:95], v[216:219], v[0:3]
	s_setprio 0
	s_add_i32 s72, s72, 2
	s_add_u32 s46, s46, 0x100
	s_addc_u32 s47, s47, 0
	s_add_u32 s70, s70, 0x100
	s_addc_u32 s71, s71, 0
	s_cmp_gt_u32 s72, 13
	s_barrier
	s_cbranch_scc0 .LBB0_2959
	s_and_b64 vcc, exec, s[28:29]
	s_cbranch_vccz .LBB0_2962
	s_barrier

; #define PG8_STAGE(bufoff, gbase, voff) do { _Pragma("unroll") for (int _i = 0; _i < 2; ++_i) \
;         __builtin_amdgcn_global_load_lds((const unsigned*)((const char*)(gbase) + (voff)[_i]), (PG8_LAS unsigned*)(lds + (bufoff) + ldsw + _i * 8192), 16, 0, 0); } while (0)
; #define PG8_LDA(dst, b, h) do { _Pragma("unroll") for (int m = 0; m < 4; ++m) _Pragma("unroll") for (int k = 0; k < 2; ++k) dst[m][k] = *(const PG8_LAS bf16x8*)(lds + PG8_SA(b, h) + aoff + m * 2048 + k * 1024); } while (0)
; #define PG8_LDB(dst, b, h) do { _Pragma("unroll") for (int n = 0; n < 2; ++n) _Pragma("unroll") for (int k = 0; k < 2; ++k) dst[n][k] = *(const PG8_LAS bf16x8*)(lds + PG8_SB(b, h) + boff + n * 2048 + k * 1024); } while (0)
; #define PG8_MMA(ai, bj, At, Bt) do { __builtin_amdgcn_s_setprio(1); _Pragma("unroll") for (int m = 0; m < 4; ++m) _Pragma("unroll") for (int n = 0; n < 2; ++n) _Pragma("unroll") for (int k = 0; k < 2; ++k) \
;         acc[ai][bj][m][n] = __builtin_amdgcn_mfma_f32_16x16x32_bf16(Bt[n][k], At[m][k], acc[ai][bj][m][n], 0, 0, 0); __builtin_amdgcn_s_setprio(0); } while (0)
; #define PG8_WAIT_V(n) asm volatile("s_waitcnt vmcnt(" #n ")" ::: "memory")
; #define PG8_WAIT_L(n) asm volatile("s_waitcnt lgkmcnt(" #n ")" ::: "memory")
; #define PG8_BAR __builtin_amdgcn_s_barrier()
; #define PG8_SCHED __builtin_amdgcn_sched_barrier(0)
; template <class Epi, class Sched, bool ALIGN_EPI = false, bool SP2 = false>
; __device__ __forceinline__ void gemm_phase(PG8_LAS unsigned char* lds, const Gemm g, const Sched S, const Epi E) {
;     ...
;             const bool last = (t == nt - 2);
;             const char* a1 = cA + (size_t)(t + 1) * kstepA;
;             const char* a2 = last ? nA : cA + (size_t)(t + 2) * kstepA; const char* b2 = last ? nB : cB + (size_t)(t + 2) * kstep;
;             const char* a3 = a2 + kstepA; const char* b3 = b2 + kstep;
;             if (last && has_next) S.a_ready(nxt);
;             if constexpr (SP2) {
;             PG8_LDB(B0, 0, 0); PG8_LDB(B1, 0, 1); PG8_SCHED; PG8_LDA(At, 0, 0); PG8_STAGE(PG8_SA(1, 1), a1 + hstepA, voffA);
;             PG8_WAIT_V(8); PG8_WAIT_L(0); PG8_BAR; PG8_MMA(0, 0, At, B0); PG8_MMA(0, 1, At, B1); PG8_BAR; PG8_SCHED;
;             PG8_LDA(At, 0, 1); PG8_STAGE(PG8_SB(0, 0), b2, voffB); PG8_STAGE(PG8_SB(0, 1), b2 + hstep, voffB); PG8_STAGE(PG8_SA(0, 0), a2, voffA);
.LBB0_3108:
	ds_read_b128 v[152:155], v149
	ds_read_b128 v[156:159], v149 offset:1024
	ds_read_b128 v[162:165], v149 offset:2048
	ds_read_b128 v[166:169], v149 offset:3072
	ds_read_b128 v[170:173], v150
	ds_read_b128 v[174:177], v150 offset:1024
	ds_read_b128 v[178:181], v150 offset:2048
	ds_read_b128 v[182:185], v150 offset:3072
	s_add_u32 s12, s64, 0xfffc0080
	s_addc_u32 s13, s65, -1
	s_cmp_eq_u32 s89, 12
	s_cselect_b32 s69, s45, s13
	s_cselect_b32 s68, s85, s12
	s_cselect_b32 s67, s43, s88
	s_cselect_b32 s66, s86, s87
	v_lshl_add_u64 v[144:145], s[64:65], 0, v[136:137]
	s_add_i32 m0, s15, 0xc000
	ds_read_b128 v[186:189], v151
	ds_read_b128 v[190:193], v151 offset:1024
	ds_read_b128 v[194:197], v151 offset:2048
	ds_read_b128 v[198:201], v151 offset:3072
	ds_read_b128 v[206:209], v151 offset:4096
	ds_read_b128 v[210:213], v151 offset:5120
	ds_read_b128 v[214:217], v151 offset:6144
	ds_read_b128 v[218:221], v151 offset:7168
	global_load_lds_dwordx4 v[144:145], off
	v_lshl_add_u64 v[144:145], s[64:65], 0, v[138:139]
	s_add_i32 m0, s15, 0xe000
	s_nop 0
	global_load_lds_dwordx4 v[144:145], off
	s_waitcnt vmcnt(8)
	s_waitcnt lgkmcnt(0)
	s_barrier
	s_setprio 1
	s_waitcnt lgkmcnt(0)
	v_mfma_f32_16x16x32_bf16 v[124:127], v[152:155], v[186:189], v[124:127]
	v_mfma_f32_16x16x32_bf16 v[120:123], v[162:165], v[186:189], v[120:123]
	v_mfma_f32_16x16x32_bf16 v[108:111], v[152:155], v[194:197], v[108:111]
	v_mfma_f32_16x16x32_bf16 v[104:107], v[162:165], v[194:197], v[104:107]
	v_mfma_f32_16x16x32_bf16 v[92:95], v[152:155], v[206:209], v[92:95]
	v_mfma_f32_16x16x32_bf16 v[88:91], v[162:165], v[206:209], v[88:91]
	v_mfma_f32_16x16x32_bf16 v[76:79], v[152:155], v[214:217], v[76:79]
	v_mfma_f32_16x16x32_bf16 v[72:75], v[162:165], v[214:217], v[72:75]
	v_mfma_f32_16x16x32_bf16 v[124:127], v[156:159], v[190:193], v[124:127]
	v_mfma_f32_16x16x32_bf16 v[120:123], v[166:169], v[190:193], v[120:123]
	v_mfma_f32_16x16x32_bf16 v[108:111], v[156:159], v[198:201], v[108:111]
	v_mfma_f32_16x16x32_bf16 v[104:107], v[166:169], v[198:201], v[104:107]
	v_mfma_f32_16x16x32_bf16 v[92:95], v[156:159], v[210:213], v[92:95]
	v_mfma_f32_16x16x32_bf16 v[88:91], v[166:169], v[210:213], v[88:91]
	v_mfma_f32_16x16x32_bf16 v[76:79], v[156:159], v[218:221], v[76:79]
	v_mfma_f32_16x16x32_bf16 v[72:75], v[166:169], v[218:221], v[72:75]
	s_setprio 0
	s_setprio 1
	v_mfma_f32_16x16x32_bf16 v[116:119], v[170:173], v[186:189], v[116:119]
	v_mfma_f32_16x16x32_bf16 v[112:115], v[178:181], v[186:189], v[112:115]
	v_mfma_f32_16x16x32_bf16 v[100:103], v[170:173], v[194:197], v[100:103]
	v_mfma_f32_16x16x32_bf16 v[96:99], v[178:181], v[194:197], v[96:99]
	v_mfma_f32_16x16x32_bf16 v[84:87], v[170:173], v[206:209], v[84:87]
	v_mfma_f32_16x16x32_bf16 v[80:83], v[178:181], v[206:209], v[80:83]
	v_mfma_f32_16x16x32_bf16 v[68:71], v[170:173], v[214:217], v[68:71]
	v_mfma_f32_16x16x32_bf16 v[64:67], v[178:181], v[214:217], v[64:67]
	v_mfma_f32_16x16x32_bf16 v[116:119], v[174:177], v[190:193], v[116:119]
	v_mfma_f32_16x16x32_bf16 v[112:115], v[182:185], v[190:193], v[112:115]
	v_mfma_f32_16x16x32_bf16 v[100:103], v[174:177], v[198:201], v[100:103]
	v_mfma_f32_16x16x32_bf16 v[96:99], v[182:185], v[198:201], v[96:99]
	v_mfma_f32_16x16x32_bf16 v[84:87], v[174:177], v[210:213], v[84:87]
	v_mfma_f32_16x16x32_bf16 v[80:83], v[182:185], v[210:213], v[80:83]
	v_mfma_f32_16x16x32_bf16 v[68:71], v[174:177], v[218:221], v[68:71]
	v_mfma_f32_16x16x32_bf16 v[64:67], v[182:185], v[218:221], v[64:67]
	s_setprio 0
	s_barrier
	s_add_i32 s12, s73, s4
	v_lshl_add_u64 v[144:145], s[66:67], 0, v[132:133]
	s_mov_b32 m0, s12
	ds_read_b128 v[186:189], v151 offset:16384
	ds_read_b128 v[190:193], v151 offset:17408
	ds_read_b128 v[194:197], v151 offset:18432
	ds_read_b128 v[198:201], v151 offset:19456
	ds_read_b128 v[206:209], v151 offset:20480
	ds_read_b128 v[210:213], v151 offset:21504
	ds_read_b128 v[214:217], v151 offset:22528
	ds_read_b128 v[218:221], v151 offset:23552
	global_load_lds_dwordx4 v[144:145], off
	s_add_i32 m0, s12, 0x2000
	s_add_u32 s12, s66, 0x40000
	v_lshl_add_u64 v[202:203], s[66:67], 0, v[128:129]
	s_addc_u32 s13, s67, 0
	s_add_i32 s90, s74, s4
	global_load_lds_dwordx4 v[202:203], off
	v_lshl_add_u64 v[222:223], s[12:13], 0, v[132:133]
	s_mov_b32 m0, s90
	v_lshl_add_u64 v[224:225], s[68:69], 0, v[130:131]
	global_load_lds_dwordx4 v[222:223], off
	v_lshl_add_u64 v[222:223], s[12:13], 0, v[128:129]
	s_add_i32 m0, s90, 0x2000
	s_nop 0
	global_load_lds_dwordx4 v[222:223], off
	v_lshl_add_u64 v[222:223], s[68:69], 0, v[134:135]
	s_mov_b32 m0, s15
	s_nop 0
	global_load_lds_dwordx4 v[222:223], off
	s_mov_b32 m0, s33
	s_nop 0
	global_load_lds_dwordx4 v[224:225], off
	s_waitcnt vmcnt(8)
	s_waitcnt lgkmcnt(0)
	s_barrier
; #define PG8_STAGE(bufoff, gbase, voff) do { _Pragma("unroll") for (int _i = 0; _i < 2; ++_i) \
;         __builtin_amdgcn_global_load_lds((const unsigned*)((const char*)(gbase) + (voff)[_i]), (PG8_LAS unsigned*)(lds + (bufoff) + ldsw + _i * 8192), 16, 0, 0); } while (0)
; #define PG8_LDA(dst, b, h) do { _Pragma("unroll") for (int m = 0; m < 4; ++m) _Pragma("unroll") for (int k = 0; k < 2; ++k) dst[m][k] = *(const PG8_LAS bf16x8*)(lds + PG8_SA(b, h) + aoff + m * 2048 + k * 1024); } while (0)
; #define PG8_LDB(dst, b, h) do { _Pragma("unroll") for (int n = 0; n < 2; ++n) _Pragma("unroll") for (int k = 0; k < 2; ++k) dst[n][k] = *(const PG8_LAS bf16x8*)(lds + PG8_SB(b, h) + boff + n * 2048 + k * 1024); } while (0)
; #define PG8_MMA(ai, bj, At, Bt) do { __builtin_amdgcn_s_setprio(1); _Pragma("unroll") for (int m = 0; m < 4; ++m) _Pragma("unroll") for (int n = 0; n < 2; ++n) _Pragma("unroll") for (int k = 0; k < 2; ++k) \
;         acc[ai][bj][m][n] = __builtin_amdgcn_mfma_f32_16x16x32_bf16(Bt[n][k], At[m][k], acc[ai][bj][m][n], 0, 0, 0); __builtin_amdgcn_s_setprio(0); } while (0)
; #define PG8_WAIT_V(n) asm volatile("s_waitcnt vmcnt(" #n ")" ::: "memory")
; #define PG8_WAIT_L(n) asm volatile("s_waitcnt lgkmcnt(" #n ")" ::: "memory")
; #define PG8_BAR __builtin_amdgcn_s_barrier()
; #define PG8_SCHED __builtin_amdgcn_sched_barrier(0)
; template <class Epi, class Sched, bool ALIGN_EPI = false, bool SP2 = false>
; __device__ __forceinline__ void gemm_phase(PG8_LAS unsigned char* lds, const Gemm g, const Sched S, const Epi E) {
;     ...
;             PG8_WAIT_V(8); PG8_WAIT_L(0); PG8_BAR; PG8_MMA(1, 0, At, B0); PG8_MMA(1, 1, At, B1); PG8_BAR; PG8_SCHED;
;             PG8_LDB(B0, 1, 0); PG8_LDB(B1, 1, 1); PG8_SCHED; PG8_LDA(At, 1, 0); PG8_STAGE(PG8_SA(0, 1), a2 + hstepA, voffA);
;             PG8_WAIT_V(8); PG8_WAIT_L(0); PG8_BAR; PG8_MMA(0, 0, At, B0); PG8_MMA(0, 1, At, B1); PG8_BAR; PG8_SCHED;
	s_setprio 1
	s_waitcnt lgkmcnt(0)
	v_mfma_f32_16x16x32_bf16 v[60:63], v[152:155], v[186:189], v[60:63]
	v_mfma_f32_16x16x32_bf16 v[56:59], v[162:165], v[186:189], v[56:59]
	v_mfma_f32_16x16x32_bf16 v[44:47], v[152:155], v[194:197], v[44:47]
	v_mfma_f32_16x16x32_bf16 v[40:43], v[162:165], v[194:197], v[40:43]
	v_mfma_f32_16x16x32_bf16 v[28:31], v[152:155], v[206:209], v[28:31]
	v_mfma_f32_16x16x32_bf16 v[24:27], v[162:165], v[206:209], v[24:27]
	v_mfma_f32_16x16x32_bf16 v[12:15], v[152:155], v[214:217], v[12:15]
	v_mfma_f32_16x16x32_bf16 v[8:11], v[162:165], v[214:217], v[8:11]
	v_mfma_f32_16x16x32_bf16 v[60:63], v[156:159], v[190:193], v[60:63]
	v_mfma_f32_16x16x32_bf16 v[56:59], v[166:169], v[190:193], v[56:59]
	v_mfma_f32_16x16x32_bf16 v[44:47], v[156:159], v[198:201], v[44:47]
	v_mfma_f32_16x16x32_bf16 v[40:43], v[166:169], v[198:201], v[40:43]
	v_mfma_f32_16x16x32_bf16 v[28:31], v[156:159], v[210:213], v[28:31]
	v_mfma_f32_16x16x32_bf16 v[24:27], v[166:169], v[210:213], v[24:27]
	v_mfma_f32_16x16x32_bf16 v[12:15], v[156:159], v[218:221], v[12:15]
	v_mfma_f32_16x16x32_bf16 v[8:11], v[166:169], v[218:221], v[8:11]
	s_setprio 0
	s_setprio 1
	v_mfma_f32_16x16x32_bf16 v[52:55], v[170:173], v[186:189], v[52:55]
	v_mfma_f32_16x16x32_bf16 v[48:51], v[178:181], v[186:189], v[48:51]
	v_mfma_f32_16x16x32_bf16 v[36:39], v[170:173], v[194:197], v[36:39]
	v_mfma_f32_16x16x32_bf16 v[32:35], v[178:181], v[194:197], v[32:35]
	v_mfma_f32_16x16x32_bf16 v[20:23], v[170:173], v[206:209], v[20:23]
	v_mfma_f32_16x16x32_bf16 v[16:19], v[178:181], v[206:209], v[16:19]
	v_mfma_f32_16x16x32_bf16 v[4:7], v[170:173], v[214:217], v[4:7]
	v_mfma_f32_16x16x32_bf16 v[0:3], v[178:181], v[214:217], v[0:3]
	v_mfma_f32_16x16x32_bf16 v[52:55], v[174:177], v[190:193], v[52:55]
	v_mfma_f32_16x16x32_bf16 v[48:51], v[182:185], v[190:193], v[48:51]
	v_mfma_f32_16x16x32_bf16 v[36:39], v[174:177], v[198:201], v[36:39]
	v_mfma_f32_16x16x32_bf16 v[32:35], v[182:185], v[198:201], v[32:35]
	v_mfma_f32_16x16x32_bf16 v[20:23], v[174:177], v[210:213], v[20:23]
	v_mfma_f32_16x16x32_bf16 v[16:19], v[182:185], v[210:213], v[16:19]
	v_mfma_f32_16x16x32_bf16 v[4:7], v[174:177], v[218:221], v[4:7]
	v_mfma_f32_16x16x32_bf16 v[0:3], v[182:185], v[218:221], v[0:3]
	s_setprio 0
	s_barrier
	s_add_i32 s90, 0, 0x18000
	v_add_u32_e32 v161, s90, v148
	s_add_i32 s91, 0, 0x1c000
	ds_read_b128 v[152:155], v161
	ds_read_b128 v[156:159], v161 offset:1024
	ds_read_b128 v[162:165], v161 offset:2048
	ds_read_b128 v[166:169], v161 offset:3072
	v_add_u32_e32 v161, s91, v148
	ds_read_b128 v[170:173], v161
	ds_read_b128 v[174:177], v161 offset:1024
	ds_read_b128 v[178:181], v161 offset:2048
	ds_read_b128 v[182:185], v161 offset:3072
	s_add_u32 s12, s68, 0x40000
	s_addc_u32 s13, s69, 0
	s_mov_b32 m0, s54
	v_lshl_add_u64 v[226:227], s[12:13], 0, v[134:135]
	ds_read_b128 v[186:189], v151 offset:32768
	ds_read_b128 v[190:193], v151 offset:33792
	ds_read_b128 v[194:197], v151 offset:34816
	ds_read_b128 v[198:201], v151 offset:35840
	ds_read_b128 v[206:209], v151 offset:36864
	ds_read_b128 v[210:213], v151 offset:37888
	ds_read_b128 v[214:217], v151 offset:38912
	ds_read_b128 v[218:221], v151 offset:39936
	global_load_lds_dwordx4 v[226:227], off
	v_lshl_add_u64 v[226:227], s[12:13], 0, v[130:131]
	s_mov_b32 m0, s55
	s_nop 0
	global_load_lds_dwordx4 v[226:227], off
	s_waitcnt vmcnt(8)
	s_waitcnt lgkmcnt(0)
	s_barrier
	s_setprio 1
	s_waitcnt lgkmcnt(0)
	v_mfma_f32_16x16x32_bf16 v[124:127], v[152:155], v[186:189], v[124:127]
	v_mfma_f32_16x16x32_bf16 v[120:123], v[162:165], v[186:189], v[120:123]
	v_mfma_f32_16x16x32_bf16 v[108:111], v[152:155], v[194:197], v[108:111]
	v_mfma_f32_16x16x32_bf16 v[104:107], v[162:165], v[194:197], v[104:107]
	v_mfma_f32_16x16x32_bf16 v[92:95], v[152:155], v[206:209], v[92:95]
	v_mfma_f32_16x16x32_bf16 v[88:91], v[162:165], v[206:209], v[88:91]
	v_mfma_f32_16x16x32_bf16 v[76:79], v[152:155], v[214:217], v[76:79]
	v_mfma_f32_16x16x32_bf16 v[72:75], v[162:165], v[214:217], v[72:75]
	v_mfma_f32_16x16x32_bf16 v[124:127], v[156:159], v[190:193], v[124:127]
	v_mfma_f32_16x16x32_bf16 v[120:123], v[166:169], v[190:193], v[120:123]
	v_mfma_f32_16x16x32_bf16 v[108:111], v[156:159], v[198:201], v[108:111]
	v_mfma_f32_16x16x32_bf16 v[104:107], v[166:169], v[198:201], v[104:107]
	v_mfma_f32_16x16x32_bf16 v[92:95], v[156:159], v[210:213], v[92:95]
	v_mfma_f32_16x16x32_bf16 v[88:91], v[166:169], v[210:213], v[88:91]
	v_mfma_f32_16x16x32_bf16 v[76:79], v[156:159], v[218:221], v[76:79]
	v_mfma_f32_16x16x32_bf16 v[72:75], v[166:169], v[218:221], v[72:75]
	s_setprio 0
	s_setprio 1
	v_mfma_f32_16x16x32_bf16 v[116:119], v[170:173], v[186:189], v[116:119]
	v_mfma_f32_16x16x32_bf16 v[112:115], v[178:181], v[186:189], v[112:115]
	v_mfma_f32_16x16x32_bf16 v[100:103], v[170:173], v[194:197], v[100:103]
	v_mfma_f32_16x16x32_bf16 v[96:99], v[178:181], v[194:197], v[96:99]
	v_mfma_f32_16x16x32_bf16 v[84:87], v[170:173], v[206:209], v[84:87]
	v_mfma_f32_16x16x32_bf16 v[80:83], v[178:181], v[206:209], v[80:83]
	v_mfma_f32_16x16x32_bf16 v[68:71], v[170:173], v[214:217], v[68:71]
	v_mfma_f32_16x16x32_bf16 v[64:67], v[178:181], v[214:217], v[64:67]
	v_mfma_f32_16x16x32_bf16 v[116:119], v[174:177], v[190:193], v[116:119]
	v_mfma_f32_16x16x32_bf16 v[112:115], v[182:185], v[190:193], v[112:115]
	v_mfma_f32_16x16x32_bf16 v[100:103], v[174:177], v[198:201], v[100:103]
	v_mfma_f32_16x16x32_bf16 v[96:99], v[182:185], v[198:201], v[96:99]
	v_mfma_f32_16x16x32_bf16 v[84:87], v[174:177], v[210:213], v[84:87]
	v_mfma_f32_16x16x32_bf16 v[80:83], v[182:185], v[210:213], v[80:83]
	v_mfma_f32_16x16x32_bf16 v[68:71], v[174:177], v[218:221], v[68:71]
	v_mfma_f32_16x16x32_bf16 v[64:67], v[182:185], v[218:221], v[64:67]
	s_setprio 0
	s_barrier
; #define PG8_STAGE(bufoff, gbase, voff) do { _Pragma("unroll") for (int _i = 0; _i < 2; ++_i) \
;         __builtin_amdgcn_global_load_lds((const unsigned*)((const char*)(gbase) + (voff)[_i]), (PG8_LAS unsigned*)(lds + (bufoff) + ldsw + _i * 8192), 16, 0, 0); } while (0)
; #define PG8_LDA(dst, b, h) do { _Pragma("unroll") for (int m = 0; m < 4; ++m) _Pragma("unroll") for (int k = 0; k < 2; ++k) dst[m][k] = *(const PG8_LAS bf16x8*)(lds + PG8_SA(b, h) + aoff + m * 2048 + k * 1024); } while (0)
; #define PG8_MMA(ai, bj, At, Bt) do { __builtin_amdgcn_s_setprio(1); _Pragma("unroll") for (int m = 0; m < 4; ++m) _Pragma("unroll") for (int n = 0; n < 2; ++n) _Pragma("unroll") for (int k = 0; k < 2; ++k) \
;         acc[ai][bj][m][n] = __builtin_amdgcn_mfma_f32_16x16x32_bf16(Bt[n][k], At[m][k], acc[ai][bj][m][n], 0, 0, 0); __builtin_amdgcn_s_setprio(0); } while (0)
; #define PG8_WAIT_V(n) asm volatile("s_waitcnt vmcnt(" #n ")" ::: "memory")
; #define PG8_WAIT_L(n) asm volatile("s_waitcnt lgkmcnt(" #n ")" ::: "memory")
; #define PG8_BAR __builtin_amdgcn_s_barrier()
; #define PG8_SCHED __builtin_amdgcn_sched_barrier(0)
; template <class Epi, class Sched, bool ALIGN_EPI = false, bool SP2 = false>
; __device__ __forceinline__ void gemm_phase(PG8_LAS unsigned char* lds, const Gemm g, const Sched S, const Epi E) {
;     ...
;         for (int t = 0; t < nt; t += 2) {
;             const bool last = (t == nt - 2);
;             const char* a1 = cA + (size_t)(t + 1) * kstepA;
;             const char* a2 = last ? nA : cA + (size_t)(t + 2) * kstepA; const char* b2 = last ? nB : cB + (size_t)(t + 2) * kstep;
;             const char* a3 = a2 + kstepA; const char* b3 = b2 + kstep;
;     ...
;             PG8_LDA(At, 1, 1); PG8_STAGE(PG8_SB(1, 0), b3, voffB); PG8_STAGE(PG8_SB(1, 1), b3 + hstep, voffB); PG8_STAGE(PG8_SA(1, 0), a3, voffA);
;             PG8_WAIT_V(8); PG8_WAIT_L(0); PG8_BAR; PG8_MMA(1, 0, At, B0); PG8_MMA(1, 1, At, B1); PG8_BAR; PG8_SCHED;
	s_add_i32 s12, s90, s4
	v_lshl_add_u64 v[144:145], v[144:145], 0, s[24:25]
	s_mov_b32 m0, s12
	ds_read_b128 v[186:189], v151 offset:49152
	ds_read_b128 v[190:193], v151 offset:50176
	ds_read_b128 v[194:197], v151 offset:51200
	ds_read_b128 v[198:201], v151 offset:52224
	ds_read_b128 v[206:209], v151 offset:53248
	ds_read_b128 v[210:213], v151 offset:54272
	ds_read_b128 v[214:217], v151 offset:55296
	ds_read_b128 v[218:221], v151 offset:56320
	global_load_lds_dwordx4 v[144:145], off
	s_add_i32 m0, s12, 0x2000
	s_add_u32 s12, s66, 0x40080
	v_lshl_add_u64 v[144:145], v[202:203], 0, s[24:25]
	s_addc_u32 s13, s67, 0
	s_add_i32 s66, s91, s4
	global_load_lds_dwordx4 v[144:145], off
	v_lshl_add_u64 v[144:145], s[12:13], 0, v[132:133]
	s_mov_b32 m0, s66
	s_nop 0
	global_load_lds_dwordx4 v[144:145], off
	v_lshl_add_u64 v[144:145], s[12:13], 0, v[128:129]
	s_add_i32 m0, s66, 0x2000
	s_nop 0
	global_load_lds_dwordx4 v[144:145], off
	v_lshl_add_u64 v[144:145], v[222:223], 0, s[24:25]
	s_mov_b32 m0, s71
	s_nop 0
	global_load_lds_dwordx4 v[144:145], off
	v_lshl_add_u64 v[144:145], v[224:225], 0, s[24:25]
	s_mov_b32 m0, s72
	s_nop 0
	global_load_lds_dwordx4 v[144:145], off
	s_waitcnt vmcnt(8)
	s_waitcnt lgkmcnt(0)
	s_barrier
	s_setprio 1
	s_waitcnt lgkmcnt(0)
	v_mfma_f32_16x16x32_bf16 v[60:63], v[152:155], v[186:189], v[60:63]
	v_mfma_f32_16x16x32_bf16 v[56:59], v[162:165], v[186:189], v[56:59]
	v_mfma_f32_16x16x32_bf16 v[44:47], v[152:155], v[194:197], v[44:47]
	v_mfma_f32_16x16x32_bf16 v[40:43], v[162:165], v[194:197], v[40:43]
	v_mfma_f32_16x16x32_bf16 v[28:31], v[152:155], v[206:209], v[28:31]
	v_mfma_f32_16x16x32_bf16 v[24:27], v[162:165], v[206:209], v[24:27]
	v_mfma_f32_16x16x32_bf16 v[12:15], v[152:155], v[214:217], v[12:15]
	v_mfma_f32_16x16x32_bf16 v[8:11], v[162:165], v[214:217], v[8:11]
	v_mfma_f32_16x16x32_bf16 v[60:63], v[156:159], v[190:193], v[60:63]
	v_mfma_f32_16x16x32_bf16 v[56:59], v[166:169], v[190:193], v[56:59]
	v_mfma_f32_16x16x32_bf16 v[44:47], v[156:159], v[198:201], v[44:47]
	v_mfma_f32_16x16x32_bf16 v[40:43], v[166:169], v[198:201], v[40:43]
	v_mfma_f32_16x16x32_bf16 v[28:31], v[156:159], v[210:213], v[28:31]
	v_mfma_f32_16x16x32_bf16 v[24:27], v[166:169], v[210:213], v[24:27]
	v_mfma_f32_16x16x32_bf16 v[12:15], v[156:159], v[218:221], v[12:15]
	v_mfma_f32_16x16x32_bf16 v[8:11], v[166:169], v[218:221], v[8:11]
	s_setprio 0
	s_setprio 1
	v_mfma_f32_16x16x32_bf16 v[52:55], v[170:173], v[186:189], v[52:55]
	v_mfma_f32_16x16x32_bf16 v[48:51], v[178:181], v[186:189], v[48:51]
	v_mfma_f32_16x16x32_bf16 v[36:39], v[170:173], v[194:197], v[36:39]
	v_mfma_f32_16x16x32_bf16 v[32:35], v[178:181], v[194:197], v[32:35]
	v_mfma_f32_16x16x32_bf16 v[20:23], v[170:173], v[206:209], v[20:23]
	v_mfma_f32_16x16x32_bf16 v[16:19], v[178:181], v[206:209], v[16:19]
	v_mfma_f32_16x16x32_bf16 v[4:7], v[170:173], v[214:217], v[4:7]
	v_mfma_f32_16x16x32_bf16 v[0:3], v[178:181], v[214:217], v[0:3]
	v_mfma_f32_16x16x32_bf16 v[52:55], v[174:177], v[190:193], v[52:55]
	v_mfma_f32_16x16x32_bf16 v[48:51], v[182:185], v[190:193], v[48:51]
	v_mfma_f32_16x16x32_bf16 v[36:39], v[174:177], v[198:201], v[36:39]
	v_mfma_f32_16x16x32_bf16 v[32:35], v[182:185], v[198:201], v[32:35]
	v_mfma_f32_16x16x32_bf16 v[20:23], v[174:177], v[210:213], v[20:23]
	v_mfma_f32_16x16x32_bf16 v[16:19], v[182:185], v[210:213], v[16:19]
	v_mfma_f32_16x16x32_bf16 v[4:7], v[174:177], v[218:221], v[4:7]
	v_mfma_f32_16x16x32_bf16 v[0:3], v[182:185], v[218:221], v[0:3]
	s_setprio 0
	s_add_i32 s89, s89, 2
	s_add_u32 s64, s64, 0x100
	s_addc_u32 s65, s65, 0
	s_add_u32 s87, s87, 0x100
	s_addc_u32 s88, s88, 0
	s_cmp_gt_u32 s89, 13
	s_barrier
	s_cbranch_scc0 .LBB0_3108
	s_and_b64 vcc, exec, s[26:27]
	s_cbranch_vccz .LBB0_3111
	s_barrier

; #define PG8_STAGE(bufoff, gbase, voff) do { _Pragma("unroll") for (int _i = 0; _i < 2; ++_i) \
;         __builtin_amdgcn_global_load_lds((const unsigned*)((const char*)(gbase) + (voff)[_i]), (PG8_LAS unsigned*)(lds + (bufoff) + ldsw + _i * 8192), 16, 0, 0); } while (0)
; #define PG8_LDA(dst, b, h) do { _Pragma("unroll") for (int m = 0; m < 4; ++m) _Pragma("unroll") for (int k = 0; k < 2; ++k) dst[m][k] = *(const PG8_LAS bf16x8*)(lds + PG8_SA(b, h) + aoff + m * 2048 + k * 1024); } while (0)
; #define PG8_LDB(dst, b, h) do { _Pragma("unroll") for (int n = 0; n < 2; ++n) _Pragma("unroll") for (int k = 0; k < 2; ++k) dst[n][k] = *(const PG8_LAS bf16x8*)(lds + PG8_SB(b, h) + boff + n * 2048 + k * 1024); } while (0)
; #define PG8_MMA(ai, bj, At, Bt) do { __builtin_amdgcn_s_setprio(1); _Pragma("unroll") for (int m = 0; m < 4; ++m) _Pragma("unroll") for (int n = 0; n < 2; ++n) _Pragma("unroll") for (int k = 0; k < 2; ++k) \
;         acc[ai][bj][m][n] = __builtin_amdgcn_mfma_f32_16x16x32_bf16(Bt[n][k], At[m][k], acc[ai][bj][m][n], 0, 0, 0); __builtin_amdgcn_s_setprio(0); } while (0)
; #define PG8_WAIT_V(n) asm volatile("s_waitcnt vmcnt(" #n ")" ::: "memory")
; #define PG8_WAIT_L(n) asm volatile("s_waitcnt lgkmcnt(" #n ")" ::: "memory")
; #define PG8_BAR __builtin_amdgcn_s_barrier()
; #define PG8_SCHED __builtin_amdgcn_sched_barrier(0)
; template <class Epi, class Sched, bool ALIGN_EPI = false, bool SP2 = false>
; __device__ __forceinline__ void gemm_phase(PG8_LAS unsigned char* lds, const Gemm g, const Sched S, const Epi E) {
;     ...
;             const bool last = (t == nt - 2);
;             const char* a1 = cA + (size_t)(t + 1) * kstepA;
;             const char* a2 = last ? nA : cA + (size_t)(t + 2) * kstepA; const char* b2 = last ? nB : cB + (size_t)(t + 2) * kstep;
;             const char* a3 = a2 + kstepA; const char* b3 = b2 + kstep;
;             if (last && has_next) S.a_ready(nxt);
;             if constexpr (SP2) {
;             PG8_LDB(B0, 0, 0); PG8_LDB(B1, 0, 1); PG8_SCHED; PG8_LDA(At, 0, 0); PG8_STAGE(PG8_SA(1, 1), a1 + hstepA, voffA);
;             PG8_WAIT_V(8); PG8_WAIT_L(0); PG8_BAR; PG8_MMA(0, 0, At, B0); PG8_MMA(0, 1, At, B1); PG8_BAR; PG8_SCHED;
;             PG8_LDA(At, 0, 1); PG8_STAGE(PG8_SB(0, 0), b2, voffB); PG8_STAGE(PG8_SB(0, 1), b2 + hstep, voffB); PG8_STAGE(PG8_SA(0, 0), a2, voffA);
.LBB0_3187:
	ds_read_b128 v[64:67], v188
	ds_read_b128 v[68:71], v188 offset:1024
	ds_read_b128 v[72:75], v188 offset:2048
	ds_read_b128 v[76:79], v188 offset:3072
	ds_read_b128 v[80:83], v189
	ds_read_b128 v[84:87], v189 offset:1024
	ds_read_b128 v[88:91], v189 offset:2048
	ds_read_b128 v[92:95], v189 offset:3072
	s_add_u32 s12, s50, 0xfff00080
	s_addc_u32 s13, s51, -1
	s_cmp_eq_u32 s73, 60
	s_cselect_b32 s63, s1, s13
	s_cselect_b32 s62, s41, s12
	s_cselect_b32 s61, s39, s72
	s_cselect_b32 s60, s70, s71
	v_lshl_add_u64 v[180:181], s[50:51], 0, v[166:167]
	s_add_i32 m0, s37, 0xc000
	ds_read_b128 v[174:177], v190
	ds_read_b128 v[184:187], v190 offset:1024
	ds_read_b128 v[192:195], v190 offset:2048
	ds_read_b128 v[196:199], v190 offset:3072
	ds_read_b128 v[200:203], v190 offset:4096
	ds_read_b128 v[204:207], v190 offset:5120
	ds_read_b128 v[208:211], v190 offset:6144
	ds_read_b128 v[212:215], v190 offset:7168
	global_load_lds_dwordx4 v[180:181], off
	v_lshl_add_u64 v[180:181], s[50:51], 0, v[168:169]
	s_add_i32 m0, s37, 0xe000
	s_nop 0
	global_load_lds_dwordx4 v[180:181], off
	s_waitcnt vmcnt(8)
	s_waitcnt lgkmcnt(0)
	s_barrier
	s_setprio 1
	s_waitcnt lgkmcnt(0)
	v_mfma_f32_16x16x32_bf16 v[156:159], v[64:67], v[174:177], v[156:159]
	v_mfma_f32_16x16x32_bf16 v[152:155], v[72:75], v[174:177], v[152:155]
	v_mfma_f32_16x16x32_bf16 v[140:143], v[64:67], v[192:195], v[140:143]
	v_mfma_f32_16x16x32_bf16 v[136:139], v[72:75], v[192:195], v[136:139]
	v_mfma_f32_16x16x32_bf16 v[124:127], v[64:67], v[200:203], v[124:127]
	v_mfma_f32_16x16x32_bf16 v[120:123], v[72:75], v[200:203], v[120:123]
	v_mfma_f32_16x16x32_bf16 v[108:111], v[64:67], v[208:211], v[108:111]
	v_mfma_f32_16x16x32_bf16 v[104:107], v[72:75], v[208:211], v[104:107]
	v_mfma_f32_16x16x32_bf16 v[156:159], v[68:71], v[184:187], v[156:159]
	v_mfma_f32_16x16x32_bf16 v[152:155], v[76:79], v[184:187], v[152:155]
	v_mfma_f32_16x16x32_bf16 v[140:143], v[68:71], v[196:199], v[140:143]
	v_mfma_f32_16x16x32_bf16 v[136:139], v[76:79], v[196:199], v[136:139]
	v_mfma_f32_16x16x32_bf16 v[124:127], v[68:71], v[204:207], v[124:127]
	v_mfma_f32_16x16x32_bf16 v[120:123], v[76:79], v[204:207], v[120:123]
	v_mfma_f32_16x16x32_bf16 v[108:111], v[68:71], v[212:215], v[108:111]
	v_mfma_f32_16x16x32_bf16 v[104:107], v[76:79], v[212:215], v[104:107]
	s_setprio 0
	s_setprio 1
	v_mfma_f32_16x16x32_bf16 v[148:151], v[80:83], v[174:177], v[148:151]
	v_mfma_f32_16x16x32_bf16 v[144:147], v[88:91], v[174:177], v[144:147]
	v_mfma_f32_16x16x32_bf16 v[132:135], v[80:83], v[192:195], v[132:135]
	v_mfma_f32_16x16x32_bf16 v[128:131], v[88:91], v[192:195], v[128:131]
	v_mfma_f32_16x16x32_bf16 v[116:119], v[80:83], v[200:203], v[116:119]
	v_mfma_f32_16x16x32_bf16 v[112:115], v[88:91], v[200:203], v[112:115]
	v_mfma_f32_16x16x32_bf16 v[100:103], v[80:83], v[208:211], v[100:103]
	v_mfma_f32_16x16x32_bf16 v[96:99], v[88:91], v[208:211], v[96:99]
	v_mfma_f32_16x16x32_bf16 v[148:151], v[84:87], v[184:187], v[148:151]
	v_mfma_f32_16x16x32_bf16 v[144:147], v[92:95], v[184:187], v[144:147]
	v_mfma_f32_16x16x32_bf16 v[132:135], v[84:87], v[196:199], v[132:135]
	v_mfma_f32_16x16x32_bf16 v[128:131], v[92:95], v[196:199], v[128:131]
	v_mfma_f32_16x16x32_bf16 v[116:119], v[84:87], v[204:207], v[116:119]
	v_mfma_f32_16x16x32_bf16 v[112:115], v[92:95], v[204:207], v[112:115]
	v_mfma_f32_16x16x32_bf16 v[100:103], v[84:87], v[212:215], v[100:103]
	v_mfma_f32_16x16x32_bf16 v[96:99], v[92:95], v[212:215], v[96:99]
	s_setprio 0
	s_barrier
	s_add_i32 s12, s68, s33
	v_lshl_add_u64 v[180:181], s[60:61], 0, v[162:163]
	s_mov_b32 m0, s12
	ds_read_b128 v[174:177], v190 offset:16384
	ds_read_b128 v[184:187], v190 offset:17408
	ds_read_b128 v[192:195], v190 offset:18432
	ds_read_b128 v[196:199], v190 offset:19456
	ds_read_b128 v[200:203], v190 offset:20480
	ds_read_b128 v[204:207], v190 offset:21504
	ds_read_b128 v[208:211], v190 offset:22528
	ds_read_b128 v[212:215], v190 offset:23552
	global_load_lds_dwordx4 v[180:181], off
	s_add_i32 m0, s12, 0x2000
	s_add_u32 s12, s60, 0x100000
	v_lshl_add_u64 v[216:217], s[60:61], 0, v[164:165]
	s_addc_u32 s13, s61, 0
	s_add_i32 s74, s69, s33
	global_load_lds_dwordx4 v[216:217], off
	v_lshl_add_u64 v[218:219], s[12:13], 0, v[162:163]
	s_mov_b32 m0, s74
	v_lshl_add_u64 v[220:221], s[62:63], 0, v[164:165]
	global_load_lds_dwordx4 v[218:219], off
	v_lshl_add_u64 v[218:219], s[12:13], 0, v[164:165]
	s_add_i32 m0, s74, 0x2000
	s_nop 0
	global_load_lds_dwordx4 v[218:219], off
	v_lshl_add_u64 v[218:219], s[62:63], 0, v[162:163]
	s_mov_b32 m0, s37
	s_nop 0
	global_load_lds_dwordx4 v[218:219], off
	s_mov_b32 m0, s47
	s_nop 0
	global_load_lds_dwordx4 v[220:221], off
	s_waitcnt vmcnt(8)
	s_waitcnt lgkmcnt(0)
	s_barrier
; #define PG8_STAGE(bufoff, gbase, voff) do { _Pragma("unroll") for (int _i = 0; _i < 2; ++_i) \
;         __builtin_amdgcn_global_load_lds((const unsigned*)((const char*)(gbase) + (voff)[_i]), (PG8_LAS unsigned*)(lds + (bufoff) + ldsw + _i * 8192), 16, 0, 0); } while (0)
; #define PG8_LDA(dst, b, h) do { _Pragma("unroll") for (int m = 0; m < 4; ++m) _Pragma("unroll") for (int k = 0; k < 2; ++k) dst[m][k] = *(const PG8_LAS bf16x8*)(lds + PG8_SA(b, h) + aoff + m * 2048 + k * 1024); } while (0)
; #define PG8_LDB(dst, b, h) do { _Pragma("unroll") for (int n = 0; n < 2; ++n) _Pragma("unroll") for (int k = 0; k < 2; ++k) dst[n][k] = *(const PG8_LAS bf16x8*)(lds + PG8_SB(b, h) + boff + n * 2048 + k * 1024); } while (0)
; #define PG8_MMA(ai, bj, At, Bt) do { __builtin_amdgcn_s_setprio(1); _Pragma("unroll") for (int m = 0; m < 4; ++m) _Pragma("unroll") for (int n = 0; n < 2; ++n) _Pragma("unroll") for (int k = 0; k < 2; ++k) \
;         acc[ai][bj][m][n] = __builtin_amdgcn_mfma_f32_16x16x32_bf16(Bt[n][k], At[m][k], acc[ai][bj][m][n], 0, 0, 0); __builtin_amdgcn_s_setprio(0); } while (0)
; #define PG8_WAIT_V(n) asm volatile("s_waitcnt vmcnt(" #n ")" ::: "memory")
; #define PG8_WAIT_L(n) asm volatile("s_waitcnt lgkmcnt(" #n ")" ::: "memory")
; #define PG8_BAR __builtin_amdgcn_s_barrier()
; #define PG8_SCHED __builtin_amdgcn_sched_barrier(0)
; template <class Epi, class Sched, bool ALIGN_EPI = false, bool SP2 = false>
; __device__ __forceinline__ void gemm_phase(PG8_LAS unsigned char* lds, const Gemm g, const Sched S, const Epi E) {
;     ...
;             PG8_WAIT_V(8); PG8_WAIT_L(0); PG8_BAR; PG8_MMA(1, 0, At, B0); PG8_MMA(1, 1, At, B1); PG8_BAR; PG8_SCHED;
;             PG8_LDB(B0, 1, 0); PG8_LDB(B1, 1, 1); PG8_SCHED; PG8_LDA(At, 1, 0); PG8_STAGE(PG8_SA(0, 1), a2 + hstepA, voffA);
;             PG8_WAIT_V(8); PG8_WAIT_L(0); PG8_BAR; PG8_MMA(0, 0, At, B0); PG8_MMA(0, 1, At, B1); PG8_BAR; PG8_SCHED;
	s_setprio 1
	s_waitcnt lgkmcnt(0)
	v_mfma_f32_16x16x32_bf16 v[60:63], v[64:67], v[174:177], v[60:63]
	v_mfma_f32_16x16x32_bf16 v[56:59], v[72:75], v[174:177], v[56:59]
	v_mfma_f32_16x16x32_bf16 v[44:47], v[64:67], v[192:195], v[44:47]
	v_mfma_f32_16x16x32_bf16 v[40:43], v[72:75], v[192:195], v[40:43]
	v_mfma_f32_16x16x32_bf16 v[28:31], v[64:67], v[200:203], v[28:31]
	v_mfma_f32_16x16x32_bf16 v[24:27], v[72:75], v[200:203], v[24:27]
	v_mfma_f32_16x16x32_bf16 v[12:15], v[64:67], v[208:211], v[12:15]
	v_mfma_f32_16x16x32_bf16 v[8:11], v[72:75], v[208:211], v[8:11]
	v_mfma_f32_16x16x32_bf16 v[60:63], v[68:71], v[184:187], v[60:63]
	v_mfma_f32_16x16x32_bf16 v[56:59], v[76:79], v[184:187], v[56:59]
	v_mfma_f32_16x16x32_bf16 v[44:47], v[68:71], v[196:199], v[44:47]
	v_mfma_f32_16x16x32_bf16 v[40:43], v[76:79], v[196:199], v[40:43]
	v_mfma_f32_16x16x32_bf16 v[28:31], v[68:71], v[204:207], v[28:31]
	v_mfma_f32_16x16x32_bf16 v[24:27], v[76:79], v[204:207], v[24:27]
	v_mfma_f32_16x16x32_bf16 v[12:15], v[68:71], v[212:215], v[12:15]
	v_mfma_f32_16x16x32_bf16 v[8:11], v[76:79], v[212:215], v[8:11]
	s_setprio 0
	s_setprio 1
	v_mfma_f32_16x16x32_bf16 v[52:55], v[80:83], v[174:177], v[52:55]
	v_mfma_f32_16x16x32_bf16 v[48:51], v[88:91], v[174:177], v[48:51]
	v_mfma_f32_16x16x32_bf16 v[36:39], v[80:83], v[192:195], v[36:39]
	v_mfma_f32_16x16x32_bf16 v[32:35], v[88:91], v[192:195], v[32:35]
	v_mfma_f32_16x16x32_bf16 v[20:23], v[80:83], v[200:203], v[20:23]
	v_mfma_f32_16x16x32_bf16 v[16:19], v[88:91], v[200:203], v[16:19]
	v_mfma_f32_16x16x32_bf16 v[4:7], v[80:83], v[208:211], v[4:7]
	v_mfma_f32_16x16x32_bf16 v[0:3], v[88:91], v[208:211], v[0:3]
	v_mfma_f32_16x16x32_bf16 v[52:55], v[84:87], v[184:187], v[52:55]
	v_mfma_f32_16x16x32_bf16 v[48:51], v[92:95], v[184:187], v[48:51]
	v_mfma_f32_16x16x32_bf16 v[36:39], v[84:87], v[196:199], v[36:39]
	v_mfma_f32_16x16x32_bf16 v[32:35], v[92:95], v[196:199], v[32:35]
	v_mfma_f32_16x16x32_bf16 v[20:23], v[84:87], v[204:207], v[20:23]
	v_mfma_f32_16x16x32_bf16 v[16:19], v[92:95], v[204:207], v[16:19]
	v_mfma_f32_16x16x32_bf16 v[4:7], v[84:87], v[212:215], v[4:7]
	v_mfma_f32_16x16x32_bf16 v[0:3], v[92:95], v[212:215], v[0:3]
	s_setprio 0
	s_barrier
	s_add_i32 s74, 0, 0x18000
	s_add_i32 s75, 0, 0x1c000
	v_add_u32_e32 v76, s74, v183
	v_add_u32_e32 v92, s75, v183
	ds_read_b128 v[64:67], v76
	ds_read_b128 v[68:71], v76 offset:1024
	ds_read_b128 v[72:75], v76 offset:2048
	ds_read_b128 v[76:79], v76 offset:3072
	ds_read_b128 v[80:83], v92
	ds_read_b128 v[84:87], v92 offset:1024
	ds_read_b128 v[88:91], v92 offset:2048
	ds_read_b128 v[92:95], v92 offset:3072
	s_add_u32 s12, s62, 0x100000
	s_addc_u32 s13, s63, 0
	s_mov_b32 m0, s54
	v_lshl_add_u64 v[222:223], s[12:13], 0, v[162:163]
	ds_read_b128 v[174:177], v190 offset:32768
	ds_read_b128 v[184:187], v190 offset:33792
	ds_read_b128 v[192:195], v190 offset:34816
	ds_read_b128 v[196:199], v190 offset:35840
	ds_read_b128 v[200:203], v190 offset:36864
	ds_read_b128 v[204:207], v190 offset:37888
	ds_read_b128 v[208:211], v190 offset:38912
	ds_read_b128 v[212:215], v190 offset:39936
	global_load_lds_dwordx4 v[222:223], off
	v_lshl_add_u64 v[222:223], s[12:13], 0, v[164:165]
	s_mov_b32 m0, s55
	s_nop 0
	global_load_lds_dwordx4 v[222:223], off
	s_waitcnt vmcnt(8)
	s_waitcnt lgkmcnt(0)
	s_barrier
	s_setprio 1
	s_waitcnt lgkmcnt(0)
	v_mfma_f32_16x16x32_bf16 v[156:159], v[64:67], v[174:177], v[156:159]
	v_mfma_f32_16x16x32_bf16 v[152:155], v[72:75], v[174:177], v[152:155]
	v_mfma_f32_16x16x32_bf16 v[140:143], v[64:67], v[192:195], v[140:143]
	v_mfma_f32_16x16x32_bf16 v[136:139], v[72:75], v[192:195], v[136:139]
	v_mfma_f32_16x16x32_bf16 v[124:127], v[64:67], v[200:203], v[124:127]
	v_mfma_f32_16x16x32_bf16 v[120:123], v[72:75], v[200:203], v[120:123]
	v_mfma_f32_16x16x32_bf16 v[108:111], v[64:67], v[208:211], v[108:111]
	v_mfma_f32_16x16x32_bf16 v[104:107], v[72:75], v[208:211], v[104:107]
	v_mfma_f32_16x16x32_bf16 v[156:159], v[68:71], v[184:187], v[156:159]
	v_mfma_f32_16x16x32_bf16 v[152:155], v[76:79], v[184:187], v[152:155]
	v_mfma_f32_16x16x32_bf16 v[140:143], v[68:71], v[196:199], v[140:143]
	v_mfma_f32_16x16x32_bf16 v[136:139], v[76:79], v[196:199], v[136:139]
	v_mfma_f32_16x16x32_bf16 v[124:127], v[68:71], v[204:207], v[124:127]
	v_mfma_f32_16x16x32_bf16 v[120:123], v[76:79], v[204:207], v[120:123]
	v_mfma_f32_16x16x32_bf16 v[108:111], v[68:71], v[212:215], v[108:111]
	v_mfma_f32_16x16x32_bf16 v[104:107], v[76:79], v[212:215], v[104:107]
	s_setprio 0
	s_setprio 1
	v_mfma_f32_16x16x32_bf16 v[148:151], v[80:83], v[174:177], v[148:151]
	v_mfma_f32_16x16x32_bf16 v[144:147], v[88:91], v[174:177], v[144:147]
	v_mfma_f32_16x16x32_bf16 v[132:135], v[80:83], v[192:195], v[132:135]
	v_mfma_f32_16x16x32_bf16 v[128:131], v[88:91], v[192:195], v[128:131]
	v_mfma_f32_16x16x32_bf16 v[116:119], v[80:83], v[200:203], v[116:119]
	v_mfma_f32_16x16x32_bf16 v[112:115], v[88:91], v[200:203], v[112:115]
	v_mfma_f32_16x16x32_bf16 v[100:103], v[80:83], v[208:211], v[100:103]
	v_mfma_f32_16x16x32_bf16 v[96:99], v[88:91], v[208:211], v[96:99]
	v_mfma_f32_16x16x32_bf16 v[148:151], v[84:87], v[184:187], v[148:151]
	v_mfma_f32_16x16x32_bf16 v[144:147], v[92:95], v[184:187], v[144:147]
	v_mfma_f32_16x16x32_bf16 v[132:135], v[84:87], v[196:199], v[132:135]
	v_mfma_f32_16x16x32_bf16 v[128:131], v[92:95], v[196:199], v[128:131]
	v_mfma_f32_16x16x32_bf16 v[116:119], v[84:87], v[204:207], v[116:119]
	v_mfma_f32_16x16x32_bf16 v[112:115], v[92:95], v[204:207], v[112:115]
	v_mfma_f32_16x16x32_bf16 v[100:103], v[84:87], v[212:215], v[100:103]
	v_mfma_f32_16x16x32_bf16 v[96:99], v[92:95], v[212:215], v[96:99]
	s_setprio 0
	s_barrier
; #define PG8_STAGE(bufoff, gbase, voff) do { _Pragma("unroll") for (int _i = 0; _i < 2; ++_i) \
;         __builtin_amdgcn_global_load_lds((const unsigned*)((const char*)(gbase) + (voff)[_i]), (PG8_LAS unsigned*)(lds + (bufoff) + ldsw + _i * 8192), 16, 0, 0); } while (0)
; #define PG8_LDA(dst, b, h) do { _Pragma("unroll") for (int m = 0; m < 4; ++m) _Pragma("unroll") for (int k = 0; k < 2; ++k) dst[m][k] = *(const PG8_LAS bf16x8*)(lds + PG8_SA(b, h) + aoff + m * 2048 + k * 1024); } while (0)
; #define PG8_MMA(ai, bj, At, Bt) do { __builtin_amdgcn_s_setprio(1); _Pragma("unroll") for (int m = 0; m < 4; ++m) _Pragma("unroll") for (int n = 0; n < 2; ++n) _Pragma("unroll") for (int k = 0; k < 2; ++k) \
;         acc[ai][bj][m][n] = __builtin_amdgcn_mfma_f32_16x16x32_bf16(Bt[n][k], At[m][k], acc[ai][bj][m][n], 0, 0, 0); __builtin_amdgcn_s_setprio(0); } while (0)
; #define PG8_WAIT_V(n) asm volatile("s_waitcnt vmcnt(" #n ")" ::: "memory")
; #define PG8_WAIT_L(n) asm volatile("s_waitcnt lgkmcnt(" #n ")" ::: "memory")
; #define PG8_BAR __builtin_amdgcn_s_barrier()
; #define PG8_SCHED __builtin_amdgcn_sched_barrier(0)
; template <class Epi, class Sched, bool ALIGN_EPI = false, bool SP2 = false>
; __device__ __forceinline__ void gemm_phase(PG8_LAS unsigned char* lds, const Gemm g, const Sched S, const Epi E) {
;     ...
;         for (int t = 0; t < nt; t += 2) {
;             const bool last = (t == nt - 2);
;             const char* a1 = cA + (size_t)(t + 1) * kstepA;
;             const char* a2 = last ? nA : cA + (size_t)(t + 2) * kstepA; const char* b2 = last ? nB : cB + (size_t)(t + 2) * kstep;
;             const char* a3 = a2 + kstepA; const char* b3 = b2 + kstep;
;     ...
;             PG8_LDA(At, 1, 1); PG8_STAGE(PG8_SB(1, 0), b3, voffB); PG8_STAGE(PG8_SB(1, 1), b3 + hstep, voffB); PG8_STAGE(PG8_SA(1, 0), a3, voffA);
;             PG8_WAIT_V(8); PG8_WAIT_L(0); PG8_BAR; PG8_MMA(1, 0, At, B0); PG8_MMA(1, 1, At, B1); PG8_BAR; PG8_SCHED;
	s_add_i32 s12, s74, s33
	v_lshl_add_u64 v[180:181], v[180:181], 0, s[28:29]
	s_mov_b32 m0, s12
	ds_read_b128 v[174:177], v190 offset:49152
	ds_read_b128 v[184:187], v190 offset:50176
	ds_read_b128 v[192:195], v190 offset:51200
	ds_read_b128 v[196:199], v190 offset:52224
	ds_read_b128 v[200:203], v190 offset:53248
	ds_read_b128 v[204:207], v190 offset:54272
	ds_read_b128 v[208:211], v190 offset:55296
	ds_read_b128 v[212:215], v190 offset:56320
	global_load_lds_dwordx4 v[180:181], off
	s_add_i32 m0, s12, 0x2000
	s_add_u32 s12, s60, 0x100080
	v_lshl_add_u64 v[180:181], v[216:217], 0, s[28:29]
	s_addc_u32 s13, s61, 0
	s_add_i32 s60, s75, s33
	global_load_lds_dwordx4 v[180:181], off
	v_lshl_add_u64 v[180:181], s[12:13], 0, v[162:163]
	s_mov_b32 m0, s60
	s_nop 0
	global_load_lds_dwordx4 v[180:181], off
	v_lshl_add_u64 v[180:181], s[12:13], 0, v[164:165]
	s_add_i32 m0, s60, 0x2000
	s_nop 0
	global_load_lds_dwordx4 v[180:181], off
	v_lshl_add_u64 v[180:181], v[218:219], 0, s[28:29]
	s_mov_b32 m0, s66
	s_nop 0
	global_load_lds_dwordx4 v[180:181], off
	v_lshl_add_u64 v[180:181], v[220:221], 0, s[28:29]
	s_mov_b32 m0, s67
	s_nop 0
	global_load_lds_dwordx4 v[180:181], off
	s_waitcnt vmcnt(8)
	s_waitcnt lgkmcnt(0)
	s_barrier
	s_setprio 1
	s_waitcnt lgkmcnt(0)
	v_mfma_f32_16x16x32_bf16 v[60:63], v[64:67], v[174:177], v[60:63]
	v_mfma_f32_16x16x32_bf16 v[56:59], v[72:75], v[174:177], v[56:59]
	v_mfma_f32_16x16x32_bf16 v[44:47], v[64:67], v[192:195], v[44:47]
	v_mfma_f32_16x16x32_bf16 v[40:43], v[72:75], v[192:195], v[40:43]
	v_mfma_f32_16x16x32_bf16 v[28:31], v[64:67], v[200:203], v[28:31]
	v_mfma_f32_16x16x32_bf16 v[24:27], v[72:75], v[200:203], v[24:27]
	v_mfma_f32_16x16x32_bf16 v[12:15], v[64:67], v[208:211], v[12:15]
	v_mfma_f32_16x16x32_bf16 v[8:11], v[72:75], v[208:211], v[8:11]
	v_mfma_f32_16x16x32_bf16 v[60:63], v[68:71], v[184:187], v[60:63]
	v_mfma_f32_16x16x32_bf16 v[56:59], v[76:79], v[184:187], v[56:59]
	v_mfma_f32_16x16x32_bf16 v[44:47], v[68:71], v[196:199], v[44:47]
	v_mfma_f32_16x16x32_bf16 v[40:43], v[76:79], v[196:199], v[40:43]
	v_mfma_f32_16x16x32_bf16 v[28:31], v[68:71], v[204:207], v[28:31]
	v_mfma_f32_16x16x32_bf16 v[24:27], v[76:79], v[204:207], v[24:27]
	v_mfma_f32_16x16x32_bf16 v[12:15], v[68:71], v[212:215], v[12:15]
	v_mfma_f32_16x16x32_bf16 v[8:11], v[76:79], v[212:215], v[8:11]
	s_setprio 0
	s_setprio 1
	v_mfma_f32_16x16x32_bf16 v[52:55], v[80:83], v[174:177], v[52:55]
	v_mfma_f32_16x16x32_bf16 v[48:51], v[88:91], v[174:177], v[48:51]
	v_mfma_f32_16x16x32_bf16 v[36:39], v[80:83], v[192:195], v[36:39]
	v_mfma_f32_16x16x32_bf16 v[32:35], v[88:91], v[192:195], v[32:35]
	v_mfma_f32_16x16x32_bf16 v[20:23], v[80:83], v[200:203], v[20:23]
	v_mfma_f32_16x16x32_bf16 v[16:19], v[88:91], v[200:203], v[16:19]
	v_mfma_f32_16x16x32_bf16 v[4:7], v[80:83], v[208:211], v[4:7]
	v_mfma_f32_16x16x32_bf16 v[0:3], v[88:91], v[208:211], v[0:3]
	v_mfma_f32_16x16x32_bf16 v[52:55], v[84:87], v[184:187], v[52:55]
	v_mfma_f32_16x16x32_bf16 v[48:51], v[92:95], v[184:187], v[48:51]
	v_mfma_f32_16x16x32_bf16 v[36:39], v[84:87], v[196:199], v[36:39]
	v_mfma_f32_16x16x32_bf16 v[32:35], v[92:95], v[196:199], v[32:35]
	v_mfma_f32_16x16x32_bf16 v[20:23], v[84:87], v[204:207], v[20:23]
	v_mfma_f32_16x16x32_bf16 v[16:19], v[92:95], v[204:207], v[16:19]
	v_mfma_f32_16x16x32_bf16 v[4:7], v[84:87], v[212:215], v[4:7]
	v_mfma_f32_16x16x32_bf16 v[0:3], v[92:95], v[212:215], v[0:3]
	s_setprio 0
	s_add_i32 s73, s73, 2
	s_add_u32 s50, s50, 0x100
	s_addc_u32 s51, s51, 0
	s_add_u32 s71, s71, 0x100
	s_addc_u32 s72, s72, 0
	s_cmp_gt_u32 s73, 61
	s_barrier
	s_cbranch_scc0 .LBB0_3187
	s_and_b64 vcc, exec, s[30:31]
	s_cbranch_vccz .LBB0_3190
	s_barrier
